# on top of v15: in every GEMM load segment the LDS-DMA staging (address math, m0, global_load_lds) is issued before the ds_reads
# speedup vs baseline: 1.0496x; 1.0063x over previous
.LBB0_274:
	s_add_u32 s34, s76, 0xfff80080
	s_addc_u32 s35, s77, -1
	s_cmp_eq_u32 s85, 28
	s_cselect_b32 s79, s0, s35
	s_cselect_b32 s78, s1, s34
	s_cselect_b32 s35, s67, s84
	s_cselect_b32 s34, s69, s83
	v_lshl_add_u64 v[218:219], s[76:77], 0, v[138:139]
	s_add_i32 m0, s54, 0xc000
	s_nop 0
	global_load_lds_dwordx4 v[218:219], off
	v_lshl_add_u64 v[218:219], s[76:77], 0, v[140:141]
	s_add_i32 m0, s54, 0xe000
	s_nop 0
	global_load_lds_dwordx4 v[218:219], off
	ds_read_b128 v[146:149], v153
	ds_read_b128 v[156:159], v153 offset:1024
	ds_read_b128 v[160:163], v153 offset:2048
	ds_read_b128 v[164:167], v153 offset:3072
	ds_read_b128 v[168:171], v154
	ds_read_b128 v[172:175], v154 offset:1024
	ds_read_b128 v[176:179], v154 offset:2048
	ds_read_b128 v[180:183], v154 offset:3072
	ds_read_b128 v[184:187], v155
	ds_read_b128 v[188:191], v155 offset:1024
	ds_read_b128 v[192:195], v155 offset:2048
	ds_read_b128 v[196:199], v155 offset:3072
	ds_read_b128 v[200:203], v155 offset:4096
	ds_read_b128 v[204:207], v155 offset:5120
	ds_read_b128 v[208:211], v155 offset:6144
	ds_read_b128 v[212:215], v155 offset:7168
	s_waitcnt vmcnt(8)
	s_waitcnt lgkmcnt(0)
	s_barrier
	s_setprio 1
	s_waitcnt lgkmcnt(0)
	v_mfma_f32_16x16x32_bf16 v[126:129], v[146:149], v[184:187], v[126:129]
	v_mfma_f32_16x16x32_bf16 v[118:121], v[160:163], v[184:187], v[118:121]
	v_mfma_f32_16x16x32_bf16 v[110:113], v[146:149], v[192:195], v[110:113]
	v_mfma_f32_16x16x32_bf16 v[102:105], v[160:163], v[192:195], v[102:105]
	v_mfma_f32_16x16x32_bf16 v[94:97], v[146:149], v[200:203], v[94:97]
	v_mfma_f32_16x16x32_bf16 v[86:89], v[160:163], v[200:203], v[86:89]
	v_mfma_f32_16x16x32_bf16 v[78:81], v[146:149], v[208:211], v[78:81]
	v_mfma_f32_16x16x32_bf16 v[70:73], v[160:163], v[208:211], v[70:73]
	v_mfma_f32_16x16x32_bf16 v[126:129], v[156:159], v[188:191], v[126:129]
	v_mfma_f32_16x16x32_bf16 v[118:121], v[164:167], v[188:191], v[118:121]
	v_mfma_f32_16x16x32_bf16 v[110:113], v[156:159], v[196:199], v[110:113]
	v_mfma_f32_16x16x32_bf16 v[102:105], v[164:167], v[196:199], v[102:105]
	v_mfma_f32_16x16x32_bf16 v[94:97], v[156:159], v[204:207], v[94:97]
	v_mfma_f32_16x16x32_bf16 v[86:89], v[164:167], v[204:207], v[86:89]
	v_mfma_f32_16x16x32_bf16 v[78:81], v[156:159], v[212:215], v[78:81]
	v_mfma_f32_16x16x32_bf16 v[70:73], v[164:167], v[212:215], v[70:73]
	s_setprio 0
	s_setprio 1
	v_mfma_f32_16x16x32_bf16 v[122:125], v[168:171], v[184:187], v[122:125]
	v_mfma_f32_16x16x32_bf16 v[114:117], v[176:179], v[184:187], v[114:117]
	v_mfma_f32_16x16x32_bf16 v[106:109], v[168:171], v[192:195], v[106:109]
	v_mfma_f32_16x16x32_bf16 v[98:101], v[176:179], v[192:195], v[98:101]
	v_mfma_f32_16x16x32_bf16 v[90:93], v[168:171], v[200:203], v[90:93]
	v_mfma_f32_16x16x32_bf16 v[82:85], v[176:179], v[200:203], v[82:85]
	v_mfma_f32_16x16x32_bf16 v[74:77], v[168:171], v[208:211], v[74:77]
	v_mfma_f32_16x16x32_bf16 v[66:69], v[176:179], v[208:211], v[66:69]
	v_mfma_f32_16x16x32_bf16 v[122:125], v[172:175], v[188:191], v[122:125]
	v_mfma_f32_16x16x32_bf16 v[114:117], v[180:183], v[188:191], v[114:117]
	v_mfma_f32_16x16x32_bf16 v[106:109], v[172:175], v[196:199], v[106:109]
	v_mfma_f32_16x16x32_bf16 v[98:101], v[180:183], v[196:199], v[98:101]
	v_mfma_f32_16x16x32_bf16 v[90:93], v[172:175], v[204:207], v[90:93]
	v_mfma_f32_16x16x32_bf16 v[82:85], v[180:183], v[204:207], v[82:85]
	v_mfma_f32_16x16x32_bf16 v[74:77], v[172:175], v[212:215], v[74:77]
	v_mfma_f32_16x16x32_bf16 v[66:69], v[180:183], v[212:215], v[66:69]
	s_setprio 0
	s_barrier
	s_add_i32 s62, s75, s33
	v_lshl_add_u64 v[218:219], s[34:35], 0, v[134:135]
	s_mov_b32 m0, s62
	s_nop 0
	global_load_lds_dwordx4 v[218:219], off
	s_add_i32 m0, s62, 0x2000
	s_add_u32 s62, s34, 0x80000
	v_lshl_add_u64 v[220:221], s[34:35], 0, v[130:131]
	s_addc_u32 s63, s35, 0
	s_add_i32 s86, s80, s33
	global_load_lds_dwordx4 v[220:221], off
	v_lshl_add_u64 v[222:223], s[62:63], 0, v[134:135]
	s_mov_b32 m0, s86
	v_lshl_add_u64 v[224:225], s[78:79], 0, v[132:133]
	global_load_lds_dwordx4 v[222:223], off
	v_lshl_add_u64 v[222:223], s[62:63], 0, v[130:131]
	s_add_i32 m0, s86, 0x2000
	s_nop 0
	global_load_lds_dwordx4 v[222:223], off
	v_lshl_add_u64 v[222:223], s[78:79], 0, v[136:137]
	s_mov_b32 m0, s54
	s_nop 0
	global_load_lds_dwordx4 v[222:223], off
	s_mov_b32 m0, s55
	s_nop 0
	global_load_lds_dwordx4 v[224:225], off
	ds_read_b128 v[184:187], v155 offset:16384
	ds_read_b128 v[188:191], v155 offset:17408
	ds_read_b128 v[192:195], v155 offset:18432
	ds_read_b128 v[196:199], v155 offset:19456
	ds_read_b128 v[200:203], v155 offset:20480
	ds_read_b128 v[204:207], v155 offset:21504
	ds_read_b128 v[208:211], v155 offset:22528
	ds_read_b128 v[212:215], v155 offset:23552
	s_waitcnt vmcnt(8)
	s_waitcnt lgkmcnt(0)
	s_barrier
	s_setprio 1
	s_waitcnt lgkmcnt(0)
	v_mfma_f32_16x16x32_bf16 v[62:65], v[146:149], v[184:187], v[62:65]
	v_mfma_f32_16x16x32_bf16 v[54:57], v[160:163], v[184:187], v[54:57]
	v_mfma_f32_16x16x32_bf16 v[46:49], v[146:149], v[192:195], v[46:49]
	v_mfma_f32_16x16x32_bf16 v[38:41], v[160:163], v[192:195], v[38:41]
	v_mfma_f32_16x16x32_bf16 v[30:33], v[146:149], v[200:203], v[30:33]
	v_mfma_f32_16x16x32_bf16 v[22:25], v[160:163], v[200:203], v[22:25]
	v_mfma_f32_16x16x32_bf16 v[14:17], v[146:149], v[208:211], v[14:17]
	v_mfma_f32_16x16x32_bf16 v[6:9], v[160:163], v[208:211], v[6:9]
	v_mfma_f32_16x16x32_bf16 v[62:65], v[156:159], v[188:191], v[62:65]
	v_mfma_f32_16x16x32_bf16 v[54:57], v[164:167], v[188:191], v[54:57]
	v_mfma_f32_16x16x32_bf16 v[46:49], v[156:159], v[196:199], v[46:49]
	v_mfma_f32_16x16x32_bf16 v[38:41], v[164:167], v[196:199], v[38:41]
	v_mfma_f32_16x16x32_bf16 v[30:33], v[156:159], v[204:207], v[30:33]
	v_mfma_f32_16x16x32_bf16 v[22:25], v[164:167], v[204:207], v[22:25]
	v_mfma_f32_16x16x32_bf16 v[14:17], v[156:159], v[212:215], v[14:17]
	v_mfma_f32_16x16x32_bf16 v[6:9], v[164:167], v[212:215], v[6:9]
	s_setprio 0
	s_setprio 1
	v_mfma_f32_16x16x32_bf16 v[58:61], v[168:171], v[184:187], v[58:61]
	v_mfma_f32_16x16x32_bf16 v[50:53], v[176:179], v[184:187], v[50:53]
	v_mfma_f32_16x16x32_bf16 v[42:45], v[168:171], v[192:195], v[42:45]
	v_mfma_f32_16x16x32_bf16 v[34:37], v[176:179], v[192:195], v[34:37]
	v_mfma_f32_16x16x32_bf16 v[26:29], v[168:171], v[200:203], v[26:29]
	v_mfma_f32_16x16x32_bf16 v[18:21], v[176:179], v[200:203], v[18:21]
	v_mfma_f32_16x16x32_bf16 v[10:13], v[168:171], v[208:211], v[10:13]
	v_mfma_f32_16x16x32_bf16 v[2:5], v[176:179], v[208:211], v[2:5]
	v_mfma_f32_16x16x32_bf16 v[58:61], v[172:175], v[188:191], v[58:61]
	v_mfma_f32_16x16x32_bf16 v[50:53], v[180:183], v[188:191], v[50:53]
	v_mfma_f32_16x16x32_bf16 v[42:45], v[172:175], v[196:199], v[42:45]
	v_mfma_f32_16x16x32_bf16 v[34:37], v[180:183], v[196:199], v[34:37]
	v_mfma_f32_16x16x32_bf16 v[26:29], v[172:175], v[204:207], v[26:29]
	v_mfma_f32_16x16x32_bf16 v[18:21], v[180:183], v[204:207], v[18:21]
	v_mfma_f32_16x16x32_bf16 v[10:13], v[172:175], v[212:215], v[10:13]
	v_mfma_f32_16x16x32_bf16 v[2:5], v[180:183], v[212:215], v[2:5]
	s_setprio 0
	s_barrier
	s_add_i32 s86, 0, 0x18000
	s_add_i32 s87, 0, 0x1c000
	s_add_u32 s62, s78, 0x80000
	s_addc_u32 s63, s79, 0
	s_mov_b32 m0, s56
	v_lshl_add_u64 v[226:227], s[62:63], 0, v[136:137]
	global_load_lds_dwordx4 v[226:227], off
	v_lshl_add_u64 v[226:227], s[62:63], 0, v[132:133]
	s_mov_b32 m0, s57
	s_nop 0
	global_load_lds_dwordx4 v[226:227], off
	v_add_u32_e32 v164, s86, v151
	v_add_u32_e32 v180, s87, v151
	ds_read_b128 v[146:149], v164
	ds_read_b128 v[156:159], v164 offset:1024
	ds_read_b128 v[160:163], v164 offset:2048
	ds_read_b128 v[164:167], v164 offset:3072
	ds_read_b128 v[168:171], v180
	ds_read_b128 v[172:175], v180 offset:1024
	ds_read_b128 v[176:179], v180 offset:2048
	ds_read_b128 v[180:183], v180 offset:3072
	ds_read_b128 v[184:187], v155 offset:32768
	ds_read_b128 v[188:191], v155 offset:33792
	ds_read_b128 v[192:195], v155 offset:34816
	ds_read_b128 v[196:199], v155 offset:35840
	ds_read_b128 v[200:203], v155 offset:36864
	ds_read_b128 v[204:207], v155 offset:37888
	ds_read_b128 v[208:211], v155 offset:38912
	ds_read_b128 v[212:215], v155 offset:39936
	s_waitcnt vmcnt(8)
	s_waitcnt lgkmcnt(0)
	s_barrier
	s_setprio 1
	s_waitcnt lgkmcnt(0)
	v_mfma_f32_16x16x32_bf16 v[126:129], v[146:149], v[184:187], v[126:129]
	v_mfma_f32_16x16x32_bf16 v[118:121], v[160:163], v[184:187], v[118:121]
	v_mfma_f32_16x16x32_bf16 v[110:113], v[146:149], v[192:195], v[110:113]
	v_mfma_f32_16x16x32_bf16 v[102:105], v[160:163], v[192:195], v[102:105]
	v_mfma_f32_16x16x32_bf16 v[94:97], v[146:149], v[200:203], v[94:97]
	v_mfma_f32_16x16x32_bf16 v[86:89], v[160:163], v[200:203], v[86:89]
	v_mfma_f32_16x16x32_bf16 v[78:81], v[146:149], v[208:211], v[78:81]
	v_mfma_f32_16x16x32_bf16 v[70:73], v[160:163], v[208:211], v[70:73]
	v_mfma_f32_16x16x32_bf16 v[126:129], v[156:159], v[188:191], v[126:129]
	v_mfma_f32_16x16x32_bf16 v[118:121], v[164:167], v[188:191], v[118:121]
	v_mfma_f32_16x16x32_bf16 v[110:113], v[156:159], v[196:199], v[110:113]
	v_mfma_f32_16x16x32_bf16 v[102:105], v[164:167], v[196:199], v[102:105]
	v_mfma_f32_16x16x32_bf16 v[94:97], v[156:159], v[204:207], v[94:97]
	v_mfma_f32_16x16x32_bf16 v[86:89], v[164:167], v[204:207], v[86:89]
	v_mfma_f32_16x16x32_bf16 v[78:81], v[156:159], v[212:215], v[78:81]
	v_mfma_f32_16x16x32_bf16 v[70:73], v[164:167], v[212:215], v[70:73]
	s_setprio 0
	s_setprio 1
	v_mfma_f32_16x16x32_bf16 v[122:125], v[168:171], v[184:187], v[122:125]
	v_mfma_f32_16x16x32_bf16 v[114:117], v[176:179], v[184:187], v[114:117]
	v_mfma_f32_16x16x32_bf16 v[106:109], v[168:171], v[192:195], v[106:109]
	v_mfma_f32_16x16x32_bf16 v[98:101], v[176:179], v[192:195], v[98:101]
	v_mfma_f32_16x16x32_bf16 v[90:93], v[168:171], v[200:203], v[90:93]
	v_mfma_f32_16x16x32_bf16 v[82:85], v[176:179], v[200:203], v[82:85]
	v_mfma_f32_16x16x32_bf16 v[74:77], v[168:171], v[208:211], v[74:77]
	v_mfma_f32_16x16x32_bf16 v[66:69], v[176:179], v[208:211], v[66:69]
	v_mfma_f32_16x16x32_bf16 v[122:125], v[172:175], v[188:191], v[122:125]
	v_mfma_f32_16x16x32_bf16 v[114:117], v[180:183], v[188:191], v[114:117]
	v_mfma_f32_16x16x32_bf16 v[106:109], v[172:175], v[196:199], v[106:109]
	v_mfma_f32_16x16x32_bf16 v[98:101], v[180:183], v[196:199], v[98:101]
	v_mfma_f32_16x16x32_bf16 v[90:93], v[172:175], v[204:207], v[90:93]
	v_mfma_f32_16x16x32_bf16 v[82:85], v[180:183], v[204:207], v[82:85]
	v_mfma_f32_16x16x32_bf16 v[74:77], v[172:175], v[212:215], v[74:77]
	v_mfma_f32_16x16x32_bf16 v[66:69], v[180:183], v[212:215], v[66:69]
	s_setprio 0
	s_barrier
	s_add_i32 s62, s86, s33
	v_lshl_add_u64 v[218:219], v[218:219], 0, s[8:9]
	s_mov_b32 m0, s62
	s_nop 0
	global_load_lds_dwordx4 v[218:219], off
	s_add_i32 m0, s62, 0x2000
	s_add_u32 s34, s34, 0x80080
	v_lshl_add_u64 v[218:219], v[220:221], 0, s[8:9]
	s_addc_u32 s35, s35, 0
	s_add_i32 s62, s87, s33
	global_load_lds_dwordx4 v[218:219], off
	v_lshl_add_u64 v[218:219], s[34:35], 0, v[134:135]
	s_mov_b32 m0, s62
	s_nop 0
	global_load_lds_dwordx4 v[218:219], off
	v_lshl_add_u64 v[218:219], s[34:35], 0, v[130:131]
	s_add_i32 m0, s62, 0x2000
	s_nop 0
	global_load_lds_dwordx4 v[218:219], off
	v_lshl_add_u64 v[218:219], v[222:223], 0, s[8:9]
	s_mov_b32 m0, s59
	s_nop 0
	global_load_lds_dwordx4 v[218:219], off
	v_lshl_add_u64 v[218:219], v[224:225], 0, s[8:9]
	s_mov_b32 m0, s60
	s_nop 0
	global_load_lds_dwordx4 v[218:219], off
	ds_read_b128 v[184:187], v155 offset:49152
	ds_read_b128 v[188:191], v155 offset:50176
	ds_read_b128 v[192:195], v155 offset:51200
	ds_read_b128 v[196:199], v155 offset:52224
	ds_read_b128 v[200:203], v155 offset:53248
	ds_read_b128 v[204:207], v155 offset:54272
	ds_read_b128 v[208:211], v155 offset:55296
	ds_read_b128 v[212:215], v155 offset:56320
	s_waitcnt vmcnt(8)
	s_waitcnt lgkmcnt(0)
	s_barrier
	s_setprio 1
	s_waitcnt lgkmcnt(0)
	v_mfma_f32_16x16x32_bf16 v[62:65], v[146:149], v[184:187], v[62:65]
	v_mfma_f32_16x16x32_bf16 v[54:57], v[160:163], v[184:187], v[54:57]
	v_mfma_f32_16x16x32_bf16 v[46:49], v[146:149], v[192:195], v[46:49]
	v_mfma_f32_16x16x32_bf16 v[38:41], v[160:163], v[192:195], v[38:41]
	v_mfma_f32_16x16x32_bf16 v[30:33], v[146:149], v[200:203], v[30:33]
	v_mfma_f32_16x16x32_bf16 v[22:25], v[160:163], v[200:203], v[22:25]
	v_mfma_f32_16x16x32_bf16 v[14:17], v[146:149], v[208:211], v[14:17]
	v_mfma_f32_16x16x32_bf16 v[6:9], v[160:163], v[208:211], v[6:9]
	v_mfma_f32_16x16x32_bf16 v[62:65], v[156:159], v[188:191], v[62:65]
	v_mfma_f32_16x16x32_bf16 v[54:57], v[164:167], v[188:191], v[54:57]
	v_mfma_f32_16x16x32_bf16 v[46:49], v[156:159], v[196:199], v[46:49]
	v_mfma_f32_16x16x32_bf16 v[38:41], v[164:167], v[196:199], v[38:41]
	v_mfma_f32_16x16x32_bf16 v[30:33], v[156:159], v[204:207], v[30:33]
	v_mfma_f32_16x16x32_bf16 v[22:25], v[164:167], v[204:207], v[22:25]
	v_mfma_f32_16x16x32_bf16 v[14:17], v[156:159], v[212:215], v[14:17]
	v_mfma_f32_16x16x32_bf16 v[6:9], v[164:167], v[212:215], v[6:9]
	s_setprio 0
	s_setprio 1
	v_mfma_f32_16x16x32_bf16 v[58:61], v[168:171], v[184:187], v[58:61]
	v_mfma_f32_16x16x32_bf16 v[50:53], v[176:179], v[184:187], v[50:53]
	v_mfma_f32_16x16x32_bf16 v[42:45], v[168:171], v[192:195], v[42:45]
	v_mfma_f32_16x16x32_bf16 v[34:37], v[176:179], v[192:195], v[34:37]
	v_mfma_f32_16x16x32_bf16 v[26:29], v[168:171], v[200:203], v[26:29]
	v_mfma_f32_16x16x32_bf16 v[18:21], v[176:179], v[200:203], v[18:21]
	v_mfma_f32_16x16x32_bf16 v[10:13], v[168:171], v[208:211], v[10:13]
	v_mfma_f32_16x16x32_bf16 v[2:5], v[176:179], v[208:211], v[2:5]
	v_mfma_f32_16x16x32_bf16 v[58:61], v[172:175], v[188:191], v[58:61]
	v_mfma_f32_16x16x32_bf16 v[50:53], v[180:183], v[188:191], v[50:53]
	v_mfma_f32_16x16x32_bf16 v[42:45], v[172:175], v[196:199], v[42:45]
	v_mfma_f32_16x16x32_bf16 v[34:37], v[180:183], v[196:199], v[34:37]
	v_mfma_f32_16x16x32_bf16 v[26:29], v[172:175], v[204:207], v[26:29]
	v_mfma_f32_16x16x32_bf16 v[18:21], v[180:183], v[204:207], v[18:21]
	v_mfma_f32_16x16x32_bf16 v[10:13], v[172:175], v[212:215], v[10:13]
	v_mfma_f32_16x16x32_bf16 v[2:5], v[180:183], v[212:215], v[2:5]
	s_setprio 0
	s_barrier
	s_add_i32 s85, s85, 2
	s_add_u32 s76, s76, 0x100
	s_addc_u32 s77, s77, 0
	s_add_u32 s83, s83, 0x100
	s_addc_u32 s84, s84, 0
	s_cmp_gt_u32 s85, 29
	s_cbranch_scc0 .LBB0_274
	s_and_b64 vcc, exec, s[64:65]
	s_cbranch_vccz .LBB0_277
	s_barrier

.LBB0_387:
	s_add_u32 s34, s72, 0xffea0080
	s_addc_u32 s35, s73, -1
	s_cmpk_eq_i32 s81, 0x54
	s_cselect_b32 s75, s5, s35
	s_cselect_b32 s74, s4, s34
	s_cselect_b32 s35, s71, s1
	s_cselect_b32 s34, s70, s0
	v_lshl_add_u64 v[150:151], s[72:73], 0, v[138:139]
	s_add_i32 m0, s53, 0xc000
	s_nop 0
	global_load_lds_dwordx4 v[150:151], off
	v_lshl_add_u64 v[150:151], s[72:73], 0, v[140:141]
	s_add_i32 m0, s53, 0xe000
	s_nop 0
	global_load_lds_dwordx4 v[150:151], off
	ds_read_b128 v[146:149], v154
	ds_read_b128 v[158:161], v154 offset:1024
	ds_read_b128 v[162:165], v154 offset:2048
	ds_read_b128 v[166:169], v154 offset:3072
	ds_read_b128 v[170:173], v155
	ds_read_b128 v[174:177], v155 offset:1024
	ds_read_b128 v[178:181], v155 offset:2048
	ds_read_b128 v[182:185], v155 offset:3072
	ds_read_b128 v[186:189], v156
	ds_read_b128 v[190:193], v156 offset:1024
	ds_read_b128 v[194:197], v156 offset:2048
	ds_read_b128 v[198:201], v156 offset:3072
	ds_read_b128 v[202:205], v156 offset:4096
	ds_read_b128 v[206:209], v156 offset:5120
	ds_read_b128 v[210:213], v156 offset:6144
	ds_read_b128 v[218:221], v156 offset:7168
	s_waitcnt vmcnt(8)
	s_waitcnt lgkmcnt(0)
	s_barrier
	s_setprio 1
	s_waitcnt lgkmcnt(0)
	v_mfma_f32_16x16x32_bf16 v[126:129], v[146:149], v[186:189], v[126:129]
	v_mfma_f32_16x16x32_bf16 v[122:125], v[162:165], v[186:189], v[122:125]
	v_mfma_f32_16x16x32_bf16 v[118:121], v[146:149], v[194:197], v[118:121]
	v_mfma_f32_16x16x32_bf16 v[114:117], v[162:165], v[194:197], v[114:117]
	v_mfma_f32_16x16x32_bf16 v[94:97], v[146:149], v[202:205], v[94:97]
	v_mfma_f32_16x16x32_bf16 v[90:93], v[162:165], v[202:205], v[90:93]
	v_mfma_f32_16x16x32_bf16 v[86:89], v[146:149], v[210:213], v[86:89]
	v_mfma_f32_16x16x32_bf16 v[82:85], v[162:165], v[210:213], v[82:85]
	v_mfma_f32_16x16x32_bf16 v[126:129], v[158:161], v[190:193], v[126:129]
	v_mfma_f32_16x16x32_bf16 v[122:125], v[166:169], v[190:193], v[122:125]
	v_mfma_f32_16x16x32_bf16 v[118:121], v[158:161], v[198:201], v[118:121]
	v_mfma_f32_16x16x32_bf16 v[114:117], v[166:169], v[198:201], v[114:117]
	v_mfma_f32_16x16x32_bf16 v[94:97], v[158:161], v[206:209], v[94:97]
	v_mfma_f32_16x16x32_bf16 v[90:93], v[166:169], v[206:209], v[90:93]
	v_mfma_f32_16x16x32_bf16 v[86:89], v[158:161], v[218:221], v[86:89]
	v_mfma_f32_16x16x32_bf16 v[82:85], v[166:169], v[218:221], v[82:85]
	s_setprio 0
	s_setprio 1
	v_mfma_f32_16x16x32_bf16 v[110:113], v[170:173], v[186:189], v[110:113]
	v_mfma_f32_16x16x32_bf16 v[106:109], v[178:181], v[186:189], v[106:109]
	v_mfma_f32_16x16x32_bf16 v[102:105], v[170:173], v[194:197], v[102:105]
	v_mfma_f32_16x16x32_bf16 v[98:101], v[178:181], v[194:197], v[98:101]
	v_mfma_f32_16x16x32_bf16 v[78:81], v[170:173], v[202:205], v[78:81]
	v_mfma_f32_16x16x32_bf16 v[74:77], v[178:181], v[202:205], v[74:77]
	v_mfma_f32_16x16x32_bf16 v[70:73], v[170:173], v[210:213], v[70:73]
	v_mfma_f32_16x16x32_bf16 v[66:69], v[178:181], v[210:213], v[66:69]
	v_mfma_f32_16x16x32_bf16 v[110:113], v[174:177], v[190:193], v[110:113]
	v_mfma_f32_16x16x32_bf16 v[106:109], v[182:185], v[190:193], v[106:109]
	v_mfma_f32_16x16x32_bf16 v[102:105], v[174:177], v[198:201], v[102:105]
	v_mfma_f32_16x16x32_bf16 v[98:101], v[182:185], v[198:201], v[98:101]
	v_mfma_f32_16x16x32_bf16 v[78:81], v[174:177], v[206:209], v[78:81]
	v_mfma_f32_16x16x32_bf16 v[74:77], v[182:185], v[206:209], v[74:77]
	v_mfma_f32_16x16x32_bf16 v[70:73], v[174:177], v[218:221], v[70:73]
	v_mfma_f32_16x16x32_bf16 v[66:69], v[182:185], v[218:221], v[66:69]
	s_setprio 0
	s_barrier
	s_add_i32 s62, s61, s52
	v_lshl_add_u64 v[150:151], s[34:35], 0, v[132:133]
	s_mov_b32 m0, s62
	s_nop 0
	global_load_lds_dwordx4 v[150:151], off
	s_add_i32 m0, s62, 0x2000
	s_add_u32 s62, s34, 0x160000
	v_lshl_add_u64 v[214:215], s[34:35], 0, v[136:137]
	s_addc_u32 s63, s35, 0
	s_add_i32 s82, s76, s52
	global_load_lds_dwordx4 v[214:215], off
	v_lshl_add_u64 v[222:223], s[62:63], 0, v[132:133]
	s_mov_b32 m0, s82
	v_lshl_add_u64 v[224:225], s[74:75], 0, v[134:135]
	global_load_lds_dwordx4 v[222:223], off
	v_lshl_add_u64 v[222:223], s[62:63], 0, v[136:137]
	s_add_i32 m0, s82, 0x2000
	s_nop 0
	global_load_lds_dwordx4 v[222:223], off
	v_lshl_add_u64 v[222:223], s[74:75], 0, v[130:131]
	s_mov_b32 m0, s53
	s_nop 0
	global_load_lds_dwordx4 v[222:223], off
	s_mov_b32 m0, s54
	s_nop 0
	global_load_lds_dwordx4 v[224:225], off
	ds_read_b128 v[186:189], v156 offset:16384
	ds_read_b128 v[190:193], v156 offset:17408
	ds_read_b128 v[194:197], v156 offset:18432
	ds_read_b128 v[198:201], v156 offset:19456
	ds_read_b128 v[202:205], v156 offset:20480
	ds_read_b128 v[206:209], v156 offset:21504
	ds_read_b128 v[210:213], v156 offset:22528
	ds_read_b128 v[218:221], v156 offset:23552
	s_waitcnt vmcnt(8)
	s_waitcnt lgkmcnt(0)
	s_barrier
	s_setprio 1
	s_waitcnt lgkmcnt(0)
	v_mfma_f32_16x16x32_bf16 v[62:65], v[146:149], v[186:189], v[62:65]
	v_mfma_f32_16x16x32_bf16 v[58:61], v[162:165], v[186:189], v[58:61]
	v_mfma_f32_16x16x32_bf16 v[54:57], v[146:149], v[194:197], v[54:57]
	v_mfma_f32_16x16x32_bf16 v[50:53], v[162:165], v[194:197], v[50:53]
	v_mfma_f32_16x16x32_bf16 v[30:33], v[146:149], v[202:205], v[30:33]
	v_mfma_f32_16x16x32_bf16 v[26:29], v[162:165], v[202:205], v[26:29]
	v_mfma_f32_16x16x32_bf16 v[22:25], v[146:149], v[210:213], v[22:25]
	v_mfma_f32_16x16x32_bf16 v[18:21], v[162:165], v[210:213], v[18:21]
	v_mfma_f32_16x16x32_bf16 v[62:65], v[158:161], v[190:193], v[62:65]
	v_mfma_f32_16x16x32_bf16 v[58:61], v[166:169], v[190:193], v[58:61]
	v_mfma_f32_16x16x32_bf16 v[54:57], v[158:161], v[198:201], v[54:57]
	v_mfma_f32_16x16x32_bf16 v[50:53], v[166:169], v[198:201], v[50:53]
	v_mfma_f32_16x16x32_bf16 v[30:33], v[158:161], v[206:209], v[30:33]
	v_mfma_f32_16x16x32_bf16 v[26:29], v[166:169], v[206:209], v[26:29]
	v_mfma_f32_16x16x32_bf16 v[22:25], v[158:161], v[218:221], v[22:25]
	v_mfma_f32_16x16x32_bf16 v[18:21], v[166:169], v[218:221], v[18:21]
	s_setprio 0
	s_setprio 1
	v_mfma_f32_16x16x32_bf16 v[46:49], v[170:173], v[186:189], v[46:49]
	v_mfma_f32_16x16x32_bf16 v[42:45], v[178:181], v[186:189], v[42:45]
	v_mfma_f32_16x16x32_bf16 v[38:41], v[170:173], v[194:197], v[38:41]
	v_mfma_f32_16x16x32_bf16 v[34:37], v[178:181], v[194:197], v[34:37]
	v_mfma_f32_16x16x32_bf16 v[14:17], v[170:173], v[202:205], v[14:17]
	v_mfma_f32_16x16x32_bf16 v[10:13], v[178:181], v[202:205], v[10:13]
	v_mfma_f32_16x16x32_bf16 v[6:9], v[170:173], v[210:213], v[6:9]
	v_mfma_f32_16x16x32_bf16 v[2:5], v[178:181], v[210:213], v[2:5]
	v_mfma_f32_16x16x32_bf16 v[46:49], v[174:177], v[190:193], v[46:49]
	v_mfma_f32_16x16x32_bf16 v[42:45], v[182:185], v[190:193], v[42:45]
	v_mfma_f32_16x16x32_bf16 v[38:41], v[174:177], v[198:201], v[38:41]
	v_mfma_f32_16x16x32_bf16 v[34:37], v[182:185], v[198:201], v[34:37]
	v_mfma_f32_16x16x32_bf16 v[14:17], v[174:177], v[206:209], v[14:17]
	v_mfma_f32_16x16x32_bf16 v[10:13], v[182:185], v[206:209], v[10:13]
	v_mfma_f32_16x16x32_bf16 v[6:9], v[174:177], v[218:221], v[6:9]
	v_mfma_f32_16x16x32_bf16 v[2:5], v[182:185], v[218:221], v[2:5]
	s_setprio 0
	s_barrier
	s_add_i32 s82, 0, 0x18000
	s_add_i32 s83, 0, 0x1c000
	s_add_u32 s62, s74, 0x160000
	s_addc_u32 s63, s75, 0
	s_mov_b32 m0, s55
	v_lshl_add_u64 v[226:227], s[62:63], 0, v[130:131]
	global_load_lds_dwordx4 v[226:227], off
	v_lshl_add_u64 v[226:227], s[62:63], 0, v[134:135]
	s_mov_b32 m0, s56
	s_nop 0
	global_load_lds_dwordx4 v[226:227], off
	v_add_u32_e32 v157, s82, v152
	ds_read_b128 v[146:149], v157
	ds_read_b128 v[158:161], v157 offset:1024
	ds_read_b128 v[162:165], v157 offset:2048
	ds_read_b128 v[166:169], v157 offset:3072
	v_add_u32_e32 v157, s83, v152
	ds_read_b128 v[170:173], v157
	ds_read_b128 v[174:177], v157 offset:1024
	ds_read_b128 v[178:181], v157 offset:2048
	ds_read_b128 v[182:185], v157 offset:3072
	ds_read_b128 v[186:189], v156 offset:32768
	ds_read_b128 v[190:193], v156 offset:33792
	ds_read_b128 v[194:197], v156 offset:34816
	ds_read_b128 v[198:201], v156 offset:35840
	ds_read_b128 v[202:205], v156 offset:36864
	ds_read_b128 v[206:209], v156 offset:37888
	ds_read_b128 v[210:213], v156 offset:38912
	ds_read_b128 v[218:221], v156 offset:39936
	s_waitcnt vmcnt(8)
	s_waitcnt lgkmcnt(0)
	s_barrier
	s_setprio 1
	s_waitcnt lgkmcnt(0)
	v_mfma_f32_16x16x32_bf16 v[126:129], v[146:149], v[186:189], v[126:129]
	v_mfma_f32_16x16x32_bf16 v[122:125], v[162:165], v[186:189], v[122:125]
	v_mfma_f32_16x16x32_bf16 v[118:121], v[146:149], v[194:197], v[118:121]
	v_mfma_f32_16x16x32_bf16 v[114:117], v[162:165], v[194:197], v[114:117]
	v_mfma_f32_16x16x32_bf16 v[94:97], v[146:149], v[202:205], v[94:97]
	v_mfma_f32_16x16x32_bf16 v[90:93], v[162:165], v[202:205], v[90:93]
	v_mfma_f32_16x16x32_bf16 v[86:89], v[146:149], v[210:213], v[86:89]
	v_mfma_f32_16x16x32_bf16 v[82:85], v[162:165], v[210:213], v[82:85]
	v_mfma_f32_16x16x32_bf16 v[126:129], v[158:161], v[190:193], v[126:129]
	v_mfma_f32_16x16x32_bf16 v[122:125], v[166:169], v[190:193], v[122:125]
	v_mfma_f32_16x16x32_bf16 v[118:121], v[158:161], v[198:201], v[118:121]
	v_mfma_f32_16x16x32_bf16 v[114:117], v[166:169], v[198:201], v[114:117]
	v_mfma_f32_16x16x32_bf16 v[94:97], v[158:161], v[206:209], v[94:97]
	v_mfma_f32_16x16x32_bf16 v[90:93], v[166:169], v[206:209], v[90:93]
	v_mfma_f32_16x16x32_bf16 v[86:89], v[158:161], v[218:221], v[86:89]
	v_mfma_f32_16x16x32_bf16 v[82:85], v[166:169], v[218:221], v[82:85]
	s_setprio 0
	s_setprio 1
	v_mfma_f32_16x16x32_bf16 v[110:113], v[170:173], v[186:189], v[110:113]
	v_mfma_f32_16x16x32_bf16 v[106:109], v[178:181], v[186:189], v[106:109]
	v_mfma_f32_16x16x32_bf16 v[102:105], v[170:173], v[194:197], v[102:105]
	v_mfma_f32_16x16x32_bf16 v[98:101], v[178:181], v[194:197], v[98:101]
	v_mfma_f32_16x16x32_bf16 v[78:81], v[170:173], v[202:205], v[78:81]
	v_mfma_f32_16x16x32_bf16 v[74:77], v[178:181], v[202:205], v[74:77]
	v_mfma_f32_16x16x32_bf16 v[70:73], v[170:173], v[210:213], v[70:73]
	v_mfma_f32_16x16x32_bf16 v[66:69], v[178:181], v[210:213], v[66:69]
	v_mfma_f32_16x16x32_bf16 v[110:113], v[174:177], v[190:193], v[110:113]
	v_mfma_f32_16x16x32_bf16 v[106:109], v[182:185], v[190:193], v[106:109]
	v_mfma_f32_16x16x32_bf16 v[102:105], v[174:177], v[198:201], v[102:105]
	v_mfma_f32_16x16x32_bf16 v[98:101], v[182:185], v[198:201], v[98:101]
	v_mfma_f32_16x16x32_bf16 v[78:81], v[174:177], v[206:209], v[78:81]
	v_mfma_f32_16x16x32_bf16 v[74:77], v[182:185], v[206:209], v[74:77]
	v_mfma_f32_16x16x32_bf16 v[70:73], v[174:177], v[218:221], v[70:73]
	v_mfma_f32_16x16x32_bf16 v[66:69], v[182:185], v[218:221], v[66:69]
	s_setprio 0
	s_barrier
	s_add_i32 s62, s82, s52
	v_lshl_add_u64 v[150:151], v[150:151], 0, s[66:67]
	s_mov_b32 m0, s62
	s_nop 0
	global_load_lds_dwordx4 v[150:151], off
	s_add_i32 m0, s62, 0x2000
	s_add_u32 s34, s34, 0x160080
	v_lshl_add_u64 v[150:151], v[214:215], 0, s[66:67]
	s_addc_u32 s35, s35, 0
	s_add_i32 s62, s83, s52
	global_load_lds_dwordx4 v[150:151], off
	v_lshl_add_u64 v[150:151], s[34:35], 0, v[132:133]
	s_mov_b32 m0, s62
	s_nop 0
	global_load_lds_dwordx4 v[150:151], off
	v_lshl_add_u64 v[150:151], s[34:35], 0, v[136:137]
	s_add_i32 m0, s62, 0x2000
	s_nop 0
	global_load_lds_dwordx4 v[150:151], off
	v_lshl_add_u64 v[150:151], v[222:223], 0, s[66:67]
	s_mov_b32 m0, s58
	s_nop 0
	global_load_lds_dwordx4 v[150:151], off
	v_lshl_add_u64 v[150:151], v[224:225], 0, s[66:67]
	s_mov_b32 m0, s59
	s_nop 0
	global_load_lds_dwordx4 v[150:151], off
	ds_read_b128 v[186:189], v156 offset:49152
	ds_read_b128 v[190:193], v156 offset:50176
	ds_read_b128 v[194:197], v156 offset:51200
	ds_read_b128 v[198:201], v156 offset:52224
	ds_read_b128 v[202:205], v156 offset:53248
	ds_read_b128 v[206:209], v156 offset:54272
	ds_read_b128 v[210:213], v156 offset:55296
	ds_read_b128 v[218:221], v156 offset:56320
	s_waitcnt vmcnt(8)
	s_waitcnt lgkmcnt(0)
	s_barrier
	s_setprio 1
	s_waitcnt lgkmcnt(0)
	v_mfma_f32_16x16x32_bf16 v[62:65], v[146:149], v[186:189], v[62:65]
	v_mfma_f32_16x16x32_bf16 v[58:61], v[162:165], v[186:189], v[58:61]
	v_mfma_f32_16x16x32_bf16 v[54:57], v[146:149], v[194:197], v[54:57]
	v_mfma_f32_16x16x32_bf16 v[50:53], v[162:165], v[194:197], v[50:53]
	v_mfma_f32_16x16x32_bf16 v[30:33], v[146:149], v[202:205], v[30:33]
	v_mfma_f32_16x16x32_bf16 v[26:29], v[162:165], v[202:205], v[26:29]
	v_mfma_f32_16x16x32_bf16 v[22:25], v[146:149], v[210:213], v[22:25]
	v_mfma_f32_16x16x32_bf16 v[18:21], v[162:165], v[210:213], v[18:21]
	v_mfma_f32_16x16x32_bf16 v[62:65], v[158:161], v[190:193], v[62:65]
	v_mfma_f32_16x16x32_bf16 v[58:61], v[166:169], v[190:193], v[58:61]
	v_mfma_f32_16x16x32_bf16 v[54:57], v[158:161], v[198:201], v[54:57]
	v_mfma_f32_16x16x32_bf16 v[50:53], v[166:169], v[198:201], v[50:53]
	v_mfma_f32_16x16x32_bf16 v[30:33], v[158:161], v[206:209], v[30:33]
	v_mfma_f32_16x16x32_bf16 v[26:29], v[166:169], v[206:209], v[26:29]
	v_mfma_f32_16x16x32_bf16 v[22:25], v[158:161], v[218:221], v[22:25]
	v_mfma_f32_16x16x32_bf16 v[18:21], v[166:169], v[218:221], v[18:21]
	s_setprio 0
	s_setprio 1
	v_mfma_f32_16x16x32_bf16 v[46:49], v[170:173], v[186:189], v[46:49]
	v_mfma_f32_16x16x32_bf16 v[42:45], v[178:181], v[186:189], v[42:45]
	v_mfma_f32_16x16x32_bf16 v[38:41], v[170:173], v[194:197], v[38:41]
	v_mfma_f32_16x16x32_bf16 v[34:37], v[178:181], v[194:197], v[34:37]
	v_mfma_f32_16x16x32_bf16 v[14:17], v[170:173], v[202:205], v[14:17]
	v_mfma_f32_16x16x32_bf16 v[10:13], v[178:181], v[202:205], v[10:13]
	v_mfma_f32_16x16x32_bf16 v[6:9], v[170:173], v[210:213], v[6:9]
	v_mfma_f32_16x16x32_bf16 v[2:5], v[178:181], v[210:213], v[2:5]
	v_mfma_f32_16x16x32_bf16 v[46:49], v[174:177], v[190:193], v[46:49]
	v_mfma_f32_16x16x32_bf16 v[42:45], v[182:185], v[190:193], v[42:45]
	v_mfma_f32_16x16x32_bf16 v[38:41], v[174:177], v[198:201], v[38:41]
	v_mfma_f32_16x16x32_bf16 v[34:37], v[182:185], v[198:201], v[34:37]
	v_mfma_f32_16x16x32_bf16 v[14:17], v[174:177], v[206:209], v[14:17]
	v_mfma_f32_16x16x32_bf16 v[10:13], v[182:185], v[206:209], v[10:13]
	v_mfma_f32_16x16x32_bf16 v[6:9], v[174:177], v[218:221], v[6:9]
	v_mfma_f32_16x16x32_bf16 v[2:5], v[182:185], v[218:221], v[2:5]
	s_setprio 0
	s_barrier
	s_add_i32 s81, s81, 2
	s_add_u32 s72, s72, 0x100
	s_addc_u32 s73, s73, 0
	s_add_u32 s0, s0, 0x100
	s_addc_u32 s1, s1, 0
	s_cmpk_gt_u32 s81, 0x55
	s_cbranch_scc0 .LBB0_387
	s_and_b64 vcc, exec, s[68:69]
	s_cbranch_vccz .LBB0_390
	s_barrier

.LBB0_518:
	s_add_u32 s34, s90, 0xfff80080
	s_addc_u32 s35, s91, -1
	s_cmp_eq_u32 s83, 28
	s_cselect_b32 s93, s0, s35
	s_cselect_b32 s92, s1, s34
	s_cselect_b32 s35, s7, s68
	s_cselect_b32 s34, s9, s52
	v_lshl_add_u64 v[152:153], s[90:91], 0, v[144:145]
	s_add_i32 m0, s56, 0xc000
	s_nop 0
	global_load_lds_dwordx4 v[152:153], off
	v_lshl_add_u64 v[152:153], s[90:91], 0, v[146:147]
	s_add_i32 m0, s56, 0xe000
	s_nop 0
	global_load_lds_dwordx4 v[152:153], off
	ds_read_b128 v[160:163], v155
	ds_read_b128 v[164:167], v155 offset:1024
	ds_read_b128 v[168:171], v155 offset:2048
	ds_read_b128 v[172:175], v155 offset:3072
	ds_read_b128 v[176:179], v156
	ds_read_b128 v[180:183], v156 offset:1024
	ds_read_b128 v[184:187], v156 offset:2048
	ds_read_b128 v[188:191], v156 offset:3072
	ds_read_b128 v[192:195], v157
	ds_read_b128 v[196:199], v157 offset:1024
	ds_read_b128 v[200:203], v157 offset:2048
	ds_read_b128 v[204:207], v157 offset:3072
	ds_read_b128 v[208:211], v157 offset:4096
	ds_read_b128 v[212:215], v157 offset:5120
	ds_read_b128 v[218:221], v157 offset:6144
	ds_read_b128 v[222:225], v157 offset:7168
	s_waitcnt vmcnt(8)
	s_waitcnt lgkmcnt(0)
	s_barrier
	s_setprio 1
	s_waitcnt lgkmcnt(0)
	v_mfma_f32_16x16x32_bf16 v[126:129], v[160:163], v[192:195], v[126:129]
	v_mfma_f32_16x16x32_bf16 v[122:125], v[168:171], v[192:195], v[122:125]
	v_mfma_f32_16x16x32_bf16 v[110:113], v[160:163], v[200:203], v[110:113]
	v_mfma_f32_16x16x32_bf16 v[106:109], v[168:171], v[200:203], v[106:109]
	v_mfma_f32_16x16x32_bf16 v[94:97], v[160:163], v[208:211], v[94:97]
	v_mfma_f32_16x16x32_bf16 v[90:93], v[168:171], v[208:211], v[90:93]
	v_mfma_f32_16x16x32_bf16 v[78:81], v[160:163], v[218:221], v[78:81]
	v_mfma_f32_16x16x32_bf16 v[74:77], v[168:171], v[218:221], v[74:77]
	v_mfma_f32_16x16x32_bf16 v[126:129], v[164:167], v[196:199], v[126:129]
	v_mfma_f32_16x16x32_bf16 v[122:125], v[172:175], v[196:199], v[122:125]
	v_mfma_f32_16x16x32_bf16 v[110:113], v[164:167], v[204:207], v[110:113]
	v_mfma_f32_16x16x32_bf16 v[106:109], v[172:175], v[204:207], v[106:109]
	v_mfma_f32_16x16x32_bf16 v[94:97], v[164:167], v[212:215], v[94:97]
	v_mfma_f32_16x16x32_bf16 v[90:93], v[172:175], v[212:215], v[90:93]
	v_mfma_f32_16x16x32_bf16 v[78:81], v[164:167], v[222:225], v[78:81]
	v_mfma_f32_16x16x32_bf16 v[74:77], v[172:175], v[222:225], v[74:77]
	s_setprio 0
	s_setprio 1
	v_mfma_f32_16x16x32_bf16 v[118:121], v[176:179], v[192:195], v[118:121]
	v_mfma_f32_16x16x32_bf16 v[114:117], v[184:187], v[192:195], v[114:117]
	v_mfma_f32_16x16x32_bf16 v[102:105], v[176:179], v[200:203], v[102:105]
	v_mfma_f32_16x16x32_bf16 v[98:101], v[184:187], v[200:203], v[98:101]
	v_mfma_f32_16x16x32_bf16 v[86:89], v[176:179], v[208:211], v[86:89]
	v_mfma_f32_16x16x32_bf16 v[82:85], v[184:187], v[208:211], v[82:85]
	v_mfma_f32_16x16x32_bf16 v[70:73], v[176:179], v[218:221], v[70:73]
	v_mfma_f32_16x16x32_bf16 v[66:69], v[184:187], v[218:221], v[66:69]
	v_mfma_f32_16x16x32_bf16 v[118:121], v[180:183], v[196:199], v[118:121]
	v_mfma_f32_16x16x32_bf16 v[114:117], v[188:191], v[196:199], v[114:117]
	v_mfma_f32_16x16x32_bf16 v[102:105], v[180:183], v[204:207], v[102:105]
	v_mfma_f32_16x16x32_bf16 v[98:101], v[188:191], v[204:207], v[98:101]
	v_mfma_f32_16x16x32_bf16 v[86:89], v[180:183], v[212:215], v[86:89]
	v_mfma_f32_16x16x32_bf16 v[82:85], v[188:191], v[212:215], v[82:85]
	v_mfma_f32_16x16x32_bf16 v[70:73], v[180:183], v[222:225], v[70:73]
	v_mfma_f32_16x16x32_bf16 v[66:69], v[188:191], v[222:225], v[66:69]
	s_setprio 0
	s_barrier
	s_add_i32 s53, s75, s30
	v_lshl_add_u64 v[152:153], s[34:35], 0, v[132:133]
	s_mov_b32 m0, s53
	s_nop 0
	global_load_lds_dwordx4 v[152:153], off
	s_add_i32 m0, s53, 0x2000
	s_add_u32 s54, s34, 0x80000
	v_lshl_add_u64 v[226:227], s[34:35], 0, v[136:137]
	s_addc_u32 s55, s35, 0
	s_add_i32 s53, s94, s30
	global_load_lds_dwordx4 v[226:227], off
	v_lshl_add_u64 v[228:229], s[54:55], 0, v[132:133]
	s_mov_b32 m0, s53
	v_lshl_add_u64 v[230:231], s[92:93], 0, v[134:135]
	global_load_lds_dwordx4 v[228:229], off
	v_lshl_add_u64 v[228:229], s[54:55], 0, v[136:137]
	s_add_i32 m0, s53, 0x2000
	s_nop 0
	global_load_lds_dwordx4 v[228:229], off
	v_lshl_add_u64 v[228:229], s[92:93], 0, v[130:131]
	s_mov_b32 m0, s56
	s_nop 0
	global_load_lds_dwordx4 v[228:229], off
	s_mov_b32 m0, s57
	s_nop 0
	global_load_lds_dwordx4 v[230:231], off
	ds_read_b128 v[192:195], v157 offset:16384
	ds_read_b128 v[196:199], v157 offset:17408
	ds_read_b128 v[200:203], v157 offset:18432
	ds_read_b128 v[204:207], v157 offset:19456
	ds_read_b128 v[208:211], v157 offset:20480
	ds_read_b128 v[212:215], v157 offset:21504
	ds_read_b128 v[218:221], v157 offset:22528
	ds_read_b128 v[222:225], v157 offset:23552
	s_waitcnt vmcnt(8)
	s_waitcnt lgkmcnt(0)
	s_barrier
	s_setprio 1
	s_waitcnt lgkmcnt(0)
	v_mfma_f32_16x16x32_bf16 v[62:65], v[160:163], v[192:195], v[62:65]
	v_mfma_f32_16x16x32_bf16 v[58:61], v[168:171], v[192:195], v[58:61]
	v_mfma_f32_16x16x32_bf16 v[46:49], v[160:163], v[200:203], v[46:49]
	v_mfma_f32_16x16x32_bf16 v[42:45], v[168:171], v[200:203], v[42:45]
	v_mfma_f32_16x16x32_bf16 v[30:33], v[160:163], v[208:211], v[30:33]
	v_mfma_f32_16x16x32_bf16 v[26:29], v[168:171], v[208:211], v[26:29]
	v_mfma_f32_16x16x32_bf16 v[14:17], v[160:163], v[218:221], v[14:17]
	v_mfma_f32_16x16x32_bf16 v[10:13], v[168:171], v[218:221], v[10:13]
	v_mfma_f32_16x16x32_bf16 v[62:65], v[164:167], v[196:199], v[62:65]
	v_mfma_f32_16x16x32_bf16 v[58:61], v[172:175], v[196:199], v[58:61]
	v_mfma_f32_16x16x32_bf16 v[46:49], v[164:167], v[204:207], v[46:49]
	v_mfma_f32_16x16x32_bf16 v[42:45], v[172:175], v[204:207], v[42:45]
	v_mfma_f32_16x16x32_bf16 v[30:33], v[164:167], v[212:215], v[30:33]
	v_mfma_f32_16x16x32_bf16 v[26:29], v[172:175], v[212:215], v[26:29]
	v_mfma_f32_16x16x32_bf16 v[14:17], v[164:167], v[222:225], v[14:17]
	v_mfma_f32_16x16x32_bf16 v[10:13], v[172:175], v[222:225], v[10:13]
	s_setprio 0
	s_setprio 1
	v_mfma_f32_16x16x32_bf16 v[54:57], v[176:179], v[192:195], v[54:57]
	v_mfma_f32_16x16x32_bf16 v[50:53], v[184:187], v[192:195], v[50:53]
	v_mfma_f32_16x16x32_bf16 v[38:41], v[176:179], v[200:203], v[38:41]
	v_mfma_f32_16x16x32_bf16 v[34:37], v[184:187], v[200:203], v[34:37]
	v_mfma_f32_16x16x32_bf16 v[22:25], v[176:179], v[208:211], v[22:25]
	v_mfma_f32_16x16x32_bf16 v[18:21], v[184:187], v[208:211], v[18:21]
	v_mfma_f32_16x16x32_bf16 v[6:9], v[176:179], v[218:221], v[6:9]
	v_mfma_f32_16x16x32_bf16 v[2:5], v[184:187], v[218:221], v[2:5]
	v_mfma_f32_16x16x32_bf16 v[54:57], v[180:183], v[196:199], v[54:57]
	v_mfma_f32_16x16x32_bf16 v[50:53], v[188:191], v[196:199], v[50:53]
	v_mfma_f32_16x16x32_bf16 v[38:41], v[180:183], v[204:207], v[38:41]
	v_mfma_f32_16x16x32_bf16 v[34:37], v[188:191], v[204:207], v[34:37]
	v_mfma_f32_16x16x32_bf16 v[22:25], v[180:183], v[212:215], v[22:25]
	v_mfma_f32_16x16x32_bf16 v[18:21], v[188:191], v[212:215], v[18:21]
	v_mfma_f32_16x16x32_bf16 v[6:9], v[180:183], v[222:225], v[6:9]
	v_mfma_f32_16x16x32_bf16 v[2:5], v[188:191], v[222:225], v[2:5]
	s_setprio 0
	s_barrier
	s_add_i32 s53, 0, 0x18000
	s_add_i32 s62, 0, 0x1c000
	s_add_u32 s54, s92, 0x80000
	s_addc_u32 s55, s93, 0
	s_mov_b32 m0, s58
	v_lshl_add_u64 v[232:233], s[54:55], 0, v[130:131]
	global_load_lds_dwordx4 v[232:233], off
	v_lshl_add_u64 v[232:233], s[54:55], 0, v[134:135]
	s_mov_b32 m0, s59
	s_nop 0
	global_load_lds_dwordx4 v[232:233], off
	v_add_u32_e32 v138, s53, v154
	ds_read_b128 v[160:163], v138
	ds_read_b128 v[164:167], v138 offset:1024
	ds_read_b128 v[168:171], v138 offset:2048
	ds_read_b128 v[172:175], v138 offset:3072
	v_add_u32_e32 v138, s62, v154
	ds_read_b128 v[176:179], v138
	ds_read_b128 v[180:183], v138 offset:1024
	ds_read_b128 v[184:187], v138 offset:2048
	ds_read_b128 v[188:191], v138 offset:3072
	ds_read_b128 v[192:195], v157 offset:32768
	ds_read_b128 v[196:199], v157 offset:33792
	ds_read_b128 v[200:203], v157 offset:34816
	ds_read_b128 v[204:207], v157 offset:35840
	ds_read_b128 v[208:211], v157 offset:36864
	ds_read_b128 v[212:215], v157 offset:37888
	ds_read_b128 v[218:221], v157 offset:38912
	ds_read_b128 v[222:225], v157 offset:39936
	s_waitcnt vmcnt(8)
	s_waitcnt lgkmcnt(0)
	s_barrier
	s_setprio 1
	s_waitcnt lgkmcnt(0)
	v_mfma_f32_16x16x32_bf16 v[126:129], v[160:163], v[192:195], v[126:129]
	v_mfma_f32_16x16x32_bf16 v[122:125], v[168:171], v[192:195], v[122:125]
	v_mfma_f32_16x16x32_bf16 v[110:113], v[160:163], v[200:203], v[110:113]
	v_mfma_f32_16x16x32_bf16 v[106:109], v[168:171], v[200:203], v[106:109]
	v_mfma_f32_16x16x32_bf16 v[94:97], v[160:163], v[208:211], v[94:97]
	v_mfma_f32_16x16x32_bf16 v[90:93], v[168:171], v[208:211], v[90:93]
	v_mfma_f32_16x16x32_bf16 v[78:81], v[160:163], v[218:221], v[78:81]
	v_mfma_f32_16x16x32_bf16 v[74:77], v[168:171], v[218:221], v[74:77]
	v_mfma_f32_16x16x32_bf16 v[126:129], v[164:167], v[196:199], v[126:129]
	v_mfma_f32_16x16x32_bf16 v[122:125], v[172:175], v[196:199], v[122:125]
	v_mfma_f32_16x16x32_bf16 v[110:113], v[164:167], v[204:207], v[110:113]
	v_mfma_f32_16x16x32_bf16 v[106:109], v[172:175], v[204:207], v[106:109]
	v_mfma_f32_16x16x32_bf16 v[94:97], v[164:167], v[212:215], v[94:97]
	v_mfma_f32_16x16x32_bf16 v[90:93], v[172:175], v[212:215], v[90:93]
	v_mfma_f32_16x16x32_bf16 v[78:81], v[164:167], v[222:225], v[78:81]
	v_mfma_f32_16x16x32_bf16 v[74:77], v[172:175], v[222:225], v[74:77]
	s_setprio 0
	s_setprio 1
	v_mfma_f32_16x16x32_bf16 v[118:121], v[176:179], v[192:195], v[118:121]
	v_mfma_f32_16x16x32_bf16 v[114:117], v[184:187], v[192:195], v[114:117]
	v_mfma_f32_16x16x32_bf16 v[102:105], v[176:179], v[200:203], v[102:105]
	v_mfma_f32_16x16x32_bf16 v[98:101], v[184:187], v[200:203], v[98:101]
	v_mfma_f32_16x16x32_bf16 v[86:89], v[176:179], v[208:211], v[86:89]
	v_mfma_f32_16x16x32_bf16 v[82:85], v[184:187], v[208:211], v[82:85]
	v_mfma_f32_16x16x32_bf16 v[70:73], v[176:179], v[218:221], v[70:73]
	v_mfma_f32_16x16x32_bf16 v[66:69], v[184:187], v[218:221], v[66:69]
	v_mfma_f32_16x16x32_bf16 v[118:121], v[180:183], v[196:199], v[118:121]
	v_mfma_f32_16x16x32_bf16 v[114:117], v[188:191], v[196:199], v[114:117]
	v_mfma_f32_16x16x32_bf16 v[102:105], v[180:183], v[204:207], v[102:105]
	v_mfma_f32_16x16x32_bf16 v[98:101], v[188:191], v[204:207], v[98:101]
	v_mfma_f32_16x16x32_bf16 v[86:89], v[180:183], v[212:215], v[86:89]
	v_mfma_f32_16x16x32_bf16 v[82:85], v[188:191], v[212:215], v[82:85]
	v_mfma_f32_16x16x32_bf16 v[70:73], v[180:183], v[222:225], v[70:73]
	v_mfma_f32_16x16x32_bf16 v[66:69], v[188:191], v[222:225], v[66:69]
	s_setprio 0
	s_barrier
	s_add_i32 s53, s53, s30
	v_lshl_add_u64 v[152:153], v[152:153], 0, s[76:77]
	s_mov_b32 m0, s53
	s_nop 0
	global_load_lds_dwordx4 v[152:153], off
	s_add_i32 m0, s53, 0x2000
	s_add_u32 s34, s34, 0x80080
	v_lshl_add_u64 v[152:153], v[226:227], 0, s[76:77]
	s_addc_u32 s35, s35, 0
	s_add_i32 s53, s62, s30
	global_load_lds_dwordx4 v[152:153], off
	v_lshl_add_u64 v[152:153], s[34:35], 0, v[132:133]
	s_mov_b32 m0, s53
	s_nop 0
	global_load_lds_dwordx4 v[152:153], off
	v_lshl_add_u64 v[152:153], s[34:35], 0, v[136:137]
	s_add_i32 m0, s53, 0x2000
	s_nop 0
	global_load_lds_dwordx4 v[152:153], off
	v_lshl_add_u64 v[152:153], v[228:229], 0, s[76:77]
	s_mov_b32 m0, s61
	s_nop 0
	global_load_lds_dwordx4 v[152:153], off
	v_lshl_add_u64 v[152:153], v[230:231], 0, s[76:77]
	s_mov_b32 m0, s72
	s_nop 0
	global_load_lds_dwordx4 v[152:153], off
	ds_read_b128 v[192:195], v157 offset:49152
	ds_read_b128 v[196:199], v157 offset:50176
	ds_read_b128 v[200:203], v157 offset:51200
	ds_read_b128 v[204:207], v157 offset:52224
	ds_read_b128 v[208:211], v157 offset:53248
	ds_read_b128 v[212:215], v157 offset:54272
	ds_read_b128 v[218:221], v157 offset:55296
	ds_read_b128 v[222:225], v157 offset:56320
	s_waitcnt vmcnt(8)
	s_waitcnt lgkmcnt(0)
	s_barrier
	s_setprio 1
	s_waitcnt lgkmcnt(0)
	v_mfma_f32_16x16x32_bf16 v[62:65], v[160:163], v[192:195], v[62:65]
	v_mfma_f32_16x16x32_bf16 v[58:61], v[168:171], v[192:195], v[58:61]
	v_mfma_f32_16x16x32_bf16 v[46:49], v[160:163], v[200:203], v[46:49]
	v_mfma_f32_16x16x32_bf16 v[42:45], v[168:171], v[200:203], v[42:45]
	v_mfma_f32_16x16x32_bf16 v[30:33], v[160:163], v[208:211], v[30:33]
	v_mfma_f32_16x16x32_bf16 v[26:29], v[168:171], v[208:211], v[26:29]
	v_mfma_f32_16x16x32_bf16 v[14:17], v[160:163], v[218:221], v[14:17]
	v_mfma_f32_16x16x32_bf16 v[10:13], v[168:171], v[218:221], v[10:13]
	v_mfma_f32_16x16x32_bf16 v[62:65], v[164:167], v[196:199], v[62:65]
	v_mfma_f32_16x16x32_bf16 v[58:61], v[172:175], v[196:199], v[58:61]
	v_mfma_f32_16x16x32_bf16 v[46:49], v[164:167], v[204:207], v[46:49]
	v_mfma_f32_16x16x32_bf16 v[42:45], v[172:175], v[204:207], v[42:45]
	v_mfma_f32_16x16x32_bf16 v[30:33], v[164:167], v[212:215], v[30:33]
	v_mfma_f32_16x16x32_bf16 v[26:29], v[172:175], v[212:215], v[26:29]
	v_mfma_f32_16x16x32_bf16 v[14:17], v[164:167], v[222:225], v[14:17]
	v_mfma_f32_16x16x32_bf16 v[10:13], v[172:175], v[222:225], v[10:13]
	s_setprio 0
	s_setprio 1
	v_mfma_f32_16x16x32_bf16 v[54:57], v[176:179], v[192:195], v[54:57]
	v_mfma_f32_16x16x32_bf16 v[50:53], v[184:187], v[192:195], v[50:53]
	v_mfma_f32_16x16x32_bf16 v[38:41], v[176:179], v[200:203], v[38:41]
	v_mfma_f32_16x16x32_bf16 v[34:37], v[184:187], v[200:203], v[34:37]
	v_mfma_f32_16x16x32_bf16 v[22:25], v[176:179], v[208:211], v[22:25]
	v_mfma_f32_16x16x32_bf16 v[18:21], v[184:187], v[208:211], v[18:21]
	v_mfma_f32_16x16x32_bf16 v[6:9], v[176:179], v[218:221], v[6:9]
	v_mfma_f32_16x16x32_bf16 v[2:5], v[184:187], v[218:221], v[2:5]
	v_mfma_f32_16x16x32_bf16 v[54:57], v[180:183], v[196:199], v[54:57]
	v_mfma_f32_16x16x32_bf16 v[50:53], v[188:191], v[196:199], v[50:53]
	v_mfma_f32_16x16x32_bf16 v[38:41], v[180:183], v[204:207], v[38:41]
	v_mfma_f32_16x16x32_bf16 v[34:37], v[188:191], v[204:207], v[34:37]
	v_mfma_f32_16x16x32_bf16 v[22:25], v[180:183], v[212:215], v[22:25]
	v_mfma_f32_16x16x32_bf16 v[18:21], v[188:191], v[212:215], v[18:21]
	v_mfma_f32_16x16x32_bf16 v[6:9], v[180:183], v[222:225], v[6:9]
	v_mfma_f32_16x16x32_bf16 v[2:5], v[188:191], v[222:225], v[2:5]
	s_setprio 0
	s_barrier
	s_add_i32 s83, s83, 2
	s_add_u32 s90, s90, 0x100
	s_addc_u32 s91, s91, 0
	s_add_u32 s52, s52, 0x100
	s_addc_u32 s68, s68, 0
	s_cmp_gt_u32 s83, 29
	s_cbranch_scc0 .LBB0_518
	s_and_b64 vcc, exec, s[78:79]
	s_cbranch_vccz .LBB0_521
	s_barrier

.LBB0_685:
	s_add_u32 s34, s84, 0xfffe0080
	s_addc_u32 s35, s85, -1
	s_cmp_eq_u32 s89, 4
	s_cselect_b32 s87, s0, s35
	s_cselect_b32 s86, s1, s34
	s_cselect_b32 s35, s52, s88
	s_cselect_b32 s34, s71, s77
	v_lshl_add_u64 v[226:227], s[84:85], 0, v[138:139]
	s_add_i32 m0, s33, 0xc000
	s_nop 0
	global_load_lds_dwordx4 v[226:227], off
	v_lshl_add_u64 v[226:227], s[84:85], 0, v[140:141]
	s_add_i32 m0, s33, 0xe000
	s_nop 0
	global_load_lds_dwordx4 v[226:227], off
	ds_read_b128 v[146:149], v165
	ds_read_b128 v[150:153], v165 offset:1024
	ds_read_b128 v[168:171], v165 offset:2048
	ds_read_b128 v[172:175], v165 offset:3072
	ds_read_b128 v[176:179], v166
	ds_read_b128 v[180:183], v166 offset:1024
	ds_read_b128 v[184:187], v166 offset:2048
	ds_read_b128 v[188:191], v166 offset:3072
	ds_read_b128 v[192:195], v167
	ds_read_b128 v[196:199], v167 offset:1024
	ds_read_b128 v[200:203], v167 offset:2048
	ds_read_b128 v[204:207], v167 offset:3072
	ds_read_b128 v[208:211], v167 offset:4096
	ds_read_b128 v[212:215], v167 offset:5120
	ds_read_b128 v[218:221], v167 offset:6144
	ds_read_b128 v[222:225], v167 offset:7168
	s_waitcnt vmcnt(8)
	s_waitcnt lgkmcnt(0)
	s_barrier
	s_setprio 1
	s_waitcnt lgkmcnt(0)
	v_mfma_f32_16x16x32_bf16 v[126:129], v[146:149], v[192:195], v[126:129]
	v_mfma_f32_16x16x32_bf16 v[122:125], v[168:171], v[192:195], v[122:125]
	v_mfma_f32_16x16x32_bf16 v[114:117], v[146:149], v[200:203], v[114:117]
	v_mfma_f32_16x16x32_bf16 v[106:109], v[168:171], v[200:203], v[106:109]
	v_mfma_f32_16x16x32_bf16 v[98:101], v[146:149], v[208:211], v[98:101]
	v_mfma_f32_16x16x32_bf16 v[90:93], v[168:171], v[208:211], v[90:93]
	v_mfma_f32_16x16x32_bf16 v[82:85], v[146:149], v[218:221], v[82:85]
	v_mfma_f32_16x16x32_bf16 v[74:77], v[168:171], v[218:221], v[74:77]
	v_mfma_f32_16x16x32_bf16 v[126:129], v[150:153], v[196:199], v[126:129]
	v_mfma_f32_16x16x32_bf16 v[122:125], v[172:175], v[196:199], v[122:125]
	v_mfma_f32_16x16x32_bf16 v[114:117], v[150:153], v[204:207], v[114:117]
	v_mfma_f32_16x16x32_bf16 v[106:109], v[172:175], v[204:207], v[106:109]
	v_mfma_f32_16x16x32_bf16 v[98:101], v[150:153], v[212:215], v[98:101]
	v_mfma_f32_16x16x32_bf16 v[90:93], v[172:175], v[212:215], v[90:93]
	v_mfma_f32_16x16x32_bf16 v[82:85], v[150:153], v[222:225], v[82:85]
	v_mfma_f32_16x16x32_bf16 v[74:77], v[172:175], v[222:225], v[74:77]
	s_setprio 0
	s_setprio 1
	v_mfma_f32_16x16x32_bf16 v[118:121], v[176:179], v[192:195], v[118:121]
	v_mfma_f32_16x16x32_bf16 v[110:113], v[184:187], v[192:195], v[110:113]
	v_mfma_f32_16x16x32_bf16 v[102:105], v[176:179], v[200:203], v[102:105]
	v_mfma_f32_16x16x32_bf16 v[94:97], v[184:187], v[200:203], v[94:97]
	v_mfma_f32_16x16x32_bf16 v[86:89], v[176:179], v[208:211], v[86:89]
	v_mfma_f32_16x16x32_bf16 v[78:81], v[184:187], v[208:211], v[78:81]
	v_mfma_f32_16x16x32_bf16 v[70:73], v[176:179], v[218:221], v[70:73]
	v_mfma_f32_16x16x32_bf16 v[66:69], v[184:187], v[218:221], v[66:69]
	v_mfma_f32_16x16x32_bf16 v[118:121], v[180:183], v[196:199], v[118:121]
	v_mfma_f32_16x16x32_bf16 v[110:113], v[188:191], v[196:199], v[110:113]
	v_mfma_f32_16x16x32_bf16 v[102:105], v[180:183], v[204:207], v[102:105]
	v_mfma_f32_16x16x32_bf16 v[94:97], v[188:191], v[204:207], v[94:97]
	v_mfma_f32_16x16x32_bf16 v[86:89], v[180:183], v[212:215], v[86:89]
	v_mfma_f32_16x16x32_bf16 v[78:81], v[188:191], v[212:215], v[78:81]
	v_mfma_f32_16x16x32_bf16 v[70:73], v[180:183], v[222:225], v[70:73]
	v_mfma_f32_16x16x32_bf16 v[66:69], v[188:191], v[222:225], v[66:69]
	s_setprio 0
	s_barrier
	s_add_i32 s53, s73, s12
	v_lshl_add_u64 v[226:227], s[34:35], 0, v[132:133]
	s_mov_b32 m0, s53
	s_nop 0
	global_load_lds_dwordx4 v[226:227], off
	s_add_i32 m0, s53, 0x2000
	s_add_u32 s54, s34, 0x20000
	v_lshl_add_u64 v[228:229], s[34:35], 0, v[136:137]
	s_addc_u32 s55, s35, 0
	s_add_i32 s53, s74, s12
	global_load_lds_dwordx4 v[228:229], off
	v_lshl_add_u64 v[230:231], s[54:55], 0, v[132:133]
	s_mov_b32 m0, s53
	v_lshl_add_u64 v[232:233], s[86:87], 0, v[134:135]
	global_load_lds_dwordx4 v[230:231], off
	v_lshl_add_u64 v[230:231], s[54:55], 0, v[136:137]
	s_add_i32 m0, s53, 0x2000
	s_nop 0
	global_load_lds_dwordx4 v[230:231], off
	v_lshl_add_u64 v[230:231], s[86:87], 0, v[130:131]
	s_mov_b32 m0, s33
	s_nop 0
	global_load_lds_dwordx4 v[230:231], off
	s_mov_b32 m0, s56
	s_nop 0
	global_load_lds_dwordx4 v[232:233], off
	ds_read_b128 v[192:195], v167 offset:16384
	ds_read_b128 v[196:199], v167 offset:17408
	ds_read_b128 v[200:203], v167 offset:18432
	ds_read_b128 v[204:207], v167 offset:19456
	ds_read_b128 v[208:211], v167 offset:20480
	ds_read_b128 v[212:215], v167 offset:21504
	ds_read_b128 v[218:221], v167 offset:22528
	ds_read_b128 v[222:225], v167 offset:23552
	s_waitcnt vmcnt(8)
	s_waitcnt lgkmcnt(0)
	s_barrier
	s_setprio 1
	s_waitcnt lgkmcnt(0)
	v_mfma_f32_16x16x32_bf16 v[62:65], v[146:149], v[192:195], v[62:65]
	v_mfma_f32_16x16x32_bf16 v[58:61], v[168:171], v[192:195], v[58:61]
	v_mfma_f32_16x16x32_bf16 v[50:53], v[146:149], v[200:203], v[50:53]
	v_mfma_f32_16x16x32_bf16 v[42:45], v[168:171], v[200:203], v[42:45]
	v_mfma_f32_16x16x32_bf16 v[34:37], v[146:149], v[208:211], v[34:37]
	v_mfma_f32_16x16x32_bf16 v[26:29], v[168:171], v[208:211], v[26:29]
	v_mfma_f32_16x16x32_bf16 v[18:21], v[146:149], v[218:221], v[18:21]
	v_mfma_f32_16x16x32_bf16 v[10:13], v[168:171], v[218:221], v[10:13]
	v_mfma_f32_16x16x32_bf16 v[62:65], v[150:153], v[196:199], v[62:65]
	v_mfma_f32_16x16x32_bf16 v[58:61], v[172:175], v[196:199], v[58:61]
	v_mfma_f32_16x16x32_bf16 v[50:53], v[150:153], v[204:207], v[50:53]
	v_mfma_f32_16x16x32_bf16 v[42:45], v[172:175], v[204:207], v[42:45]
	v_mfma_f32_16x16x32_bf16 v[34:37], v[150:153], v[212:215], v[34:37]
	v_mfma_f32_16x16x32_bf16 v[26:29], v[172:175], v[212:215], v[26:29]
	v_mfma_f32_16x16x32_bf16 v[18:21], v[150:153], v[222:225], v[18:21]
	v_mfma_f32_16x16x32_bf16 v[10:13], v[172:175], v[222:225], v[10:13]
	s_setprio 0
	s_setprio 1
	v_mfma_f32_16x16x32_bf16 v[54:57], v[176:179], v[192:195], v[54:57]
	v_mfma_f32_16x16x32_bf16 v[46:49], v[184:187], v[192:195], v[46:49]
	v_mfma_f32_16x16x32_bf16 v[38:41], v[176:179], v[200:203], v[38:41]
	v_mfma_f32_16x16x32_bf16 v[30:33], v[184:187], v[200:203], v[30:33]
	v_mfma_f32_16x16x32_bf16 v[22:25], v[176:179], v[208:211], v[22:25]
	v_mfma_f32_16x16x32_bf16 v[14:17], v[184:187], v[208:211], v[14:17]
	v_mfma_f32_16x16x32_bf16 v[6:9], v[176:179], v[218:221], v[6:9]
	v_mfma_f32_16x16x32_bf16 v[2:5], v[184:187], v[218:221], v[2:5]
	v_mfma_f32_16x16x32_bf16 v[54:57], v[180:183], v[196:199], v[54:57]
	v_mfma_f32_16x16x32_bf16 v[46:49], v[188:191], v[196:199], v[46:49]
	v_mfma_f32_16x16x32_bf16 v[38:41], v[180:183], v[204:207], v[38:41]
	v_mfma_f32_16x16x32_bf16 v[30:33], v[188:191], v[204:207], v[30:33]
	v_mfma_f32_16x16x32_bf16 v[22:25], v[180:183], v[212:215], v[22:25]
	v_mfma_f32_16x16x32_bf16 v[14:17], v[188:191], v[212:215], v[14:17]
	v_mfma_f32_16x16x32_bf16 v[6:9], v[180:183], v[222:225], v[6:9]
	v_mfma_f32_16x16x32_bf16 v[2:5], v[188:191], v[222:225], v[2:5]
	s_setprio 0
	s_barrier
	s_add_i32 s53, 0, 0x18000
	s_add_i32 s62, 0, 0x1c000
	s_add_u32 s54, s86, 0x20000
	s_addc_u32 s55, s87, 0
	s_mov_b32 m0, s57
	v_lshl_add_u64 v[234:235], s[54:55], 0, v[130:131]
	global_load_lds_dwordx4 v[234:235], off
	v_lshl_add_u64 v[234:235], s[54:55], 0, v[134:135]
	s_mov_b32 m0, s58
	s_nop 0
	global_load_lds_dwordx4 v[234:235], off
	v_add_u32_e32 v172, s53, v162
	v_add_u32_e32 v188, s62, v162
	ds_read_b128 v[146:149], v172
	ds_read_b128 v[150:153], v172 offset:1024
	ds_read_b128 v[168:171], v172 offset:2048
	ds_read_b128 v[172:175], v172 offset:3072
	ds_read_b128 v[176:179], v188
	ds_read_b128 v[180:183], v188 offset:1024
	ds_read_b128 v[184:187], v188 offset:2048
	ds_read_b128 v[188:191], v188 offset:3072
	ds_read_b128 v[192:195], v167 offset:32768
	ds_read_b128 v[196:199], v167 offset:33792
	ds_read_b128 v[200:203], v167 offset:34816
	ds_read_b128 v[204:207], v167 offset:35840
	ds_read_b128 v[208:211], v167 offset:36864
	ds_read_b128 v[212:215], v167 offset:37888
	ds_read_b128 v[218:221], v167 offset:38912
	ds_read_b128 v[222:225], v167 offset:39936
	s_waitcnt vmcnt(8)
	s_waitcnt lgkmcnt(0)
	s_barrier
	s_setprio 1
	s_waitcnt lgkmcnt(0)
	v_mfma_f32_16x16x32_bf16 v[126:129], v[146:149], v[192:195], v[126:129]
	v_mfma_f32_16x16x32_bf16 v[122:125], v[168:171], v[192:195], v[122:125]
	v_mfma_f32_16x16x32_bf16 v[114:117], v[146:149], v[200:203], v[114:117]
	v_mfma_f32_16x16x32_bf16 v[106:109], v[168:171], v[200:203], v[106:109]
	v_mfma_f32_16x16x32_bf16 v[98:101], v[146:149], v[208:211], v[98:101]
	v_mfma_f32_16x16x32_bf16 v[90:93], v[168:171], v[208:211], v[90:93]
	v_mfma_f32_16x16x32_bf16 v[82:85], v[146:149], v[218:221], v[82:85]
	v_mfma_f32_16x16x32_bf16 v[74:77], v[168:171], v[218:221], v[74:77]
	v_mfma_f32_16x16x32_bf16 v[126:129], v[150:153], v[196:199], v[126:129]
	v_mfma_f32_16x16x32_bf16 v[122:125], v[172:175], v[196:199], v[122:125]
	v_mfma_f32_16x16x32_bf16 v[114:117], v[150:153], v[204:207], v[114:117]
	v_mfma_f32_16x16x32_bf16 v[106:109], v[172:175], v[204:207], v[106:109]
	v_mfma_f32_16x16x32_bf16 v[98:101], v[150:153], v[212:215], v[98:101]
	v_mfma_f32_16x16x32_bf16 v[90:93], v[172:175], v[212:215], v[90:93]
	v_mfma_f32_16x16x32_bf16 v[82:85], v[150:153], v[222:225], v[82:85]
	v_mfma_f32_16x16x32_bf16 v[74:77], v[172:175], v[222:225], v[74:77]
	s_setprio 0
	s_setprio 1
	v_mfma_f32_16x16x32_bf16 v[118:121], v[176:179], v[192:195], v[118:121]
	v_mfma_f32_16x16x32_bf16 v[110:113], v[184:187], v[192:195], v[110:113]
	v_mfma_f32_16x16x32_bf16 v[102:105], v[176:179], v[200:203], v[102:105]
	v_mfma_f32_16x16x32_bf16 v[94:97], v[184:187], v[200:203], v[94:97]
	v_mfma_f32_16x16x32_bf16 v[86:89], v[176:179], v[208:211], v[86:89]
	v_mfma_f32_16x16x32_bf16 v[78:81], v[184:187], v[208:211], v[78:81]
	v_mfma_f32_16x16x32_bf16 v[70:73], v[176:179], v[218:221], v[70:73]
	v_mfma_f32_16x16x32_bf16 v[66:69], v[184:187], v[218:221], v[66:69]
	v_mfma_f32_16x16x32_bf16 v[118:121], v[180:183], v[196:199], v[118:121]
	v_mfma_f32_16x16x32_bf16 v[110:113], v[188:191], v[196:199], v[110:113]
	v_mfma_f32_16x16x32_bf16 v[102:105], v[180:183], v[204:207], v[102:105]
	v_mfma_f32_16x16x32_bf16 v[94:97], v[188:191], v[204:207], v[94:97]
	v_mfma_f32_16x16x32_bf16 v[86:89], v[180:183], v[212:215], v[86:89]
	v_mfma_f32_16x16x32_bf16 v[78:81], v[188:191], v[212:215], v[78:81]
	v_mfma_f32_16x16x32_bf16 v[70:73], v[180:183], v[222:225], v[70:73]
	v_mfma_f32_16x16x32_bf16 v[66:69], v[188:191], v[222:225], v[66:69]
	s_setprio 0
	s_barrier
	s_add_i32 s53, s53, s12
	v_lshl_add_u64 v[226:227], v[226:227], 0, s[8:9]
	s_mov_b32 m0, s53
	s_nop 0
	global_load_lds_dwordx4 v[226:227], off
	s_add_i32 m0, s53, 0x2000
	s_add_u32 s34, s34, 0x20080
	v_lshl_add_u64 v[226:227], v[228:229], 0, s[8:9]
	s_addc_u32 s35, s35, 0
	s_add_i32 s53, s62, s12
	global_load_lds_dwordx4 v[226:227], off
	v_lshl_add_u64 v[226:227], s[34:35], 0, v[132:133]
	s_mov_b32 m0, s53
	s_nop 0
	global_load_lds_dwordx4 v[226:227], off
	v_lshl_add_u64 v[226:227], s[34:35], 0, v[136:137]
	s_add_i32 m0, s53, 0x2000
	s_nop 0
	global_load_lds_dwordx4 v[226:227], off
	v_lshl_add_u64 v[226:227], v[230:231], 0, s[8:9]
	s_mov_b32 m0, s60
	s_nop 0
	global_load_lds_dwordx4 v[226:227], off
	v_lshl_add_u64 v[226:227], v[232:233], 0, s[8:9]
	s_mov_b32 m0, s61
	s_nop 0
	global_load_lds_dwordx4 v[226:227], off
	ds_read_b128 v[192:195], v167 offset:49152
	ds_read_b128 v[196:199], v167 offset:50176
	ds_read_b128 v[200:203], v167 offset:51200
	ds_read_b128 v[204:207], v167 offset:52224
	ds_read_b128 v[208:211], v167 offset:53248
	ds_read_b128 v[212:215], v167 offset:54272
	ds_read_b128 v[218:221], v167 offset:55296
	ds_read_b128 v[222:225], v167 offset:56320
	s_waitcnt vmcnt(8)
	s_waitcnt lgkmcnt(0)
	s_barrier
	s_setprio 1
	s_waitcnt lgkmcnt(0)
	v_mfma_f32_16x16x32_bf16 v[62:65], v[146:149], v[192:195], v[62:65]
	v_mfma_f32_16x16x32_bf16 v[58:61], v[168:171], v[192:195], v[58:61]
	v_mfma_f32_16x16x32_bf16 v[50:53], v[146:149], v[200:203], v[50:53]
	v_mfma_f32_16x16x32_bf16 v[42:45], v[168:171], v[200:203], v[42:45]
	v_mfma_f32_16x16x32_bf16 v[34:37], v[146:149], v[208:211], v[34:37]
	v_mfma_f32_16x16x32_bf16 v[26:29], v[168:171], v[208:211], v[26:29]
	v_mfma_f32_16x16x32_bf16 v[18:21], v[146:149], v[218:221], v[18:21]
	v_mfma_f32_16x16x32_bf16 v[10:13], v[168:171], v[218:221], v[10:13]
	v_mfma_f32_16x16x32_bf16 v[62:65], v[150:153], v[196:199], v[62:65]
	v_mfma_f32_16x16x32_bf16 v[58:61], v[172:175], v[196:199], v[58:61]
	v_mfma_f32_16x16x32_bf16 v[50:53], v[150:153], v[204:207], v[50:53]
	v_mfma_f32_16x16x32_bf16 v[42:45], v[172:175], v[204:207], v[42:45]
	v_mfma_f32_16x16x32_bf16 v[34:37], v[150:153], v[212:215], v[34:37]
	v_mfma_f32_16x16x32_bf16 v[26:29], v[172:175], v[212:215], v[26:29]
	v_mfma_f32_16x16x32_bf16 v[18:21], v[150:153], v[222:225], v[18:21]
	v_mfma_f32_16x16x32_bf16 v[10:13], v[172:175], v[222:225], v[10:13]
	s_setprio 0
	s_setprio 1
	v_mfma_f32_16x16x32_bf16 v[54:57], v[176:179], v[192:195], v[54:57]
	v_mfma_f32_16x16x32_bf16 v[46:49], v[184:187], v[192:195], v[46:49]
	v_mfma_f32_16x16x32_bf16 v[38:41], v[176:179], v[200:203], v[38:41]
	v_mfma_f32_16x16x32_bf16 v[30:33], v[184:187], v[200:203], v[30:33]
	v_mfma_f32_16x16x32_bf16 v[22:25], v[176:179], v[208:211], v[22:25]
	v_mfma_f32_16x16x32_bf16 v[14:17], v[184:187], v[208:211], v[14:17]
	v_mfma_f32_16x16x32_bf16 v[6:9], v[176:179], v[218:221], v[6:9]
	v_mfma_f32_16x16x32_bf16 v[2:5], v[184:187], v[218:221], v[2:5]
	v_mfma_f32_16x16x32_bf16 v[54:57], v[180:183], v[196:199], v[54:57]
	v_mfma_f32_16x16x32_bf16 v[46:49], v[188:191], v[196:199], v[46:49]
	v_mfma_f32_16x16x32_bf16 v[38:41], v[180:183], v[204:207], v[38:41]
	v_mfma_f32_16x16x32_bf16 v[30:33], v[188:191], v[204:207], v[30:33]
	v_mfma_f32_16x16x32_bf16 v[22:25], v[180:183], v[212:215], v[22:25]
	v_mfma_f32_16x16x32_bf16 v[14:17], v[188:191], v[212:215], v[14:17]
	v_mfma_f32_16x16x32_bf16 v[6:9], v[180:183], v[222:225], v[6:9]
	v_mfma_f32_16x16x32_bf16 v[2:5], v[188:191], v[222:225], v[2:5]
	s_setprio 0
	s_barrier
	s_add_i32 s89, s89, 2
	s_add_u32 s84, s84, 0x100
	s_addc_u32 s85, s85, 0
	s_add_u32 s77, s77, 0x100
	s_addc_u32 s88, s88, 0
	s_cmp_gt_u32 s89, 5
	s_cbranch_scc0 .LBB0_685
	s_and_b64 vcc, exec, s[66:67]
	s_cbranch_vccz .LBB0_688
	s_barrier

.LBB0_715:
	s_add_u32 s34, s84, 0xfffe0080
	s_addc_u32 s35, s85, -1
	s_cmp_eq_u32 s88, 4
	s_cselect_b32 s87, s0, s35
	s_cselect_b32 s86, s1, s34
	s_cselect_b32 s35, s52, s83
	s_cselect_b32 s34, s71, s77
	v_lshl_add_u64 v[150:151], s[84:85], 0, v[138:139]
	s_add_i32 m0, s33, 0xc000
	s_nop 0
	global_load_lds_dwordx4 v[150:151], off
	v_lshl_add_u64 v[150:151], s[84:85], 0, v[140:141]
	s_add_i32 m0, s33, 0xe000
	s_nop 0
	global_load_lds_dwordx4 v[150:151], off
	ds_read_b128 v[146:149], v1
	ds_read_b128 v[160:163], v1 offset:1024
	ds_read_b128 v[164:167], v1 offset:2048
	ds_read_b128 v[168:171], v1 offset:3072
	ds_read_b128 v[172:175], v154
	ds_read_b128 v[176:179], v154 offset:1024
	ds_read_b128 v[180:183], v154 offset:2048
	ds_read_b128 v[184:187], v154 offset:3072
	ds_read_b128 v[188:191], v155
	ds_read_b128 v[192:195], v155 offset:1024
	ds_read_b128 v[196:199], v155 offset:2048
	ds_read_b128 v[200:203], v155 offset:3072
	ds_read_b128 v[204:207], v155 offset:4096
	ds_read_b128 v[208:211], v155 offset:5120
	ds_read_b128 v[212:215], v155 offset:6144
	ds_read_b128 v[218:221], v155 offset:7168
	s_waitcnt vmcnt(8)
	s_waitcnt lgkmcnt(0)
	s_barrier
	s_setprio 1
	s_waitcnt lgkmcnt(0)
	v_mfma_f32_16x16x32_bf16 v[126:129], v[146:149], v[188:191], v[126:129]
	v_mfma_f32_16x16x32_bf16 v[122:125], v[164:167], v[188:191], v[122:125]
	v_mfma_f32_16x16x32_bf16 v[110:113], v[146:149], v[196:199], v[110:113]
	v_mfma_f32_16x16x32_bf16 v[106:109], v[164:167], v[196:199], v[106:109]
	v_mfma_f32_16x16x32_bf16 v[94:97], v[146:149], v[204:207], v[94:97]
	v_mfma_f32_16x16x32_bf16 v[90:93], v[164:167], v[204:207], v[90:93]
	v_mfma_f32_16x16x32_bf16 v[78:81], v[146:149], v[212:215], v[78:81]
	v_mfma_f32_16x16x32_bf16 v[74:77], v[164:167], v[212:215], v[74:77]
	v_mfma_f32_16x16x32_bf16 v[126:129], v[160:163], v[192:195], v[126:129]
	v_mfma_f32_16x16x32_bf16 v[122:125], v[168:171], v[192:195], v[122:125]
	v_mfma_f32_16x16x32_bf16 v[110:113], v[160:163], v[200:203], v[110:113]
	v_mfma_f32_16x16x32_bf16 v[106:109], v[168:171], v[200:203], v[106:109]
	v_mfma_f32_16x16x32_bf16 v[94:97], v[160:163], v[208:211], v[94:97]
	v_mfma_f32_16x16x32_bf16 v[90:93], v[168:171], v[208:211], v[90:93]
	v_mfma_f32_16x16x32_bf16 v[78:81], v[160:163], v[218:221], v[78:81]
	v_mfma_f32_16x16x32_bf16 v[74:77], v[168:171], v[218:221], v[74:77]
	s_setprio 0
	s_setprio 1
	v_mfma_f32_16x16x32_bf16 v[118:121], v[172:175], v[188:191], v[118:121]
	v_mfma_f32_16x16x32_bf16 v[114:117], v[180:183], v[188:191], v[114:117]
	v_mfma_f32_16x16x32_bf16 v[102:105], v[172:175], v[196:199], v[102:105]
	v_mfma_f32_16x16x32_bf16 v[98:101], v[180:183], v[196:199], v[98:101]
	v_mfma_f32_16x16x32_bf16 v[86:89], v[172:175], v[204:207], v[86:89]
	v_mfma_f32_16x16x32_bf16 v[82:85], v[180:183], v[204:207], v[82:85]
	v_mfma_f32_16x16x32_bf16 v[70:73], v[172:175], v[212:215], v[70:73]
	v_mfma_f32_16x16x32_bf16 v[66:69], v[180:183], v[212:215], v[66:69]
	v_mfma_f32_16x16x32_bf16 v[118:121], v[176:179], v[192:195], v[118:121]
	v_mfma_f32_16x16x32_bf16 v[114:117], v[184:187], v[192:195], v[114:117]
	v_mfma_f32_16x16x32_bf16 v[102:105], v[176:179], v[200:203], v[102:105]
	v_mfma_f32_16x16x32_bf16 v[98:101], v[184:187], v[200:203], v[98:101]
	v_mfma_f32_16x16x32_bf16 v[86:89], v[176:179], v[208:211], v[86:89]
	v_mfma_f32_16x16x32_bf16 v[82:85], v[184:187], v[208:211], v[82:85]
	v_mfma_f32_16x16x32_bf16 v[70:73], v[176:179], v[218:221], v[70:73]
	v_mfma_f32_16x16x32_bf16 v[66:69], v[184:187], v[218:221], v[66:69]
	s_setprio 0
	s_barrier
	s_add_i32 s53, s73, s13
	v_lshl_add_u64 v[150:151], s[34:35], 0, v[132:133]
	s_mov_b32 m0, s53
	s_nop 0
	global_load_lds_dwordx4 v[150:151], off
	s_add_i32 m0, s53, 0x2000
	s_add_u32 s54, s34, 0x20000
	v_lshl_add_u64 v[222:223], s[34:35], 0, v[136:137]
	s_addc_u32 s55, s35, 0
	s_add_i32 s53, s74, s13
	global_load_lds_dwordx4 v[222:223], off
	v_lshl_add_u64 v[224:225], s[54:55], 0, v[132:133]
	s_mov_b32 m0, s53
	v_lshl_add_u64 v[226:227], s[86:87], 0, v[134:135]
	global_load_lds_dwordx4 v[224:225], off
	v_lshl_add_u64 v[224:225], s[54:55], 0, v[136:137]
	s_add_i32 m0, s53, 0x2000
	s_nop 0
	global_load_lds_dwordx4 v[224:225], off
	v_lshl_add_u64 v[224:225], s[86:87], 0, v[130:131]
	s_mov_b32 m0, s33
	s_nop 0
	global_load_lds_dwordx4 v[224:225], off
	s_mov_b32 m0, s56
	s_nop 0
	global_load_lds_dwordx4 v[226:227], off
	ds_read_b128 v[188:191], v155 offset:16384
	ds_read_b128 v[192:195], v155 offset:17408
	ds_read_b128 v[196:199], v155 offset:18432
	ds_read_b128 v[200:203], v155 offset:19456
	ds_read_b128 v[204:207], v155 offset:20480
	ds_read_b128 v[208:211], v155 offset:21504
	ds_read_b128 v[212:215], v155 offset:22528
	ds_read_b128 v[218:221], v155 offset:23552
	s_waitcnt vmcnt(8)
	s_waitcnt lgkmcnt(0)
	s_barrier
	s_setprio 1
	s_waitcnt lgkmcnt(0)
	v_mfma_f32_16x16x32_bf16 v[62:65], v[146:149], v[188:191], v[62:65]
	v_mfma_f32_16x16x32_bf16 v[58:61], v[164:167], v[188:191], v[58:61]
	v_mfma_f32_16x16x32_bf16 v[50:53], v[146:149], v[196:199], v[50:53]
	v_mfma_f32_16x16x32_bf16 v[42:45], v[164:167], v[196:199], v[42:45]
	v_mfma_f32_16x16x32_bf16 v[34:37], v[146:149], v[204:207], v[34:37]
	v_mfma_f32_16x16x32_bf16 v[26:29], v[164:167], v[204:207], v[26:29]
	v_mfma_f32_16x16x32_bf16 v[18:21], v[146:149], v[212:215], v[18:21]
	v_mfma_f32_16x16x32_bf16 v[10:13], v[164:167], v[212:215], v[10:13]
	v_mfma_f32_16x16x32_bf16 v[62:65], v[160:163], v[192:195], v[62:65]
	v_mfma_f32_16x16x32_bf16 v[58:61], v[168:171], v[192:195], v[58:61]
	v_mfma_f32_16x16x32_bf16 v[50:53], v[160:163], v[200:203], v[50:53]
	v_mfma_f32_16x16x32_bf16 v[42:45], v[168:171], v[200:203], v[42:45]
	v_mfma_f32_16x16x32_bf16 v[34:37], v[160:163], v[208:211], v[34:37]
	v_mfma_f32_16x16x32_bf16 v[26:29], v[168:171], v[208:211], v[26:29]
	v_mfma_f32_16x16x32_bf16 v[18:21], v[160:163], v[218:221], v[18:21]
	v_mfma_f32_16x16x32_bf16 v[10:13], v[168:171], v[218:221], v[10:13]
	s_setprio 0
	s_setprio 1
	v_mfma_f32_16x16x32_bf16 v[54:57], v[172:175], v[188:191], v[54:57]
	v_mfma_f32_16x16x32_bf16 v[46:49], v[180:183], v[188:191], v[46:49]
	v_mfma_f32_16x16x32_bf16 v[38:41], v[172:175], v[196:199], v[38:41]
	v_mfma_f32_16x16x32_bf16 v[30:33], v[180:183], v[196:199], v[30:33]
	v_mfma_f32_16x16x32_bf16 v[22:25], v[172:175], v[204:207], v[22:25]
	v_mfma_f32_16x16x32_bf16 v[14:17], v[180:183], v[204:207], v[14:17]
	v_mfma_f32_16x16x32_bf16 v[6:9], v[172:175], v[212:215], v[6:9]
	v_mfma_f32_16x16x32_bf16 v[2:5], v[180:183], v[212:215], v[2:5]
	v_mfma_f32_16x16x32_bf16 v[54:57], v[176:179], v[192:195], v[54:57]
	v_mfma_f32_16x16x32_bf16 v[46:49], v[184:187], v[192:195], v[46:49]
	v_mfma_f32_16x16x32_bf16 v[38:41], v[176:179], v[200:203], v[38:41]
	v_mfma_f32_16x16x32_bf16 v[30:33], v[184:187], v[200:203], v[30:33]
	v_mfma_f32_16x16x32_bf16 v[22:25], v[176:179], v[208:211], v[22:25]
	v_mfma_f32_16x16x32_bf16 v[14:17], v[184:187], v[208:211], v[14:17]
	v_mfma_f32_16x16x32_bf16 v[6:9], v[176:179], v[218:221], v[6:9]
	v_mfma_f32_16x16x32_bf16 v[2:5], v[184:187], v[218:221], v[2:5]
	s_setprio 0
	s_barrier
	s_add_i32 s53, 0, 0x18000
	s_add_i32 s62, 0, 0x1c000
	s_add_u32 s54, s86, 0x20000
	s_addc_u32 s55, s87, 0
	s_mov_b32 m0, s57
	v_lshl_add_u64 v[228:229], s[54:55], 0, v[130:131]
	global_load_lds_dwordx4 v[228:229], off
	v_lshl_add_u64 v[228:229], s[54:55], 0, v[134:135]
	s_mov_b32 m0, s58
	s_nop 0
	global_load_lds_dwordx4 v[228:229], off
	v_add_u32_e32 v156, s53, v153
	ds_read_b128 v[146:149], v156
	ds_read_b128 v[160:163], v156 offset:1024
	ds_read_b128 v[164:167], v156 offset:2048
	ds_read_b128 v[168:171], v156 offset:3072
	v_add_u32_e32 v156, s62, v153
	ds_read_b128 v[172:175], v156
	ds_read_b128 v[176:179], v156 offset:1024
	ds_read_b128 v[180:183], v156 offset:2048
	ds_read_b128 v[184:187], v156 offset:3072
	ds_read_b128 v[188:191], v155 offset:32768
	ds_read_b128 v[192:195], v155 offset:33792
	ds_read_b128 v[196:199], v155 offset:34816
	ds_read_b128 v[200:203], v155 offset:35840
	ds_read_b128 v[204:207], v155 offset:36864
	ds_read_b128 v[208:211], v155 offset:37888
	ds_read_b128 v[212:215], v155 offset:38912
	ds_read_b128 v[218:221], v155 offset:39936
	s_waitcnt vmcnt(8)
	s_waitcnt lgkmcnt(0)
	s_barrier
	s_setprio 1
	s_waitcnt lgkmcnt(0)
	v_mfma_f32_16x16x32_bf16 v[126:129], v[146:149], v[188:191], v[126:129]
	v_mfma_f32_16x16x32_bf16 v[122:125], v[164:167], v[188:191], v[122:125]
	v_mfma_f32_16x16x32_bf16 v[110:113], v[146:149], v[196:199], v[110:113]
	v_mfma_f32_16x16x32_bf16 v[106:109], v[164:167], v[196:199], v[106:109]
	v_mfma_f32_16x16x32_bf16 v[94:97], v[146:149], v[204:207], v[94:97]
	v_mfma_f32_16x16x32_bf16 v[90:93], v[164:167], v[204:207], v[90:93]
	v_mfma_f32_16x16x32_bf16 v[78:81], v[146:149], v[212:215], v[78:81]
	v_mfma_f32_16x16x32_bf16 v[74:77], v[164:167], v[212:215], v[74:77]
	v_mfma_f32_16x16x32_bf16 v[126:129], v[160:163], v[192:195], v[126:129]
	v_mfma_f32_16x16x32_bf16 v[122:125], v[168:171], v[192:195], v[122:125]
	v_mfma_f32_16x16x32_bf16 v[110:113], v[160:163], v[200:203], v[110:113]
	v_mfma_f32_16x16x32_bf16 v[106:109], v[168:171], v[200:203], v[106:109]
	v_mfma_f32_16x16x32_bf16 v[94:97], v[160:163], v[208:211], v[94:97]
	v_mfma_f32_16x16x32_bf16 v[90:93], v[168:171], v[208:211], v[90:93]
	v_mfma_f32_16x16x32_bf16 v[78:81], v[160:163], v[218:221], v[78:81]
	v_mfma_f32_16x16x32_bf16 v[74:77], v[168:171], v[218:221], v[74:77]
	s_setprio 0
	s_setprio 1
	v_mfma_f32_16x16x32_bf16 v[118:121], v[172:175], v[188:191], v[118:121]
	v_mfma_f32_16x16x32_bf16 v[114:117], v[180:183], v[188:191], v[114:117]
	v_mfma_f32_16x16x32_bf16 v[102:105], v[172:175], v[196:199], v[102:105]
	v_mfma_f32_16x16x32_bf16 v[98:101], v[180:183], v[196:199], v[98:101]
	v_mfma_f32_16x16x32_bf16 v[86:89], v[172:175], v[204:207], v[86:89]
	v_mfma_f32_16x16x32_bf16 v[82:85], v[180:183], v[204:207], v[82:85]
	v_mfma_f32_16x16x32_bf16 v[70:73], v[172:175], v[212:215], v[70:73]
	v_mfma_f32_16x16x32_bf16 v[66:69], v[180:183], v[212:215], v[66:69]
	v_mfma_f32_16x16x32_bf16 v[118:121], v[176:179], v[192:195], v[118:121]
	v_mfma_f32_16x16x32_bf16 v[114:117], v[184:187], v[192:195], v[114:117]
	v_mfma_f32_16x16x32_bf16 v[102:105], v[176:179], v[200:203], v[102:105]
	v_mfma_f32_16x16x32_bf16 v[98:101], v[184:187], v[200:203], v[98:101]
	v_mfma_f32_16x16x32_bf16 v[86:89], v[176:179], v[208:211], v[86:89]
	v_mfma_f32_16x16x32_bf16 v[82:85], v[184:187], v[208:211], v[82:85]
	v_mfma_f32_16x16x32_bf16 v[70:73], v[176:179], v[218:221], v[70:73]
	v_mfma_f32_16x16x32_bf16 v[66:69], v[184:187], v[218:221], v[66:69]
	s_setprio 0
	s_barrier
	s_add_i32 s53, s53, s13
	v_lshl_add_u64 v[150:151], v[150:151], 0, s[8:9]
	s_mov_b32 m0, s53
	s_nop 0
	global_load_lds_dwordx4 v[150:151], off
	s_add_i32 m0, s53, 0x2000
	s_add_u32 s34, s34, 0x20080
	v_lshl_add_u64 v[150:151], v[222:223], 0, s[8:9]
	s_addc_u32 s35, s35, 0
	s_add_i32 s53, s62, s13
	global_load_lds_dwordx4 v[150:151], off
	v_lshl_add_u64 v[150:151], s[34:35], 0, v[132:133]
	s_mov_b32 m0, s53
	s_nop 0
	global_load_lds_dwordx4 v[150:151], off
	v_lshl_add_u64 v[150:151], s[34:35], 0, v[136:137]
	s_add_i32 m0, s53, 0x2000
	s_nop 0
	global_load_lds_dwordx4 v[150:151], off
	v_lshl_add_u64 v[150:151], v[224:225], 0, s[8:9]
	s_mov_b32 m0, s60
	s_nop 0
	global_load_lds_dwordx4 v[150:151], off
	v_lshl_add_u64 v[150:151], v[226:227], 0, s[8:9]
	s_mov_b32 m0, s61
	s_nop 0
	global_load_lds_dwordx4 v[150:151], off
	ds_read_b128 v[188:191], v155 offset:49152
	ds_read_b128 v[192:195], v155 offset:50176
	ds_read_b128 v[196:199], v155 offset:51200
	ds_read_b128 v[200:203], v155 offset:52224
	ds_read_b128 v[204:207], v155 offset:53248
	ds_read_b128 v[208:211], v155 offset:54272
	ds_read_b128 v[212:215], v155 offset:55296
	ds_read_b128 v[218:221], v155 offset:56320
	s_waitcnt vmcnt(8)
	s_waitcnt lgkmcnt(0)
	s_barrier
	s_setprio 1
	s_waitcnt lgkmcnt(0)
	v_mfma_f32_16x16x32_bf16 v[62:65], v[146:149], v[188:191], v[62:65]
	v_mfma_f32_16x16x32_bf16 v[58:61], v[164:167], v[188:191], v[58:61]
	v_mfma_f32_16x16x32_bf16 v[50:53], v[146:149], v[196:199], v[50:53]
	v_mfma_f32_16x16x32_bf16 v[42:45], v[164:167], v[196:199], v[42:45]
	v_mfma_f32_16x16x32_bf16 v[34:37], v[146:149], v[204:207], v[34:37]
	v_mfma_f32_16x16x32_bf16 v[26:29], v[164:167], v[204:207], v[26:29]
	v_mfma_f32_16x16x32_bf16 v[18:21], v[146:149], v[212:215], v[18:21]
	v_mfma_f32_16x16x32_bf16 v[10:13], v[164:167], v[212:215], v[10:13]
	v_mfma_f32_16x16x32_bf16 v[62:65], v[160:163], v[192:195], v[62:65]
	v_mfma_f32_16x16x32_bf16 v[58:61], v[168:171], v[192:195], v[58:61]
	v_mfma_f32_16x16x32_bf16 v[50:53], v[160:163], v[200:203], v[50:53]
	v_mfma_f32_16x16x32_bf16 v[42:45], v[168:171], v[200:203], v[42:45]
	v_mfma_f32_16x16x32_bf16 v[34:37], v[160:163], v[208:211], v[34:37]
	v_mfma_f32_16x16x32_bf16 v[26:29], v[168:171], v[208:211], v[26:29]
	v_mfma_f32_16x16x32_bf16 v[18:21], v[160:163], v[218:221], v[18:21]
	v_mfma_f32_16x16x32_bf16 v[10:13], v[168:171], v[218:221], v[10:13]
	s_setprio 0
	s_setprio 1
	v_mfma_f32_16x16x32_bf16 v[54:57], v[172:175], v[188:191], v[54:57]
	v_mfma_f32_16x16x32_bf16 v[46:49], v[180:183], v[188:191], v[46:49]
	v_mfma_f32_16x16x32_bf16 v[38:41], v[172:175], v[196:199], v[38:41]
	v_mfma_f32_16x16x32_bf16 v[30:33], v[180:183], v[196:199], v[30:33]
	v_mfma_f32_16x16x32_bf16 v[22:25], v[172:175], v[204:207], v[22:25]
	v_mfma_f32_16x16x32_bf16 v[14:17], v[180:183], v[204:207], v[14:17]
	v_mfma_f32_16x16x32_bf16 v[6:9], v[172:175], v[212:215], v[6:9]
	v_mfma_f32_16x16x32_bf16 v[2:5], v[180:183], v[212:215], v[2:5]
	v_mfma_f32_16x16x32_bf16 v[54:57], v[176:179], v[192:195], v[54:57]
	v_mfma_f32_16x16x32_bf16 v[46:49], v[184:187], v[192:195], v[46:49]
	v_mfma_f32_16x16x32_bf16 v[38:41], v[176:179], v[200:203], v[38:41]
	v_mfma_f32_16x16x32_bf16 v[30:33], v[184:187], v[200:203], v[30:33]
	v_mfma_f32_16x16x32_bf16 v[22:25], v[176:179], v[208:211], v[22:25]
	v_mfma_f32_16x16x32_bf16 v[14:17], v[184:187], v[208:211], v[14:17]
	v_mfma_f32_16x16x32_bf16 v[6:9], v[176:179], v[218:221], v[6:9]
	v_mfma_f32_16x16x32_bf16 v[2:5], v[184:187], v[218:221], v[2:5]
	s_setprio 0
	s_barrier
	s_add_i32 s88, s88, 2
	s_add_u32 s84, s84, 0x100
	s_addc_u32 s85, s85, 0
	s_add_u32 s77, s77, 0x100
	s_addc_u32 s83, s83, 0
	s_cmp_gt_u32 s88, 5
	s_cbranch_scc0 .LBB0_715
	s_and_b64 vcc, exec, s[66:67]
	s_cbranch_vccz .LBB0_718
	s_barrier

.LBB0_995:
	s_add_u32 s34, s88, 0xfff80080
	s_addc_u32 s35, s89, -1
	s_cmp_eq_u32 s81, 28
	s_cselect_b32 s91, s0, s35
	s_cselect_b32 s90, s1, s34
	s_cselect_b32 s35, s52, s77
	s_cselect_b32 s34, s74, s75
	v_lshl_add_u64 v[218:219], s[88:89], 0, v[138:139]
	s_add_i32 m0, s33, 0xc000
	s_nop 0
	global_load_lds_dwordx4 v[218:219], off
	v_lshl_add_u64 v[218:219], s[88:89], 0, v[140:141]
	s_add_i32 m0, s33, 0xe000
	s_nop 0
	global_load_lds_dwordx4 v[218:219], off
	ds_read_b128 v[146:149], v164
	ds_read_b128 v[150:153], v164 offset:1024
	ds_read_b128 v[154:157], v164 offset:2048
	ds_read_b128 v[158:161], v164 offset:3072
	ds_read_b128 v[168:171], v165
	ds_read_b128 v[172:175], v165 offset:1024
	ds_read_b128 v[176:179], v165 offset:2048
	ds_read_b128 v[180:183], v165 offset:3072
	ds_read_b128 v[184:187], v166
	ds_read_b128 v[188:191], v166 offset:1024
	ds_read_b128 v[192:195], v166 offset:2048
	ds_read_b128 v[196:199], v166 offset:3072
	ds_read_b128 v[200:203], v166 offset:4096
	ds_read_b128 v[204:207], v166 offset:5120
	ds_read_b128 v[208:211], v166 offset:6144
	ds_read_b128 v[212:215], v166 offset:7168
	s_waitcnt vmcnt(8)
	s_waitcnt lgkmcnt(0)
	s_barrier
	s_setprio 1
	s_waitcnt lgkmcnt(0)
	v_mfma_f32_16x16x32_bf16 v[126:129], v[146:149], v[184:187], v[126:129]
	v_mfma_f32_16x16x32_bf16 v[122:125], v[154:157], v[184:187], v[122:125]
	v_mfma_f32_16x16x32_bf16 v[110:113], v[146:149], v[192:195], v[110:113]
	v_mfma_f32_16x16x32_bf16 v[106:109], v[154:157], v[192:195], v[106:109]
	v_mfma_f32_16x16x32_bf16 v[94:97], v[146:149], v[200:203], v[94:97]
	v_mfma_f32_16x16x32_bf16 v[90:93], v[154:157], v[200:203], v[90:93]
	v_mfma_f32_16x16x32_bf16 v[78:81], v[146:149], v[208:211], v[78:81]
	v_mfma_f32_16x16x32_bf16 v[74:77], v[154:157], v[208:211], v[74:77]
	v_mfma_f32_16x16x32_bf16 v[126:129], v[150:153], v[188:191], v[126:129]
	v_mfma_f32_16x16x32_bf16 v[122:125], v[158:161], v[188:191], v[122:125]
	v_mfma_f32_16x16x32_bf16 v[110:113], v[150:153], v[196:199], v[110:113]
	v_mfma_f32_16x16x32_bf16 v[106:109], v[158:161], v[196:199], v[106:109]
	v_mfma_f32_16x16x32_bf16 v[94:97], v[150:153], v[204:207], v[94:97]
	v_mfma_f32_16x16x32_bf16 v[90:93], v[158:161], v[204:207], v[90:93]
	v_mfma_f32_16x16x32_bf16 v[78:81], v[150:153], v[212:215], v[78:81]
	v_mfma_f32_16x16x32_bf16 v[74:77], v[158:161], v[212:215], v[74:77]
	s_setprio 0
	s_setprio 1
	v_mfma_f32_16x16x32_bf16 v[118:121], v[168:171], v[184:187], v[118:121]
	v_mfma_f32_16x16x32_bf16 v[114:117], v[176:179], v[184:187], v[114:117]
	v_mfma_f32_16x16x32_bf16 v[102:105], v[168:171], v[192:195], v[102:105]
	v_mfma_f32_16x16x32_bf16 v[98:101], v[176:179], v[192:195], v[98:101]
	v_mfma_f32_16x16x32_bf16 v[86:89], v[168:171], v[200:203], v[86:89]
	v_mfma_f32_16x16x32_bf16 v[82:85], v[176:179], v[200:203], v[82:85]
	v_mfma_f32_16x16x32_bf16 v[70:73], v[168:171], v[208:211], v[70:73]
	v_mfma_f32_16x16x32_bf16 v[66:69], v[176:179], v[208:211], v[66:69]
	v_mfma_f32_16x16x32_bf16 v[118:121], v[172:175], v[188:191], v[118:121]
	v_mfma_f32_16x16x32_bf16 v[114:117], v[180:183], v[188:191], v[114:117]
	v_mfma_f32_16x16x32_bf16 v[102:105], v[172:175], v[196:199], v[102:105]
	v_mfma_f32_16x16x32_bf16 v[98:101], v[180:183], v[196:199], v[98:101]
	v_mfma_f32_16x16x32_bf16 v[86:89], v[172:175], v[204:207], v[86:89]
	v_mfma_f32_16x16x32_bf16 v[82:85], v[180:183], v[204:207], v[82:85]
	v_mfma_f32_16x16x32_bf16 v[70:73], v[172:175], v[212:215], v[70:73]
	v_mfma_f32_16x16x32_bf16 v[66:69], v[180:183], v[212:215], v[66:69]
	s_setprio 0
	s_barrier
	s_add_i32 s53, s71, s31
	v_lshl_add_u64 v[218:219], s[34:35], 0, v[132:133]
	s_mov_b32 m0, s53
	s_nop 0
	global_load_lds_dwordx4 v[218:219], off
	s_add_i32 m0, s53, 0x2000
	s_add_u32 s54, s34, 0x80000
	v_lshl_add_u64 v[220:221], s[34:35], 0, v[136:137]
	s_addc_u32 s55, s35, 0
	s_add_i32 s53, s72, s31
	global_load_lds_dwordx4 v[220:221], off
	v_lshl_add_u64 v[222:223], s[54:55], 0, v[132:133]
	s_mov_b32 m0, s53
	v_lshl_add_u64 v[224:225], s[90:91], 0, v[134:135]
	global_load_lds_dwordx4 v[222:223], off
	v_lshl_add_u64 v[222:223], s[54:55], 0, v[136:137]
	s_add_i32 m0, s53, 0x2000
	s_nop 0
	global_load_lds_dwordx4 v[222:223], off
	v_lshl_add_u64 v[222:223], s[90:91], 0, v[130:131]
	s_mov_b32 m0, s33
	s_nop 0
	global_load_lds_dwordx4 v[222:223], off
	s_mov_b32 m0, s56
	s_nop 0
	global_load_lds_dwordx4 v[224:225], off
	ds_read_b128 v[184:187], v166 offset:16384
	ds_read_b128 v[188:191], v166 offset:17408
	ds_read_b128 v[192:195], v166 offset:18432
	ds_read_b128 v[196:199], v166 offset:19456
	ds_read_b128 v[200:203], v166 offset:20480
	ds_read_b128 v[204:207], v166 offset:21504
	ds_read_b128 v[208:211], v166 offset:22528
	ds_read_b128 v[212:215], v166 offset:23552
	s_waitcnt vmcnt(8)
	s_waitcnt lgkmcnt(0)
	s_barrier
	s_setprio 1
	s_waitcnt lgkmcnt(0)
	v_mfma_f32_16x16x32_bf16 v[62:65], v[146:149], v[184:187], v[62:65]
	v_mfma_f32_16x16x32_bf16 v[58:61], v[154:157], v[184:187], v[58:61]
	v_mfma_f32_16x16x32_bf16 v[46:49], v[146:149], v[192:195], v[46:49]
	v_mfma_f32_16x16x32_bf16 v[42:45], v[154:157], v[192:195], v[42:45]
	v_mfma_f32_16x16x32_bf16 v[30:33], v[146:149], v[200:203], v[30:33]
	v_mfma_f32_16x16x32_bf16 v[26:29], v[154:157], v[200:203], v[26:29]
	v_mfma_f32_16x16x32_bf16 v[14:17], v[146:149], v[208:211], v[14:17]
	v_mfma_f32_16x16x32_bf16 v[10:13], v[154:157], v[208:211], v[10:13]
	v_mfma_f32_16x16x32_bf16 v[62:65], v[150:153], v[188:191], v[62:65]
	v_mfma_f32_16x16x32_bf16 v[58:61], v[158:161], v[188:191], v[58:61]
	v_mfma_f32_16x16x32_bf16 v[46:49], v[150:153], v[196:199], v[46:49]
	v_mfma_f32_16x16x32_bf16 v[42:45], v[158:161], v[196:199], v[42:45]
	v_mfma_f32_16x16x32_bf16 v[30:33], v[150:153], v[204:207], v[30:33]
	v_mfma_f32_16x16x32_bf16 v[26:29], v[158:161], v[204:207], v[26:29]
	v_mfma_f32_16x16x32_bf16 v[14:17], v[150:153], v[212:215], v[14:17]
	v_mfma_f32_16x16x32_bf16 v[10:13], v[158:161], v[212:215], v[10:13]
	s_setprio 0
	s_setprio 1
	v_mfma_f32_16x16x32_bf16 v[54:57], v[168:171], v[184:187], v[54:57]
	v_mfma_f32_16x16x32_bf16 v[50:53], v[176:179], v[184:187], v[50:53]
	v_mfma_f32_16x16x32_bf16 v[38:41], v[168:171], v[192:195], v[38:41]
	v_mfma_f32_16x16x32_bf16 v[34:37], v[176:179], v[192:195], v[34:37]
	v_mfma_f32_16x16x32_bf16 v[22:25], v[168:171], v[200:203], v[22:25]
	v_mfma_f32_16x16x32_bf16 v[18:21], v[176:179], v[200:203], v[18:21]
	v_mfma_f32_16x16x32_bf16 v[6:9], v[168:171], v[208:211], v[6:9]
	v_mfma_f32_16x16x32_bf16 v[2:5], v[176:179], v[208:211], v[2:5]
	v_mfma_f32_16x16x32_bf16 v[54:57], v[172:175], v[188:191], v[54:57]
	v_mfma_f32_16x16x32_bf16 v[50:53], v[180:183], v[188:191], v[50:53]
	v_mfma_f32_16x16x32_bf16 v[38:41], v[172:175], v[196:199], v[38:41]
	v_mfma_f32_16x16x32_bf16 v[34:37], v[180:183], v[196:199], v[34:37]
	v_mfma_f32_16x16x32_bf16 v[22:25], v[172:175], v[204:207], v[22:25]
	v_mfma_f32_16x16x32_bf16 v[18:21], v[180:183], v[204:207], v[18:21]
	v_mfma_f32_16x16x32_bf16 v[6:9], v[172:175], v[212:215], v[6:9]
	v_mfma_f32_16x16x32_bf16 v[2:5], v[180:183], v[212:215], v[2:5]
	s_setprio 0
	s_barrier
	s_add_i32 s53, 0, 0x18000
	s_add_i32 s62, 0, 0x1c000
	s_add_u32 s54, s90, 0x80000
	s_addc_u32 s55, s91, 0
	s_mov_b32 m0, s57
	v_lshl_add_u64 v[226:227], s[54:55], 0, v[130:131]
	global_load_lds_dwordx4 v[226:227], off
	v_lshl_add_u64 v[226:227], s[54:55], 0, v[134:135]
	s_mov_b32 m0, s58
	s_nop 0
	global_load_lds_dwordx4 v[226:227], off
	v_add_u32_e32 v158, s53, v162
	v_add_u32_e32 v167, s62, v162
	ds_read_b128 v[146:149], v158
	ds_read_b128 v[150:153], v158 offset:1024
	ds_read_b128 v[154:157], v158 offset:2048
	ds_read_b128 v[158:161], v158 offset:3072
	ds_read_b128 v[168:171], v167
	ds_read_b128 v[172:175], v167 offset:1024
	ds_read_b128 v[176:179], v167 offset:2048
	ds_read_b128 v[180:183], v167 offset:3072
	ds_read_b128 v[184:187], v166 offset:32768
	ds_read_b128 v[188:191], v166 offset:33792
	ds_read_b128 v[192:195], v166 offset:34816
	ds_read_b128 v[196:199], v166 offset:35840
	ds_read_b128 v[200:203], v166 offset:36864
	ds_read_b128 v[204:207], v166 offset:37888
	ds_read_b128 v[208:211], v166 offset:38912
	ds_read_b128 v[212:215], v166 offset:39936
	s_waitcnt vmcnt(8)
	s_waitcnt lgkmcnt(0)
	s_barrier
	s_setprio 1
	s_waitcnt lgkmcnt(0)
	v_mfma_f32_16x16x32_bf16 v[126:129], v[146:149], v[184:187], v[126:129]
	v_mfma_f32_16x16x32_bf16 v[122:125], v[154:157], v[184:187], v[122:125]
	v_mfma_f32_16x16x32_bf16 v[110:113], v[146:149], v[192:195], v[110:113]
	v_mfma_f32_16x16x32_bf16 v[106:109], v[154:157], v[192:195], v[106:109]
	v_mfma_f32_16x16x32_bf16 v[94:97], v[146:149], v[200:203], v[94:97]
	v_mfma_f32_16x16x32_bf16 v[90:93], v[154:157], v[200:203], v[90:93]
	v_mfma_f32_16x16x32_bf16 v[78:81], v[146:149], v[208:211], v[78:81]
	v_mfma_f32_16x16x32_bf16 v[74:77], v[154:157], v[208:211], v[74:77]
	v_mfma_f32_16x16x32_bf16 v[126:129], v[150:153], v[188:191], v[126:129]
	v_mfma_f32_16x16x32_bf16 v[122:125], v[158:161], v[188:191], v[122:125]
	v_mfma_f32_16x16x32_bf16 v[110:113], v[150:153], v[196:199], v[110:113]
	v_mfma_f32_16x16x32_bf16 v[106:109], v[158:161], v[196:199], v[106:109]
	v_mfma_f32_16x16x32_bf16 v[94:97], v[150:153], v[204:207], v[94:97]
	v_mfma_f32_16x16x32_bf16 v[90:93], v[158:161], v[204:207], v[90:93]
	v_mfma_f32_16x16x32_bf16 v[78:81], v[150:153], v[212:215], v[78:81]
	v_mfma_f32_16x16x32_bf16 v[74:77], v[158:161], v[212:215], v[74:77]
	s_setprio 0
	s_setprio 1
	v_mfma_f32_16x16x32_bf16 v[118:121], v[168:171], v[184:187], v[118:121]
	v_mfma_f32_16x16x32_bf16 v[114:117], v[176:179], v[184:187], v[114:117]
	v_mfma_f32_16x16x32_bf16 v[102:105], v[168:171], v[192:195], v[102:105]
	v_mfma_f32_16x16x32_bf16 v[98:101], v[176:179], v[192:195], v[98:101]
	v_mfma_f32_16x16x32_bf16 v[86:89], v[168:171], v[200:203], v[86:89]
	v_mfma_f32_16x16x32_bf16 v[82:85], v[176:179], v[200:203], v[82:85]
	v_mfma_f32_16x16x32_bf16 v[70:73], v[168:171], v[208:211], v[70:73]
	v_mfma_f32_16x16x32_bf16 v[66:69], v[176:179], v[208:211], v[66:69]
	v_mfma_f32_16x16x32_bf16 v[118:121], v[172:175], v[188:191], v[118:121]
	v_mfma_f32_16x16x32_bf16 v[114:117], v[180:183], v[188:191], v[114:117]
	v_mfma_f32_16x16x32_bf16 v[102:105], v[172:175], v[196:199], v[102:105]
	v_mfma_f32_16x16x32_bf16 v[98:101], v[180:183], v[196:199], v[98:101]
	v_mfma_f32_16x16x32_bf16 v[86:89], v[172:175], v[204:207], v[86:89]
	v_mfma_f32_16x16x32_bf16 v[82:85], v[180:183], v[204:207], v[82:85]
	v_mfma_f32_16x16x32_bf16 v[70:73], v[172:175], v[212:215], v[70:73]
	v_mfma_f32_16x16x32_bf16 v[66:69], v[180:183], v[212:215], v[66:69]
	s_setprio 0
	s_barrier
	s_add_i32 s53, s53, s31
	v_lshl_add_u64 v[218:219], v[218:219], 0, s[8:9]
	s_mov_b32 m0, s53
	s_nop 0
	global_load_lds_dwordx4 v[218:219], off
	s_add_i32 m0, s53, 0x2000
	s_add_u32 s34, s34, 0x80080
	v_lshl_add_u64 v[218:219], v[220:221], 0, s[8:9]
	s_addc_u32 s35, s35, 0
	s_add_i32 s53, s62, s31
	global_load_lds_dwordx4 v[218:219], off
	v_lshl_add_u64 v[218:219], s[34:35], 0, v[132:133]
	s_mov_b32 m0, s53
	s_nop 0
	global_load_lds_dwordx4 v[218:219], off
	v_lshl_add_u64 v[218:219], s[34:35], 0, v[136:137]
	s_add_i32 m0, s53, 0x2000
	s_nop 0
	global_load_lds_dwordx4 v[218:219], off
	v_lshl_add_u64 v[218:219], v[222:223], 0, s[8:9]
	s_mov_b32 m0, s60
	s_nop 0
	global_load_lds_dwordx4 v[218:219], off
	v_lshl_add_u64 v[218:219], v[224:225], 0, s[8:9]
	s_mov_b32 m0, s61
	s_nop 0
	global_load_lds_dwordx4 v[218:219], off
	ds_read_b128 v[184:187], v166 offset:49152
	ds_read_b128 v[188:191], v166 offset:50176
	ds_read_b128 v[192:195], v166 offset:51200
	ds_read_b128 v[196:199], v166 offset:52224
	ds_read_b128 v[200:203], v166 offset:53248
	ds_read_b128 v[204:207], v166 offset:54272
	ds_read_b128 v[208:211], v166 offset:55296
	ds_read_b128 v[212:215], v166 offset:56320
	s_waitcnt vmcnt(8)
	s_waitcnt lgkmcnt(0)
	s_barrier
	s_setprio 1
	s_waitcnt lgkmcnt(0)
	v_mfma_f32_16x16x32_bf16 v[62:65], v[146:149], v[184:187], v[62:65]
	v_mfma_f32_16x16x32_bf16 v[58:61], v[154:157], v[184:187], v[58:61]
	v_mfma_f32_16x16x32_bf16 v[46:49], v[146:149], v[192:195], v[46:49]
	v_mfma_f32_16x16x32_bf16 v[42:45], v[154:157], v[192:195], v[42:45]
	v_mfma_f32_16x16x32_bf16 v[30:33], v[146:149], v[200:203], v[30:33]
	v_mfma_f32_16x16x32_bf16 v[26:29], v[154:157], v[200:203], v[26:29]
	v_mfma_f32_16x16x32_bf16 v[14:17], v[146:149], v[208:211], v[14:17]
	v_mfma_f32_16x16x32_bf16 v[10:13], v[154:157], v[208:211], v[10:13]
	v_mfma_f32_16x16x32_bf16 v[62:65], v[150:153], v[188:191], v[62:65]
	v_mfma_f32_16x16x32_bf16 v[58:61], v[158:161], v[188:191], v[58:61]
	v_mfma_f32_16x16x32_bf16 v[46:49], v[150:153], v[196:199], v[46:49]
	v_mfma_f32_16x16x32_bf16 v[42:45], v[158:161], v[196:199], v[42:45]
	v_mfma_f32_16x16x32_bf16 v[30:33], v[150:153], v[204:207], v[30:33]
	v_mfma_f32_16x16x32_bf16 v[26:29], v[158:161], v[204:207], v[26:29]
	v_mfma_f32_16x16x32_bf16 v[14:17], v[150:153], v[212:215], v[14:17]
	v_mfma_f32_16x16x32_bf16 v[10:13], v[158:161], v[212:215], v[10:13]
	s_setprio 0
	s_setprio 1
	v_mfma_f32_16x16x32_bf16 v[54:57], v[168:171], v[184:187], v[54:57]
	v_mfma_f32_16x16x32_bf16 v[50:53], v[176:179], v[184:187], v[50:53]
	v_mfma_f32_16x16x32_bf16 v[38:41], v[168:171], v[192:195], v[38:41]
	v_mfma_f32_16x16x32_bf16 v[34:37], v[176:179], v[192:195], v[34:37]
	v_mfma_f32_16x16x32_bf16 v[22:25], v[168:171], v[200:203], v[22:25]
	v_mfma_f32_16x16x32_bf16 v[18:21], v[176:179], v[200:203], v[18:21]
	v_mfma_f32_16x16x32_bf16 v[6:9], v[168:171], v[208:211], v[6:9]
	v_mfma_f32_16x16x32_bf16 v[2:5], v[176:179], v[208:211], v[2:5]
	v_mfma_f32_16x16x32_bf16 v[54:57], v[172:175], v[188:191], v[54:57]
	v_mfma_f32_16x16x32_bf16 v[50:53], v[180:183], v[188:191], v[50:53]
	v_mfma_f32_16x16x32_bf16 v[38:41], v[172:175], v[196:199], v[38:41]
	v_mfma_f32_16x16x32_bf16 v[34:37], v[180:183], v[196:199], v[34:37]
	v_mfma_f32_16x16x32_bf16 v[22:25], v[172:175], v[204:207], v[22:25]
	v_mfma_f32_16x16x32_bf16 v[18:21], v[180:183], v[204:207], v[18:21]
	v_mfma_f32_16x16x32_bf16 v[6:9], v[172:175], v[212:215], v[6:9]
	v_mfma_f32_16x16x32_bf16 v[2:5], v[180:183], v[212:215], v[2:5]
	s_setprio 0
	s_barrier
	s_add_i32 s81, s81, 2
	s_add_u32 s88, s88, 0x100
	s_addc_u32 s89, s89, 0
	s_add_u32 s75, s75, 0x100
	s_addc_u32 s77, s77, 0
	s_cmp_gt_u32 s81, 29
	s_cbranch_scc0 .LBB0_995
	s_and_b64 vcc, exec, s[78:79]
	s_cbranch_vccz .LBB0_998
	s_barrier

.LBB0_1124:
	s_add_u32 s34, s88, 0xfff80080
	s_addc_u32 s35, s89, -1
	s_cmp_eq_u32 s92, 28
	s_cselect_b32 s91, s0, s35
	s_cselect_b32 s90, s1, s34
	s_cselect_b32 s35, s52, s83
	s_cselect_b32 s34, s77, s81
	v_lshl_add_u64 v[218:219], s[88:89], 0, v[138:139]
	s_add_i32 m0, s56, 0xc000
	s_nop 0
	global_load_lds_dwordx4 v[218:219], off
	v_lshl_add_u64 v[218:219], s[88:89], 0, v[140:141]
	s_add_i32 m0, s56, 0xe000
	s_nop 0
	global_load_lds_dwordx4 v[218:219], off
	ds_read_b128 v[146:149], v153
	ds_read_b128 v[156:159], v153 offset:1024
	ds_read_b128 v[160:163], v153 offset:2048
	ds_read_b128 v[164:167], v153 offset:3072
	ds_read_b128 v[168:171], v154
	ds_read_b128 v[172:175], v154 offset:1024
	ds_read_b128 v[176:179], v154 offset:2048
	ds_read_b128 v[180:183], v154 offset:3072
	ds_read_b128 v[184:187], v155
	ds_read_b128 v[188:191], v155 offset:1024
	ds_read_b128 v[192:195], v155 offset:2048
	ds_read_b128 v[196:199], v155 offset:3072
	ds_read_b128 v[200:203], v155 offset:4096
	ds_read_b128 v[204:207], v155 offset:5120
	ds_read_b128 v[208:211], v155 offset:6144
	ds_read_b128 v[212:215], v155 offset:7168
	s_waitcnt vmcnt(8)
	s_waitcnt lgkmcnt(0)
	s_barrier
	s_setprio 1
	s_waitcnt lgkmcnt(0)
	v_mfma_f32_16x16x32_bf16 v[126:129], v[146:149], v[184:187], v[126:129]
	v_mfma_f32_16x16x32_bf16 v[118:121], v[160:163], v[184:187], v[118:121]
	v_mfma_f32_16x16x32_bf16 v[110:113], v[146:149], v[192:195], v[110:113]
	v_mfma_f32_16x16x32_bf16 v[102:105], v[160:163], v[192:195], v[102:105]
	v_mfma_f32_16x16x32_bf16 v[94:97], v[146:149], v[200:203], v[94:97]
	v_mfma_f32_16x16x32_bf16 v[86:89], v[160:163], v[200:203], v[86:89]
	v_mfma_f32_16x16x32_bf16 v[78:81], v[146:149], v[208:211], v[78:81]
	v_mfma_f32_16x16x32_bf16 v[70:73], v[160:163], v[208:211], v[70:73]
	v_mfma_f32_16x16x32_bf16 v[126:129], v[156:159], v[188:191], v[126:129]
	v_mfma_f32_16x16x32_bf16 v[118:121], v[164:167], v[188:191], v[118:121]
	v_mfma_f32_16x16x32_bf16 v[110:113], v[156:159], v[196:199], v[110:113]
	v_mfma_f32_16x16x32_bf16 v[102:105], v[164:167], v[196:199], v[102:105]
	v_mfma_f32_16x16x32_bf16 v[94:97], v[156:159], v[204:207], v[94:97]
	v_mfma_f32_16x16x32_bf16 v[86:89], v[164:167], v[204:207], v[86:89]
	v_mfma_f32_16x16x32_bf16 v[78:81], v[156:159], v[212:215], v[78:81]
	v_mfma_f32_16x16x32_bf16 v[70:73], v[164:167], v[212:215], v[70:73]
	s_setprio 0
	s_setprio 1
	v_mfma_f32_16x16x32_bf16 v[122:125], v[168:171], v[184:187], v[122:125]
	v_mfma_f32_16x16x32_bf16 v[114:117], v[176:179], v[184:187], v[114:117]
	v_mfma_f32_16x16x32_bf16 v[106:109], v[168:171], v[192:195], v[106:109]
	v_mfma_f32_16x16x32_bf16 v[98:101], v[176:179], v[192:195], v[98:101]
	v_mfma_f32_16x16x32_bf16 v[90:93], v[168:171], v[200:203], v[90:93]
	v_mfma_f32_16x16x32_bf16 v[82:85], v[176:179], v[200:203], v[82:85]
	v_mfma_f32_16x16x32_bf16 v[74:77], v[168:171], v[208:211], v[74:77]
	v_mfma_f32_16x16x32_bf16 v[66:69], v[176:179], v[208:211], v[66:69]
	v_mfma_f32_16x16x32_bf16 v[122:125], v[172:175], v[188:191], v[122:125]
	v_mfma_f32_16x16x32_bf16 v[114:117], v[180:183], v[188:191], v[114:117]
	v_mfma_f32_16x16x32_bf16 v[106:109], v[172:175], v[196:199], v[106:109]
	v_mfma_f32_16x16x32_bf16 v[98:101], v[180:183], v[196:199], v[98:101]
	v_mfma_f32_16x16x32_bf16 v[90:93], v[172:175], v[204:207], v[90:93]
	v_mfma_f32_16x16x32_bf16 v[82:85], v[180:183], v[204:207], v[82:85]
	v_mfma_f32_16x16x32_bf16 v[74:77], v[172:175], v[212:215], v[74:77]
	v_mfma_f32_16x16x32_bf16 v[66:69], v[180:183], v[212:215], v[66:69]
	s_setprio 0
	s_barrier
	s_add_i32 s53, s72, s30
	v_lshl_add_u64 v[218:219], s[34:35], 0, v[134:135]
	s_mov_b32 m0, s53
	s_nop 0
	global_load_lds_dwordx4 v[218:219], off
	s_add_i32 m0, s53, 0x2000
	s_add_u32 s54, s34, 0x80000
	v_lshl_add_u64 v[220:221], s[34:35], 0, v[130:131]
	s_addc_u32 s55, s35, 0
	s_add_i32 s53, s73, s30
	global_load_lds_dwordx4 v[220:221], off
	v_lshl_add_u64 v[222:223], s[54:55], 0, v[134:135]
	s_mov_b32 m0, s53
	v_lshl_add_u64 v[224:225], s[90:91], 0, v[132:133]
	global_load_lds_dwordx4 v[222:223], off
	v_lshl_add_u64 v[222:223], s[54:55], 0, v[130:131]
	s_add_i32 m0, s53, 0x2000
	s_nop 0
	global_load_lds_dwordx4 v[222:223], off
	v_lshl_add_u64 v[222:223], s[90:91], 0, v[136:137]
	s_mov_b32 m0, s56
	s_nop 0
	global_load_lds_dwordx4 v[222:223], off
	s_mov_b32 m0, s57
	s_nop 0
	global_load_lds_dwordx4 v[224:225], off
	ds_read_b128 v[184:187], v155 offset:16384
	ds_read_b128 v[188:191], v155 offset:17408
	ds_read_b128 v[192:195], v155 offset:18432
	ds_read_b128 v[196:199], v155 offset:19456
	ds_read_b128 v[200:203], v155 offset:20480
	ds_read_b128 v[204:207], v155 offset:21504
	ds_read_b128 v[208:211], v155 offset:22528
	ds_read_b128 v[212:215], v155 offset:23552
	s_waitcnt vmcnt(8)
	s_waitcnt lgkmcnt(0)
	s_barrier
	s_setprio 1
	s_waitcnt lgkmcnt(0)
	v_mfma_f32_16x16x32_bf16 v[62:65], v[146:149], v[184:187], v[62:65]
	v_mfma_f32_16x16x32_bf16 v[54:57], v[160:163], v[184:187], v[54:57]
	v_mfma_f32_16x16x32_bf16 v[46:49], v[146:149], v[192:195], v[46:49]
	v_mfma_f32_16x16x32_bf16 v[38:41], v[160:163], v[192:195], v[38:41]
	v_mfma_f32_16x16x32_bf16 v[30:33], v[146:149], v[200:203], v[30:33]
	v_mfma_f32_16x16x32_bf16 v[22:25], v[160:163], v[200:203], v[22:25]
	v_mfma_f32_16x16x32_bf16 v[14:17], v[146:149], v[208:211], v[14:17]
	v_mfma_f32_16x16x32_bf16 v[6:9], v[160:163], v[208:211], v[6:9]
	v_mfma_f32_16x16x32_bf16 v[62:65], v[156:159], v[188:191], v[62:65]
	v_mfma_f32_16x16x32_bf16 v[54:57], v[164:167], v[188:191], v[54:57]
	v_mfma_f32_16x16x32_bf16 v[46:49], v[156:159], v[196:199], v[46:49]
	v_mfma_f32_16x16x32_bf16 v[38:41], v[164:167], v[196:199], v[38:41]
	v_mfma_f32_16x16x32_bf16 v[30:33], v[156:159], v[204:207], v[30:33]
	v_mfma_f32_16x16x32_bf16 v[22:25], v[164:167], v[204:207], v[22:25]
	v_mfma_f32_16x16x32_bf16 v[14:17], v[156:159], v[212:215], v[14:17]
	v_mfma_f32_16x16x32_bf16 v[6:9], v[164:167], v[212:215], v[6:9]
	s_setprio 0
	s_setprio 1
	v_mfma_f32_16x16x32_bf16 v[58:61], v[168:171], v[184:187], v[58:61]
	v_mfma_f32_16x16x32_bf16 v[50:53], v[176:179], v[184:187], v[50:53]
	v_mfma_f32_16x16x32_bf16 v[42:45], v[168:171], v[192:195], v[42:45]
	v_mfma_f32_16x16x32_bf16 v[34:37], v[176:179], v[192:195], v[34:37]
	v_mfma_f32_16x16x32_bf16 v[26:29], v[168:171], v[200:203], v[26:29]
	v_mfma_f32_16x16x32_bf16 v[18:21], v[176:179], v[200:203], v[18:21]
	v_mfma_f32_16x16x32_bf16 v[10:13], v[168:171], v[208:211], v[10:13]
	v_mfma_f32_16x16x32_bf16 v[2:5], v[176:179], v[208:211], v[2:5]
	v_mfma_f32_16x16x32_bf16 v[58:61], v[172:175], v[188:191], v[58:61]
	v_mfma_f32_16x16x32_bf16 v[50:53], v[180:183], v[188:191], v[50:53]
	v_mfma_f32_16x16x32_bf16 v[42:45], v[172:175], v[196:199], v[42:45]
	v_mfma_f32_16x16x32_bf16 v[34:37], v[180:183], v[196:199], v[34:37]
	v_mfma_f32_16x16x32_bf16 v[26:29], v[172:175], v[204:207], v[26:29]
	v_mfma_f32_16x16x32_bf16 v[18:21], v[180:183], v[204:207], v[18:21]
	v_mfma_f32_16x16x32_bf16 v[10:13], v[172:175], v[212:215], v[10:13]
	v_mfma_f32_16x16x32_bf16 v[2:5], v[180:183], v[212:215], v[2:5]
	s_setprio 0
	s_barrier
	s_add_i32 s53, 0, 0x18000
	s_add_i32 s62, 0, 0x1c000
	s_add_u32 s54, s90, 0x80000
	s_addc_u32 s55, s91, 0
	s_mov_b32 m0, s58
	v_lshl_add_u64 v[226:227], s[54:55], 0, v[136:137]
	global_load_lds_dwordx4 v[226:227], off
	v_lshl_add_u64 v[226:227], s[54:55], 0, v[132:133]
	s_mov_b32 m0, s59
	s_nop 0
	global_load_lds_dwordx4 v[226:227], off
	v_add_u32_e32 v164, s53, v151
	v_add_u32_e32 v180, s62, v151
	ds_read_b128 v[146:149], v164
	ds_read_b128 v[156:159], v164 offset:1024
	ds_read_b128 v[160:163], v164 offset:2048
	ds_read_b128 v[164:167], v164 offset:3072
	ds_read_b128 v[168:171], v180
	ds_read_b128 v[172:175], v180 offset:1024
	ds_read_b128 v[176:179], v180 offset:2048
	ds_read_b128 v[180:183], v180 offset:3072
	ds_read_b128 v[184:187], v155 offset:32768
	ds_read_b128 v[188:191], v155 offset:33792
	ds_read_b128 v[192:195], v155 offset:34816
	ds_read_b128 v[196:199], v155 offset:35840
	ds_read_b128 v[200:203], v155 offset:36864
	ds_read_b128 v[204:207], v155 offset:37888
	ds_read_b128 v[208:211], v155 offset:38912
	ds_read_b128 v[212:215], v155 offset:39936
	s_waitcnt vmcnt(8)
	s_waitcnt lgkmcnt(0)
	s_barrier
	s_setprio 1
	s_waitcnt lgkmcnt(0)
	v_mfma_f32_16x16x32_bf16 v[126:129], v[146:149], v[184:187], v[126:129]
	v_mfma_f32_16x16x32_bf16 v[118:121], v[160:163], v[184:187], v[118:121]
	v_mfma_f32_16x16x32_bf16 v[110:113], v[146:149], v[192:195], v[110:113]
	v_mfma_f32_16x16x32_bf16 v[102:105], v[160:163], v[192:195], v[102:105]
	v_mfma_f32_16x16x32_bf16 v[94:97], v[146:149], v[200:203], v[94:97]
	v_mfma_f32_16x16x32_bf16 v[86:89], v[160:163], v[200:203], v[86:89]
	v_mfma_f32_16x16x32_bf16 v[78:81], v[146:149], v[208:211], v[78:81]
	v_mfma_f32_16x16x32_bf16 v[70:73], v[160:163], v[208:211], v[70:73]
	v_mfma_f32_16x16x32_bf16 v[126:129], v[156:159], v[188:191], v[126:129]
	v_mfma_f32_16x16x32_bf16 v[118:121], v[164:167], v[188:191], v[118:121]
	v_mfma_f32_16x16x32_bf16 v[110:113], v[156:159], v[196:199], v[110:113]
	v_mfma_f32_16x16x32_bf16 v[102:105], v[164:167], v[196:199], v[102:105]
	v_mfma_f32_16x16x32_bf16 v[94:97], v[156:159], v[204:207], v[94:97]
	v_mfma_f32_16x16x32_bf16 v[86:89], v[164:167], v[204:207], v[86:89]
	v_mfma_f32_16x16x32_bf16 v[78:81], v[156:159], v[212:215], v[78:81]
	v_mfma_f32_16x16x32_bf16 v[70:73], v[164:167], v[212:215], v[70:73]
	s_setprio 0
	s_setprio 1
	v_mfma_f32_16x16x32_bf16 v[122:125], v[168:171], v[184:187], v[122:125]
	v_mfma_f32_16x16x32_bf16 v[114:117], v[176:179], v[184:187], v[114:117]
	v_mfma_f32_16x16x32_bf16 v[106:109], v[168:171], v[192:195], v[106:109]
	v_mfma_f32_16x16x32_bf16 v[98:101], v[176:179], v[192:195], v[98:101]
	v_mfma_f32_16x16x32_bf16 v[90:93], v[168:171], v[200:203], v[90:93]
	v_mfma_f32_16x16x32_bf16 v[82:85], v[176:179], v[200:203], v[82:85]
	v_mfma_f32_16x16x32_bf16 v[74:77], v[168:171], v[208:211], v[74:77]
	v_mfma_f32_16x16x32_bf16 v[66:69], v[176:179], v[208:211], v[66:69]
	v_mfma_f32_16x16x32_bf16 v[122:125], v[172:175], v[188:191], v[122:125]
	v_mfma_f32_16x16x32_bf16 v[114:117], v[180:183], v[188:191], v[114:117]
	v_mfma_f32_16x16x32_bf16 v[106:109], v[172:175], v[196:199], v[106:109]
	v_mfma_f32_16x16x32_bf16 v[98:101], v[180:183], v[196:199], v[98:101]
	v_mfma_f32_16x16x32_bf16 v[90:93], v[172:175], v[204:207], v[90:93]
	v_mfma_f32_16x16x32_bf16 v[82:85], v[180:183], v[204:207], v[82:85]
	v_mfma_f32_16x16x32_bf16 v[74:77], v[172:175], v[212:215], v[74:77]
	v_mfma_f32_16x16x32_bf16 v[66:69], v[180:183], v[212:215], v[66:69]
	s_setprio 0
	s_barrier
	s_add_i32 s53, s53, s30
	v_lshl_add_u64 v[218:219], v[218:219], 0, s[8:9]
	s_mov_b32 m0, s53
	s_nop 0
	global_load_lds_dwordx4 v[218:219], off
	s_add_i32 m0, s53, 0x2000
	s_add_u32 s34, s34, 0x80080
	v_lshl_add_u64 v[218:219], v[220:221], 0, s[8:9]
	s_addc_u32 s35, s35, 0
	s_add_i32 s53, s62, s30
	global_load_lds_dwordx4 v[218:219], off
	v_lshl_add_u64 v[218:219], s[34:35], 0, v[134:135]
	s_mov_b32 m0, s53
	s_nop 0
	global_load_lds_dwordx4 v[218:219], off
	v_lshl_add_u64 v[218:219], s[34:35], 0, v[130:131]
	s_add_i32 m0, s53, 0x2000
	s_nop 0
	global_load_lds_dwordx4 v[218:219], off
	v_lshl_add_u64 v[218:219], v[222:223], 0, s[8:9]
	s_mov_b32 m0, s61
	s_nop 0
	global_load_lds_dwordx4 v[218:219], off
	v_lshl_add_u64 v[218:219], v[224:225], 0, s[8:9]
	s_mov_b32 m0, s70
	s_nop 0
	global_load_lds_dwordx4 v[218:219], off
	ds_read_b128 v[184:187], v155 offset:49152
	ds_read_b128 v[188:191], v155 offset:50176
	ds_read_b128 v[192:195], v155 offset:51200
	ds_read_b128 v[196:199], v155 offset:52224
	ds_read_b128 v[200:203], v155 offset:53248
	ds_read_b128 v[204:207], v155 offset:54272
	ds_read_b128 v[208:211], v155 offset:55296
	ds_read_b128 v[212:215], v155 offset:56320
	s_waitcnt vmcnt(8)
	s_waitcnt lgkmcnt(0)
	s_barrier
	s_setprio 1
	s_waitcnt lgkmcnt(0)
	v_mfma_f32_16x16x32_bf16 v[62:65], v[146:149], v[184:187], v[62:65]
	v_mfma_f32_16x16x32_bf16 v[54:57], v[160:163], v[184:187], v[54:57]
	v_mfma_f32_16x16x32_bf16 v[46:49], v[146:149], v[192:195], v[46:49]
	v_mfma_f32_16x16x32_bf16 v[38:41], v[160:163], v[192:195], v[38:41]
	v_mfma_f32_16x16x32_bf16 v[30:33], v[146:149], v[200:203], v[30:33]
	v_mfma_f32_16x16x32_bf16 v[22:25], v[160:163], v[200:203], v[22:25]
	v_mfma_f32_16x16x32_bf16 v[14:17], v[146:149], v[208:211], v[14:17]
	v_mfma_f32_16x16x32_bf16 v[6:9], v[160:163], v[208:211], v[6:9]
	v_mfma_f32_16x16x32_bf16 v[62:65], v[156:159], v[188:191], v[62:65]
	v_mfma_f32_16x16x32_bf16 v[54:57], v[164:167], v[188:191], v[54:57]
	v_mfma_f32_16x16x32_bf16 v[46:49], v[156:159], v[196:199], v[46:49]
	v_mfma_f32_16x16x32_bf16 v[38:41], v[164:167], v[196:199], v[38:41]
	v_mfma_f32_16x16x32_bf16 v[30:33], v[156:159], v[204:207], v[30:33]
	v_mfma_f32_16x16x32_bf16 v[22:25], v[164:167], v[204:207], v[22:25]
	v_mfma_f32_16x16x32_bf16 v[14:17], v[156:159], v[212:215], v[14:17]
	v_mfma_f32_16x16x32_bf16 v[6:9], v[164:167], v[212:215], v[6:9]
	s_setprio 0
	s_setprio 1
	v_mfma_f32_16x16x32_bf16 v[58:61], v[168:171], v[184:187], v[58:61]
	v_mfma_f32_16x16x32_bf16 v[50:53], v[176:179], v[184:187], v[50:53]
	v_mfma_f32_16x16x32_bf16 v[42:45], v[168:171], v[192:195], v[42:45]
	v_mfma_f32_16x16x32_bf16 v[34:37], v[176:179], v[192:195], v[34:37]
	v_mfma_f32_16x16x32_bf16 v[26:29], v[168:171], v[200:203], v[26:29]
	v_mfma_f32_16x16x32_bf16 v[18:21], v[176:179], v[200:203], v[18:21]
	v_mfma_f32_16x16x32_bf16 v[10:13], v[168:171], v[208:211], v[10:13]
	v_mfma_f32_16x16x32_bf16 v[2:5], v[176:179], v[208:211], v[2:5]
	v_mfma_f32_16x16x32_bf16 v[58:61], v[172:175], v[188:191], v[58:61]
	v_mfma_f32_16x16x32_bf16 v[50:53], v[180:183], v[188:191], v[50:53]
	v_mfma_f32_16x16x32_bf16 v[42:45], v[172:175], v[196:199], v[42:45]
	v_mfma_f32_16x16x32_bf16 v[34:37], v[180:183], v[196:199], v[34:37]
	v_mfma_f32_16x16x32_bf16 v[26:29], v[172:175], v[204:207], v[26:29]
	v_mfma_f32_16x16x32_bf16 v[18:21], v[180:183], v[204:207], v[18:21]
	v_mfma_f32_16x16x32_bf16 v[10:13], v[172:175], v[212:215], v[10:13]
	v_mfma_f32_16x16x32_bf16 v[2:5], v[180:183], v[212:215], v[2:5]
	s_setprio 0
	s_barrier
	s_add_i32 s92, s92, 2
	s_add_u32 s88, s88, 0x100
	s_addc_u32 s89, s89, 0
	s_add_u32 s81, s81, 0x100
	s_addc_u32 s83, s83, 0
	s_cmp_gt_u32 s92, 29
	s_cbranch_scc0 .LBB0_1124
	s_and_b64 vcc, exec, s[78:79]
	s_cbranch_vccz .LBB0_1127
	s_barrier

.LBB0_1237:
	s_add_u32 s34, s76, 0xffea0080
	s_addc_u32 s35, s77, -1
	s_cmpk_eq_i32 s52, 0x54
	s_cselect_b32 s85, s5, s35
	s_cselect_b32 s84, s4, s34
	s_cselect_b32 s35, s83, s1
	s_cselect_b32 s34, s82, s0
	v_lshl_add_u64 v[218:219], s[76:77], 0, v[138:139]
	s_add_i32 m0, s33, 0xc000
	s_nop 0
	global_load_lds_dwordx4 v[218:219], off
	v_lshl_add_u64 v[218:219], s[76:77], 0, v[140:141]
	s_add_i32 m0, s33, 0xe000
	s_nop 0
	global_load_lds_dwordx4 v[218:219], off
	ds_read_b128 v[146:149], v164
	ds_read_b128 v[150:153], v164 offset:1024
	ds_read_b128 v[154:157], v164 offset:2048
	ds_read_b128 v[158:161], v164 offset:3072
	ds_read_b128 v[168:171], v165
	ds_read_b128 v[172:175], v165 offset:1024
	ds_read_b128 v[176:179], v165 offset:2048
	ds_read_b128 v[180:183], v165 offset:3072
	ds_read_b128 v[184:187], v166
	ds_read_b128 v[188:191], v166 offset:1024
	ds_read_b128 v[192:195], v166 offset:2048
	ds_read_b128 v[196:199], v166 offset:3072
	ds_read_b128 v[200:203], v166 offset:4096
	ds_read_b128 v[204:207], v166 offset:5120
	ds_read_b128 v[208:211], v166 offset:6144
	ds_read_b128 v[212:215], v166 offset:7168
	s_waitcnt vmcnt(8)
	s_waitcnt lgkmcnt(0)
	s_barrier
	s_setprio 1
	s_waitcnt lgkmcnt(0)
	v_mfma_f32_16x16x32_bf16 v[126:129], v[146:149], v[184:187], v[126:129]
	v_mfma_f32_16x16x32_bf16 v[122:125], v[154:157], v[184:187], v[122:125]
	v_mfma_f32_16x16x32_bf16 v[110:113], v[146:149], v[192:195], v[110:113]
	v_mfma_f32_16x16x32_bf16 v[106:109], v[154:157], v[192:195], v[106:109]
	v_mfma_f32_16x16x32_bf16 v[94:97], v[146:149], v[200:203], v[94:97]
	v_mfma_f32_16x16x32_bf16 v[90:93], v[154:157], v[200:203], v[90:93]
	v_mfma_f32_16x16x32_bf16 v[78:81], v[146:149], v[208:211], v[78:81]
	v_mfma_f32_16x16x32_bf16 v[74:77], v[154:157], v[208:211], v[74:77]
	v_mfma_f32_16x16x32_bf16 v[126:129], v[150:153], v[188:191], v[126:129]
	v_mfma_f32_16x16x32_bf16 v[122:125], v[158:161], v[188:191], v[122:125]
	v_mfma_f32_16x16x32_bf16 v[110:113], v[150:153], v[196:199], v[110:113]
	v_mfma_f32_16x16x32_bf16 v[106:109], v[158:161], v[196:199], v[106:109]
	v_mfma_f32_16x16x32_bf16 v[94:97], v[150:153], v[204:207], v[94:97]
	v_mfma_f32_16x16x32_bf16 v[90:93], v[158:161], v[204:207], v[90:93]
	v_mfma_f32_16x16x32_bf16 v[78:81], v[150:153], v[212:215], v[78:81]
	v_mfma_f32_16x16x32_bf16 v[74:77], v[158:161], v[212:215], v[74:77]
	s_setprio 0
	s_setprio 1
	v_mfma_f32_16x16x32_bf16 v[118:121], v[168:171], v[184:187], v[118:121]
	v_mfma_f32_16x16x32_bf16 v[114:117], v[176:179], v[184:187], v[114:117]
	v_mfma_f32_16x16x32_bf16 v[102:105], v[168:171], v[192:195], v[102:105]
	v_mfma_f32_16x16x32_bf16 v[98:101], v[176:179], v[192:195], v[98:101]
	v_mfma_f32_16x16x32_bf16 v[86:89], v[168:171], v[200:203], v[86:89]
	v_mfma_f32_16x16x32_bf16 v[82:85], v[176:179], v[200:203], v[82:85]
	v_mfma_f32_16x16x32_bf16 v[70:73], v[168:171], v[208:211], v[70:73]
	v_mfma_f32_16x16x32_bf16 v[66:69], v[176:179], v[208:211], v[66:69]
	v_mfma_f32_16x16x32_bf16 v[118:121], v[172:175], v[188:191], v[118:121]
	v_mfma_f32_16x16x32_bf16 v[114:117], v[180:183], v[188:191], v[114:117]
	v_mfma_f32_16x16x32_bf16 v[102:105], v[172:175], v[196:199], v[102:105]
	v_mfma_f32_16x16x32_bf16 v[98:101], v[180:183], v[196:199], v[98:101]
	v_mfma_f32_16x16x32_bf16 v[86:89], v[172:175], v[204:207], v[86:89]
	v_mfma_f32_16x16x32_bf16 v[82:85], v[180:183], v[204:207], v[82:85]
	v_mfma_f32_16x16x32_bf16 v[70:73], v[172:175], v[212:215], v[70:73]
	v_mfma_f32_16x16x32_bf16 v[66:69], v[180:183], v[212:215], v[66:69]
	s_setprio 0
	s_barrier
	s_add_i32 s53, s71, s31
	v_lshl_add_u64 v[218:219], s[34:35], 0, v[132:133]
	s_mov_b32 m0, s53
	s_nop 0
	global_load_lds_dwordx4 v[218:219], off
	s_add_i32 m0, s53, 0x2000
	s_add_u32 s54, s34, 0x160000
	v_lshl_add_u64 v[220:221], s[34:35], 0, v[136:137]
	s_addc_u32 s55, s35, 0
	s_add_i32 s53, s72, s31
	global_load_lds_dwordx4 v[220:221], off
	v_lshl_add_u64 v[222:223], s[54:55], 0, v[132:133]
	s_mov_b32 m0, s53
	v_lshl_add_u64 v[224:225], s[84:85], 0, v[134:135]
	global_load_lds_dwordx4 v[222:223], off
	v_lshl_add_u64 v[222:223], s[54:55], 0, v[136:137]
	s_add_i32 m0, s53, 0x2000
	s_nop 0
	global_load_lds_dwordx4 v[222:223], off
	v_lshl_add_u64 v[222:223], s[84:85], 0, v[130:131]
	s_mov_b32 m0, s33
	s_nop 0
	global_load_lds_dwordx4 v[222:223], off
	s_mov_b32 m0, s56
	s_nop 0
	global_load_lds_dwordx4 v[224:225], off
	ds_read_b128 v[184:187], v166 offset:16384
	ds_read_b128 v[188:191], v166 offset:17408
	ds_read_b128 v[192:195], v166 offset:18432
	ds_read_b128 v[196:199], v166 offset:19456
	ds_read_b128 v[200:203], v166 offset:20480
	ds_read_b128 v[204:207], v166 offset:21504
	ds_read_b128 v[208:211], v166 offset:22528
	ds_read_b128 v[212:215], v166 offset:23552
	s_waitcnt vmcnt(8)
	s_waitcnt lgkmcnt(0)
	s_barrier
	s_setprio 1
	s_waitcnt lgkmcnt(0)
	v_mfma_f32_16x16x32_bf16 v[62:65], v[146:149], v[184:187], v[62:65]
	v_mfma_f32_16x16x32_bf16 v[58:61], v[154:157], v[184:187], v[58:61]
	v_mfma_f32_16x16x32_bf16 v[46:49], v[146:149], v[192:195], v[46:49]
	v_mfma_f32_16x16x32_bf16 v[42:45], v[154:157], v[192:195], v[42:45]
	v_mfma_f32_16x16x32_bf16 v[30:33], v[146:149], v[200:203], v[30:33]
	v_mfma_f32_16x16x32_bf16 v[26:29], v[154:157], v[200:203], v[26:29]
	v_mfma_f32_16x16x32_bf16 v[14:17], v[146:149], v[208:211], v[14:17]
	v_mfma_f32_16x16x32_bf16 v[10:13], v[154:157], v[208:211], v[10:13]
	v_mfma_f32_16x16x32_bf16 v[62:65], v[150:153], v[188:191], v[62:65]
	v_mfma_f32_16x16x32_bf16 v[58:61], v[158:161], v[188:191], v[58:61]
	v_mfma_f32_16x16x32_bf16 v[46:49], v[150:153], v[196:199], v[46:49]
	v_mfma_f32_16x16x32_bf16 v[42:45], v[158:161], v[196:199], v[42:45]
	v_mfma_f32_16x16x32_bf16 v[30:33], v[150:153], v[204:207], v[30:33]
	v_mfma_f32_16x16x32_bf16 v[26:29], v[158:161], v[204:207], v[26:29]
	v_mfma_f32_16x16x32_bf16 v[14:17], v[150:153], v[212:215], v[14:17]
	v_mfma_f32_16x16x32_bf16 v[10:13], v[158:161], v[212:215], v[10:13]
	s_setprio 0
	s_setprio 1
	v_mfma_f32_16x16x32_bf16 v[54:57], v[168:171], v[184:187], v[54:57]
	v_mfma_f32_16x16x32_bf16 v[50:53], v[176:179], v[184:187], v[50:53]
	v_mfma_f32_16x16x32_bf16 v[38:41], v[168:171], v[192:195], v[38:41]
	v_mfma_f32_16x16x32_bf16 v[34:37], v[176:179], v[192:195], v[34:37]
	v_mfma_f32_16x16x32_bf16 v[22:25], v[168:171], v[200:203], v[22:25]
	v_mfma_f32_16x16x32_bf16 v[18:21], v[176:179], v[200:203], v[18:21]
	v_mfma_f32_16x16x32_bf16 v[6:9], v[168:171], v[208:211], v[6:9]
	v_mfma_f32_16x16x32_bf16 v[2:5], v[176:179], v[208:211], v[2:5]
	v_mfma_f32_16x16x32_bf16 v[54:57], v[172:175], v[188:191], v[54:57]
	v_mfma_f32_16x16x32_bf16 v[50:53], v[180:183], v[188:191], v[50:53]
	v_mfma_f32_16x16x32_bf16 v[38:41], v[172:175], v[196:199], v[38:41]
	v_mfma_f32_16x16x32_bf16 v[34:37], v[180:183], v[196:199], v[34:37]
	v_mfma_f32_16x16x32_bf16 v[22:25], v[172:175], v[204:207], v[22:25]
	v_mfma_f32_16x16x32_bf16 v[18:21], v[180:183], v[204:207], v[18:21]
	v_mfma_f32_16x16x32_bf16 v[6:9], v[172:175], v[212:215], v[6:9]
	v_mfma_f32_16x16x32_bf16 v[2:5], v[180:183], v[212:215], v[2:5]
	s_setprio 0
	s_barrier
	s_add_i32 s53, 0, 0x18000
	s_add_i32 s62, 0, 0x1c000
	s_add_u32 s54, s84, 0x160000
	s_addc_u32 s55, s85, 0
	s_mov_b32 m0, s57
	v_lshl_add_u64 v[226:227], s[54:55], 0, v[130:131]
	global_load_lds_dwordx4 v[226:227], off
	v_lshl_add_u64 v[226:227], s[54:55], 0, v[134:135]
	s_mov_b32 m0, s58
	s_nop 0
	global_load_lds_dwordx4 v[226:227], off
	v_add_u32_e32 v158, s53, v162
	v_add_u32_e32 v167, s62, v162
	ds_read_b128 v[146:149], v158
	ds_read_b128 v[150:153], v158 offset:1024
	ds_read_b128 v[154:157], v158 offset:2048
	ds_read_b128 v[158:161], v158 offset:3072
	ds_read_b128 v[168:171], v167
	ds_read_b128 v[172:175], v167 offset:1024
	ds_read_b128 v[176:179], v167 offset:2048
	ds_read_b128 v[180:183], v167 offset:3072
	ds_read_b128 v[184:187], v166 offset:32768
	ds_read_b128 v[188:191], v166 offset:33792
	ds_read_b128 v[192:195], v166 offset:34816
	ds_read_b128 v[196:199], v166 offset:35840
	ds_read_b128 v[200:203], v166 offset:36864
	ds_read_b128 v[204:207], v166 offset:37888
	ds_read_b128 v[208:211], v166 offset:38912
	ds_read_b128 v[212:215], v166 offset:39936
	s_waitcnt vmcnt(8)
	s_waitcnt lgkmcnt(0)
	s_barrier
	s_setprio 1
	s_waitcnt lgkmcnt(0)
	v_mfma_f32_16x16x32_bf16 v[126:129], v[146:149], v[184:187], v[126:129]
	v_mfma_f32_16x16x32_bf16 v[122:125], v[154:157], v[184:187], v[122:125]
	v_mfma_f32_16x16x32_bf16 v[110:113], v[146:149], v[192:195], v[110:113]
	v_mfma_f32_16x16x32_bf16 v[106:109], v[154:157], v[192:195], v[106:109]
	v_mfma_f32_16x16x32_bf16 v[94:97], v[146:149], v[200:203], v[94:97]
	v_mfma_f32_16x16x32_bf16 v[90:93], v[154:157], v[200:203], v[90:93]
	v_mfma_f32_16x16x32_bf16 v[78:81], v[146:149], v[208:211], v[78:81]
	v_mfma_f32_16x16x32_bf16 v[74:77], v[154:157], v[208:211], v[74:77]
	v_mfma_f32_16x16x32_bf16 v[126:129], v[150:153], v[188:191], v[126:129]
	v_mfma_f32_16x16x32_bf16 v[122:125], v[158:161], v[188:191], v[122:125]
	v_mfma_f32_16x16x32_bf16 v[110:113], v[150:153], v[196:199], v[110:113]
	v_mfma_f32_16x16x32_bf16 v[106:109], v[158:161], v[196:199], v[106:109]
	v_mfma_f32_16x16x32_bf16 v[94:97], v[150:153], v[204:207], v[94:97]
	v_mfma_f32_16x16x32_bf16 v[90:93], v[158:161], v[204:207], v[90:93]
	v_mfma_f32_16x16x32_bf16 v[78:81], v[150:153], v[212:215], v[78:81]
	v_mfma_f32_16x16x32_bf16 v[74:77], v[158:161], v[212:215], v[74:77]
	s_setprio 0
	s_setprio 1
	v_mfma_f32_16x16x32_bf16 v[118:121], v[168:171], v[184:187], v[118:121]
	v_mfma_f32_16x16x32_bf16 v[114:117], v[176:179], v[184:187], v[114:117]
	v_mfma_f32_16x16x32_bf16 v[102:105], v[168:171], v[192:195], v[102:105]
	v_mfma_f32_16x16x32_bf16 v[98:101], v[176:179], v[192:195], v[98:101]
	v_mfma_f32_16x16x32_bf16 v[86:89], v[168:171], v[200:203], v[86:89]
	v_mfma_f32_16x16x32_bf16 v[82:85], v[176:179], v[200:203], v[82:85]
	v_mfma_f32_16x16x32_bf16 v[70:73], v[168:171], v[208:211], v[70:73]
	v_mfma_f32_16x16x32_bf16 v[66:69], v[176:179], v[208:211], v[66:69]
	v_mfma_f32_16x16x32_bf16 v[118:121], v[172:175], v[188:191], v[118:121]
	v_mfma_f32_16x16x32_bf16 v[114:117], v[180:183], v[188:191], v[114:117]
	v_mfma_f32_16x16x32_bf16 v[102:105], v[172:175], v[196:199], v[102:105]
	v_mfma_f32_16x16x32_bf16 v[98:101], v[180:183], v[196:199], v[98:101]
	v_mfma_f32_16x16x32_bf16 v[86:89], v[172:175], v[204:207], v[86:89]
	v_mfma_f32_16x16x32_bf16 v[82:85], v[180:183], v[204:207], v[82:85]
	v_mfma_f32_16x16x32_bf16 v[70:73], v[172:175], v[212:215], v[70:73]
	v_mfma_f32_16x16x32_bf16 v[66:69], v[180:183], v[212:215], v[66:69]
	s_setprio 0
	s_barrier
	s_add_i32 s53, s53, s31
	v_lshl_add_u64 v[218:219], v[218:219], 0, s[78:79]
	s_mov_b32 m0, s53
	s_nop 0
	global_load_lds_dwordx4 v[218:219], off
	s_add_i32 m0, s53, 0x2000
	s_add_u32 s34, s34, 0x160080
	v_lshl_add_u64 v[218:219], v[220:221], 0, s[78:79]
	s_addc_u32 s35, s35, 0
	s_add_i32 s53, s62, s31
	global_load_lds_dwordx4 v[218:219], off
	v_lshl_add_u64 v[218:219], s[34:35], 0, v[132:133]
	s_mov_b32 m0, s53
	s_nop 0
	global_load_lds_dwordx4 v[218:219], off
	v_lshl_add_u64 v[218:219], s[34:35], 0, v[136:137]
	s_add_i32 m0, s53, 0x2000
	s_nop 0
	global_load_lds_dwordx4 v[218:219], off
	v_lshl_add_u64 v[218:219], v[222:223], 0, s[78:79]
	s_mov_b32 m0, s60
	s_nop 0
	global_load_lds_dwordx4 v[218:219], off
	v_lshl_add_u64 v[218:219], v[224:225], 0, s[78:79]
	s_mov_b32 m0, s61
	s_nop 0
	global_load_lds_dwordx4 v[218:219], off
	ds_read_b128 v[184:187], v166 offset:49152
	ds_read_b128 v[188:191], v166 offset:50176
	ds_read_b128 v[192:195], v166 offset:51200
	ds_read_b128 v[196:199], v166 offset:52224
	ds_read_b128 v[200:203], v166 offset:53248
	ds_read_b128 v[204:207], v166 offset:54272
	ds_read_b128 v[208:211], v166 offset:55296
	ds_read_b128 v[212:215], v166 offset:56320
	s_waitcnt vmcnt(8)
	s_waitcnt lgkmcnt(0)
	s_barrier
	s_setprio 1
	s_waitcnt lgkmcnt(0)
	v_mfma_f32_16x16x32_bf16 v[62:65], v[146:149], v[184:187], v[62:65]
	v_mfma_f32_16x16x32_bf16 v[58:61], v[154:157], v[184:187], v[58:61]
	v_mfma_f32_16x16x32_bf16 v[46:49], v[146:149], v[192:195], v[46:49]
	v_mfma_f32_16x16x32_bf16 v[42:45], v[154:157], v[192:195], v[42:45]
	v_mfma_f32_16x16x32_bf16 v[30:33], v[146:149], v[200:203], v[30:33]
	v_mfma_f32_16x16x32_bf16 v[26:29], v[154:157], v[200:203], v[26:29]
	v_mfma_f32_16x16x32_bf16 v[14:17], v[146:149], v[208:211], v[14:17]
	v_mfma_f32_16x16x32_bf16 v[10:13], v[154:157], v[208:211], v[10:13]
	v_mfma_f32_16x16x32_bf16 v[62:65], v[150:153], v[188:191], v[62:65]
	v_mfma_f32_16x16x32_bf16 v[58:61], v[158:161], v[188:191], v[58:61]
	v_mfma_f32_16x16x32_bf16 v[46:49], v[150:153], v[196:199], v[46:49]
	v_mfma_f32_16x16x32_bf16 v[42:45], v[158:161], v[196:199], v[42:45]
	v_mfma_f32_16x16x32_bf16 v[30:33], v[150:153], v[204:207], v[30:33]
	v_mfma_f32_16x16x32_bf16 v[26:29], v[158:161], v[204:207], v[26:29]
	v_mfma_f32_16x16x32_bf16 v[14:17], v[150:153], v[212:215], v[14:17]
	v_mfma_f32_16x16x32_bf16 v[10:13], v[158:161], v[212:215], v[10:13]
	s_setprio 0
	s_setprio 1
	v_mfma_f32_16x16x32_bf16 v[54:57], v[168:171], v[184:187], v[54:57]
	v_mfma_f32_16x16x32_bf16 v[50:53], v[176:179], v[184:187], v[50:53]
	v_mfma_f32_16x16x32_bf16 v[38:41], v[168:171], v[192:195], v[38:41]
	v_mfma_f32_16x16x32_bf16 v[34:37], v[176:179], v[192:195], v[34:37]
	v_mfma_f32_16x16x32_bf16 v[22:25], v[168:171], v[200:203], v[22:25]
	v_mfma_f32_16x16x32_bf16 v[18:21], v[176:179], v[200:203], v[18:21]
	v_mfma_f32_16x16x32_bf16 v[6:9], v[168:171], v[208:211], v[6:9]
	v_mfma_f32_16x16x32_bf16 v[2:5], v[176:179], v[208:211], v[2:5]
	v_mfma_f32_16x16x32_bf16 v[54:57], v[172:175], v[188:191], v[54:57]
	v_mfma_f32_16x16x32_bf16 v[50:53], v[180:183], v[188:191], v[50:53]
	v_mfma_f32_16x16x32_bf16 v[38:41], v[172:175], v[196:199], v[38:41]
	v_mfma_f32_16x16x32_bf16 v[34:37], v[180:183], v[196:199], v[34:37]
	v_mfma_f32_16x16x32_bf16 v[22:25], v[172:175], v[204:207], v[22:25]
	v_mfma_f32_16x16x32_bf16 v[18:21], v[180:183], v[204:207], v[18:21]
	v_mfma_f32_16x16x32_bf16 v[6:9], v[172:175], v[212:215], v[6:9]
	v_mfma_f32_16x16x32_bf16 v[2:5], v[180:183], v[212:215], v[2:5]
	s_setprio 0
	s_barrier
	s_add_i32 s52, s52, 2
	s_add_u32 s76, s76, 0x100
	s_addc_u32 s77, s77, 0
	s_add_u32 s0, s0, 0x100
	s_addc_u32 s1, s1, 0
	s_cmpk_gt_u32 s52, 0x55
	s_cbranch_scc0 .LBB0_1237
	s_and_b64 vcc, exec, s[80:81]
	s_cbranch_vccz .LBB0_1240
	s_barrier

.LBB0_1624:
	s_add_u32 s34, s88, 0xfff80080
	s_addc_u32 s35, s89, -1
	s_cmp_eq_u32 s83, 28
	s_cselect_b32 s91, s0, s35
	s_cselect_b32 s90, s1, s34
	s_cselect_b32 s35, s52, s81
	s_cselect_b32 s34, s75, s77
	v_lshl_add_u64 v[146:147], s[88:89], 0, v[138:139]
	s_add_i32 m0, s33, 0xc000
	s_nop 0
	global_load_lds_dwordx4 v[146:147], off
	v_lshl_add_u64 v[146:147], s[88:89], 0, v[140:141]
	s_add_i32 m0, s33, 0xe000
	s_nop 0
	global_load_lds_dwordx4 v[146:147], off
	ds_read_b128 v[154:157], v151
	ds_read_b128 v[158:161], v151 offset:1024
	ds_read_b128 v[162:165], v151 offset:2048
	ds_read_b128 v[166:169], v151 offset:3072
	ds_read_b128 v[170:173], v152
	ds_read_b128 v[174:177], v152 offset:1024
	ds_read_b128 v[178:181], v152 offset:2048
	ds_read_b128 v[182:185], v152 offset:3072
	ds_read_b128 v[186:189], v153
	ds_read_b128 v[190:193], v153 offset:1024
	ds_read_b128 v[194:197], v153 offset:2048
	ds_read_b128 v[198:201], v153 offset:3072
	ds_read_b128 v[202:205], v153 offset:4096
	ds_read_b128 v[206:209], v153 offset:5120
	ds_read_b128 v[210:213], v153 offset:6144
	ds_read_b128 v[218:221], v153 offset:7168
	s_waitcnt vmcnt(8)
	s_waitcnt lgkmcnt(0)
	s_barrier
	s_setprio 1
	s_waitcnt lgkmcnt(0)
	v_mfma_f32_16x16x32_bf16 v[126:129], v[154:157], v[186:189], v[126:129]
	v_mfma_f32_16x16x32_bf16 v[122:125], v[162:165], v[186:189], v[122:125]
	v_mfma_f32_16x16x32_bf16 v[114:117], v[154:157], v[194:197], v[114:117]
	v_mfma_f32_16x16x32_bf16 v[106:109], v[162:165], v[194:197], v[106:109]
	v_mfma_f32_16x16x32_bf16 v[98:101], v[154:157], v[202:205], v[98:101]
	v_mfma_f32_16x16x32_bf16 v[90:93], v[162:165], v[202:205], v[90:93]
	v_mfma_f32_16x16x32_bf16 v[82:85], v[154:157], v[210:213], v[82:85]
	v_mfma_f32_16x16x32_bf16 v[74:77], v[162:165], v[210:213], v[74:77]
	v_mfma_f32_16x16x32_bf16 v[126:129], v[158:161], v[190:193], v[126:129]
	v_mfma_f32_16x16x32_bf16 v[122:125], v[166:169], v[190:193], v[122:125]
	v_mfma_f32_16x16x32_bf16 v[114:117], v[158:161], v[198:201], v[114:117]
	v_mfma_f32_16x16x32_bf16 v[106:109], v[166:169], v[198:201], v[106:109]
	v_mfma_f32_16x16x32_bf16 v[98:101], v[158:161], v[206:209], v[98:101]
	v_mfma_f32_16x16x32_bf16 v[90:93], v[166:169], v[206:209], v[90:93]
	v_mfma_f32_16x16x32_bf16 v[82:85], v[158:161], v[218:221], v[82:85]
	v_mfma_f32_16x16x32_bf16 v[74:77], v[166:169], v[218:221], v[74:77]
	s_setprio 0
	s_setprio 1
	v_mfma_f32_16x16x32_bf16 v[118:121], v[170:173], v[186:189], v[118:121]
	v_mfma_f32_16x16x32_bf16 v[110:113], v[178:181], v[186:189], v[110:113]
	v_mfma_f32_16x16x32_bf16 v[102:105], v[170:173], v[194:197], v[102:105]
	v_mfma_f32_16x16x32_bf16 v[94:97], v[178:181], v[194:197], v[94:97]
	v_mfma_f32_16x16x32_bf16 v[86:89], v[170:173], v[202:205], v[86:89]
	v_mfma_f32_16x16x32_bf16 v[78:81], v[178:181], v[202:205], v[78:81]
	v_mfma_f32_16x16x32_bf16 v[70:73], v[170:173], v[210:213], v[70:73]
	v_mfma_f32_16x16x32_bf16 v[66:69], v[178:181], v[210:213], v[66:69]
	v_mfma_f32_16x16x32_bf16 v[118:121], v[174:177], v[190:193], v[118:121]
	v_mfma_f32_16x16x32_bf16 v[110:113], v[182:185], v[190:193], v[110:113]
	v_mfma_f32_16x16x32_bf16 v[102:105], v[174:177], v[198:201], v[102:105]
	v_mfma_f32_16x16x32_bf16 v[94:97], v[182:185], v[198:201], v[94:97]
	v_mfma_f32_16x16x32_bf16 v[86:89], v[174:177], v[206:209], v[86:89]
	v_mfma_f32_16x16x32_bf16 v[78:81], v[182:185], v[206:209], v[78:81]
	v_mfma_f32_16x16x32_bf16 v[70:73], v[174:177], v[218:221], v[70:73]
	v_mfma_f32_16x16x32_bf16 v[66:69], v[182:185], v[218:221], v[66:69]
	s_setprio 0
	s_barrier
	s_add_i32 s53, s71, s12
	v_lshl_add_u64 v[146:147], s[34:35], 0, v[134:135]
	s_mov_b32 m0, s53
	s_nop 0
	global_load_lds_dwordx4 v[146:147], off
	s_add_i32 m0, s53, 0x2000
	s_add_u32 s54, s34, 0x80000
	v_lshl_add_u64 v[214:215], s[34:35], 0, v[130:131]
	s_addc_u32 s55, s35, 0
	s_add_i32 s53, s72, s12
	global_load_lds_dwordx4 v[214:215], off
	v_lshl_add_u64 v[222:223], s[54:55], 0, v[134:135]
	s_mov_b32 m0, s53
	v_lshl_add_u64 v[224:225], s[90:91], 0, v[132:133]
	global_load_lds_dwordx4 v[222:223], off
	v_lshl_add_u64 v[222:223], s[54:55], 0, v[130:131]
	s_add_i32 m0, s53, 0x2000
	s_nop 0
	global_load_lds_dwordx4 v[222:223], off
	v_lshl_add_u64 v[222:223], s[90:91], 0, v[136:137]
	s_mov_b32 m0, s33
	s_nop 0
	global_load_lds_dwordx4 v[222:223], off
	s_mov_b32 m0, s56
	s_nop 0
	global_load_lds_dwordx4 v[224:225], off
	ds_read_b128 v[186:189], v153 offset:16384
	ds_read_b128 v[190:193], v153 offset:17408
	ds_read_b128 v[194:197], v153 offset:18432
	ds_read_b128 v[198:201], v153 offset:19456
	ds_read_b128 v[202:205], v153 offset:20480
	ds_read_b128 v[206:209], v153 offset:21504
	ds_read_b128 v[210:213], v153 offset:22528
	ds_read_b128 v[218:221], v153 offset:23552
	s_waitcnt vmcnt(8)
	s_waitcnt lgkmcnt(0)
	s_barrier
	s_setprio 1
	s_waitcnt lgkmcnt(0)
	v_mfma_f32_16x16x32_bf16 v[62:65], v[154:157], v[186:189], v[62:65]
	v_mfma_f32_16x16x32_bf16 v[58:61], v[162:165], v[186:189], v[58:61]
	v_mfma_f32_16x16x32_bf16 v[50:53], v[154:157], v[194:197], v[50:53]
	v_mfma_f32_16x16x32_bf16 v[42:45], v[162:165], v[194:197], v[42:45]
	v_mfma_f32_16x16x32_bf16 v[34:37], v[154:157], v[202:205], v[34:37]
	v_mfma_f32_16x16x32_bf16 v[26:29], v[162:165], v[202:205], v[26:29]
	v_mfma_f32_16x16x32_bf16 v[18:21], v[154:157], v[210:213], v[18:21]
	v_mfma_f32_16x16x32_bf16 v[10:13], v[162:165], v[210:213], v[10:13]
	v_mfma_f32_16x16x32_bf16 v[62:65], v[158:161], v[190:193], v[62:65]
	v_mfma_f32_16x16x32_bf16 v[58:61], v[166:169], v[190:193], v[58:61]
	v_mfma_f32_16x16x32_bf16 v[50:53], v[158:161], v[198:201], v[50:53]
	v_mfma_f32_16x16x32_bf16 v[42:45], v[166:169], v[198:201], v[42:45]
	v_mfma_f32_16x16x32_bf16 v[34:37], v[158:161], v[206:209], v[34:37]
	v_mfma_f32_16x16x32_bf16 v[26:29], v[166:169], v[206:209], v[26:29]
	v_mfma_f32_16x16x32_bf16 v[18:21], v[158:161], v[218:221], v[18:21]
	v_mfma_f32_16x16x32_bf16 v[10:13], v[166:169], v[218:221], v[10:13]
	s_setprio 0
	s_setprio 1
	v_mfma_f32_16x16x32_bf16 v[54:57], v[170:173], v[186:189], v[54:57]
	v_mfma_f32_16x16x32_bf16 v[46:49], v[178:181], v[186:189], v[46:49]
	v_mfma_f32_16x16x32_bf16 v[38:41], v[170:173], v[194:197], v[38:41]
	v_mfma_f32_16x16x32_bf16 v[30:33], v[178:181], v[194:197], v[30:33]
	v_mfma_f32_16x16x32_bf16 v[22:25], v[170:173], v[202:205], v[22:25]
	v_mfma_f32_16x16x32_bf16 v[14:17], v[178:181], v[202:205], v[14:17]
	v_mfma_f32_16x16x32_bf16 v[6:9], v[170:173], v[210:213], v[6:9]
	v_mfma_f32_16x16x32_bf16 v[2:5], v[178:181], v[210:213], v[2:5]
	v_mfma_f32_16x16x32_bf16 v[54:57], v[174:177], v[190:193], v[54:57]
	v_mfma_f32_16x16x32_bf16 v[46:49], v[182:185], v[190:193], v[46:49]
	v_mfma_f32_16x16x32_bf16 v[38:41], v[174:177], v[198:201], v[38:41]
	v_mfma_f32_16x16x32_bf16 v[30:33], v[182:185], v[198:201], v[30:33]
	v_mfma_f32_16x16x32_bf16 v[22:25], v[174:177], v[206:209], v[22:25]
	v_mfma_f32_16x16x32_bf16 v[14:17], v[182:185], v[206:209], v[14:17]
	v_mfma_f32_16x16x32_bf16 v[6:9], v[174:177], v[218:221], v[6:9]
	v_mfma_f32_16x16x32_bf16 v[2:5], v[182:185], v[218:221], v[2:5]
	s_setprio 0
	s_barrier
	s_add_i32 s53, 0, 0x18000
	s_add_i32 s62, 0, 0x1c000
	s_add_u32 s54, s90, 0x80000
	s_addc_u32 s55, s91, 0
	s_mov_b32 m0, s57
	v_lshl_add_u64 v[226:227], s[54:55], 0, v[136:137]
	global_load_lds_dwordx4 v[226:227], off
	v_lshl_add_u64 v[226:227], s[54:55], 0, v[132:133]
	s_mov_b32 m0, s58
	s_nop 0
	global_load_lds_dwordx4 v[226:227], off
	v_add_u32_e32 v166, s53, v149
	v_add_u32_e32 v182, s62, v149
	ds_read_b128 v[154:157], v166
	ds_read_b128 v[158:161], v166 offset:1024
	ds_read_b128 v[162:165], v166 offset:2048
	ds_read_b128 v[166:169], v166 offset:3072
	ds_read_b128 v[170:173], v182
	ds_read_b128 v[174:177], v182 offset:1024
	ds_read_b128 v[178:181], v182 offset:2048
	ds_read_b128 v[182:185], v182 offset:3072
	ds_read_b128 v[186:189], v153 offset:32768
	ds_read_b128 v[190:193], v153 offset:33792
	ds_read_b128 v[194:197], v153 offset:34816
	ds_read_b128 v[198:201], v153 offset:35840
	ds_read_b128 v[202:205], v153 offset:36864
	ds_read_b128 v[206:209], v153 offset:37888
	ds_read_b128 v[210:213], v153 offset:38912
	ds_read_b128 v[218:221], v153 offset:39936
	s_waitcnt vmcnt(8)
	s_waitcnt lgkmcnt(0)
	s_barrier
	s_setprio 1
	s_waitcnt lgkmcnt(0)
	v_mfma_f32_16x16x32_bf16 v[126:129], v[154:157], v[186:189], v[126:129]
	v_mfma_f32_16x16x32_bf16 v[122:125], v[162:165], v[186:189], v[122:125]
	v_mfma_f32_16x16x32_bf16 v[114:117], v[154:157], v[194:197], v[114:117]
	v_mfma_f32_16x16x32_bf16 v[106:109], v[162:165], v[194:197], v[106:109]
	v_mfma_f32_16x16x32_bf16 v[98:101], v[154:157], v[202:205], v[98:101]
	v_mfma_f32_16x16x32_bf16 v[90:93], v[162:165], v[202:205], v[90:93]
	v_mfma_f32_16x16x32_bf16 v[82:85], v[154:157], v[210:213], v[82:85]
	v_mfma_f32_16x16x32_bf16 v[74:77], v[162:165], v[210:213], v[74:77]
	v_mfma_f32_16x16x32_bf16 v[126:129], v[158:161], v[190:193], v[126:129]
	v_mfma_f32_16x16x32_bf16 v[122:125], v[166:169], v[190:193], v[122:125]
	v_mfma_f32_16x16x32_bf16 v[114:117], v[158:161], v[198:201], v[114:117]
	v_mfma_f32_16x16x32_bf16 v[106:109], v[166:169], v[198:201], v[106:109]
	v_mfma_f32_16x16x32_bf16 v[98:101], v[158:161], v[206:209], v[98:101]
	v_mfma_f32_16x16x32_bf16 v[90:93], v[166:169], v[206:209], v[90:93]
	v_mfma_f32_16x16x32_bf16 v[82:85], v[158:161], v[218:221], v[82:85]
	v_mfma_f32_16x16x32_bf16 v[74:77], v[166:169], v[218:221], v[74:77]
	s_setprio 0
	s_setprio 1
	v_mfma_f32_16x16x32_bf16 v[118:121], v[170:173], v[186:189], v[118:121]
	v_mfma_f32_16x16x32_bf16 v[110:113], v[178:181], v[186:189], v[110:113]
	v_mfma_f32_16x16x32_bf16 v[102:105], v[170:173], v[194:197], v[102:105]
	v_mfma_f32_16x16x32_bf16 v[94:97], v[178:181], v[194:197], v[94:97]
	v_mfma_f32_16x16x32_bf16 v[86:89], v[170:173], v[202:205], v[86:89]
	v_mfma_f32_16x16x32_bf16 v[78:81], v[178:181], v[202:205], v[78:81]
	v_mfma_f32_16x16x32_bf16 v[70:73], v[170:173], v[210:213], v[70:73]
	v_mfma_f32_16x16x32_bf16 v[66:69], v[178:181], v[210:213], v[66:69]
	v_mfma_f32_16x16x32_bf16 v[118:121], v[174:177], v[190:193], v[118:121]
	v_mfma_f32_16x16x32_bf16 v[110:113], v[182:185], v[190:193], v[110:113]
	v_mfma_f32_16x16x32_bf16 v[102:105], v[174:177], v[198:201], v[102:105]
	v_mfma_f32_16x16x32_bf16 v[94:97], v[182:185], v[198:201], v[94:97]
	v_mfma_f32_16x16x32_bf16 v[86:89], v[174:177], v[206:209], v[86:89]
	v_mfma_f32_16x16x32_bf16 v[78:81], v[182:185], v[206:209], v[78:81]
	v_mfma_f32_16x16x32_bf16 v[70:73], v[174:177], v[218:221], v[70:73]
	v_mfma_f32_16x16x32_bf16 v[66:69], v[182:185], v[218:221], v[66:69]
	s_setprio 0
	s_barrier
	s_add_i32 s53, s53, s12
	v_lshl_add_u64 v[146:147], v[146:147], 0, s[8:9]
	s_mov_b32 m0, s53
	s_nop 0
	global_load_lds_dwordx4 v[146:147], off
	s_add_i32 m0, s53, 0x2000
	s_add_u32 s34, s34, 0x80080
	v_lshl_add_u64 v[146:147], v[214:215], 0, s[8:9]
	s_addc_u32 s35, s35, 0
	s_add_i32 s53, s62, s12
	global_load_lds_dwordx4 v[146:147], off
	v_lshl_add_u64 v[146:147], s[34:35], 0, v[134:135]
	s_mov_b32 m0, s53
	s_nop 0
	global_load_lds_dwordx4 v[146:147], off
	v_lshl_add_u64 v[146:147], s[34:35], 0, v[130:131]
	s_add_i32 m0, s53, 0x2000
	s_nop 0
	global_load_lds_dwordx4 v[146:147], off
	v_lshl_add_u64 v[146:147], v[222:223], 0, s[8:9]
	s_mov_b32 m0, s60
	s_nop 0
	global_load_lds_dwordx4 v[146:147], off
	v_lshl_add_u64 v[146:147], v[224:225], 0, s[8:9]
	s_mov_b32 m0, s61
	s_nop 0
	global_load_lds_dwordx4 v[146:147], off
	ds_read_b128 v[186:189], v153 offset:49152
	ds_read_b128 v[190:193], v153 offset:50176
	ds_read_b128 v[194:197], v153 offset:51200
	ds_read_b128 v[198:201], v153 offset:52224
	ds_read_b128 v[202:205], v153 offset:53248
	ds_read_b128 v[206:209], v153 offset:54272
	ds_read_b128 v[210:213], v153 offset:55296
	ds_read_b128 v[218:221], v153 offset:56320
	s_waitcnt vmcnt(8)
	s_waitcnt lgkmcnt(0)
	s_barrier
	s_setprio 1
	s_waitcnt lgkmcnt(0)
	v_mfma_f32_16x16x32_bf16 v[62:65], v[154:157], v[186:189], v[62:65]
	v_mfma_f32_16x16x32_bf16 v[58:61], v[162:165], v[186:189], v[58:61]
	v_mfma_f32_16x16x32_bf16 v[50:53], v[154:157], v[194:197], v[50:53]
	v_mfma_f32_16x16x32_bf16 v[42:45], v[162:165], v[194:197], v[42:45]
	v_mfma_f32_16x16x32_bf16 v[34:37], v[154:157], v[202:205], v[34:37]
	v_mfma_f32_16x16x32_bf16 v[26:29], v[162:165], v[202:205], v[26:29]
	v_mfma_f32_16x16x32_bf16 v[18:21], v[154:157], v[210:213], v[18:21]
	v_mfma_f32_16x16x32_bf16 v[10:13], v[162:165], v[210:213], v[10:13]
	v_mfma_f32_16x16x32_bf16 v[62:65], v[158:161], v[190:193], v[62:65]
	v_mfma_f32_16x16x32_bf16 v[58:61], v[166:169], v[190:193], v[58:61]
	v_mfma_f32_16x16x32_bf16 v[50:53], v[158:161], v[198:201], v[50:53]
	v_mfma_f32_16x16x32_bf16 v[42:45], v[166:169], v[198:201], v[42:45]
	v_mfma_f32_16x16x32_bf16 v[34:37], v[158:161], v[206:209], v[34:37]
	v_mfma_f32_16x16x32_bf16 v[26:29], v[166:169], v[206:209], v[26:29]
	v_mfma_f32_16x16x32_bf16 v[18:21], v[158:161], v[218:221], v[18:21]
	v_mfma_f32_16x16x32_bf16 v[10:13], v[166:169], v[218:221], v[10:13]
	s_setprio 0
	s_setprio 1
	v_mfma_f32_16x16x32_bf16 v[54:57], v[170:173], v[186:189], v[54:57]
	v_mfma_f32_16x16x32_bf16 v[46:49], v[178:181], v[186:189], v[46:49]
	v_mfma_f32_16x16x32_bf16 v[38:41], v[170:173], v[194:197], v[38:41]
	v_mfma_f32_16x16x32_bf16 v[30:33], v[178:181], v[194:197], v[30:33]
	v_mfma_f32_16x16x32_bf16 v[22:25], v[170:173], v[202:205], v[22:25]
	v_mfma_f32_16x16x32_bf16 v[14:17], v[178:181], v[202:205], v[14:17]
	v_mfma_f32_16x16x32_bf16 v[6:9], v[170:173], v[210:213], v[6:9]
	v_mfma_f32_16x16x32_bf16 v[2:5], v[178:181], v[210:213], v[2:5]
	v_mfma_f32_16x16x32_bf16 v[54:57], v[174:177], v[190:193], v[54:57]
	v_mfma_f32_16x16x32_bf16 v[46:49], v[182:185], v[190:193], v[46:49]
	v_mfma_f32_16x16x32_bf16 v[38:41], v[174:177], v[198:201], v[38:41]
	v_mfma_f32_16x16x32_bf16 v[30:33], v[182:185], v[198:201], v[30:33]
	v_mfma_f32_16x16x32_bf16 v[22:25], v[174:177], v[206:209], v[22:25]
	v_mfma_f32_16x16x32_bf16 v[14:17], v[182:185], v[206:209], v[14:17]
	v_mfma_f32_16x16x32_bf16 v[6:9], v[174:177], v[218:221], v[6:9]
	v_mfma_f32_16x16x32_bf16 v[2:5], v[182:185], v[218:221], v[2:5]
	s_setprio 0
	s_barrier
	s_add_i32 s83, s83, 2
	s_add_u32 s88, s88, 0x100
	s_addc_u32 s89, s89, 0
	s_add_u32 s77, s77, 0x100
	s_addc_u32 s81, s81, 0
	s_cmp_gt_u32 s83, 29
	s_cbranch_scc0 .LBB0_1624
	s_and_b64 vcc, exec, s[78:79]
	s_cbranch_vccz .LBB0_1627
	s_barrier

.LBB0_2089:
	s_add_u32 s34, s38, 0xffea0080
	s_addc_u32 s35, s39, -1
	s_cmpk_eq_i32 s52, 0x54
	s_cselect_b32 s41, s5, s35
	s_cselect_b32 s40, s4, s34
	s_cselect_b32 s35, s37, s1
	s_cselect_b32 s34, s36, s0
	v_lshl_add_u64 v[174:175], s[38:39], 0, v[154:155]
	s_add_i32 m0, s33, 0xc000
	s_nop 0
	global_load_lds_dwordx4 v[174:175], off
	v_lshl_add_u64 v[174:175], s[38:39], 0, v[156:157]
	s_add_i32 m0, s33, 0xe000
	s_nop 0
	global_load_lds_dwordx4 v[174:175], off
	ds_read_b128 v[130:133], v178
	ds_read_b128 v[134:137], v178 offset:1024
	ds_read_b128 v[138:141], v178 offset:2048
	ds_read_b128 v[142:145], v178 offset:3072
	ds_read_b128 v[162:165], v179
	ds_read_b128 v[166:169], v179 offset:1024
	ds_read_b128 v[170:173], v179 offset:2048
	ds_read_b128 v[182:185], v179 offset:3072
	ds_read_b128 v[186:189], v180
	ds_read_b128 v[190:193], v180 offset:1024
	ds_read_b128 v[194:197], v180 offset:2048
	ds_read_b128 v[198:201], v180 offset:3072
	ds_read_b128 v[202:205], v180 offset:4096
	ds_read_b128 v[206:209], v180 offset:5120
	ds_read_b128 v[210:213], v180 offset:6144
	ds_read_b128 v[218:221], v180 offset:7168
	s_waitcnt vmcnt(8)
	s_waitcnt lgkmcnt(0)
	s_barrier
	s_setprio 1
	s_waitcnt lgkmcnt(0)
	v_mfma_f32_16x16x32_bf16 v[126:129], v[130:133], v[186:189], v[126:129]
	v_mfma_f32_16x16x32_bf16 v[122:125], v[138:141], v[186:189], v[122:125]
	v_mfma_f32_16x16x32_bf16 v[110:113], v[130:133], v[194:197], v[110:113]
	v_mfma_f32_16x16x32_bf16 v[106:109], v[138:141], v[194:197], v[106:109]
	v_mfma_f32_16x16x32_bf16 v[94:97], v[130:133], v[202:205], v[94:97]
	v_mfma_f32_16x16x32_bf16 v[90:93], v[138:141], v[202:205], v[90:93]
	v_mfma_f32_16x16x32_bf16 v[78:81], v[130:133], v[210:213], v[78:81]
	v_mfma_f32_16x16x32_bf16 v[74:77], v[138:141], v[210:213], v[74:77]
	v_mfma_f32_16x16x32_bf16 v[126:129], v[134:137], v[190:193], v[126:129]
	v_mfma_f32_16x16x32_bf16 v[122:125], v[142:145], v[190:193], v[122:125]
	v_mfma_f32_16x16x32_bf16 v[110:113], v[134:137], v[198:201], v[110:113]
	v_mfma_f32_16x16x32_bf16 v[106:109], v[142:145], v[198:201], v[106:109]
	v_mfma_f32_16x16x32_bf16 v[94:97], v[134:137], v[206:209], v[94:97]
	v_mfma_f32_16x16x32_bf16 v[90:93], v[142:145], v[206:209], v[90:93]
	v_mfma_f32_16x16x32_bf16 v[78:81], v[134:137], v[218:221], v[78:81]
	v_mfma_f32_16x16x32_bf16 v[74:77], v[142:145], v[218:221], v[74:77]
	s_setprio 0
	s_setprio 1
	v_mfma_f32_16x16x32_bf16 v[118:121], v[162:165], v[186:189], v[118:121]
	v_mfma_f32_16x16x32_bf16 v[114:117], v[170:173], v[186:189], v[114:117]
	v_mfma_f32_16x16x32_bf16 v[102:105], v[162:165], v[194:197], v[102:105]
	v_mfma_f32_16x16x32_bf16 v[98:101], v[170:173], v[194:197], v[98:101]
	v_mfma_f32_16x16x32_bf16 v[86:89], v[162:165], v[202:205], v[86:89]
	v_mfma_f32_16x16x32_bf16 v[82:85], v[170:173], v[202:205], v[82:85]
	v_mfma_f32_16x16x32_bf16 v[70:73], v[162:165], v[210:213], v[70:73]
	v_mfma_f32_16x16x32_bf16 v[66:69], v[170:173], v[210:213], v[66:69]
	v_mfma_f32_16x16x32_bf16 v[118:121], v[166:169], v[190:193], v[118:121]
	v_mfma_f32_16x16x32_bf16 v[114:117], v[182:185], v[190:193], v[114:117]
	v_mfma_f32_16x16x32_bf16 v[102:105], v[166:169], v[198:201], v[102:105]
	v_mfma_f32_16x16x32_bf16 v[98:101], v[182:185], v[198:201], v[98:101]
	v_mfma_f32_16x16x32_bf16 v[86:89], v[166:169], v[206:209], v[86:89]
	v_mfma_f32_16x16x32_bf16 v[82:85], v[182:185], v[206:209], v[82:85]
	v_mfma_f32_16x16x32_bf16 v[70:73], v[166:169], v[218:221], v[70:73]
	v_mfma_f32_16x16x32_bf16 v[66:69], v[182:185], v[218:221], v[66:69]
	s_setprio 0
	s_barrier
	s_add_i32 s53, s61, s31
	v_lshl_add_u64 v[174:175], s[34:35], 0, v[148:149]
	s_mov_b32 m0, s53
	s_nop 0
	global_load_lds_dwordx4 v[174:175], off
	s_add_i32 m0, s53, 0x2000
	s_add_u32 s54, s34, 0x160000
	v_lshl_add_u64 v[214:215], s[34:35], 0, v[152:153]
	s_addc_u32 s55, s35, 0
	s_add_i32 s53, s70, s31
	global_load_lds_dwordx4 v[214:215], off
	v_lshl_add_u64 v[222:223], s[54:55], 0, v[148:149]
	s_mov_b32 m0, s53
	v_lshl_add_u64 v[224:225], s[40:41], 0, v[150:151]
	global_load_lds_dwordx4 v[222:223], off
	v_lshl_add_u64 v[222:223], s[54:55], 0, v[152:153]
	s_add_i32 m0, s53, 0x2000
	s_nop 0
	global_load_lds_dwordx4 v[222:223], off
	v_lshl_add_u64 v[222:223], s[40:41], 0, v[146:147]
	s_mov_b32 m0, s33
	s_nop 0
	global_load_lds_dwordx4 v[222:223], off
	s_mov_b32 m0, s46
	s_nop 0
	global_load_lds_dwordx4 v[224:225], off
	ds_read_b128 v[186:189], v180 offset:16384
	ds_read_b128 v[190:193], v180 offset:17408
	ds_read_b128 v[194:197], v180 offset:18432
	ds_read_b128 v[198:201], v180 offset:19456
	ds_read_b128 v[202:205], v180 offset:20480
	ds_read_b128 v[206:209], v180 offset:21504
	ds_read_b128 v[210:213], v180 offset:22528
	ds_read_b128 v[218:221], v180 offset:23552
	s_waitcnt vmcnt(8)
	s_waitcnt lgkmcnt(0)
	s_barrier
	s_setprio 1
	s_waitcnt lgkmcnt(0)
	v_mfma_f32_16x16x32_bf16 v[62:65], v[130:133], v[186:189], v[62:65]
	v_mfma_f32_16x16x32_bf16 v[58:61], v[138:141], v[186:189], v[58:61]
	v_mfma_f32_16x16x32_bf16 v[50:53], v[130:133], v[194:197], v[50:53]
	v_mfma_f32_16x16x32_bf16 v[42:45], v[138:141], v[194:197], v[42:45]
	v_mfma_f32_16x16x32_bf16 v[38:41], v[130:133], v[202:205], v[38:41]
	v_mfma_f32_16x16x32_bf16 v[34:37], v[138:141], v[202:205], v[34:37]
	v_mfma_f32_16x16x32_bf16 v[14:17], v[130:133], v[210:213], v[14:17]
	v_mfma_f32_16x16x32_bf16 v[10:13], v[138:141], v[210:213], v[10:13]
	v_mfma_f32_16x16x32_bf16 v[62:65], v[134:137], v[190:193], v[62:65]
	v_mfma_f32_16x16x32_bf16 v[58:61], v[142:145], v[190:193], v[58:61]
	v_mfma_f32_16x16x32_bf16 v[50:53], v[134:137], v[198:201], v[50:53]
	v_mfma_f32_16x16x32_bf16 v[42:45], v[142:145], v[198:201], v[42:45]
	v_mfma_f32_16x16x32_bf16 v[38:41], v[134:137], v[206:209], v[38:41]
	v_mfma_f32_16x16x32_bf16 v[34:37], v[142:145], v[206:209], v[34:37]
	v_mfma_f32_16x16x32_bf16 v[14:17], v[134:137], v[218:221], v[14:17]
	v_mfma_f32_16x16x32_bf16 v[10:13], v[142:145], v[218:221], v[10:13]
	s_setprio 0
	s_setprio 1
	v_mfma_f32_16x16x32_bf16 v[54:57], v[162:165], v[186:189], v[54:57]
	v_mfma_f32_16x16x32_bf16 v[46:49], v[170:173], v[186:189], v[46:49]
	v_mfma_f32_16x16x32_bf16 v[30:33], v[162:165], v[194:197], v[30:33]
	v_mfma_f32_16x16x32_bf16 v[26:29], v[170:173], v[194:197], v[26:29]
	v_mfma_f32_16x16x32_bf16 v[22:25], v[162:165], v[202:205], v[22:25]
	v_mfma_f32_16x16x32_bf16 v[18:21], v[170:173], v[202:205], v[18:21]
	v_mfma_f32_16x16x32_bf16 v[6:9], v[162:165], v[210:213], v[6:9]
	v_mfma_f32_16x16x32_bf16 v[2:5], v[170:173], v[210:213], v[2:5]
	v_mfma_f32_16x16x32_bf16 v[54:57], v[166:169], v[190:193], v[54:57]
	v_mfma_f32_16x16x32_bf16 v[46:49], v[182:185], v[190:193], v[46:49]
	v_mfma_f32_16x16x32_bf16 v[30:33], v[166:169], v[198:201], v[30:33]
	v_mfma_f32_16x16x32_bf16 v[26:29], v[182:185], v[198:201], v[26:29]
	v_mfma_f32_16x16x32_bf16 v[22:25], v[166:169], v[206:209], v[22:25]
	v_mfma_f32_16x16x32_bf16 v[18:21], v[182:185], v[206:209], v[18:21]
	v_mfma_f32_16x16x32_bf16 v[6:9], v[166:169], v[218:221], v[6:9]
	v_mfma_f32_16x16x32_bf16 v[2:5], v[182:185], v[218:221], v[2:5]
	s_setprio 0
	s_barrier
	s_add_i32 s53, 0, 0x18000
	s_add_i32 s54, 0, 0x1c000
	s_add_u32 s40, s40, 0x160000
	s_addc_u32 s41, s41, 0
	s_mov_b32 m0, s47
	v_lshl_add_u64 v[226:227], s[40:41], 0, v[146:147]
	global_load_lds_dwordx4 v[226:227], off
	v_lshl_add_u64 v[226:227], s[40:41], 0, v[150:151]
	s_mov_b32 m0, s56
	s_nop 0
	global_load_lds_dwordx4 v[226:227], off
	v_add_u32_e32 v142, s53, v176
	v_add_u32_e32 v181, s54, v176
	ds_read_b128 v[130:133], v142
	ds_read_b128 v[134:137], v142 offset:1024
	ds_read_b128 v[138:141], v142 offset:2048
	ds_read_b128 v[142:145], v142 offset:3072
	ds_read_b128 v[162:165], v181
	ds_read_b128 v[166:169], v181 offset:1024
	ds_read_b128 v[170:173], v181 offset:2048
	ds_read_b128 v[182:185], v181 offset:3072
	ds_read_b128 v[186:189], v180 offset:32768
	ds_read_b128 v[190:193], v180 offset:33792
	ds_read_b128 v[194:197], v180 offset:34816
	ds_read_b128 v[198:201], v180 offset:35840
	ds_read_b128 v[202:205], v180 offset:36864
	ds_read_b128 v[206:209], v180 offset:37888
	ds_read_b128 v[210:213], v180 offset:38912
	ds_read_b128 v[218:221], v180 offset:39936
	s_waitcnt vmcnt(8)
	s_waitcnt lgkmcnt(0)
	s_barrier
	s_setprio 1
	s_waitcnt lgkmcnt(0)
	v_mfma_f32_16x16x32_bf16 v[126:129], v[130:133], v[186:189], v[126:129]
	v_mfma_f32_16x16x32_bf16 v[122:125], v[138:141], v[186:189], v[122:125]
	v_mfma_f32_16x16x32_bf16 v[110:113], v[130:133], v[194:197], v[110:113]
	v_mfma_f32_16x16x32_bf16 v[106:109], v[138:141], v[194:197], v[106:109]
	v_mfma_f32_16x16x32_bf16 v[94:97], v[130:133], v[202:205], v[94:97]
	v_mfma_f32_16x16x32_bf16 v[90:93], v[138:141], v[202:205], v[90:93]
	v_mfma_f32_16x16x32_bf16 v[78:81], v[130:133], v[210:213], v[78:81]
	v_mfma_f32_16x16x32_bf16 v[74:77], v[138:141], v[210:213], v[74:77]
	v_mfma_f32_16x16x32_bf16 v[126:129], v[134:137], v[190:193], v[126:129]
	v_mfma_f32_16x16x32_bf16 v[122:125], v[142:145], v[190:193], v[122:125]
	v_mfma_f32_16x16x32_bf16 v[110:113], v[134:137], v[198:201], v[110:113]
	v_mfma_f32_16x16x32_bf16 v[106:109], v[142:145], v[198:201], v[106:109]
	v_mfma_f32_16x16x32_bf16 v[94:97], v[134:137], v[206:209], v[94:97]
	v_mfma_f32_16x16x32_bf16 v[90:93], v[142:145], v[206:209], v[90:93]
	v_mfma_f32_16x16x32_bf16 v[78:81], v[134:137], v[218:221], v[78:81]
	v_mfma_f32_16x16x32_bf16 v[74:77], v[142:145], v[218:221], v[74:77]
	s_setprio 0
	s_setprio 1
	v_mfma_f32_16x16x32_bf16 v[118:121], v[162:165], v[186:189], v[118:121]
	v_mfma_f32_16x16x32_bf16 v[114:117], v[170:173], v[186:189], v[114:117]
	v_mfma_f32_16x16x32_bf16 v[102:105], v[162:165], v[194:197], v[102:105]
	v_mfma_f32_16x16x32_bf16 v[98:101], v[170:173], v[194:197], v[98:101]
	v_mfma_f32_16x16x32_bf16 v[86:89], v[162:165], v[202:205], v[86:89]
	v_mfma_f32_16x16x32_bf16 v[82:85], v[170:173], v[202:205], v[82:85]
	v_mfma_f32_16x16x32_bf16 v[70:73], v[162:165], v[210:213], v[70:73]
	v_mfma_f32_16x16x32_bf16 v[66:69], v[170:173], v[210:213], v[66:69]
	v_mfma_f32_16x16x32_bf16 v[118:121], v[166:169], v[190:193], v[118:121]
	v_mfma_f32_16x16x32_bf16 v[114:117], v[182:185], v[190:193], v[114:117]
	v_mfma_f32_16x16x32_bf16 v[102:105], v[166:169], v[198:201], v[102:105]
	v_mfma_f32_16x16x32_bf16 v[98:101], v[182:185], v[198:201], v[98:101]
	v_mfma_f32_16x16x32_bf16 v[86:89], v[166:169], v[206:209], v[86:89]
	v_mfma_f32_16x16x32_bf16 v[82:85], v[182:185], v[206:209], v[82:85]
	v_mfma_f32_16x16x32_bf16 v[70:73], v[166:169], v[218:221], v[70:73]
	v_mfma_f32_16x16x32_bf16 v[66:69], v[182:185], v[218:221], v[66:69]
	s_setprio 0
	s_barrier
	s_add_i32 s40, s53, s31
	v_lshl_add_u64 v[174:175], v[174:175], 0, s[24:25]
	s_mov_b32 m0, s40
	s_nop 0
	global_load_lds_dwordx4 v[174:175], off
	s_add_i32 m0, s40, 0x2000
	s_add_u32 s34, s34, 0x160080
	v_lshl_add_u64 v[174:175], v[214:215], 0, s[24:25]
	s_addc_u32 s35, s35, 0
	s_add_i32 s40, s54, s31
	global_load_lds_dwordx4 v[174:175], off
	v_lshl_add_u64 v[174:175], s[34:35], 0, v[148:149]
	s_mov_b32 m0, s40
	s_nop 0
	global_load_lds_dwordx4 v[174:175], off
	v_lshl_add_u64 v[174:175], s[34:35], 0, v[152:153]
	s_add_i32 m0, s40, 0x2000
	s_nop 0
	global_load_lds_dwordx4 v[174:175], off
	v_lshl_add_u64 v[174:175], v[222:223], 0, s[24:25]
	s_mov_b32 m0, s58
	s_nop 0
	global_load_lds_dwordx4 v[174:175], off
	v_lshl_add_u64 v[174:175], v[224:225], 0, s[24:25]
	s_mov_b32 m0, s59
	s_nop 0
	global_load_lds_dwordx4 v[174:175], off
	ds_read_b128 v[186:189], v180 offset:49152
	ds_read_b128 v[190:193], v180 offset:50176
	ds_read_b128 v[194:197], v180 offset:51200
	ds_read_b128 v[198:201], v180 offset:52224
	ds_read_b128 v[202:205], v180 offset:53248
	ds_read_b128 v[206:209], v180 offset:54272
	ds_read_b128 v[210:213], v180 offset:55296
	ds_read_b128 v[218:221], v180 offset:56320
	s_waitcnt vmcnt(8)
	s_waitcnt lgkmcnt(0)
	s_barrier
	s_setprio 1
	s_waitcnt lgkmcnt(0)
	v_mfma_f32_16x16x32_bf16 v[62:65], v[130:133], v[186:189], v[62:65]
	v_mfma_f32_16x16x32_bf16 v[58:61], v[138:141], v[186:189], v[58:61]
	v_mfma_f32_16x16x32_bf16 v[50:53], v[130:133], v[194:197], v[50:53]
	v_mfma_f32_16x16x32_bf16 v[42:45], v[138:141], v[194:197], v[42:45]
	v_mfma_f32_16x16x32_bf16 v[38:41], v[130:133], v[202:205], v[38:41]
	v_mfma_f32_16x16x32_bf16 v[34:37], v[138:141], v[202:205], v[34:37]
	v_mfma_f32_16x16x32_bf16 v[14:17], v[130:133], v[210:213], v[14:17]
	v_mfma_f32_16x16x32_bf16 v[10:13], v[138:141], v[210:213], v[10:13]
	v_mfma_f32_16x16x32_bf16 v[62:65], v[134:137], v[190:193], v[62:65]
	v_mfma_f32_16x16x32_bf16 v[58:61], v[142:145], v[190:193], v[58:61]
	v_mfma_f32_16x16x32_bf16 v[50:53], v[134:137], v[198:201], v[50:53]
	v_mfma_f32_16x16x32_bf16 v[42:45], v[142:145], v[198:201], v[42:45]
	v_mfma_f32_16x16x32_bf16 v[38:41], v[134:137], v[206:209], v[38:41]
	v_mfma_f32_16x16x32_bf16 v[34:37], v[142:145], v[206:209], v[34:37]
	v_mfma_f32_16x16x32_bf16 v[14:17], v[134:137], v[218:221], v[14:17]
	v_mfma_f32_16x16x32_bf16 v[10:13], v[142:145], v[218:221], v[10:13]
	s_setprio 0
	s_setprio 1
	v_mfma_f32_16x16x32_bf16 v[54:57], v[162:165], v[186:189], v[54:57]
	v_mfma_f32_16x16x32_bf16 v[46:49], v[170:173], v[186:189], v[46:49]
	v_mfma_f32_16x16x32_bf16 v[30:33], v[162:165], v[194:197], v[30:33]
	v_mfma_f32_16x16x32_bf16 v[26:29], v[170:173], v[194:197], v[26:29]
	v_mfma_f32_16x16x32_bf16 v[22:25], v[162:165], v[202:205], v[22:25]
	v_mfma_f32_16x16x32_bf16 v[18:21], v[170:173], v[202:205], v[18:21]
	v_mfma_f32_16x16x32_bf16 v[6:9], v[162:165], v[210:213], v[6:9]
	v_mfma_f32_16x16x32_bf16 v[2:5], v[170:173], v[210:213], v[2:5]
	v_mfma_f32_16x16x32_bf16 v[54:57], v[166:169], v[190:193], v[54:57]
	v_mfma_f32_16x16x32_bf16 v[46:49], v[182:185], v[190:193], v[46:49]
	v_mfma_f32_16x16x32_bf16 v[30:33], v[166:169], v[198:201], v[30:33]
	v_mfma_f32_16x16x32_bf16 v[26:29], v[182:185], v[198:201], v[26:29]
	v_mfma_f32_16x16x32_bf16 v[22:25], v[166:169], v[206:209], v[22:25]
	v_mfma_f32_16x16x32_bf16 v[18:21], v[182:185], v[206:209], v[18:21]
	v_mfma_f32_16x16x32_bf16 v[6:9], v[166:169], v[218:221], v[6:9]
	v_mfma_f32_16x16x32_bf16 v[2:5], v[182:185], v[218:221], v[2:5]
	s_setprio 0
	s_barrier
	s_add_i32 s52, s52, 2
	s_add_u32 s38, s38, 0x100
	s_addc_u32 s39, s39, 0
	s_add_u32 s0, s0, 0x100
	s_addc_u32 s1, s1, 0
	s_cmpk_gt_u32 s52, 0x55
	s_cbranch_scc0 .LBB0_2089
	s_and_b64 vcc, exec, s[26:27]
	s_cbranch_vccz .LBB0_2092
	s_barrier

.LBB0_2218:
	s_add_u32 s34, s76, 0xfff80080
	s_addc_u32 s35, s77, -1
	s_cmp_eq_u32 s80, 28
	s_cselect_b32 s79, s0, s35
	s_cselect_b32 s78, s1, s34
	s_cselect_b32 s35, s27, s75
	s_cselect_b32 s34, s37, s52
	v_lshl_add_u64 v[218:219], s[76:77], 0, v[138:139]
	s_add_i32 m0, s47, 0xc000
	s_nop 0
	global_load_lds_dwordx4 v[218:219], off
	v_lshl_add_u64 v[218:219], s[76:77], 0, v[140:141]
	s_add_i32 m0, s47, 0xe000
	s_nop 0
	global_load_lds_dwordx4 v[218:219], off
	ds_read_b128 v[146:149], v153
	ds_read_b128 v[156:159], v153 offset:1024
	ds_read_b128 v[160:163], v153 offset:2048
	ds_read_b128 v[164:167], v153 offset:3072
	ds_read_b128 v[168:171], v154
	ds_read_b128 v[172:175], v154 offset:1024
	ds_read_b128 v[176:179], v154 offset:2048
	ds_read_b128 v[180:183], v154 offset:3072
	ds_read_b128 v[184:187], v155
	ds_read_b128 v[188:191], v155 offset:1024
	ds_read_b128 v[192:195], v155 offset:2048
	ds_read_b128 v[196:199], v155 offset:3072
	ds_read_b128 v[200:203], v155 offset:4096
	ds_read_b128 v[204:207], v155 offset:5120
	ds_read_b128 v[208:211], v155 offset:6144
	ds_read_b128 v[212:215], v155 offset:7168
	s_waitcnt vmcnt(8)
	s_waitcnt lgkmcnt(0)
	s_barrier
	s_setprio 1
	s_waitcnt lgkmcnt(0)
	v_mfma_f32_16x16x32_bf16 v[126:129], v[146:149], v[184:187], v[126:129]
	v_mfma_f32_16x16x32_bf16 v[118:121], v[160:163], v[184:187], v[118:121]
	v_mfma_f32_16x16x32_bf16 v[110:113], v[146:149], v[192:195], v[110:113]
	v_mfma_f32_16x16x32_bf16 v[102:105], v[160:163], v[192:195], v[102:105]
	v_mfma_f32_16x16x32_bf16 v[94:97], v[146:149], v[200:203], v[94:97]
	v_mfma_f32_16x16x32_bf16 v[86:89], v[160:163], v[200:203], v[86:89]
	v_mfma_f32_16x16x32_bf16 v[78:81], v[146:149], v[208:211], v[78:81]
	v_mfma_f32_16x16x32_bf16 v[70:73], v[160:163], v[208:211], v[70:73]
	v_mfma_f32_16x16x32_bf16 v[126:129], v[156:159], v[188:191], v[126:129]
	v_mfma_f32_16x16x32_bf16 v[118:121], v[164:167], v[188:191], v[118:121]
	v_mfma_f32_16x16x32_bf16 v[110:113], v[156:159], v[196:199], v[110:113]
	v_mfma_f32_16x16x32_bf16 v[102:105], v[164:167], v[196:199], v[102:105]
	v_mfma_f32_16x16x32_bf16 v[94:97], v[156:159], v[204:207], v[94:97]
	v_mfma_f32_16x16x32_bf16 v[86:89], v[164:167], v[204:207], v[86:89]
	v_mfma_f32_16x16x32_bf16 v[78:81], v[156:159], v[212:215], v[78:81]
	v_mfma_f32_16x16x32_bf16 v[70:73], v[164:167], v[212:215], v[70:73]
	s_setprio 0
	s_setprio 1
	v_mfma_f32_16x16x32_bf16 v[122:125], v[168:171], v[184:187], v[122:125]
	v_mfma_f32_16x16x32_bf16 v[114:117], v[176:179], v[184:187], v[114:117]
	v_mfma_f32_16x16x32_bf16 v[106:109], v[168:171], v[192:195], v[106:109]
	v_mfma_f32_16x16x32_bf16 v[98:101], v[176:179], v[192:195], v[98:101]
	v_mfma_f32_16x16x32_bf16 v[90:93], v[168:171], v[200:203], v[90:93]
	v_mfma_f32_16x16x32_bf16 v[82:85], v[176:179], v[200:203], v[82:85]
	v_mfma_f32_16x16x32_bf16 v[74:77], v[168:171], v[208:211], v[74:77]
	v_mfma_f32_16x16x32_bf16 v[66:69], v[176:179], v[208:211], v[66:69]
	v_mfma_f32_16x16x32_bf16 v[122:125], v[172:175], v[188:191], v[122:125]
	v_mfma_f32_16x16x32_bf16 v[114:117], v[180:183], v[188:191], v[114:117]
	v_mfma_f32_16x16x32_bf16 v[106:109], v[172:175], v[196:199], v[106:109]
	v_mfma_f32_16x16x32_bf16 v[98:101], v[180:183], v[196:199], v[98:101]
	v_mfma_f32_16x16x32_bf16 v[90:93], v[172:175], v[204:207], v[90:93]
	v_mfma_f32_16x16x32_bf16 v[82:85], v[180:183], v[204:207], v[82:85]
	v_mfma_f32_16x16x32_bf16 v[74:77], v[172:175], v[212:215], v[74:77]
	v_mfma_f32_16x16x32_bf16 v[66:69], v[180:183], v[212:215], v[66:69]
	s_setprio 0
	s_barrier
	s_add_i32 s53, s71, s30
	v_lshl_add_u64 v[218:219], s[34:35], 0, v[134:135]
	s_mov_b32 m0, s53
	s_nop 0
	global_load_lds_dwordx4 v[218:219], off
	s_add_i32 m0, s53, 0x2000
	s_add_u32 s54, s34, 0x80000
	v_lshl_add_u64 v[220:221], s[34:35], 0, v[130:131]
	s_addc_u32 s55, s35, 0
	s_add_i32 s53, s72, s30
	global_load_lds_dwordx4 v[220:221], off
	v_lshl_add_u64 v[222:223], s[54:55], 0, v[134:135]
	s_mov_b32 m0, s53
	v_lshl_add_u64 v[224:225], s[78:79], 0, v[132:133]
	global_load_lds_dwordx4 v[222:223], off
	v_lshl_add_u64 v[222:223], s[54:55], 0, v[130:131]
	s_add_i32 m0, s53, 0x2000
	s_nop 0
	global_load_lds_dwordx4 v[222:223], off
	v_lshl_add_u64 v[222:223], s[78:79], 0, v[136:137]
	s_mov_b32 m0, s47
	s_nop 0
	global_load_lds_dwordx4 v[222:223], off
	s_mov_b32 m0, s56
	s_nop 0
	global_load_lds_dwordx4 v[224:225], off
	ds_read_b128 v[184:187], v155 offset:16384
	ds_read_b128 v[188:191], v155 offset:17408
	ds_read_b128 v[192:195], v155 offset:18432
	ds_read_b128 v[196:199], v155 offset:19456
	ds_read_b128 v[200:203], v155 offset:20480
	ds_read_b128 v[204:207], v155 offset:21504
	ds_read_b128 v[208:211], v155 offset:22528
	ds_read_b128 v[212:215], v155 offset:23552
	s_waitcnt vmcnt(8)
	s_waitcnt lgkmcnt(0)
	s_barrier
	s_setprio 1
	s_waitcnt lgkmcnt(0)
	v_mfma_f32_16x16x32_bf16 v[62:65], v[146:149], v[184:187], v[62:65]
	v_mfma_f32_16x16x32_bf16 v[54:57], v[160:163], v[184:187], v[54:57]
	v_mfma_f32_16x16x32_bf16 v[46:49], v[146:149], v[192:195], v[46:49]
	v_mfma_f32_16x16x32_bf16 v[38:41], v[160:163], v[192:195], v[38:41]
	v_mfma_f32_16x16x32_bf16 v[30:33], v[146:149], v[200:203], v[30:33]
	v_mfma_f32_16x16x32_bf16 v[22:25], v[160:163], v[200:203], v[22:25]
	v_mfma_f32_16x16x32_bf16 v[14:17], v[146:149], v[208:211], v[14:17]
	v_mfma_f32_16x16x32_bf16 v[6:9], v[160:163], v[208:211], v[6:9]
	v_mfma_f32_16x16x32_bf16 v[62:65], v[156:159], v[188:191], v[62:65]
	v_mfma_f32_16x16x32_bf16 v[54:57], v[164:167], v[188:191], v[54:57]
	v_mfma_f32_16x16x32_bf16 v[46:49], v[156:159], v[196:199], v[46:49]
	v_mfma_f32_16x16x32_bf16 v[38:41], v[164:167], v[196:199], v[38:41]
	v_mfma_f32_16x16x32_bf16 v[30:33], v[156:159], v[204:207], v[30:33]
	v_mfma_f32_16x16x32_bf16 v[22:25], v[164:167], v[204:207], v[22:25]
	v_mfma_f32_16x16x32_bf16 v[14:17], v[156:159], v[212:215], v[14:17]
	v_mfma_f32_16x16x32_bf16 v[6:9], v[164:167], v[212:215], v[6:9]
	s_setprio 0
	s_setprio 1
	v_mfma_f32_16x16x32_bf16 v[58:61], v[168:171], v[184:187], v[58:61]
	v_mfma_f32_16x16x32_bf16 v[50:53], v[176:179], v[184:187], v[50:53]
	v_mfma_f32_16x16x32_bf16 v[42:45], v[168:171], v[192:195], v[42:45]
	v_mfma_f32_16x16x32_bf16 v[34:37], v[176:179], v[192:195], v[34:37]
	v_mfma_f32_16x16x32_bf16 v[26:29], v[168:171], v[200:203], v[26:29]
	v_mfma_f32_16x16x32_bf16 v[18:21], v[176:179], v[200:203], v[18:21]
	v_mfma_f32_16x16x32_bf16 v[10:13], v[168:171], v[208:211], v[10:13]
	v_mfma_f32_16x16x32_bf16 v[2:5], v[176:179], v[208:211], v[2:5]
	v_mfma_f32_16x16x32_bf16 v[58:61], v[172:175], v[188:191], v[58:61]
	v_mfma_f32_16x16x32_bf16 v[50:53], v[180:183], v[188:191], v[50:53]
	v_mfma_f32_16x16x32_bf16 v[42:45], v[172:175], v[196:199], v[42:45]
	v_mfma_f32_16x16x32_bf16 v[34:37], v[180:183], v[196:199], v[34:37]
	v_mfma_f32_16x16x32_bf16 v[26:29], v[172:175], v[204:207], v[26:29]
	v_mfma_f32_16x16x32_bf16 v[18:21], v[180:183], v[204:207], v[18:21]
	v_mfma_f32_16x16x32_bf16 v[10:13], v[172:175], v[212:215], v[10:13]
	v_mfma_f32_16x16x32_bf16 v[2:5], v[180:183], v[212:215], v[2:5]
	s_setprio 0
	s_barrier
	s_add_i32 s53, 0, 0x18000
	s_add_i32 s62, 0, 0x1c000
	s_add_u32 s54, s78, 0x80000
	s_addc_u32 s55, s79, 0
	s_mov_b32 m0, s57
	v_lshl_add_u64 v[226:227], s[54:55], 0, v[136:137]
	global_load_lds_dwordx4 v[226:227], off
	v_lshl_add_u64 v[226:227], s[54:55], 0, v[132:133]
	s_mov_b32 m0, s58
	s_nop 0
	global_load_lds_dwordx4 v[226:227], off
	v_add_u32_e32 v164, s53, v151
	v_add_u32_e32 v180, s62, v151
	ds_read_b128 v[146:149], v164
	ds_read_b128 v[156:159], v164 offset:1024
	ds_read_b128 v[160:163], v164 offset:2048
	ds_read_b128 v[164:167], v164 offset:3072
	ds_read_b128 v[168:171], v180
	ds_read_b128 v[172:175], v180 offset:1024
	ds_read_b128 v[176:179], v180 offset:2048
	ds_read_b128 v[180:183], v180 offset:3072
	ds_read_b128 v[184:187], v155 offset:32768
	ds_read_b128 v[188:191], v155 offset:33792
	ds_read_b128 v[192:195], v155 offset:34816
	ds_read_b128 v[196:199], v155 offset:35840
	ds_read_b128 v[200:203], v155 offset:36864
	ds_read_b128 v[204:207], v155 offset:37888
	ds_read_b128 v[208:211], v155 offset:38912
	ds_read_b128 v[212:215], v155 offset:39936
	s_waitcnt vmcnt(8)
	s_waitcnt lgkmcnt(0)
	s_barrier
	s_setprio 1
	s_waitcnt lgkmcnt(0)
	v_mfma_f32_16x16x32_bf16 v[126:129], v[146:149], v[184:187], v[126:129]
	v_mfma_f32_16x16x32_bf16 v[118:121], v[160:163], v[184:187], v[118:121]
	v_mfma_f32_16x16x32_bf16 v[110:113], v[146:149], v[192:195], v[110:113]
	v_mfma_f32_16x16x32_bf16 v[102:105], v[160:163], v[192:195], v[102:105]
	v_mfma_f32_16x16x32_bf16 v[94:97], v[146:149], v[200:203], v[94:97]
	v_mfma_f32_16x16x32_bf16 v[86:89], v[160:163], v[200:203], v[86:89]
	v_mfma_f32_16x16x32_bf16 v[78:81], v[146:149], v[208:211], v[78:81]
	v_mfma_f32_16x16x32_bf16 v[70:73], v[160:163], v[208:211], v[70:73]
	v_mfma_f32_16x16x32_bf16 v[126:129], v[156:159], v[188:191], v[126:129]
	v_mfma_f32_16x16x32_bf16 v[118:121], v[164:167], v[188:191], v[118:121]
	v_mfma_f32_16x16x32_bf16 v[110:113], v[156:159], v[196:199], v[110:113]
	v_mfma_f32_16x16x32_bf16 v[102:105], v[164:167], v[196:199], v[102:105]
	v_mfma_f32_16x16x32_bf16 v[94:97], v[156:159], v[204:207], v[94:97]
	v_mfma_f32_16x16x32_bf16 v[86:89], v[164:167], v[204:207], v[86:89]
	v_mfma_f32_16x16x32_bf16 v[78:81], v[156:159], v[212:215], v[78:81]
	v_mfma_f32_16x16x32_bf16 v[70:73], v[164:167], v[212:215], v[70:73]
	s_setprio 0
	s_setprio 1
	v_mfma_f32_16x16x32_bf16 v[122:125], v[168:171], v[184:187], v[122:125]
	v_mfma_f32_16x16x32_bf16 v[114:117], v[176:179], v[184:187], v[114:117]
	v_mfma_f32_16x16x32_bf16 v[106:109], v[168:171], v[192:195], v[106:109]
	v_mfma_f32_16x16x32_bf16 v[98:101], v[176:179], v[192:195], v[98:101]
	v_mfma_f32_16x16x32_bf16 v[90:93], v[168:171], v[200:203], v[90:93]
	v_mfma_f32_16x16x32_bf16 v[82:85], v[176:179], v[200:203], v[82:85]
	v_mfma_f32_16x16x32_bf16 v[74:77], v[168:171], v[208:211], v[74:77]
	v_mfma_f32_16x16x32_bf16 v[66:69], v[176:179], v[208:211], v[66:69]
	v_mfma_f32_16x16x32_bf16 v[122:125], v[172:175], v[188:191], v[122:125]
	v_mfma_f32_16x16x32_bf16 v[114:117], v[180:183], v[188:191], v[114:117]
	v_mfma_f32_16x16x32_bf16 v[106:109], v[172:175], v[196:199], v[106:109]
	v_mfma_f32_16x16x32_bf16 v[98:101], v[180:183], v[196:199], v[98:101]
	v_mfma_f32_16x16x32_bf16 v[90:93], v[172:175], v[204:207], v[90:93]
	v_mfma_f32_16x16x32_bf16 v[82:85], v[180:183], v[204:207], v[82:85]
	v_mfma_f32_16x16x32_bf16 v[74:77], v[172:175], v[212:215], v[74:77]
	v_mfma_f32_16x16x32_bf16 v[66:69], v[180:183], v[212:215], v[66:69]
	s_setprio 0
	s_barrier
	s_add_i32 s53, s53, s30
	v_lshl_add_u64 v[218:219], v[218:219], 0, s[8:9]
	s_mov_b32 m0, s53
	s_nop 0
	global_load_lds_dwordx4 v[218:219], off
	s_add_i32 m0, s53, 0x2000
	s_add_u32 s34, s34, 0x80080
	v_lshl_add_u64 v[218:219], v[220:221], 0, s[8:9]
	s_addc_u32 s35, s35, 0
	s_add_i32 s53, s62, s30
	global_load_lds_dwordx4 v[218:219], off
	v_lshl_add_u64 v[218:219], s[34:35], 0, v[134:135]
	s_mov_b32 m0, s53
	s_nop 0
	global_load_lds_dwordx4 v[218:219], off
	v_lshl_add_u64 v[218:219], s[34:35], 0, v[130:131]
	s_add_i32 m0, s53, 0x2000
	s_nop 0
	global_load_lds_dwordx4 v[218:219], off
	v_lshl_add_u64 v[218:219], v[222:223], 0, s[8:9]
	s_mov_b32 m0, s60
	s_nop 0
	global_load_lds_dwordx4 v[218:219], off
	v_lshl_add_u64 v[218:219], v[224:225], 0, s[8:9]
	s_mov_b32 m0, s61
	s_nop 0
	global_load_lds_dwordx4 v[218:219], off
	ds_read_b128 v[184:187], v155 offset:49152
	ds_read_b128 v[188:191], v155 offset:50176
	ds_read_b128 v[192:195], v155 offset:51200
	ds_read_b128 v[196:199], v155 offset:52224
	ds_read_b128 v[200:203], v155 offset:53248
	ds_read_b128 v[204:207], v155 offset:54272
	ds_read_b128 v[208:211], v155 offset:55296
	ds_read_b128 v[212:215], v155 offset:56320
	s_waitcnt vmcnt(8)
	s_waitcnt lgkmcnt(0)
	s_barrier
	s_setprio 1
	s_waitcnt lgkmcnt(0)
	v_mfma_f32_16x16x32_bf16 v[62:65], v[146:149], v[184:187], v[62:65]
	v_mfma_f32_16x16x32_bf16 v[54:57], v[160:163], v[184:187], v[54:57]
	v_mfma_f32_16x16x32_bf16 v[46:49], v[146:149], v[192:195], v[46:49]
	v_mfma_f32_16x16x32_bf16 v[38:41], v[160:163], v[192:195], v[38:41]
	v_mfma_f32_16x16x32_bf16 v[30:33], v[146:149], v[200:203], v[30:33]
	v_mfma_f32_16x16x32_bf16 v[22:25], v[160:163], v[200:203], v[22:25]
	v_mfma_f32_16x16x32_bf16 v[14:17], v[146:149], v[208:211], v[14:17]
	v_mfma_f32_16x16x32_bf16 v[6:9], v[160:163], v[208:211], v[6:9]
	v_mfma_f32_16x16x32_bf16 v[62:65], v[156:159], v[188:191], v[62:65]
	v_mfma_f32_16x16x32_bf16 v[54:57], v[164:167], v[188:191], v[54:57]
	v_mfma_f32_16x16x32_bf16 v[46:49], v[156:159], v[196:199], v[46:49]
	v_mfma_f32_16x16x32_bf16 v[38:41], v[164:167], v[196:199], v[38:41]
	v_mfma_f32_16x16x32_bf16 v[30:33], v[156:159], v[204:207], v[30:33]
	v_mfma_f32_16x16x32_bf16 v[22:25], v[164:167], v[204:207], v[22:25]
	v_mfma_f32_16x16x32_bf16 v[14:17], v[156:159], v[212:215], v[14:17]
	v_mfma_f32_16x16x32_bf16 v[6:9], v[164:167], v[212:215], v[6:9]
	s_setprio 0
	s_setprio 1
	v_mfma_f32_16x16x32_bf16 v[58:61], v[168:171], v[184:187], v[58:61]
	v_mfma_f32_16x16x32_bf16 v[50:53], v[176:179], v[184:187], v[50:53]
	v_mfma_f32_16x16x32_bf16 v[42:45], v[168:171], v[192:195], v[42:45]
	v_mfma_f32_16x16x32_bf16 v[34:37], v[176:179], v[192:195], v[34:37]
	v_mfma_f32_16x16x32_bf16 v[26:29], v[168:171], v[200:203], v[26:29]
	v_mfma_f32_16x16x32_bf16 v[18:21], v[176:179], v[200:203], v[18:21]
	v_mfma_f32_16x16x32_bf16 v[10:13], v[168:171], v[208:211], v[10:13]
	v_mfma_f32_16x16x32_bf16 v[2:5], v[176:179], v[208:211], v[2:5]
	v_mfma_f32_16x16x32_bf16 v[58:61], v[172:175], v[188:191], v[58:61]
	v_mfma_f32_16x16x32_bf16 v[50:53], v[180:183], v[188:191], v[50:53]
	v_mfma_f32_16x16x32_bf16 v[42:45], v[172:175], v[196:199], v[42:45]
	v_mfma_f32_16x16x32_bf16 v[34:37], v[180:183], v[196:199], v[34:37]
	v_mfma_f32_16x16x32_bf16 v[26:29], v[172:175], v[204:207], v[26:29]
	v_mfma_f32_16x16x32_bf16 v[18:21], v[180:183], v[204:207], v[18:21]
	v_mfma_f32_16x16x32_bf16 v[10:13], v[172:175], v[212:215], v[10:13]
	v_mfma_f32_16x16x32_bf16 v[2:5], v[180:183], v[212:215], v[2:5]
	s_setprio 0
	s_barrier
	s_add_i32 s80, s80, 2
	s_add_u32 s76, s76, 0x100
	s_addc_u32 s77, s77, 0
	s_add_u32 s52, s52, 0x100
	s_addc_u32 s75, s75, 0
	s_cmp_gt_u32 s80, 29
	s_cbranch_scc0 .LBB0_2218
	s_and_b64 vcc, exec, s[24:25]
	s_cbranch_vccz .LBB0_2221
	s_barrier

.LBB0_2462:
	s_add_u32 s34, s76, 0xfff80080
	s_addc_u32 s35, s77, -1
	s_cmp_eq_u32 s74, 28
	s_cselect_b32 s89, s0, s35
	s_cselect_b32 s88, s1, s34
	s_cselect_b32 s35, s7, s52
	s_cselect_b32 s34, s9, s36
	v_lshl_add_u64 v[152:153], s[76:77], 0, v[144:145]
	s_add_i32 m0, s31, 0xc000
	s_nop 0
	global_load_lds_dwordx4 v[152:153], off
	v_lshl_add_u64 v[152:153], s[76:77], 0, v[146:147]
	s_add_i32 m0, s31, 0xe000
	s_nop 0
	global_load_lds_dwordx4 v[152:153], off
	ds_read_b128 v[160:163], v155
	ds_read_b128 v[164:167], v155 offset:1024
	ds_read_b128 v[168:171], v155 offset:2048
	ds_read_b128 v[172:175], v155 offset:3072
	ds_read_b128 v[176:179], v156
	ds_read_b128 v[180:183], v156 offset:1024
	ds_read_b128 v[184:187], v156 offset:2048
	ds_read_b128 v[188:191], v156 offset:3072
	ds_read_b128 v[192:195], v157
	ds_read_b128 v[196:199], v157 offset:1024
	ds_read_b128 v[200:203], v157 offset:2048
	ds_read_b128 v[204:207], v157 offset:3072
	ds_read_b128 v[208:211], v157 offset:4096
	ds_read_b128 v[212:215], v157 offset:5120
	ds_read_b128 v[218:221], v157 offset:6144
	ds_read_b128 v[222:225], v157 offset:7168
	s_waitcnt vmcnt(8)
	s_waitcnt lgkmcnt(0)
	s_barrier
	s_setprio 1
	s_waitcnt lgkmcnt(0)
	v_mfma_f32_16x16x32_bf16 v[126:129], v[160:163], v[192:195], v[126:129]
	v_mfma_f32_16x16x32_bf16 v[122:125], v[168:171], v[192:195], v[122:125]
	v_mfma_f32_16x16x32_bf16 v[110:113], v[160:163], v[200:203], v[110:113]
	v_mfma_f32_16x16x32_bf16 v[106:109], v[168:171], v[200:203], v[106:109]
	v_mfma_f32_16x16x32_bf16 v[94:97], v[160:163], v[208:211], v[94:97]
	v_mfma_f32_16x16x32_bf16 v[90:93], v[168:171], v[208:211], v[90:93]
	v_mfma_f32_16x16x32_bf16 v[78:81], v[160:163], v[218:221], v[78:81]
	v_mfma_f32_16x16x32_bf16 v[74:77], v[168:171], v[218:221], v[74:77]
	v_mfma_f32_16x16x32_bf16 v[126:129], v[164:167], v[196:199], v[126:129]
	v_mfma_f32_16x16x32_bf16 v[122:125], v[172:175], v[196:199], v[122:125]
	v_mfma_f32_16x16x32_bf16 v[110:113], v[164:167], v[204:207], v[110:113]
	v_mfma_f32_16x16x32_bf16 v[106:109], v[172:175], v[204:207], v[106:109]
	v_mfma_f32_16x16x32_bf16 v[94:97], v[164:167], v[212:215], v[94:97]
	v_mfma_f32_16x16x32_bf16 v[90:93], v[172:175], v[212:215], v[90:93]
	v_mfma_f32_16x16x32_bf16 v[78:81], v[164:167], v[222:225], v[78:81]
	v_mfma_f32_16x16x32_bf16 v[74:77], v[172:175], v[222:225], v[74:77]
	s_setprio 0
	s_setprio 1
	v_mfma_f32_16x16x32_bf16 v[118:121], v[176:179], v[192:195], v[118:121]
	v_mfma_f32_16x16x32_bf16 v[114:117], v[184:187], v[192:195], v[114:117]
	v_mfma_f32_16x16x32_bf16 v[102:105], v[176:179], v[200:203], v[102:105]
	v_mfma_f32_16x16x32_bf16 v[98:101], v[184:187], v[200:203], v[98:101]
	v_mfma_f32_16x16x32_bf16 v[86:89], v[176:179], v[208:211], v[86:89]
	v_mfma_f32_16x16x32_bf16 v[82:85], v[184:187], v[208:211], v[82:85]
	v_mfma_f32_16x16x32_bf16 v[70:73], v[176:179], v[218:221], v[70:73]
	v_mfma_f32_16x16x32_bf16 v[66:69], v[184:187], v[218:221], v[66:69]
	v_mfma_f32_16x16x32_bf16 v[118:121], v[180:183], v[196:199], v[118:121]
	v_mfma_f32_16x16x32_bf16 v[114:117], v[188:191], v[196:199], v[114:117]
	v_mfma_f32_16x16x32_bf16 v[102:105], v[180:183], v[204:207], v[102:105]
	v_mfma_f32_16x16x32_bf16 v[98:101], v[188:191], v[204:207], v[98:101]
	v_mfma_f32_16x16x32_bf16 v[86:89], v[180:183], v[212:215], v[86:89]
	v_mfma_f32_16x16x32_bf16 v[82:85], v[188:191], v[212:215], v[82:85]
	v_mfma_f32_16x16x32_bf16 v[70:73], v[180:183], v[222:225], v[70:73]
	v_mfma_f32_16x16x32_bf16 v[66:69], v[188:191], v[222:225], v[66:69]
	s_setprio 0
	s_barrier
	s_add_i32 s53, s71, s12
	v_lshl_add_u64 v[152:153], s[34:35], 0, v[132:133]
	s_mov_b32 m0, s53
	s_nop 0
	global_load_lds_dwordx4 v[152:153], off
	s_add_i32 m0, s53, 0x2000
	s_add_u32 s54, s34, 0x80000
	v_lshl_add_u64 v[226:227], s[34:35], 0, v[136:137]
	s_addc_u32 s55, s35, 0
	s_add_i32 s53, s72, s12
	global_load_lds_dwordx4 v[226:227], off
	v_lshl_add_u64 v[228:229], s[54:55], 0, v[132:133]
	s_mov_b32 m0, s53
	v_lshl_add_u64 v[230:231], s[88:89], 0, v[134:135]
	global_load_lds_dwordx4 v[228:229], off
	v_lshl_add_u64 v[228:229], s[54:55], 0, v[136:137]
	s_add_i32 m0, s53, 0x2000
	s_nop 0
	global_load_lds_dwordx4 v[228:229], off
	v_lshl_add_u64 v[228:229], s[88:89], 0, v[130:131]
	s_mov_b32 m0, s31
	s_nop 0
	global_load_lds_dwordx4 v[228:229], off
	s_mov_b32 m0, s33
	s_nop 0
	global_load_lds_dwordx4 v[230:231], off
	ds_read_b128 v[192:195], v157 offset:16384
	ds_read_b128 v[196:199], v157 offset:17408
	ds_read_b128 v[200:203], v157 offset:18432
	ds_read_b128 v[204:207], v157 offset:19456
	ds_read_b128 v[208:211], v157 offset:20480
	ds_read_b128 v[212:215], v157 offset:21504
	ds_read_b128 v[218:221], v157 offset:22528
	ds_read_b128 v[222:225], v157 offset:23552
	s_waitcnt vmcnt(8)
	s_waitcnt lgkmcnt(0)
	s_barrier
	s_setprio 1
	s_waitcnt lgkmcnt(0)
	v_mfma_f32_16x16x32_bf16 v[62:65], v[160:163], v[192:195], v[62:65]
	v_mfma_f32_16x16x32_bf16 v[58:61], v[168:171], v[192:195], v[58:61]
	v_mfma_f32_16x16x32_bf16 v[46:49], v[160:163], v[200:203], v[46:49]
	v_mfma_f32_16x16x32_bf16 v[42:45], v[168:171], v[200:203], v[42:45]
	v_mfma_f32_16x16x32_bf16 v[30:33], v[160:163], v[208:211], v[30:33]
	v_mfma_f32_16x16x32_bf16 v[26:29], v[168:171], v[208:211], v[26:29]
	v_mfma_f32_16x16x32_bf16 v[14:17], v[160:163], v[218:221], v[14:17]
	v_mfma_f32_16x16x32_bf16 v[10:13], v[168:171], v[218:221], v[10:13]
	v_mfma_f32_16x16x32_bf16 v[62:65], v[164:167], v[196:199], v[62:65]
	v_mfma_f32_16x16x32_bf16 v[58:61], v[172:175], v[196:199], v[58:61]
	v_mfma_f32_16x16x32_bf16 v[46:49], v[164:167], v[204:207], v[46:49]
	v_mfma_f32_16x16x32_bf16 v[42:45], v[172:175], v[204:207], v[42:45]
	v_mfma_f32_16x16x32_bf16 v[30:33], v[164:167], v[212:215], v[30:33]
	v_mfma_f32_16x16x32_bf16 v[26:29], v[172:175], v[212:215], v[26:29]
	v_mfma_f32_16x16x32_bf16 v[14:17], v[164:167], v[222:225], v[14:17]
	v_mfma_f32_16x16x32_bf16 v[10:13], v[172:175], v[222:225], v[10:13]
	s_setprio 0
	s_setprio 1
	v_mfma_f32_16x16x32_bf16 v[54:57], v[176:179], v[192:195], v[54:57]
	v_mfma_f32_16x16x32_bf16 v[50:53], v[184:187], v[192:195], v[50:53]
	v_mfma_f32_16x16x32_bf16 v[38:41], v[176:179], v[200:203], v[38:41]
	v_mfma_f32_16x16x32_bf16 v[34:37], v[184:187], v[200:203], v[34:37]
	v_mfma_f32_16x16x32_bf16 v[22:25], v[176:179], v[208:211], v[22:25]
	v_mfma_f32_16x16x32_bf16 v[18:21], v[184:187], v[208:211], v[18:21]
	v_mfma_f32_16x16x32_bf16 v[6:9], v[176:179], v[218:221], v[6:9]
	v_mfma_f32_16x16x32_bf16 v[2:5], v[184:187], v[218:221], v[2:5]
	v_mfma_f32_16x16x32_bf16 v[54:57], v[180:183], v[196:199], v[54:57]
	v_mfma_f32_16x16x32_bf16 v[50:53], v[188:191], v[196:199], v[50:53]
	v_mfma_f32_16x16x32_bf16 v[38:41], v[180:183], v[204:207], v[38:41]
	v_mfma_f32_16x16x32_bf16 v[34:37], v[188:191], v[204:207], v[34:37]
	v_mfma_f32_16x16x32_bf16 v[22:25], v[180:183], v[212:215], v[22:25]
	v_mfma_f32_16x16x32_bf16 v[18:21], v[188:191], v[212:215], v[18:21]
	v_mfma_f32_16x16x32_bf16 v[6:9], v[180:183], v[222:225], v[6:9]
	v_mfma_f32_16x16x32_bf16 v[2:5], v[188:191], v[222:225], v[2:5]
	s_setprio 0
	s_barrier
	s_add_i32 s53, 0, 0x18000
	s_add_i32 s62, 0, 0x1c000
	s_add_u32 s54, s88, 0x80000
	s_addc_u32 s55, s89, 0
	s_mov_b32 m0, s56
	v_lshl_add_u64 v[232:233], s[54:55], 0, v[130:131]
	global_load_lds_dwordx4 v[232:233], off
	v_lshl_add_u64 v[232:233], s[54:55], 0, v[134:135]
	s_mov_b32 m0, s57
	s_nop 0
	global_load_lds_dwordx4 v[232:233], off
	v_add_u32_e32 v138, s53, v154
	ds_read_b128 v[160:163], v138
	ds_read_b128 v[164:167], v138 offset:1024
	ds_read_b128 v[168:171], v138 offset:2048
	ds_read_b128 v[172:175], v138 offset:3072
	v_add_u32_e32 v138, s62, v154
	ds_read_b128 v[176:179], v138
	ds_read_b128 v[180:183], v138 offset:1024
	ds_read_b128 v[184:187], v138 offset:2048
	ds_read_b128 v[188:191], v138 offset:3072
	ds_read_b128 v[192:195], v157 offset:32768
	ds_read_b128 v[196:199], v157 offset:33792
	ds_read_b128 v[200:203], v157 offset:34816
	ds_read_b128 v[204:207], v157 offset:35840
	ds_read_b128 v[208:211], v157 offset:36864
	ds_read_b128 v[212:215], v157 offset:37888
	ds_read_b128 v[218:221], v157 offset:38912
	ds_read_b128 v[222:225], v157 offset:39936
	s_waitcnt vmcnt(8)
	s_waitcnt lgkmcnt(0)
	s_barrier
	s_setprio 1
	s_waitcnt lgkmcnt(0)
	v_mfma_f32_16x16x32_bf16 v[126:129], v[160:163], v[192:195], v[126:129]
	v_mfma_f32_16x16x32_bf16 v[122:125], v[168:171], v[192:195], v[122:125]
	v_mfma_f32_16x16x32_bf16 v[110:113], v[160:163], v[200:203], v[110:113]
	v_mfma_f32_16x16x32_bf16 v[106:109], v[168:171], v[200:203], v[106:109]
	v_mfma_f32_16x16x32_bf16 v[94:97], v[160:163], v[208:211], v[94:97]
	v_mfma_f32_16x16x32_bf16 v[90:93], v[168:171], v[208:211], v[90:93]
	v_mfma_f32_16x16x32_bf16 v[78:81], v[160:163], v[218:221], v[78:81]
	v_mfma_f32_16x16x32_bf16 v[74:77], v[168:171], v[218:221], v[74:77]
	v_mfma_f32_16x16x32_bf16 v[126:129], v[164:167], v[196:199], v[126:129]
	v_mfma_f32_16x16x32_bf16 v[122:125], v[172:175], v[196:199], v[122:125]
	v_mfma_f32_16x16x32_bf16 v[110:113], v[164:167], v[204:207], v[110:113]
	v_mfma_f32_16x16x32_bf16 v[106:109], v[172:175], v[204:207], v[106:109]
	v_mfma_f32_16x16x32_bf16 v[94:97], v[164:167], v[212:215], v[94:97]
	v_mfma_f32_16x16x32_bf16 v[90:93], v[172:175], v[212:215], v[90:93]
	v_mfma_f32_16x16x32_bf16 v[78:81], v[164:167], v[222:225], v[78:81]
	v_mfma_f32_16x16x32_bf16 v[74:77], v[172:175], v[222:225], v[74:77]
	s_setprio 0
	s_setprio 1
	v_mfma_f32_16x16x32_bf16 v[118:121], v[176:179], v[192:195], v[118:121]
	v_mfma_f32_16x16x32_bf16 v[114:117], v[184:187], v[192:195], v[114:117]
	v_mfma_f32_16x16x32_bf16 v[102:105], v[176:179], v[200:203], v[102:105]
	v_mfma_f32_16x16x32_bf16 v[98:101], v[184:187], v[200:203], v[98:101]
	v_mfma_f32_16x16x32_bf16 v[86:89], v[176:179], v[208:211], v[86:89]
	v_mfma_f32_16x16x32_bf16 v[82:85], v[184:187], v[208:211], v[82:85]
	v_mfma_f32_16x16x32_bf16 v[70:73], v[176:179], v[218:221], v[70:73]
	v_mfma_f32_16x16x32_bf16 v[66:69], v[184:187], v[218:221], v[66:69]
	v_mfma_f32_16x16x32_bf16 v[118:121], v[180:183], v[196:199], v[118:121]
	v_mfma_f32_16x16x32_bf16 v[114:117], v[188:191], v[196:199], v[114:117]
	v_mfma_f32_16x16x32_bf16 v[102:105], v[180:183], v[204:207], v[102:105]
	v_mfma_f32_16x16x32_bf16 v[98:101], v[188:191], v[204:207], v[98:101]
	v_mfma_f32_16x16x32_bf16 v[86:89], v[180:183], v[212:215], v[86:89]
	v_mfma_f32_16x16x32_bf16 v[82:85], v[188:191], v[212:215], v[82:85]
	v_mfma_f32_16x16x32_bf16 v[70:73], v[180:183], v[222:225], v[70:73]
	v_mfma_f32_16x16x32_bf16 v[66:69], v[188:191], v[222:225], v[66:69]
	s_setprio 0
	s_barrier
	s_add_i32 s53, s53, s12
	v_lshl_add_u64 v[152:153], v[152:153], 0, s[40:41]
	s_mov_b32 m0, s53
	s_nop 0
	global_load_lds_dwordx4 v[152:153], off
	s_add_i32 m0, s53, 0x2000
	s_add_u32 s34, s34, 0x80080
	v_lshl_add_u64 v[152:153], v[226:227], 0, s[40:41]
	s_addc_u32 s35, s35, 0
	s_add_i32 s53, s62, s12
	global_load_lds_dwordx4 v[152:153], off
	v_lshl_add_u64 v[152:153], s[34:35], 0, v[132:133]
	s_mov_b32 m0, s53
	s_nop 0
	global_load_lds_dwordx4 v[152:153], off
	v_lshl_add_u64 v[152:153], s[34:35], 0, v[136:137]
	s_add_i32 m0, s53, 0x2000
	s_nop 0
	global_load_lds_dwordx4 v[152:153], off
	v_lshl_add_u64 v[152:153], v[228:229], 0, s[40:41]
	s_mov_b32 m0, s59
	s_nop 0
	global_load_lds_dwordx4 v[152:153], off
	v_lshl_add_u64 v[152:153], v[230:231], 0, s[40:41]
	s_mov_b32 m0, s60
	s_nop 0
	global_load_lds_dwordx4 v[152:153], off
	ds_read_b128 v[192:195], v157 offset:49152
	ds_read_b128 v[196:199], v157 offset:50176
	ds_read_b128 v[200:203], v157 offset:51200
	ds_read_b128 v[204:207], v157 offset:52224
	ds_read_b128 v[208:211], v157 offset:53248
	ds_read_b128 v[212:215], v157 offset:54272
	ds_read_b128 v[218:221], v157 offset:55296
	ds_read_b128 v[222:225], v157 offset:56320
	s_waitcnt vmcnt(8)
	s_waitcnt lgkmcnt(0)
	s_barrier
	s_setprio 1
	s_waitcnt lgkmcnt(0)
	v_mfma_f32_16x16x32_bf16 v[62:65], v[160:163], v[192:195], v[62:65]
	v_mfma_f32_16x16x32_bf16 v[58:61], v[168:171], v[192:195], v[58:61]
	v_mfma_f32_16x16x32_bf16 v[46:49], v[160:163], v[200:203], v[46:49]
	v_mfma_f32_16x16x32_bf16 v[42:45], v[168:171], v[200:203], v[42:45]
	v_mfma_f32_16x16x32_bf16 v[30:33], v[160:163], v[208:211], v[30:33]
	v_mfma_f32_16x16x32_bf16 v[26:29], v[168:171], v[208:211], v[26:29]
	v_mfma_f32_16x16x32_bf16 v[14:17], v[160:163], v[218:221], v[14:17]
	v_mfma_f32_16x16x32_bf16 v[10:13], v[168:171], v[218:221], v[10:13]
	v_mfma_f32_16x16x32_bf16 v[62:65], v[164:167], v[196:199], v[62:65]
	v_mfma_f32_16x16x32_bf16 v[58:61], v[172:175], v[196:199], v[58:61]
	v_mfma_f32_16x16x32_bf16 v[46:49], v[164:167], v[204:207], v[46:49]
	v_mfma_f32_16x16x32_bf16 v[42:45], v[172:175], v[204:207], v[42:45]
	v_mfma_f32_16x16x32_bf16 v[30:33], v[164:167], v[212:215], v[30:33]
	v_mfma_f32_16x16x32_bf16 v[26:29], v[172:175], v[212:215], v[26:29]
	v_mfma_f32_16x16x32_bf16 v[14:17], v[164:167], v[222:225], v[14:17]
	v_mfma_f32_16x16x32_bf16 v[10:13], v[172:175], v[222:225], v[10:13]
	s_setprio 0
	s_setprio 1
	v_mfma_f32_16x16x32_bf16 v[54:57], v[176:179], v[192:195], v[54:57]
	v_mfma_f32_16x16x32_bf16 v[50:53], v[184:187], v[192:195], v[50:53]
	v_mfma_f32_16x16x32_bf16 v[38:41], v[176:179], v[200:203], v[38:41]
	v_mfma_f32_16x16x32_bf16 v[34:37], v[184:187], v[200:203], v[34:37]
	v_mfma_f32_16x16x32_bf16 v[22:25], v[176:179], v[208:211], v[22:25]
	v_mfma_f32_16x16x32_bf16 v[18:21], v[184:187], v[208:211], v[18:21]
	v_mfma_f32_16x16x32_bf16 v[6:9], v[176:179], v[218:221], v[6:9]
	v_mfma_f32_16x16x32_bf16 v[2:5], v[184:187], v[218:221], v[2:5]
	v_mfma_f32_16x16x32_bf16 v[54:57], v[180:183], v[196:199], v[54:57]
	v_mfma_f32_16x16x32_bf16 v[50:53], v[188:191], v[196:199], v[50:53]
	v_mfma_f32_16x16x32_bf16 v[38:41], v[180:183], v[204:207], v[38:41]
	v_mfma_f32_16x16x32_bf16 v[34:37], v[188:191], v[204:207], v[34:37]
	v_mfma_f32_16x16x32_bf16 v[22:25], v[180:183], v[212:215], v[22:25]
	v_mfma_f32_16x16x32_bf16 v[18:21], v[188:191], v[212:215], v[18:21]
	v_mfma_f32_16x16x32_bf16 v[6:9], v[180:183], v[222:225], v[6:9]
	v_mfma_f32_16x16x32_bf16 v[2:5], v[188:191], v[222:225], v[2:5]
	s_setprio 0
	s_barrier
	s_add_i32 s74, s74, 2
	s_add_u32 s76, s76, 0x100
	s_addc_u32 s77, s77, 0
	s_add_u32 s36, s36, 0x100
	s_addc_u32 s52, s52, 0
	s_cmp_gt_u32 s74, 29
	s_cbranch_scc0 .LBB0_2462
	s_and_b64 vcc, exec, s[46:47]
	s_cbranch_vccz .LBB0_2465
	s_barrier

.LBB0_2629:
	s_add_u32 s34, s74, 0xfffe0080
	s_addc_u32 s35, s75, -1
	s_cmp_eq_u32 s79, 4
	s_cselect_b32 s77, s0, s35
	s_cselect_b32 s76, s1, s34
	s_cselect_b32 s35, s27, s78
	s_cselect_b32 s34, s37, s52
	v_lshl_add_u64 v[226:227], s[74:75], 0, v[138:139]
	s_add_i32 m0, s33, 0xc000
	s_nop 0
	global_load_lds_dwordx4 v[226:227], off
	v_lshl_add_u64 v[226:227], s[74:75], 0, v[140:141]
	s_add_i32 m0, s33, 0xe000
	s_nop 0
	global_load_lds_dwordx4 v[226:227], off
	ds_read_b128 v[146:149], v165
	ds_read_b128 v[150:153], v165 offset:1024
	ds_read_b128 v[168:171], v165 offset:2048
	ds_read_b128 v[172:175], v165 offset:3072
	ds_read_b128 v[176:179], v166
	ds_read_b128 v[180:183], v166 offset:1024
	ds_read_b128 v[184:187], v166 offset:2048
	ds_read_b128 v[188:191], v166 offset:3072
	ds_read_b128 v[192:195], v167
	ds_read_b128 v[196:199], v167 offset:1024
	ds_read_b128 v[200:203], v167 offset:2048
	ds_read_b128 v[204:207], v167 offset:3072
	ds_read_b128 v[208:211], v167 offset:4096
	ds_read_b128 v[212:215], v167 offset:5120
	ds_read_b128 v[218:221], v167 offset:6144
	ds_read_b128 v[222:225], v167 offset:7168
	s_waitcnt vmcnt(8)
	s_waitcnt lgkmcnt(0)
	s_barrier
	s_setprio 1
	s_waitcnt lgkmcnt(0)
	v_mfma_f32_16x16x32_bf16 v[126:129], v[146:149], v[192:195], v[126:129]
	v_mfma_f32_16x16x32_bf16 v[122:125], v[168:171], v[192:195], v[122:125]
	v_mfma_f32_16x16x32_bf16 v[114:117], v[146:149], v[200:203], v[114:117]
	v_mfma_f32_16x16x32_bf16 v[106:109], v[168:171], v[200:203], v[106:109]
	v_mfma_f32_16x16x32_bf16 v[98:101], v[146:149], v[208:211], v[98:101]
	v_mfma_f32_16x16x32_bf16 v[90:93], v[168:171], v[208:211], v[90:93]
	v_mfma_f32_16x16x32_bf16 v[82:85], v[146:149], v[218:221], v[82:85]
	v_mfma_f32_16x16x32_bf16 v[74:77], v[168:171], v[218:221], v[74:77]
	v_mfma_f32_16x16x32_bf16 v[126:129], v[150:153], v[196:199], v[126:129]
	v_mfma_f32_16x16x32_bf16 v[122:125], v[172:175], v[196:199], v[122:125]
	v_mfma_f32_16x16x32_bf16 v[114:117], v[150:153], v[204:207], v[114:117]
	v_mfma_f32_16x16x32_bf16 v[106:109], v[172:175], v[204:207], v[106:109]
	v_mfma_f32_16x16x32_bf16 v[98:101], v[150:153], v[212:215], v[98:101]
	v_mfma_f32_16x16x32_bf16 v[90:93], v[172:175], v[212:215], v[90:93]
	v_mfma_f32_16x16x32_bf16 v[82:85], v[150:153], v[222:225], v[82:85]
	v_mfma_f32_16x16x32_bf16 v[74:77], v[172:175], v[222:225], v[74:77]
	s_setprio 0
	s_setprio 1
	v_mfma_f32_16x16x32_bf16 v[118:121], v[176:179], v[192:195], v[118:121]
	v_mfma_f32_16x16x32_bf16 v[110:113], v[184:187], v[192:195], v[110:113]
	v_mfma_f32_16x16x32_bf16 v[102:105], v[176:179], v[200:203], v[102:105]
	v_mfma_f32_16x16x32_bf16 v[94:97], v[184:187], v[200:203], v[94:97]
	v_mfma_f32_16x16x32_bf16 v[86:89], v[176:179], v[208:211], v[86:89]
	v_mfma_f32_16x16x32_bf16 v[78:81], v[184:187], v[208:211], v[78:81]
	v_mfma_f32_16x16x32_bf16 v[70:73], v[176:179], v[218:221], v[70:73]
	v_mfma_f32_16x16x32_bf16 v[66:69], v[184:187], v[218:221], v[66:69]
	v_mfma_f32_16x16x32_bf16 v[118:121], v[180:183], v[196:199], v[118:121]
	v_mfma_f32_16x16x32_bf16 v[110:113], v[188:191], v[196:199], v[110:113]
	v_mfma_f32_16x16x32_bf16 v[102:105], v[180:183], v[204:207], v[102:105]
	v_mfma_f32_16x16x32_bf16 v[94:97], v[188:191], v[204:207], v[94:97]
	v_mfma_f32_16x16x32_bf16 v[86:89], v[180:183], v[212:215], v[86:89]
	v_mfma_f32_16x16x32_bf16 v[78:81], v[188:191], v[212:215], v[78:81]
	v_mfma_f32_16x16x32_bf16 v[70:73], v[180:183], v[222:225], v[70:73]
	v_mfma_f32_16x16x32_bf16 v[66:69], v[188:191], v[222:225], v[66:69]
	s_setprio 0
	s_barrier
	s_add_i32 s53, s70, s12
	v_lshl_add_u64 v[226:227], s[34:35], 0, v[132:133]
	s_mov_b32 m0, s53
	s_nop 0
	global_load_lds_dwordx4 v[226:227], off
	s_add_i32 m0, s53, 0x2000
	s_add_u32 s54, s34, 0x20000
	v_lshl_add_u64 v[228:229], s[34:35], 0, v[136:137]
	s_addc_u32 s55, s35, 0
	s_add_i32 s53, s71, s12
	global_load_lds_dwordx4 v[228:229], off
	v_lshl_add_u64 v[230:231], s[54:55], 0, v[132:133]
	s_mov_b32 m0, s53
	v_lshl_add_u64 v[232:233], s[76:77], 0, v[134:135]
	global_load_lds_dwordx4 v[230:231], off
	v_lshl_add_u64 v[230:231], s[54:55], 0, v[136:137]
	s_add_i32 m0, s53, 0x2000
	s_nop 0
	global_load_lds_dwordx4 v[230:231], off
	v_lshl_add_u64 v[230:231], s[76:77], 0, v[130:131]
	s_mov_b32 m0, s33
	s_nop 0
	global_load_lds_dwordx4 v[230:231], off
	s_mov_b32 m0, s47
	s_nop 0
	global_load_lds_dwordx4 v[232:233], off
	ds_read_b128 v[192:195], v167 offset:16384
	ds_read_b128 v[196:199], v167 offset:17408
	ds_read_b128 v[200:203], v167 offset:18432
	ds_read_b128 v[204:207], v167 offset:19456
	ds_read_b128 v[208:211], v167 offset:20480
	ds_read_b128 v[212:215], v167 offset:21504
	ds_read_b128 v[218:221], v167 offset:22528
	ds_read_b128 v[222:225], v167 offset:23552
	s_waitcnt vmcnt(8)
	s_waitcnt lgkmcnt(0)
	s_barrier
	s_setprio 1
	s_waitcnt lgkmcnt(0)
	v_mfma_f32_16x16x32_bf16 v[62:65], v[146:149], v[192:195], v[62:65]
	v_mfma_f32_16x16x32_bf16 v[58:61], v[168:171], v[192:195], v[58:61]
	v_mfma_f32_16x16x32_bf16 v[50:53], v[146:149], v[200:203], v[50:53]
	v_mfma_f32_16x16x32_bf16 v[42:45], v[168:171], v[200:203], v[42:45]
	v_mfma_f32_16x16x32_bf16 v[34:37], v[146:149], v[208:211], v[34:37]
	v_mfma_f32_16x16x32_bf16 v[26:29], v[168:171], v[208:211], v[26:29]
	v_mfma_f32_16x16x32_bf16 v[18:21], v[146:149], v[218:221], v[18:21]
	v_mfma_f32_16x16x32_bf16 v[10:13], v[168:171], v[218:221], v[10:13]
	v_mfma_f32_16x16x32_bf16 v[62:65], v[150:153], v[196:199], v[62:65]
	v_mfma_f32_16x16x32_bf16 v[58:61], v[172:175], v[196:199], v[58:61]
	v_mfma_f32_16x16x32_bf16 v[50:53], v[150:153], v[204:207], v[50:53]
	v_mfma_f32_16x16x32_bf16 v[42:45], v[172:175], v[204:207], v[42:45]
	v_mfma_f32_16x16x32_bf16 v[34:37], v[150:153], v[212:215], v[34:37]
	v_mfma_f32_16x16x32_bf16 v[26:29], v[172:175], v[212:215], v[26:29]
	v_mfma_f32_16x16x32_bf16 v[18:21], v[150:153], v[222:225], v[18:21]
	v_mfma_f32_16x16x32_bf16 v[10:13], v[172:175], v[222:225], v[10:13]
	s_setprio 0
	s_setprio 1
	v_mfma_f32_16x16x32_bf16 v[54:57], v[176:179], v[192:195], v[54:57]
	v_mfma_f32_16x16x32_bf16 v[46:49], v[184:187], v[192:195], v[46:49]
	v_mfma_f32_16x16x32_bf16 v[38:41], v[176:179], v[200:203], v[38:41]
	v_mfma_f32_16x16x32_bf16 v[30:33], v[184:187], v[200:203], v[30:33]
	v_mfma_f32_16x16x32_bf16 v[22:25], v[176:179], v[208:211], v[22:25]
	v_mfma_f32_16x16x32_bf16 v[14:17], v[184:187], v[208:211], v[14:17]
	v_mfma_f32_16x16x32_bf16 v[6:9], v[176:179], v[218:221], v[6:9]
	v_mfma_f32_16x16x32_bf16 v[2:5], v[184:187], v[218:221], v[2:5]
	v_mfma_f32_16x16x32_bf16 v[54:57], v[180:183], v[196:199], v[54:57]
	v_mfma_f32_16x16x32_bf16 v[46:49], v[188:191], v[196:199], v[46:49]
	v_mfma_f32_16x16x32_bf16 v[38:41], v[180:183], v[204:207], v[38:41]
	v_mfma_f32_16x16x32_bf16 v[30:33], v[188:191], v[204:207], v[30:33]
	v_mfma_f32_16x16x32_bf16 v[22:25], v[180:183], v[212:215], v[22:25]
	v_mfma_f32_16x16x32_bf16 v[14:17], v[188:191], v[212:215], v[14:17]
	v_mfma_f32_16x16x32_bf16 v[6:9], v[180:183], v[222:225], v[6:9]
	v_mfma_f32_16x16x32_bf16 v[2:5], v[188:191], v[222:225], v[2:5]
	s_setprio 0
	s_barrier
	s_add_i32 s53, 0, 0x18000
	s_add_i32 s62, 0, 0x1c000
	s_add_u32 s54, s76, 0x20000
	s_addc_u32 s55, s77, 0
	s_mov_b32 m0, s56
	v_lshl_add_u64 v[234:235], s[54:55], 0, v[130:131]
	global_load_lds_dwordx4 v[234:235], off
	v_lshl_add_u64 v[234:235], s[54:55], 0, v[134:135]
	s_mov_b32 m0, s57
	s_nop 0
	global_load_lds_dwordx4 v[234:235], off
	v_add_u32_e32 v172, s53, v162
	v_add_u32_e32 v188, s62, v162
	ds_read_b128 v[146:149], v172
	ds_read_b128 v[150:153], v172 offset:1024
	ds_read_b128 v[168:171], v172 offset:2048
	ds_read_b128 v[172:175], v172 offset:3072
	ds_read_b128 v[176:179], v188
	ds_read_b128 v[180:183], v188 offset:1024
	ds_read_b128 v[184:187], v188 offset:2048
	ds_read_b128 v[188:191], v188 offset:3072
	ds_read_b128 v[192:195], v167 offset:32768
	ds_read_b128 v[196:199], v167 offset:33792
	ds_read_b128 v[200:203], v167 offset:34816
	ds_read_b128 v[204:207], v167 offset:35840
	ds_read_b128 v[208:211], v167 offset:36864
	ds_read_b128 v[212:215], v167 offset:37888
	ds_read_b128 v[218:221], v167 offset:38912
	ds_read_b128 v[222:225], v167 offset:39936
	s_waitcnt vmcnt(8)
	s_waitcnt lgkmcnt(0)
	s_barrier
	s_setprio 1
	s_waitcnt lgkmcnt(0)
	v_mfma_f32_16x16x32_bf16 v[126:129], v[146:149], v[192:195], v[126:129]
	v_mfma_f32_16x16x32_bf16 v[122:125], v[168:171], v[192:195], v[122:125]
	v_mfma_f32_16x16x32_bf16 v[114:117], v[146:149], v[200:203], v[114:117]
	v_mfma_f32_16x16x32_bf16 v[106:109], v[168:171], v[200:203], v[106:109]
	v_mfma_f32_16x16x32_bf16 v[98:101], v[146:149], v[208:211], v[98:101]
	v_mfma_f32_16x16x32_bf16 v[90:93], v[168:171], v[208:211], v[90:93]
	v_mfma_f32_16x16x32_bf16 v[82:85], v[146:149], v[218:221], v[82:85]
	v_mfma_f32_16x16x32_bf16 v[74:77], v[168:171], v[218:221], v[74:77]
	v_mfma_f32_16x16x32_bf16 v[126:129], v[150:153], v[196:199], v[126:129]
	v_mfma_f32_16x16x32_bf16 v[122:125], v[172:175], v[196:199], v[122:125]
	v_mfma_f32_16x16x32_bf16 v[114:117], v[150:153], v[204:207], v[114:117]
	v_mfma_f32_16x16x32_bf16 v[106:109], v[172:175], v[204:207], v[106:109]
	v_mfma_f32_16x16x32_bf16 v[98:101], v[150:153], v[212:215], v[98:101]
	v_mfma_f32_16x16x32_bf16 v[90:93], v[172:175], v[212:215], v[90:93]
	v_mfma_f32_16x16x32_bf16 v[82:85], v[150:153], v[222:225], v[82:85]
	v_mfma_f32_16x16x32_bf16 v[74:77], v[172:175], v[222:225], v[74:77]
	s_setprio 0
	s_setprio 1
	v_mfma_f32_16x16x32_bf16 v[118:121], v[176:179], v[192:195], v[118:121]
	v_mfma_f32_16x16x32_bf16 v[110:113], v[184:187], v[192:195], v[110:113]
	v_mfma_f32_16x16x32_bf16 v[102:105], v[176:179], v[200:203], v[102:105]
	v_mfma_f32_16x16x32_bf16 v[94:97], v[184:187], v[200:203], v[94:97]
	v_mfma_f32_16x16x32_bf16 v[86:89], v[176:179], v[208:211], v[86:89]
	v_mfma_f32_16x16x32_bf16 v[78:81], v[184:187], v[208:211], v[78:81]
	v_mfma_f32_16x16x32_bf16 v[70:73], v[176:179], v[218:221], v[70:73]
	v_mfma_f32_16x16x32_bf16 v[66:69], v[184:187], v[218:221], v[66:69]
	v_mfma_f32_16x16x32_bf16 v[118:121], v[180:183], v[196:199], v[118:121]
	v_mfma_f32_16x16x32_bf16 v[110:113], v[188:191], v[196:199], v[110:113]
	v_mfma_f32_16x16x32_bf16 v[102:105], v[180:183], v[204:207], v[102:105]
	v_mfma_f32_16x16x32_bf16 v[94:97], v[188:191], v[204:207], v[94:97]
	v_mfma_f32_16x16x32_bf16 v[86:89], v[180:183], v[212:215], v[86:89]
	v_mfma_f32_16x16x32_bf16 v[78:81], v[188:191], v[212:215], v[78:81]
	v_mfma_f32_16x16x32_bf16 v[70:73], v[180:183], v[222:225], v[70:73]
	v_mfma_f32_16x16x32_bf16 v[66:69], v[188:191], v[222:225], v[66:69]
	s_setprio 0
	s_barrier
	s_add_i32 s53, s53, s12
	v_lshl_add_u64 v[226:227], v[226:227], 0, s[8:9]
	s_mov_b32 m0, s53
	s_nop 0
	global_load_lds_dwordx4 v[226:227], off
	s_add_i32 m0, s53, 0x2000
	s_add_u32 s34, s34, 0x20080
	v_lshl_add_u64 v[226:227], v[228:229], 0, s[8:9]
	s_addc_u32 s35, s35, 0
	s_add_i32 s53, s62, s12
	global_load_lds_dwordx4 v[226:227], off
	v_lshl_add_u64 v[226:227], s[34:35], 0, v[132:133]
	s_mov_b32 m0, s53
	s_nop 0
	global_load_lds_dwordx4 v[226:227], off
	v_lshl_add_u64 v[226:227], s[34:35], 0, v[136:137]
	s_add_i32 m0, s53, 0x2000
	s_nop 0
	global_load_lds_dwordx4 v[226:227], off
	v_lshl_add_u64 v[226:227], v[230:231], 0, s[8:9]
	s_mov_b32 m0, s59
	s_nop 0
	global_load_lds_dwordx4 v[226:227], off
	v_lshl_add_u64 v[226:227], v[232:233], 0, s[8:9]
	s_mov_b32 m0, s60
	s_nop 0
	global_load_lds_dwordx4 v[226:227], off
	ds_read_b128 v[192:195], v167 offset:49152
	ds_read_b128 v[196:199], v167 offset:50176
	ds_read_b128 v[200:203], v167 offset:51200
	ds_read_b128 v[204:207], v167 offset:52224
	ds_read_b128 v[208:211], v167 offset:53248
	ds_read_b128 v[212:215], v167 offset:54272
	ds_read_b128 v[218:221], v167 offset:55296
	ds_read_b128 v[222:225], v167 offset:56320
	s_waitcnt vmcnt(8)
	s_waitcnt lgkmcnt(0)
	s_barrier
	s_setprio 1
	s_waitcnt lgkmcnt(0)
	v_mfma_f32_16x16x32_bf16 v[62:65], v[146:149], v[192:195], v[62:65]
	v_mfma_f32_16x16x32_bf16 v[58:61], v[168:171], v[192:195], v[58:61]
	v_mfma_f32_16x16x32_bf16 v[50:53], v[146:149], v[200:203], v[50:53]
	v_mfma_f32_16x16x32_bf16 v[42:45], v[168:171], v[200:203], v[42:45]
	v_mfma_f32_16x16x32_bf16 v[34:37], v[146:149], v[208:211], v[34:37]
	v_mfma_f32_16x16x32_bf16 v[26:29], v[168:171], v[208:211], v[26:29]
	v_mfma_f32_16x16x32_bf16 v[18:21], v[146:149], v[218:221], v[18:21]
	v_mfma_f32_16x16x32_bf16 v[10:13], v[168:171], v[218:221], v[10:13]
	v_mfma_f32_16x16x32_bf16 v[62:65], v[150:153], v[196:199], v[62:65]
	v_mfma_f32_16x16x32_bf16 v[58:61], v[172:175], v[196:199], v[58:61]
	v_mfma_f32_16x16x32_bf16 v[50:53], v[150:153], v[204:207], v[50:53]
	v_mfma_f32_16x16x32_bf16 v[42:45], v[172:175], v[204:207], v[42:45]
	v_mfma_f32_16x16x32_bf16 v[34:37], v[150:153], v[212:215], v[34:37]
	v_mfma_f32_16x16x32_bf16 v[26:29], v[172:175], v[212:215], v[26:29]
	v_mfma_f32_16x16x32_bf16 v[18:21], v[150:153], v[222:225], v[18:21]
	v_mfma_f32_16x16x32_bf16 v[10:13], v[172:175], v[222:225], v[10:13]
	s_setprio 0
	s_setprio 1
	v_mfma_f32_16x16x32_bf16 v[54:57], v[176:179], v[192:195], v[54:57]
	v_mfma_f32_16x16x32_bf16 v[46:49], v[184:187], v[192:195], v[46:49]
	v_mfma_f32_16x16x32_bf16 v[38:41], v[176:179], v[200:203], v[38:41]
	v_mfma_f32_16x16x32_bf16 v[30:33], v[184:187], v[200:203], v[30:33]
	v_mfma_f32_16x16x32_bf16 v[22:25], v[176:179], v[208:211], v[22:25]
	v_mfma_f32_16x16x32_bf16 v[14:17], v[184:187], v[208:211], v[14:17]
	v_mfma_f32_16x16x32_bf16 v[6:9], v[176:179], v[218:221], v[6:9]
	v_mfma_f32_16x16x32_bf16 v[2:5], v[184:187], v[218:221], v[2:5]
	v_mfma_f32_16x16x32_bf16 v[54:57], v[180:183], v[196:199], v[54:57]
	v_mfma_f32_16x16x32_bf16 v[46:49], v[188:191], v[196:199], v[46:49]
	v_mfma_f32_16x16x32_bf16 v[38:41], v[180:183], v[204:207], v[38:41]
	v_mfma_f32_16x16x32_bf16 v[30:33], v[188:191], v[204:207], v[30:33]
	v_mfma_f32_16x16x32_bf16 v[22:25], v[180:183], v[212:215], v[22:25]
	v_mfma_f32_16x16x32_bf16 v[14:17], v[188:191], v[212:215], v[14:17]
	v_mfma_f32_16x16x32_bf16 v[6:9], v[180:183], v[222:225], v[6:9]
	v_mfma_f32_16x16x32_bf16 v[2:5], v[188:191], v[222:225], v[2:5]
	s_setprio 0
	s_barrier
	s_add_i32 s79, s79, 2
	s_add_u32 s74, s74, 0x100
	s_addc_u32 s75, s75, 0
	s_add_u32 s52, s52, 0x100
	s_addc_u32 s78, s78, 0
	s_cmp_gt_u32 s79, 5
	s_cbranch_scc0 .LBB0_2629
	s_and_b64 vcc, exec, s[24:25]
	s_cbranch_vccz .LBB0_2632
	s_barrier

.LBB0_2659:
	s_add_u32 s34, s74, 0xfffe0080
	s_addc_u32 s35, s75, -1
	s_cmp_eq_u32 s72, 4
	s_cselect_b32 s77, s0, s35
	s_cselect_b32 s76, s1, s34
	s_cselect_b32 s35, s27, s71
	s_cselect_b32 s34, s37, s52
	v_lshl_add_u64 v[150:151], s[74:75], 0, v[138:139]
	s_add_i32 m0, s33, 0xc000
	s_nop 0
	global_load_lds_dwordx4 v[150:151], off
	v_lshl_add_u64 v[150:151], s[74:75], 0, v[140:141]
	s_add_i32 m0, s33, 0xe000
	s_nop 0
	global_load_lds_dwordx4 v[150:151], off
	ds_read_b128 v[146:149], v1
	ds_read_b128 v[160:163], v1 offset:1024
	ds_read_b128 v[164:167], v1 offset:2048
	ds_read_b128 v[168:171], v1 offset:3072
	ds_read_b128 v[172:175], v154
	ds_read_b128 v[176:179], v154 offset:1024
	ds_read_b128 v[180:183], v154 offset:2048
	ds_read_b128 v[184:187], v154 offset:3072
	ds_read_b128 v[188:191], v155
	ds_read_b128 v[192:195], v155 offset:1024
	ds_read_b128 v[196:199], v155 offset:2048
	ds_read_b128 v[200:203], v155 offset:3072
	ds_read_b128 v[204:207], v155 offset:4096
	ds_read_b128 v[208:211], v155 offset:5120
	ds_read_b128 v[212:215], v155 offset:6144
	ds_read_b128 v[218:221], v155 offset:7168
	s_waitcnt vmcnt(8)
	s_waitcnt lgkmcnt(0)
	s_barrier
	s_setprio 1
	s_waitcnt lgkmcnt(0)
	v_mfma_f32_16x16x32_bf16 v[126:129], v[146:149], v[188:191], v[126:129]
	v_mfma_f32_16x16x32_bf16 v[122:125], v[164:167], v[188:191], v[122:125]
	v_mfma_f32_16x16x32_bf16 v[110:113], v[146:149], v[196:199], v[110:113]
	v_mfma_f32_16x16x32_bf16 v[106:109], v[164:167], v[196:199], v[106:109]
	v_mfma_f32_16x16x32_bf16 v[94:97], v[146:149], v[204:207], v[94:97]
	v_mfma_f32_16x16x32_bf16 v[90:93], v[164:167], v[204:207], v[90:93]
	v_mfma_f32_16x16x32_bf16 v[78:81], v[146:149], v[212:215], v[78:81]
	v_mfma_f32_16x16x32_bf16 v[74:77], v[164:167], v[212:215], v[74:77]
	v_mfma_f32_16x16x32_bf16 v[126:129], v[160:163], v[192:195], v[126:129]
	v_mfma_f32_16x16x32_bf16 v[122:125], v[168:171], v[192:195], v[122:125]
	v_mfma_f32_16x16x32_bf16 v[110:113], v[160:163], v[200:203], v[110:113]
	v_mfma_f32_16x16x32_bf16 v[106:109], v[168:171], v[200:203], v[106:109]
	v_mfma_f32_16x16x32_bf16 v[94:97], v[160:163], v[208:211], v[94:97]
	v_mfma_f32_16x16x32_bf16 v[90:93], v[168:171], v[208:211], v[90:93]
	v_mfma_f32_16x16x32_bf16 v[78:81], v[160:163], v[218:221], v[78:81]
	v_mfma_f32_16x16x32_bf16 v[74:77], v[168:171], v[218:221], v[74:77]
	s_setprio 0
	s_setprio 1
	v_mfma_f32_16x16x32_bf16 v[118:121], v[172:175], v[188:191], v[118:121]
	v_mfma_f32_16x16x32_bf16 v[114:117], v[180:183], v[188:191], v[114:117]
	v_mfma_f32_16x16x32_bf16 v[102:105], v[172:175], v[196:199], v[102:105]
	v_mfma_f32_16x16x32_bf16 v[98:101], v[180:183], v[196:199], v[98:101]
	v_mfma_f32_16x16x32_bf16 v[86:89], v[172:175], v[204:207], v[86:89]
	v_mfma_f32_16x16x32_bf16 v[82:85], v[180:183], v[204:207], v[82:85]
	v_mfma_f32_16x16x32_bf16 v[70:73], v[172:175], v[212:215], v[70:73]
	v_mfma_f32_16x16x32_bf16 v[66:69], v[180:183], v[212:215], v[66:69]
	v_mfma_f32_16x16x32_bf16 v[118:121], v[176:179], v[192:195], v[118:121]
	v_mfma_f32_16x16x32_bf16 v[114:117], v[184:187], v[192:195], v[114:117]
	v_mfma_f32_16x16x32_bf16 v[102:105], v[176:179], v[200:203], v[102:105]
	v_mfma_f32_16x16x32_bf16 v[98:101], v[184:187], v[200:203], v[98:101]
	v_mfma_f32_16x16x32_bf16 v[86:89], v[176:179], v[208:211], v[86:89]
	v_mfma_f32_16x16x32_bf16 v[82:85], v[184:187], v[208:211], v[82:85]
	v_mfma_f32_16x16x32_bf16 v[70:73], v[176:179], v[218:221], v[70:73]
	v_mfma_f32_16x16x32_bf16 v[66:69], v[184:187], v[218:221], v[66:69]
	s_setprio 0
	s_barrier
	s_add_i32 s53, s60, s13
	v_lshl_add_u64 v[150:151], s[34:35], 0, v[132:133]
	s_mov_b32 m0, s53
	s_nop 0
	global_load_lds_dwordx4 v[150:151], off
	s_add_i32 m0, s53, 0x2000
	s_add_u32 s62, s34, 0x20000
	v_lshl_add_u64 v[222:223], s[34:35], 0, v[136:137]
	s_addc_u32 s63, s35, 0
	s_add_i32 s53, s61, s13
	global_load_lds_dwordx4 v[222:223], off
	v_lshl_add_u64 v[224:225], s[62:63], 0, v[132:133]
	s_mov_b32 m0, s53
	v_lshl_add_u64 v[226:227], s[76:77], 0, v[134:135]
	global_load_lds_dwordx4 v[224:225], off
	v_lshl_add_u64 v[224:225], s[62:63], 0, v[136:137]
	s_add_i32 m0, s53, 0x2000
	s_nop 0
	global_load_lds_dwordx4 v[224:225], off
	v_lshl_add_u64 v[224:225], s[76:77], 0, v[130:131]
	s_mov_b32 m0, s33
	s_nop 0
	global_load_lds_dwordx4 v[224:225], off
	s_mov_b32 m0, s47
	s_nop 0
	global_load_lds_dwordx4 v[226:227], off
	ds_read_b128 v[188:191], v155 offset:16384
	ds_read_b128 v[192:195], v155 offset:17408
	ds_read_b128 v[196:199], v155 offset:18432
	ds_read_b128 v[200:203], v155 offset:19456
	ds_read_b128 v[204:207], v155 offset:20480
	ds_read_b128 v[208:211], v155 offset:21504
	ds_read_b128 v[212:215], v155 offset:22528
	ds_read_b128 v[218:221], v155 offset:23552
	s_waitcnt vmcnt(8)
	s_waitcnt lgkmcnt(0)
	s_barrier
	s_setprio 1
	s_waitcnt lgkmcnt(0)
	v_mfma_f32_16x16x32_bf16 v[62:65], v[146:149], v[188:191], v[62:65]
	v_mfma_f32_16x16x32_bf16 v[58:61], v[164:167], v[188:191], v[58:61]
	v_mfma_f32_16x16x32_bf16 v[50:53], v[146:149], v[196:199], v[50:53]
	v_mfma_f32_16x16x32_bf16 v[42:45], v[164:167], v[196:199], v[42:45]
	v_mfma_f32_16x16x32_bf16 v[34:37], v[146:149], v[204:207], v[34:37]
	v_mfma_f32_16x16x32_bf16 v[26:29], v[164:167], v[204:207], v[26:29]
	v_mfma_f32_16x16x32_bf16 v[18:21], v[146:149], v[212:215], v[18:21]
	v_mfma_f32_16x16x32_bf16 v[10:13], v[164:167], v[212:215], v[10:13]
	v_mfma_f32_16x16x32_bf16 v[62:65], v[160:163], v[192:195], v[62:65]
	v_mfma_f32_16x16x32_bf16 v[58:61], v[168:171], v[192:195], v[58:61]
	v_mfma_f32_16x16x32_bf16 v[50:53], v[160:163], v[200:203], v[50:53]
	v_mfma_f32_16x16x32_bf16 v[42:45], v[168:171], v[200:203], v[42:45]
	v_mfma_f32_16x16x32_bf16 v[34:37], v[160:163], v[208:211], v[34:37]
	v_mfma_f32_16x16x32_bf16 v[26:29], v[168:171], v[208:211], v[26:29]
	v_mfma_f32_16x16x32_bf16 v[18:21], v[160:163], v[218:221], v[18:21]
	v_mfma_f32_16x16x32_bf16 v[10:13], v[168:171], v[218:221], v[10:13]
	s_setprio 0
	s_setprio 1
	v_mfma_f32_16x16x32_bf16 v[54:57], v[172:175], v[188:191], v[54:57]
	v_mfma_f32_16x16x32_bf16 v[46:49], v[180:183], v[188:191], v[46:49]
	v_mfma_f32_16x16x32_bf16 v[38:41], v[172:175], v[196:199], v[38:41]
	v_mfma_f32_16x16x32_bf16 v[30:33], v[180:183], v[196:199], v[30:33]
	v_mfma_f32_16x16x32_bf16 v[22:25], v[172:175], v[204:207], v[22:25]
	v_mfma_f32_16x16x32_bf16 v[14:17], v[180:183], v[204:207], v[14:17]
	v_mfma_f32_16x16x32_bf16 v[6:9], v[172:175], v[212:215], v[6:9]
	v_mfma_f32_16x16x32_bf16 v[2:5], v[180:183], v[212:215], v[2:5]
	v_mfma_f32_16x16x32_bf16 v[54:57], v[176:179], v[192:195], v[54:57]
	v_mfma_f32_16x16x32_bf16 v[46:49], v[184:187], v[192:195], v[46:49]
	v_mfma_f32_16x16x32_bf16 v[38:41], v[176:179], v[200:203], v[38:41]
	v_mfma_f32_16x16x32_bf16 v[30:33], v[184:187], v[200:203], v[30:33]
	v_mfma_f32_16x16x32_bf16 v[22:25], v[176:179], v[208:211], v[22:25]
	v_mfma_f32_16x16x32_bf16 v[14:17], v[184:187], v[208:211], v[14:17]
	v_mfma_f32_16x16x32_bf16 v[6:9], v[176:179], v[218:221], v[6:9]
	v_mfma_f32_16x16x32_bf16 v[2:5], v[184:187], v[218:221], v[2:5]
	s_setprio 0
	s_barrier
	s_add_i32 s53, 0, 0x18000
	s_add_i32 s66, 0, 0x1c000
	s_add_u32 s62, s76, 0x20000
	s_addc_u32 s63, s77, 0
	s_mov_b32 m0, s54
	v_lshl_add_u64 v[228:229], s[62:63], 0, v[130:131]
	global_load_lds_dwordx4 v[228:229], off
	v_lshl_add_u64 v[228:229], s[62:63], 0, v[134:135]
	s_mov_b32 m0, s55
	s_nop 0
	global_load_lds_dwordx4 v[228:229], off
	v_add_u32_e32 v156, s53, v153
	ds_read_b128 v[146:149], v156
	ds_read_b128 v[160:163], v156 offset:1024
	ds_read_b128 v[164:167], v156 offset:2048
	ds_read_b128 v[168:171], v156 offset:3072
	v_add_u32_e32 v156, s66, v153
	ds_read_b128 v[172:175], v156
	ds_read_b128 v[176:179], v156 offset:1024
	ds_read_b128 v[180:183], v156 offset:2048
	ds_read_b128 v[184:187], v156 offset:3072
	ds_read_b128 v[188:191], v155 offset:32768
	ds_read_b128 v[192:195], v155 offset:33792
	ds_read_b128 v[196:199], v155 offset:34816
	ds_read_b128 v[200:203], v155 offset:35840
	ds_read_b128 v[204:207], v155 offset:36864
	ds_read_b128 v[208:211], v155 offset:37888
	ds_read_b128 v[212:215], v155 offset:38912
	ds_read_b128 v[218:221], v155 offset:39936
	s_waitcnt vmcnt(8)
	s_waitcnt lgkmcnt(0)
	s_barrier
	s_setprio 1
	s_waitcnt lgkmcnt(0)
	v_mfma_f32_16x16x32_bf16 v[126:129], v[146:149], v[188:191], v[126:129]
	v_mfma_f32_16x16x32_bf16 v[122:125], v[164:167], v[188:191], v[122:125]
	v_mfma_f32_16x16x32_bf16 v[110:113], v[146:149], v[196:199], v[110:113]
	v_mfma_f32_16x16x32_bf16 v[106:109], v[164:167], v[196:199], v[106:109]
	v_mfma_f32_16x16x32_bf16 v[94:97], v[146:149], v[204:207], v[94:97]
	v_mfma_f32_16x16x32_bf16 v[90:93], v[164:167], v[204:207], v[90:93]
	v_mfma_f32_16x16x32_bf16 v[78:81], v[146:149], v[212:215], v[78:81]
	v_mfma_f32_16x16x32_bf16 v[74:77], v[164:167], v[212:215], v[74:77]
	v_mfma_f32_16x16x32_bf16 v[126:129], v[160:163], v[192:195], v[126:129]
	v_mfma_f32_16x16x32_bf16 v[122:125], v[168:171], v[192:195], v[122:125]
	v_mfma_f32_16x16x32_bf16 v[110:113], v[160:163], v[200:203], v[110:113]
	v_mfma_f32_16x16x32_bf16 v[106:109], v[168:171], v[200:203], v[106:109]
	v_mfma_f32_16x16x32_bf16 v[94:97], v[160:163], v[208:211], v[94:97]
	v_mfma_f32_16x16x32_bf16 v[90:93], v[168:171], v[208:211], v[90:93]
	v_mfma_f32_16x16x32_bf16 v[78:81], v[160:163], v[218:221], v[78:81]
	v_mfma_f32_16x16x32_bf16 v[74:77], v[168:171], v[218:221], v[74:77]
	s_setprio 0
	s_setprio 1
	v_mfma_f32_16x16x32_bf16 v[118:121], v[172:175], v[188:191], v[118:121]
	v_mfma_f32_16x16x32_bf16 v[114:117], v[180:183], v[188:191], v[114:117]
	v_mfma_f32_16x16x32_bf16 v[102:105], v[172:175], v[196:199], v[102:105]
	v_mfma_f32_16x16x32_bf16 v[98:101], v[180:183], v[196:199], v[98:101]
	v_mfma_f32_16x16x32_bf16 v[86:89], v[172:175], v[204:207], v[86:89]
	v_mfma_f32_16x16x32_bf16 v[82:85], v[180:183], v[204:207], v[82:85]
	v_mfma_f32_16x16x32_bf16 v[70:73], v[172:175], v[212:215], v[70:73]
	v_mfma_f32_16x16x32_bf16 v[66:69], v[180:183], v[212:215], v[66:69]
	v_mfma_f32_16x16x32_bf16 v[118:121], v[176:179], v[192:195], v[118:121]
	v_mfma_f32_16x16x32_bf16 v[114:117], v[184:187], v[192:195], v[114:117]
	v_mfma_f32_16x16x32_bf16 v[102:105], v[176:179], v[200:203], v[102:105]
	v_mfma_f32_16x16x32_bf16 v[98:101], v[184:187], v[200:203], v[98:101]
	v_mfma_f32_16x16x32_bf16 v[86:89], v[176:179], v[208:211], v[86:89]
	v_mfma_f32_16x16x32_bf16 v[82:85], v[184:187], v[208:211], v[82:85]
	v_mfma_f32_16x16x32_bf16 v[70:73], v[176:179], v[218:221], v[70:73]
	v_mfma_f32_16x16x32_bf16 v[66:69], v[184:187], v[218:221], v[66:69]
	s_setprio 0
	s_barrier
	s_add_i32 s53, s53, s13
	v_lshl_add_u64 v[150:151], v[150:151], 0, s[8:9]
	s_mov_b32 m0, s53
	s_nop 0
	global_load_lds_dwordx4 v[150:151], off
	s_add_i32 m0, s53, 0x2000
	s_add_u32 s34, s34, 0x20080
	v_lshl_add_u64 v[150:151], v[222:223], 0, s[8:9]
	s_addc_u32 s35, s35, 0
	s_add_i32 s53, s66, s13
	global_load_lds_dwordx4 v[150:151], off
	v_lshl_add_u64 v[150:151], s[34:35], 0, v[132:133]
	s_mov_b32 m0, s53
	s_nop 0
	global_load_lds_dwordx4 v[150:151], off
	v_lshl_add_u64 v[150:151], s[34:35], 0, v[136:137]
	s_add_i32 m0, s53, 0x2000
	s_nop 0
	global_load_lds_dwordx4 v[150:151], off
	v_lshl_add_u64 v[150:151], v[224:225], 0, s[8:9]
	s_mov_b32 m0, s57
	s_nop 0
	global_load_lds_dwordx4 v[150:151], off
	v_lshl_add_u64 v[150:151], v[226:227], 0, s[8:9]
	s_mov_b32 m0, s58
	s_nop 0
	global_load_lds_dwordx4 v[150:151], off
	ds_read_b128 v[188:191], v155 offset:49152
	ds_read_b128 v[192:195], v155 offset:50176
	ds_read_b128 v[196:199], v155 offset:51200
	ds_read_b128 v[200:203], v155 offset:52224
	ds_read_b128 v[204:207], v155 offset:53248
	ds_read_b128 v[208:211], v155 offset:54272
	ds_read_b128 v[212:215], v155 offset:55296
	ds_read_b128 v[218:221], v155 offset:56320
	s_waitcnt vmcnt(8)
	s_waitcnt lgkmcnt(0)
	s_barrier
	s_setprio 1
	s_waitcnt lgkmcnt(0)
	v_mfma_f32_16x16x32_bf16 v[62:65], v[146:149], v[188:191], v[62:65]
	v_mfma_f32_16x16x32_bf16 v[58:61], v[164:167], v[188:191], v[58:61]
	v_mfma_f32_16x16x32_bf16 v[50:53], v[146:149], v[196:199], v[50:53]
	v_mfma_f32_16x16x32_bf16 v[42:45], v[164:167], v[196:199], v[42:45]
	v_mfma_f32_16x16x32_bf16 v[34:37], v[146:149], v[204:207], v[34:37]
	v_mfma_f32_16x16x32_bf16 v[26:29], v[164:167], v[204:207], v[26:29]
	v_mfma_f32_16x16x32_bf16 v[18:21], v[146:149], v[212:215], v[18:21]
	v_mfma_f32_16x16x32_bf16 v[10:13], v[164:167], v[212:215], v[10:13]
	v_mfma_f32_16x16x32_bf16 v[62:65], v[160:163], v[192:195], v[62:65]
	v_mfma_f32_16x16x32_bf16 v[58:61], v[168:171], v[192:195], v[58:61]
	v_mfma_f32_16x16x32_bf16 v[50:53], v[160:163], v[200:203], v[50:53]
	v_mfma_f32_16x16x32_bf16 v[42:45], v[168:171], v[200:203], v[42:45]
	v_mfma_f32_16x16x32_bf16 v[34:37], v[160:163], v[208:211], v[34:37]
	v_mfma_f32_16x16x32_bf16 v[26:29], v[168:171], v[208:211], v[26:29]
	v_mfma_f32_16x16x32_bf16 v[18:21], v[160:163], v[218:221], v[18:21]
	v_mfma_f32_16x16x32_bf16 v[10:13], v[168:171], v[218:221], v[10:13]
	s_setprio 0
	s_setprio 1
	v_mfma_f32_16x16x32_bf16 v[54:57], v[172:175], v[188:191], v[54:57]
	v_mfma_f32_16x16x32_bf16 v[46:49], v[180:183], v[188:191], v[46:49]
	v_mfma_f32_16x16x32_bf16 v[38:41], v[172:175], v[196:199], v[38:41]
	v_mfma_f32_16x16x32_bf16 v[30:33], v[180:183], v[196:199], v[30:33]
	v_mfma_f32_16x16x32_bf16 v[22:25], v[172:175], v[204:207], v[22:25]
	v_mfma_f32_16x16x32_bf16 v[14:17], v[180:183], v[204:207], v[14:17]
	v_mfma_f32_16x16x32_bf16 v[6:9], v[172:175], v[212:215], v[6:9]
	v_mfma_f32_16x16x32_bf16 v[2:5], v[180:183], v[212:215], v[2:5]
	v_mfma_f32_16x16x32_bf16 v[54:57], v[176:179], v[192:195], v[54:57]
	v_mfma_f32_16x16x32_bf16 v[46:49], v[184:187], v[192:195], v[46:49]
	v_mfma_f32_16x16x32_bf16 v[38:41], v[176:179], v[200:203], v[38:41]
	v_mfma_f32_16x16x32_bf16 v[30:33], v[184:187], v[200:203], v[30:33]
	v_mfma_f32_16x16x32_bf16 v[22:25], v[176:179], v[208:211], v[22:25]
	v_mfma_f32_16x16x32_bf16 v[14:17], v[184:187], v[208:211], v[14:17]
	v_mfma_f32_16x16x32_bf16 v[6:9], v[176:179], v[218:221], v[6:9]
	v_mfma_f32_16x16x32_bf16 v[2:5], v[184:187], v[218:221], v[2:5]
	s_setprio 0
	s_barrier
	s_add_i32 s72, s72, 2
	s_add_u32 s74, s74, 0x100
	s_addc_u32 s75, s75, 0
	s_add_u32 s52, s52, 0x100
	s_addc_u32 s71, s71, 0
	s_cmp_gt_u32 s72, 5
	s_cbranch_scc0 .LBB0_2659
	s_and_b64 vcc, exec, s[24:25]
	s_cbranch_vccz .LBB0_2662
	s_barrier

.LBB0_2938:
	s_add_u32 s34, s46, 0xfff80080
	s_addc_u32 s35, s47, -1
	s_cmp_eq_u32 s72, 28
	s_cselect_b32 s69, s0, s35
	s_cselect_b32 s68, s1, s34
	s_cselect_b32 s35, s37, s71
	s_cselect_b32 s34, s39, s70
	v_lshl_add_u64 v[170:171], s[46:47], 0, v[150:151]
	s_add_i32 m0, s33, 0xc000
	s_nop 0
	global_load_lds_dwordx4 v[170:171], off
	v_lshl_add_u64 v[170:171], s[46:47], 0, v[152:153]
	s_add_i32 m0, s33, 0xe000
	s_nop 0
	global_load_lds_dwordx4 v[170:171], off
	ds_read_b128 v[130:133], v174
	ds_read_b128 v[134:137], v174 offset:1024
	ds_read_b128 v[138:141], v174 offset:2048
	ds_read_b128 v[158:161], v174 offset:3072
	ds_read_b128 v[162:165], v175
	ds_read_b128 v[166:169], v175 offset:1024
	ds_read_b128 v[178:181], v175 offset:2048
	ds_read_b128 v[182:185], v175 offset:3072
	ds_read_b128 v[186:189], v176
	ds_read_b128 v[190:193], v176 offset:1024
	ds_read_b128 v[194:197], v176 offset:2048
	ds_read_b128 v[198:201], v176 offset:3072
	ds_read_b128 v[202:205], v176 offset:4096
	ds_read_b128 v[206:209], v176 offset:5120
	ds_read_b128 v[210:213], v176 offset:6144
	ds_read_b128 v[218:221], v176 offset:7168
	s_waitcnt vmcnt(8)
	s_waitcnt lgkmcnt(0)
	s_barrier
	s_setprio 1
	s_waitcnt lgkmcnt(0)
	v_mfma_f32_16x16x32_bf16 v[126:129], v[130:133], v[186:189], v[126:129]
	v_mfma_f32_16x16x32_bf16 v[122:125], v[138:141], v[186:189], v[122:125]
	v_mfma_f32_16x16x32_bf16 v[110:113], v[130:133], v[194:197], v[110:113]
	v_mfma_f32_16x16x32_bf16 v[106:109], v[138:141], v[194:197], v[106:109]
	v_mfma_f32_16x16x32_bf16 v[94:97], v[130:133], v[202:205], v[94:97]
	v_mfma_f32_16x16x32_bf16 v[90:93], v[138:141], v[202:205], v[90:93]
	v_mfma_f32_16x16x32_bf16 v[78:81], v[130:133], v[210:213], v[78:81]
	v_mfma_f32_16x16x32_bf16 v[74:77], v[138:141], v[210:213], v[74:77]
	v_mfma_f32_16x16x32_bf16 v[126:129], v[134:137], v[190:193], v[126:129]
	v_mfma_f32_16x16x32_bf16 v[122:125], v[158:161], v[190:193], v[122:125]
	v_mfma_f32_16x16x32_bf16 v[110:113], v[134:137], v[198:201], v[110:113]
	v_mfma_f32_16x16x32_bf16 v[106:109], v[158:161], v[198:201], v[106:109]
	v_mfma_f32_16x16x32_bf16 v[94:97], v[134:137], v[206:209], v[94:97]
	v_mfma_f32_16x16x32_bf16 v[90:93], v[158:161], v[206:209], v[90:93]
	v_mfma_f32_16x16x32_bf16 v[78:81], v[134:137], v[218:221], v[78:81]
	v_mfma_f32_16x16x32_bf16 v[74:77], v[158:161], v[218:221], v[74:77]
	s_setprio 0
	s_setprio 1
	v_mfma_f32_16x16x32_bf16 v[118:121], v[162:165], v[186:189], v[118:121]
	v_mfma_f32_16x16x32_bf16 v[114:117], v[178:181], v[186:189], v[114:117]
	v_mfma_f32_16x16x32_bf16 v[102:105], v[162:165], v[194:197], v[102:105]
	v_mfma_f32_16x16x32_bf16 v[98:101], v[178:181], v[194:197], v[98:101]
	v_mfma_f32_16x16x32_bf16 v[86:89], v[162:165], v[202:205], v[86:89]
	v_mfma_f32_16x16x32_bf16 v[82:85], v[178:181], v[202:205], v[82:85]
	v_mfma_f32_16x16x32_bf16 v[70:73], v[162:165], v[210:213], v[70:73]
	v_mfma_f32_16x16x32_bf16 v[66:69], v[178:181], v[210:213], v[66:69]
	v_mfma_f32_16x16x32_bf16 v[118:121], v[166:169], v[190:193], v[118:121]
	v_mfma_f32_16x16x32_bf16 v[114:117], v[182:185], v[190:193], v[114:117]
	v_mfma_f32_16x16x32_bf16 v[102:105], v[166:169], v[198:201], v[102:105]
	v_mfma_f32_16x16x32_bf16 v[98:101], v[182:185], v[198:201], v[98:101]
	v_mfma_f32_16x16x32_bf16 v[86:89], v[166:169], v[206:209], v[86:89]
	v_mfma_f32_16x16x32_bf16 v[82:85], v[182:185], v[206:209], v[82:85]
	v_mfma_f32_16x16x32_bf16 v[70:73], v[166:169], v[218:221], v[70:73]
	v_mfma_f32_16x16x32_bf16 v[66:69], v[182:185], v[218:221], v[66:69]
	s_setprio 0
	s_barrier
	s_add_i32 s62, s58, s31
	v_lshl_add_u64 v[170:171], s[34:35], 0, v[144:145]
	s_mov_b32 m0, s62
	s_nop 0
	global_load_lds_dwordx4 v[170:171], off
	s_add_i32 m0, s62, 0x2000
	s_add_u32 s62, s34, 0x80000
	v_lshl_add_u64 v[214:215], s[34:35], 0, v[148:149]
	s_addc_u32 s63, s35, 0
	s_add_i32 s66, s59, s31
	global_load_lds_dwordx4 v[214:215], off
	v_lshl_add_u64 v[222:223], s[62:63], 0, v[144:145]
	s_mov_b32 m0, s66
	v_lshl_add_u64 v[224:225], s[68:69], 0, v[146:147]
	global_load_lds_dwordx4 v[222:223], off
	v_lshl_add_u64 v[222:223], s[62:63], 0, v[148:149]
	s_add_i32 m0, s66, 0x2000
	s_nop 0
	global_load_lds_dwordx4 v[222:223], off
	v_lshl_add_u64 v[222:223], s[68:69], 0, v[142:143]
	s_mov_b32 m0, s33
	s_nop 0
	global_load_lds_dwordx4 v[222:223], off
	s_mov_b32 m0, s45
	s_nop 0
	global_load_lds_dwordx4 v[224:225], off
	ds_read_b128 v[186:189], v176 offset:16384
	ds_read_b128 v[190:193], v176 offset:17408
	ds_read_b128 v[194:197], v176 offset:18432
	ds_read_b128 v[198:201], v176 offset:19456
	ds_read_b128 v[202:205], v176 offset:20480
	ds_read_b128 v[206:209], v176 offset:21504
	ds_read_b128 v[210:213], v176 offset:22528
	ds_read_b128 v[218:221], v176 offset:23552
	s_waitcnt vmcnt(8)
	s_waitcnt lgkmcnt(0)
	s_barrier
	s_setprio 1
	s_waitcnt lgkmcnt(0)
	v_mfma_f32_16x16x32_bf16 v[62:65], v[130:133], v[186:189], v[62:65]
	v_mfma_f32_16x16x32_bf16 v[58:61], v[138:141], v[186:189], v[58:61]
	v_mfma_f32_16x16x32_bf16 v[50:53], v[130:133], v[194:197], v[50:53]
	v_mfma_f32_16x16x32_bf16 v[42:45], v[138:141], v[194:197], v[42:45]
	v_mfma_f32_16x16x32_bf16 v[38:41], v[130:133], v[202:205], v[38:41]
	v_mfma_f32_16x16x32_bf16 v[34:37], v[138:141], v[202:205], v[34:37]
	v_mfma_f32_16x16x32_bf16 v[14:17], v[130:133], v[210:213], v[14:17]
	v_mfma_f32_16x16x32_bf16 v[10:13], v[138:141], v[210:213], v[10:13]
	v_mfma_f32_16x16x32_bf16 v[62:65], v[134:137], v[190:193], v[62:65]
	v_mfma_f32_16x16x32_bf16 v[58:61], v[158:161], v[190:193], v[58:61]
	v_mfma_f32_16x16x32_bf16 v[50:53], v[134:137], v[198:201], v[50:53]
	v_mfma_f32_16x16x32_bf16 v[42:45], v[158:161], v[198:201], v[42:45]
	v_mfma_f32_16x16x32_bf16 v[38:41], v[134:137], v[206:209], v[38:41]
	v_mfma_f32_16x16x32_bf16 v[34:37], v[158:161], v[206:209], v[34:37]
	v_mfma_f32_16x16x32_bf16 v[14:17], v[134:137], v[218:221], v[14:17]
	v_mfma_f32_16x16x32_bf16 v[10:13], v[158:161], v[218:221], v[10:13]
	s_setprio 0
	s_setprio 1
	v_mfma_f32_16x16x32_bf16 v[54:57], v[162:165], v[186:189], v[54:57]
	v_mfma_f32_16x16x32_bf16 v[46:49], v[178:181], v[186:189], v[46:49]
	v_mfma_f32_16x16x32_bf16 v[30:33], v[162:165], v[194:197], v[30:33]
	v_mfma_f32_16x16x32_bf16 v[26:29], v[178:181], v[194:197], v[26:29]
	v_mfma_f32_16x16x32_bf16 v[22:25], v[162:165], v[202:205], v[22:25]
	v_mfma_f32_16x16x32_bf16 v[18:21], v[178:181], v[202:205], v[18:21]
	v_mfma_f32_16x16x32_bf16 v[6:9], v[162:165], v[210:213], v[6:9]
	v_mfma_f32_16x16x32_bf16 v[2:5], v[178:181], v[210:213], v[2:5]
	v_mfma_f32_16x16x32_bf16 v[54:57], v[166:169], v[190:193], v[54:57]
	v_mfma_f32_16x16x32_bf16 v[46:49], v[182:185], v[190:193], v[46:49]
	v_mfma_f32_16x16x32_bf16 v[30:33], v[166:169], v[198:201], v[30:33]
	v_mfma_f32_16x16x32_bf16 v[26:29], v[182:185], v[198:201], v[26:29]
	v_mfma_f32_16x16x32_bf16 v[22:25], v[166:169], v[206:209], v[22:25]
	v_mfma_f32_16x16x32_bf16 v[18:21], v[182:185], v[206:209], v[18:21]
	v_mfma_f32_16x16x32_bf16 v[6:9], v[166:169], v[218:221], v[6:9]
	v_mfma_f32_16x16x32_bf16 v[2:5], v[182:185], v[218:221], v[2:5]
	s_setprio 0
	s_barrier
	s_add_i32 s66, 0, 0x18000
	s_add_i32 s67, 0, 0x1c000
	s_add_u32 s62, s68, 0x80000
	s_addc_u32 s63, s69, 0
	s_mov_b32 m0, s52
	v_lshl_add_u64 v[226:227], s[62:63], 0, v[142:143]
	global_load_lds_dwordx4 v[226:227], off
	v_lshl_add_u64 v[226:227], s[62:63], 0, v[146:147]
	s_mov_b32 m0, s53
	s_nop 0
	global_load_lds_dwordx4 v[226:227], off
	v_add_u32_e32 v158, s66, v172
	v_add_u32_e32 v177, s67, v172
	ds_read_b128 v[130:133], v158
	ds_read_b128 v[134:137], v158 offset:1024
	ds_read_b128 v[138:141], v158 offset:2048
	ds_read_b128 v[158:161], v158 offset:3072
	ds_read_b128 v[162:165], v177
	ds_read_b128 v[166:169], v177 offset:1024
	ds_read_b128 v[178:181], v177 offset:2048
	ds_read_b128 v[182:185], v177 offset:3072
	ds_read_b128 v[186:189], v176 offset:32768
	ds_read_b128 v[190:193], v176 offset:33792
	ds_read_b128 v[194:197], v176 offset:34816
	ds_read_b128 v[198:201], v176 offset:35840
	ds_read_b128 v[202:205], v176 offset:36864
	ds_read_b128 v[206:209], v176 offset:37888
	ds_read_b128 v[210:213], v176 offset:38912
	ds_read_b128 v[218:221], v176 offset:39936
	s_waitcnt vmcnt(8)
	s_waitcnt lgkmcnt(0)
	s_barrier
	s_setprio 1
	s_waitcnt lgkmcnt(0)
	v_mfma_f32_16x16x32_bf16 v[126:129], v[130:133], v[186:189], v[126:129]
	v_mfma_f32_16x16x32_bf16 v[122:125], v[138:141], v[186:189], v[122:125]
	v_mfma_f32_16x16x32_bf16 v[110:113], v[130:133], v[194:197], v[110:113]
	v_mfma_f32_16x16x32_bf16 v[106:109], v[138:141], v[194:197], v[106:109]
	v_mfma_f32_16x16x32_bf16 v[94:97], v[130:133], v[202:205], v[94:97]
	v_mfma_f32_16x16x32_bf16 v[90:93], v[138:141], v[202:205], v[90:93]
	v_mfma_f32_16x16x32_bf16 v[78:81], v[130:133], v[210:213], v[78:81]
	v_mfma_f32_16x16x32_bf16 v[74:77], v[138:141], v[210:213], v[74:77]
	v_mfma_f32_16x16x32_bf16 v[126:129], v[134:137], v[190:193], v[126:129]
	v_mfma_f32_16x16x32_bf16 v[122:125], v[158:161], v[190:193], v[122:125]
	v_mfma_f32_16x16x32_bf16 v[110:113], v[134:137], v[198:201], v[110:113]
	v_mfma_f32_16x16x32_bf16 v[106:109], v[158:161], v[198:201], v[106:109]
	v_mfma_f32_16x16x32_bf16 v[94:97], v[134:137], v[206:209], v[94:97]
	v_mfma_f32_16x16x32_bf16 v[90:93], v[158:161], v[206:209], v[90:93]
	v_mfma_f32_16x16x32_bf16 v[78:81], v[134:137], v[218:221], v[78:81]
	v_mfma_f32_16x16x32_bf16 v[74:77], v[158:161], v[218:221], v[74:77]
	s_setprio 0
	s_setprio 1
	v_mfma_f32_16x16x32_bf16 v[118:121], v[162:165], v[186:189], v[118:121]
	v_mfma_f32_16x16x32_bf16 v[114:117], v[178:181], v[186:189], v[114:117]
	v_mfma_f32_16x16x32_bf16 v[102:105], v[162:165], v[194:197], v[102:105]
	v_mfma_f32_16x16x32_bf16 v[98:101], v[178:181], v[194:197], v[98:101]
	v_mfma_f32_16x16x32_bf16 v[86:89], v[162:165], v[202:205], v[86:89]
	v_mfma_f32_16x16x32_bf16 v[82:85], v[178:181], v[202:205], v[82:85]
	v_mfma_f32_16x16x32_bf16 v[70:73], v[162:165], v[210:213], v[70:73]
	v_mfma_f32_16x16x32_bf16 v[66:69], v[178:181], v[210:213], v[66:69]
	v_mfma_f32_16x16x32_bf16 v[118:121], v[166:169], v[190:193], v[118:121]
	v_mfma_f32_16x16x32_bf16 v[114:117], v[182:185], v[190:193], v[114:117]
	v_mfma_f32_16x16x32_bf16 v[102:105], v[166:169], v[198:201], v[102:105]
	v_mfma_f32_16x16x32_bf16 v[98:101], v[182:185], v[198:201], v[98:101]
	v_mfma_f32_16x16x32_bf16 v[86:89], v[166:169], v[206:209], v[86:89]
	v_mfma_f32_16x16x32_bf16 v[82:85], v[182:185], v[206:209], v[82:85]
	v_mfma_f32_16x16x32_bf16 v[70:73], v[166:169], v[218:221], v[70:73]
	v_mfma_f32_16x16x32_bf16 v[66:69], v[182:185], v[218:221], v[66:69]
	s_setprio 0
	s_barrier
	s_add_i32 s62, s66, s31
	v_lshl_add_u64 v[170:171], v[170:171], 0, s[24:25]
	s_mov_b32 m0, s62
	s_nop 0
	global_load_lds_dwordx4 v[170:171], off
	s_add_i32 m0, s62, 0x2000
	s_add_u32 s34, s34, 0x80080
	v_lshl_add_u64 v[170:171], v[214:215], 0, s[24:25]
	s_addc_u32 s35, s35, 0
	s_add_i32 s62, s67, s31
	global_load_lds_dwordx4 v[170:171], off
	v_lshl_add_u64 v[170:171], s[34:35], 0, v[144:145]
	s_mov_b32 m0, s62
	s_nop 0
	global_load_lds_dwordx4 v[170:171], off
	v_lshl_add_u64 v[170:171], s[34:35], 0, v[148:149]
	s_add_i32 m0, s62, 0x2000
	s_nop 0
	global_load_lds_dwordx4 v[170:171], off
	v_lshl_add_u64 v[170:171], v[222:223], 0, s[24:25]
	s_mov_b32 m0, s55
	s_nop 0
	global_load_lds_dwordx4 v[170:171], off
	v_lshl_add_u64 v[170:171], v[224:225], 0, s[24:25]
	s_mov_b32 m0, s56
	s_nop 0
	global_load_lds_dwordx4 v[170:171], off
	ds_read_b128 v[186:189], v176 offset:49152
	ds_read_b128 v[190:193], v176 offset:50176
	ds_read_b128 v[194:197], v176 offset:51200
	ds_read_b128 v[198:201], v176 offset:52224
	ds_read_b128 v[202:205], v176 offset:53248
	ds_read_b128 v[206:209], v176 offset:54272
	ds_read_b128 v[210:213], v176 offset:55296
	ds_read_b128 v[218:221], v176 offset:56320
	s_waitcnt vmcnt(8)
	s_waitcnt lgkmcnt(0)
	s_barrier
	s_setprio 1
	s_waitcnt lgkmcnt(0)
	v_mfma_f32_16x16x32_bf16 v[62:65], v[130:133], v[186:189], v[62:65]
	v_mfma_f32_16x16x32_bf16 v[58:61], v[138:141], v[186:189], v[58:61]
	v_mfma_f32_16x16x32_bf16 v[50:53], v[130:133], v[194:197], v[50:53]
	v_mfma_f32_16x16x32_bf16 v[42:45], v[138:141], v[194:197], v[42:45]
	v_mfma_f32_16x16x32_bf16 v[38:41], v[130:133], v[202:205], v[38:41]
	v_mfma_f32_16x16x32_bf16 v[34:37], v[138:141], v[202:205], v[34:37]
	v_mfma_f32_16x16x32_bf16 v[14:17], v[130:133], v[210:213], v[14:17]
	v_mfma_f32_16x16x32_bf16 v[10:13], v[138:141], v[210:213], v[10:13]
	v_mfma_f32_16x16x32_bf16 v[62:65], v[134:137], v[190:193], v[62:65]
	v_mfma_f32_16x16x32_bf16 v[58:61], v[158:161], v[190:193], v[58:61]
	v_mfma_f32_16x16x32_bf16 v[50:53], v[134:137], v[198:201], v[50:53]
	v_mfma_f32_16x16x32_bf16 v[42:45], v[158:161], v[198:201], v[42:45]
	v_mfma_f32_16x16x32_bf16 v[38:41], v[134:137], v[206:209], v[38:41]
	v_mfma_f32_16x16x32_bf16 v[34:37], v[158:161], v[206:209], v[34:37]
	v_mfma_f32_16x16x32_bf16 v[14:17], v[134:137], v[218:221], v[14:17]
	v_mfma_f32_16x16x32_bf16 v[10:13], v[158:161], v[218:221], v[10:13]
	s_setprio 0
	s_setprio 1
	v_mfma_f32_16x16x32_bf16 v[54:57], v[162:165], v[186:189], v[54:57]
	v_mfma_f32_16x16x32_bf16 v[46:49], v[178:181], v[186:189], v[46:49]
	v_mfma_f32_16x16x32_bf16 v[30:33], v[162:165], v[194:197], v[30:33]
	v_mfma_f32_16x16x32_bf16 v[26:29], v[178:181], v[194:197], v[26:29]
	v_mfma_f32_16x16x32_bf16 v[22:25], v[162:165], v[202:205], v[22:25]
	v_mfma_f32_16x16x32_bf16 v[18:21], v[178:181], v[202:205], v[18:21]
	v_mfma_f32_16x16x32_bf16 v[6:9], v[162:165], v[210:213], v[6:9]
	v_mfma_f32_16x16x32_bf16 v[2:5], v[178:181], v[210:213], v[2:5]
	v_mfma_f32_16x16x32_bf16 v[54:57], v[166:169], v[190:193], v[54:57]
	v_mfma_f32_16x16x32_bf16 v[46:49], v[182:185], v[190:193], v[46:49]
	v_mfma_f32_16x16x32_bf16 v[30:33], v[166:169], v[198:201], v[30:33]
	v_mfma_f32_16x16x32_bf16 v[26:29], v[182:185], v[198:201], v[26:29]
	v_mfma_f32_16x16x32_bf16 v[22:25], v[166:169], v[206:209], v[22:25]
	v_mfma_f32_16x16x32_bf16 v[18:21], v[182:185], v[206:209], v[18:21]
	v_mfma_f32_16x16x32_bf16 v[6:9], v[166:169], v[218:221], v[6:9]
	v_mfma_f32_16x16x32_bf16 v[2:5], v[182:185], v[218:221], v[2:5]
	s_setprio 0
	s_barrier
	s_add_i32 s72, s72, 2
	s_add_u32 s46, s46, 0x100
	s_addc_u32 s47, s47, 0
	s_add_u32 s70, s70, 0x100
	s_addc_u32 s71, s71, 0
	s_cmp_gt_u32 s72, 29
	s_cbranch_scc0 .LBB0_2938
	s_and_b64 vcc, exec, s[26:27]
	s_cbranch_vccz .LBB0_2941
	s_barrier

.LBB0_3067:
	s_add_u32 s34, s44, 0xfff80080
	s_addc_u32 s35, s45, -1
	s_cmp_eq_u32 s71, 28
	s_cselect_b32 s47, s0, s35
	s_cselect_b32 s46, s1, s34
	s_cselect_b32 s35, s27, s70
	s_cselect_b32 s34, s37, s69
	v_lshl_add_u64 v[218:219], s[44:45], 0, v[138:139]
	s_add_i32 m0, s43, 0xc000
	s_nop 0
	global_load_lds_dwordx4 v[218:219], off
	v_lshl_add_u64 v[218:219], s[44:45], 0, v[140:141]
	s_add_i32 m0, s43, 0xe000
	s_nop 0
	global_load_lds_dwordx4 v[218:219], off
	ds_read_b128 v[146:149], v153
	ds_read_b128 v[156:159], v153 offset:1024
	ds_read_b128 v[160:163], v153 offset:2048
	ds_read_b128 v[164:167], v153 offset:3072
	ds_read_b128 v[168:171], v154
	ds_read_b128 v[172:175], v154 offset:1024
	ds_read_b128 v[176:179], v154 offset:2048
	ds_read_b128 v[180:183], v154 offset:3072
	ds_read_b128 v[184:187], v155
	ds_read_b128 v[188:191], v155 offset:1024
	ds_read_b128 v[192:195], v155 offset:2048
	ds_read_b128 v[196:199], v155 offset:3072
	ds_read_b128 v[200:203], v155 offset:4096
	ds_read_b128 v[204:207], v155 offset:5120
	ds_read_b128 v[208:211], v155 offset:6144
	ds_read_b128 v[212:215], v155 offset:7168
	s_waitcnt vmcnt(8)
	s_waitcnt lgkmcnt(0)
	s_barrier
	s_setprio 1
	s_waitcnt lgkmcnt(0)
	v_mfma_f32_16x16x32_bf16 v[126:129], v[146:149], v[184:187], v[126:129]
	v_mfma_f32_16x16x32_bf16 v[118:121], v[160:163], v[184:187], v[118:121]
	v_mfma_f32_16x16x32_bf16 v[110:113], v[146:149], v[192:195], v[110:113]
	v_mfma_f32_16x16x32_bf16 v[102:105], v[160:163], v[192:195], v[102:105]
	v_mfma_f32_16x16x32_bf16 v[94:97], v[146:149], v[200:203], v[94:97]
	v_mfma_f32_16x16x32_bf16 v[86:89], v[160:163], v[200:203], v[86:89]
	v_mfma_f32_16x16x32_bf16 v[78:81], v[146:149], v[208:211], v[78:81]
	v_mfma_f32_16x16x32_bf16 v[70:73], v[160:163], v[208:211], v[70:73]
	v_mfma_f32_16x16x32_bf16 v[126:129], v[156:159], v[188:191], v[126:129]
	v_mfma_f32_16x16x32_bf16 v[118:121], v[164:167], v[188:191], v[118:121]
	v_mfma_f32_16x16x32_bf16 v[110:113], v[156:159], v[196:199], v[110:113]
	v_mfma_f32_16x16x32_bf16 v[102:105], v[164:167], v[196:199], v[102:105]
	v_mfma_f32_16x16x32_bf16 v[94:97], v[156:159], v[204:207], v[94:97]
	v_mfma_f32_16x16x32_bf16 v[86:89], v[164:167], v[204:207], v[86:89]
	v_mfma_f32_16x16x32_bf16 v[78:81], v[156:159], v[212:215], v[78:81]
	v_mfma_f32_16x16x32_bf16 v[70:73], v[164:167], v[212:215], v[70:73]
	s_setprio 0
	s_setprio 1
	v_mfma_f32_16x16x32_bf16 v[122:125], v[168:171], v[184:187], v[122:125]
	v_mfma_f32_16x16x32_bf16 v[114:117], v[176:179], v[184:187], v[114:117]
	v_mfma_f32_16x16x32_bf16 v[106:109], v[168:171], v[192:195], v[106:109]
	v_mfma_f32_16x16x32_bf16 v[98:101], v[176:179], v[192:195], v[98:101]
	v_mfma_f32_16x16x32_bf16 v[90:93], v[168:171], v[200:203], v[90:93]
	v_mfma_f32_16x16x32_bf16 v[82:85], v[176:179], v[200:203], v[82:85]
	v_mfma_f32_16x16x32_bf16 v[74:77], v[168:171], v[208:211], v[74:77]
	v_mfma_f32_16x16x32_bf16 v[66:69], v[176:179], v[208:211], v[66:69]
	v_mfma_f32_16x16x32_bf16 v[122:125], v[172:175], v[188:191], v[122:125]
	v_mfma_f32_16x16x32_bf16 v[114:117], v[180:183], v[188:191], v[114:117]
	v_mfma_f32_16x16x32_bf16 v[106:109], v[172:175], v[196:199], v[106:109]
	v_mfma_f32_16x16x32_bf16 v[98:101], v[180:183], v[196:199], v[98:101]
	v_mfma_f32_16x16x32_bf16 v[90:93], v[172:175], v[204:207], v[90:93]
	v_mfma_f32_16x16x32_bf16 v[82:85], v[180:183], v[204:207], v[82:85]
	v_mfma_f32_16x16x32_bf16 v[74:77], v[172:175], v[212:215], v[74:77]
	v_mfma_f32_16x16x32_bf16 v[66:69], v[180:183], v[212:215], v[66:69]
	s_setprio 0
	s_barrier
	s_add_i32 s62, s59, s30
	v_lshl_add_u64 v[218:219], s[34:35], 0, v[134:135]
	s_mov_b32 m0, s62
	s_nop 0
	global_load_lds_dwordx4 v[218:219], off
	s_add_i32 m0, s62, 0x2000
	s_add_u32 s62, s34, 0x80000
	v_lshl_add_u64 v[220:221], s[34:35], 0, v[130:131]
	s_addc_u32 s63, s35, 0
	s_add_i32 s66, s60, s30
	global_load_lds_dwordx4 v[220:221], off
	v_lshl_add_u64 v[222:223], s[62:63], 0, v[134:135]
	s_mov_b32 m0, s66
	v_lshl_add_u64 v[224:225], s[46:47], 0, v[132:133]
	global_load_lds_dwordx4 v[222:223], off
	v_lshl_add_u64 v[222:223], s[62:63], 0, v[130:131]
	s_add_i32 m0, s66, 0x2000
	s_nop 0
	global_load_lds_dwordx4 v[222:223], off
	v_lshl_add_u64 v[222:223], s[46:47], 0, v[136:137]
	s_mov_b32 m0, s43
	s_nop 0
	global_load_lds_dwordx4 v[222:223], off
	s_mov_b32 m0, s52
	s_nop 0
	global_load_lds_dwordx4 v[224:225], off
	ds_read_b128 v[184:187], v155 offset:16384
	ds_read_b128 v[188:191], v155 offset:17408
	ds_read_b128 v[192:195], v155 offset:18432
	ds_read_b128 v[196:199], v155 offset:19456
	ds_read_b128 v[200:203], v155 offset:20480
	ds_read_b128 v[204:207], v155 offset:21504
	ds_read_b128 v[208:211], v155 offset:22528
	ds_read_b128 v[212:215], v155 offset:23552
	s_waitcnt vmcnt(8)
	s_waitcnt lgkmcnt(0)
	s_barrier
	s_setprio 1
	s_waitcnt lgkmcnt(0)
	v_mfma_f32_16x16x32_bf16 v[62:65], v[146:149], v[184:187], v[62:65]
	v_mfma_f32_16x16x32_bf16 v[54:57], v[160:163], v[184:187], v[54:57]
	v_mfma_f32_16x16x32_bf16 v[46:49], v[146:149], v[192:195], v[46:49]
	v_mfma_f32_16x16x32_bf16 v[38:41], v[160:163], v[192:195], v[38:41]
	v_mfma_f32_16x16x32_bf16 v[30:33], v[146:149], v[200:203], v[30:33]
	v_mfma_f32_16x16x32_bf16 v[22:25], v[160:163], v[200:203], v[22:25]
	v_mfma_f32_16x16x32_bf16 v[14:17], v[146:149], v[208:211], v[14:17]
	v_mfma_f32_16x16x32_bf16 v[6:9], v[160:163], v[208:211], v[6:9]
	v_mfma_f32_16x16x32_bf16 v[62:65], v[156:159], v[188:191], v[62:65]
	v_mfma_f32_16x16x32_bf16 v[54:57], v[164:167], v[188:191], v[54:57]
	v_mfma_f32_16x16x32_bf16 v[46:49], v[156:159], v[196:199], v[46:49]
	v_mfma_f32_16x16x32_bf16 v[38:41], v[164:167], v[196:199], v[38:41]
	v_mfma_f32_16x16x32_bf16 v[30:33], v[156:159], v[204:207], v[30:33]
	v_mfma_f32_16x16x32_bf16 v[22:25], v[164:167], v[204:207], v[22:25]
	v_mfma_f32_16x16x32_bf16 v[14:17], v[156:159], v[212:215], v[14:17]
	v_mfma_f32_16x16x32_bf16 v[6:9], v[164:167], v[212:215], v[6:9]
	s_setprio 0
	s_setprio 1
	v_mfma_f32_16x16x32_bf16 v[58:61], v[168:171], v[184:187], v[58:61]
	v_mfma_f32_16x16x32_bf16 v[50:53], v[176:179], v[184:187], v[50:53]
	v_mfma_f32_16x16x32_bf16 v[42:45], v[168:171], v[192:195], v[42:45]
	v_mfma_f32_16x16x32_bf16 v[34:37], v[176:179], v[192:195], v[34:37]
	v_mfma_f32_16x16x32_bf16 v[26:29], v[168:171], v[200:203], v[26:29]
	v_mfma_f32_16x16x32_bf16 v[18:21], v[176:179], v[200:203], v[18:21]
	v_mfma_f32_16x16x32_bf16 v[10:13], v[168:171], v[208:211], v[10:13]
	v_mfma_f32_16x16x32_bf16 v[2:5], v[176:179], v[208:211], v[2:5]
	v_mfma_f32_16x16x32_bf16 v[58:61], v[172:175], v[188:191], v[58:61]
	v_mfma_f32_16x16x32_bf16 v[50:53], v[180:183], v[188:191], v[50:53]
	v_mfma_f32_16x16x32_bf16 v[42:45], v[172:175], v[196:199], v[42:45]
	v_mfma_f32_16x16x32_bf16 v[34:37], v[180:183], v[196:199], v[34:37]
	v_mfma_f32_16x16x32_bf16 v[26:29], v[172:175], v[204:207], v[26:29]
	v_mfma_f32_16x16x32_bf16 v[18:21], v[180:183], v[204:207], v[18:21]
	v_mfma_f32_16x16x32_bf16 v[10:13], v[172:175], v[212:215], v[10:13]
	v_mfma_f32_16x16x32_bf16 v[2:5], v[180:183], v[212:215], v[2:5]
	s_setprio 0
	s_barrier
	s_add_i32 s62, 0, 0x18000
	s_add_i32 s63, 0, 0x1c000
	s_add_u32 s46, s46, 0x80000
	s_addc_u32 s47, s47, 0
	s_mov_b32 m0, s53
	v_lshl_add_u64 v[226:227], s[46:47], 0, v[136:137]
	global_load_lds_dwordx4 v[226:227], off
	v_lshl_add_u64 v[226:227], s[46:47], 0, v[132:133]
	s_mov_b32 m0, s54
	s_nop 0
	global_load_lds_dwordx4 v[226:227], off
	v_add_u32_e32 v164, s62, v151
	v_add_u32_e32 v180, s63, v151
	ds_read_b128 v[146:149], v164
	ds_read_b128 v[156:159], v164 offset:1024
	ds_read_b128 v[160:163], v164 offset:2048
	ds_read_b128 v[164:167], v164 offset:3072
	ds_read_b128 v[168:171], v180
	ds_read_b128 v[172:175], v180 offset:1024
	ds_read_b128 v[176:179], v180 offset:2048
	ds_read_b128 v[180:183], v180 offset:3072
	ds_read_b128 v[184:187], v155 offset:32768
	ds_read_b128 v[188:191], v155 offset:33792
	ds_read_b128 v[192:195], v155 offset:34816
	ds_read_b128 v[196:199], v155 offset:35840
	ds_read_b128 v[200:203], v155 offset:36864
	ds_read_b128 v[204:207], v155 offset:37888
	ds_read_b128 v[208:211], v155 offset:38912
	ds_read_b128 v[212:215], v155 offset:39936
	s_waitcnt vmcnt(8)
	s_waitcnt lgkmcnt(0)
	s_barrier
	s_setprio 1
	s_waitcnt lgkmcnt(0)
	v_mfma_f32_16x16x32_bf16 v[126:129], v[146:149], v[184:187], v[126:129]
	v_mfma_f32_16x16x32_bf16 v[118:121], v[160:163], v[184:187], v[118:121]
	v_mfma_f32_16x16x32_bf16 v[110:113], v[146:149], v[192:195], v[110:113]
	v_mfma_f32_16x16x32_bf16 v[102:105], v[160:163], v[192:195], v[102:105]
	v_mfma_f32_16x16x32_bf16 v[94:97], v[146:149], v[200:203], v[94:97]
	v_mfma_f32_16x16x32_bf16 v[86:89], v[160:163], v[200:203], v[86:89]
	v_mfma_f32_16x16x32_bf16 v[78:81], v[146:149], v[208:211], v[78:81]
	v_mfma_f32_16x16x32_bf16 v[70:73], v[160:163], v[208:211], v[70:73]
	v_mfma_f32_16x16x32_bf16 v[126:129], v[156:159], v[188:191], v[126:129]
	v_mfma_f32_16x16x32_bf16 v[118:121], v[164:167], v[188:191], v[118:121]
	v_mfma_f32_16x16x32_bf16 v[110:113], v[156:159], v[196:199], v[110:113]
	v_mfma_f32_16x16x32_bf16 v[102:105], v[164:167], v[196:199], v[102:105]
	v_mfma_f32_16x16x32_bf16 v[94:97], v[156:159], v[204:207], v[94:97]
	v_mfma_f32_16x16x32_bf16 v[86:89], v[164:167], v[204:207], v[86:89]
	v_mfma_f32_16x16x32_bf16 v[78:81], v[156:159], v[212:215], v[78:81]
	v_mfma_f32_16x16x32_bf16 v[70:73], v[164:167], v[212:215], v[70:73]
	s_setprio 0
	s_setprio 1
	v_mfma_f32_16x16x32_bf16 v[122:125], v[168:171], v[184:187], v[122:125]
	v_mfma_f32_16x16x32_bf16 v[114:117], v[176:179], v[184:187], v[114:117]
	v_mfma_f32_16x16x32_bf16 v[106:109], v[168:171], v[192:195], v[106:109]
	v_mfma_f32_16x16x32_bf16 v[98:101], v[176:179], v[192:195], v[98:101]
	v_mfma_f32_16x16x32_bf16 v[90:93], v[168:171], v[200:203], v[90:93]
	v_mfma_f32_16x16x32_bf16 v[82:85], v[176:179], v[200:203], v[82:85]
	v_mfma_f32_16x16x32_bf16 v[74:77], v[168:171], v[208:211], v[74:77]
	v_mfma_f32_16x16x32_bf16 v[66:69], v[176:179], v[208:211], v[66:69]
	v_mfma_f32_16x16x32_bf16 v[122:125], v[172:175], v[188:191], v[122:125]
	v_mfma_f32_16x16x32_bf16 v[114:117], v[180:183], v[188:191], v[114:117]
	v_mfma_f32_16x16x32_bf16 v[106:109], v[172:175], v[196:199], v[106:109]
	v_mfma_f32_16x16x32_bf16 v[98:101], v[180:183], v[196:199], v[98:101]
	v_mfma_f32_16x16x32_bf16 v[90:93], v[172:175], v[204:207], v[90:93]
	v_mfma_f32_16x16x32_bf16 v[82:85], v[180:183], v[204:207], v[82:85]
	v_mfma_f32_16x16x32_bf16 v[74:77], v[172:175], v[212:215], v[74:77]
	v_mfma_f32_16x16x32_bf16 v[66:69], v[180:183], v[212:215], v[66:69]
	s_setprio 0
	s_barrier
	s_add_i32 s46, s62, s30
	v_lshl_add_u64 v[218:219], v[218:219], 0, s[8:9]
	s_mov_b32 m0, s46
	s_nop 0
	global_load_lds_dwordx4 v[218:219], off
	s_add_i32 m0, s46, 0x2000
	s_add_u32 s34, s34, 0x80080
	v_lshl_add_u64 v[218:219], v[220:221], 0, s[8:9]
	s_addc_u32 s35, s35, 0
	s_add_i32 s46, s63, s30
	global_load_lds_dwordx4 v[218:219], off
	v_lshl_add_u64 v[218:219], s[34:35], 0, v[134:135]
	s_mov_b32 m0, s46
	s_nop 0
	global_load_lds_dwordx4 v[218:219], off
	v_lshl_add_u64 v[218:219], s[34:35], 0, v[130:131]
	s_add_i32 m0, s46, 0x2000
	s_nop 0
	global_load_lds_dwordx4 v[218:219], off
	v_lshl_add_u64 v[218:219], v[222:223], 0, s[8:9]
	s_mov_b32 m0, s56
	s_nop 0
	global_load_lds_dwordx4 v[218:219], off
	v_lshl_add_u64 v[218:219], v[224:225], 0, s[8:9]
	s_mov_b32 m0, s57
	s_nop 0
	global_load_lds_dwordx4 v[218:219], off
	ds_read_b128 v[184:187], v155 offset:49152
	ds_read_b128 v[188:191], v155 offset:50176
	ds_read_b128 v[192:195], v155 offset:51200
	ds_read_b128 v[196:199], v155 offset:52224
	ds_read_b128 v[200:203], v155 offset:53248
	ds_read_b128 v[204:207], v155 offset:54272
	ds_read_b128 v[208:211], v155 offset:55296
	ds_read_b128 v[212:215], v155 offset:56320
	s_waitcnt vmcnt(8)
	s_waitcnt lgkmcnt(0)
	s_barrier
	s_setprio 1
	s_waitcnt lgkmcnt(0)
	v_mfma_f32_16x16x32_bf16 v[62:65], v[146:149], v[184:187], v[62:65]
	v_mfma_f32_16x16x32_bf16 v[54:57], v[160:163], v[184:187], v[54:57]
	v_mfma_f32_16x16x32_bf16 v[46:49], v[146:149], v[192:195], v[46:49]
	v_mfma_f32_16x16x32_bf16 v[38:41], v[160:163], v[192:195], v[38:41]
	v_mfma_f32_16x16x32_bf16 v[30:33], v[146:149], v[200:203], v[30:33]
	v_mfma_f32_16x16x32_bf16 v[22:25], v[160:163], v[200:203], v[22:25]
	v_mfma_f32_16x16x32_bf16 v[14:17], v[146:149], v[208:211], v[14:17]
	v_mfma_f32_16x16x32_bf16 v[6:9], v[160:163], v[208:211], v[6:9]
	v_mfma_f32_16x16x32_bf16 v[62:65], v[156:159], v[188:191], v[62:65]
	v_mfma_f32_16x16x32_bf16 v[54:57], v[164:167], v[188:191], v[54:57]
	v_mfma_f32_16x16x32_bf16 v[46:49], v[156:159], v[196:199], v[46:49]
	v_mfma_f32_16x16x32_bf16 v[38:41], v[164:167], v[196:199], v[38:41]
	v_mfma_f32_16x16x32_bf16 v[30:33], v[156:159], v[204:207], v[30:33]
	v_mfma_f32_16x16x32_bf16 v[22:25], v[164:167], v[204:207], v[22:25]
	v_mfma_f32_16x16x32_bf16 v[14:17], v[156:159], v[212:215], v[14:17]
	v_mfma_f32_16x16x32_bf16 v[6:9], v[164:167], v[212:215], v[6:9]
	s_setprio 0
	s_setprio 1
	v_mfma_f32_16x16x32_bf16 v[58:61], v[168:171], v[184:187], v[58:61]
	v_mfma_f32_16x16x32_bf16 v[50:53], v[176:179], v[184:187], v[50:53]
	v_mfma_f32_16x16x32_bf16 v[42:45], v[168:171], v[192:195], v[42:45]
	v_mfma_f32_16x16x32_bf16 v[34:37], v[176:179], v[192:195], v[34:37]
	v_mfma_f32_16x16x32_bf16 v[26:29], v[168:171], v[200:203], v[26:29]
	v_mfma_f32_16x16x32_bf16 v[18:21], v[176:179], v[200:203], v[18:21]
	v_mfma_f32_16x16x32_bf16 v[10:13], v[168:171], v[208:211], v[10:13]
	v_mfma_f32_16x16x32_bf16 v[2:5], v[176:179], v[208:211], v[2:5]
	v_mfma_f32_16x16x32_bf16 v[58:61], v[172:175], v[188:191], v[58:61]
	v_mfma_f32_16x16x32_bf16 v[50:53], v[180:183], v[188:191], v[50:53]
	v_mfma_f32_16x16x32_bf16 v[42:45], v[172:175], v[196:199], v[42:45]
	v_mfma_f32_16x16x32_bf16 v[34:37], v[180:183], v[196:199], v[34:37]
	v_mfma_f32_16x16x32_bf16 v[26:29], v[172:175], v[204:207], v[26:29]
	v_mfma_f32_16x16x32_bf16 v[18:21], v[180:183], v[204:207], v[18:21]
	v_mfma_f32_16x16x32_bf16 v[10:13], v[172:175], v[212:215], v[10:13]
	v_mfma_f32_16x16x32_bf16 v[2:5], v[180:183], v[212:215], v[2:5]
	s_setprio 0
	s_barrier
	s_add_i32 s71, s71, 2
	s_add_u32 s44, s44, 0x100
	s_addc_u32 s45, s45, 0
	s_add_u32 s69, s69, 0x100
	s_addc_u32 s70, s70, 0
	s_cmp_gt_u32 s71, 29
	s_cbranch_scc0 .LBB0_3067
	s_and_b64 vcc, exec, s[24:25]
	s_cbranch_vccz .LBB0_3070
	s_barrier

.LBB0_3180:
	s_add_u32 s34, s40, 0xffea0080
	s_addc_u32 s35, s41, -1
	s_cmpk_eq_i32 s60, 0x54
	s_cselect_b32 s43, s5, s35
	s_cselect_b32 s42, s4, s34
	s_cselect_b32 s35, s39, s1
	s_cselect_b32 s34, s38, s0
	v_lshl_add_u64 v[170:171], s[40:41], 0, v[150:151]
	s_add_i32 m0, s33, 0xc000
	s_nop 0
	global_load_lds_dwordx4 v[170:171], off
	v_lshl_add_u64 v[170:171], s[40:41], 0, v[152:153]
	s_add_i32 m0, s33, 0xe000
	s_nop 0
	global_load_lds_dwordx4 v[170:171], off
	ds_read_b128 v[130:133], v174
	ds_read_b128 v[134:137], v174 offset:1024
	ds_read_b128 v[138:141], v174 offset:2048
	ds_read_b128 v[158:161], v174 offset:3072
	ds_read_b128 v[162:165], v175
	ds_read_b128 v[166:169], v175 offset:1024
	ds_read_b128 v[178:181], v175 offset:2048
	ds_read_b128 v[182:185], v175 offset:3072
	ds_read_b128 v[186:189], v176
	ds_read_b128 v[190:193], v176 offset:1024
	ds_read_b128 v[194:197], v176 offset:2048
	ds_read_b128 v[198:201], v176 offset:3072
	ds_read_b128 v[202:205], v176 offset:4096
	ds_read_b128 v[206:209], v176 offset:5120
	ds_read_b128 v[210:213], v176 offset:6144
	ds_read_b128 v[218:221], v176 offset:7168
	s_waitcnt vmcnt(8)
	s_waitcnt lgkmcnt(0)
	s_barrier
	s_setprio 1
	s_waitcnt lgkmcnt(0)
	v_mfma_f32_16x16x32_bf16 v[126:129], v[130:133], v[186:189], v[126:129]
	v_mfma_f32_16x16x32_bf16 v[122:125], v[138:141], v[186:189], v[122:125]
	v_mfma_f32_16x16x32_bf16 v[110:113], v[130:133], v[194:197], v[110:113]
	v_mfma_f32_16x16x32_bf16 v[106:109], v[138:141], v[194:197], v[106:109]
	v_mfma_f32_16x16x32_bf16 v[94:97], v[130:133], v[202:205], v[94:97]
	v_mfma_f32_16x16x32_bf16 v[90:93], v[138:141], v[202:205], v[90:93]
	v_mfma_f32_16x16x32_bf16 v[78:81], v[130:133], v[210:213], v[78:81]
	v_mfma_f32_16x16x32_bf16 v[74:77], v[138:141], v[210:213], v[74:77]
	v_mfma_f32_16x16x32_bf16 v[126:129], v[134:137], v[190:193], v[126:129]
	v_mfma_f32_16x16x32_bf16 v[122:125], v[158:161], v[190:193], v[122:125]
	v_mfma_f32_16x16x32_bf16 v[110:113], v[134:137], v[198:201], v[110:113]
	v_mfma_f32_16x16x32_bf16 v[106:109], v[158:161], v[198:201], v[106:109]
	v_mfma_f32_16x16x32_bf16 v[94:97], v[134:137], v[206:209], v[94:97]
	v_mfma_f32_16x16x32_bf16 v[90:93], v[158:161], v[206:209], v[90:93]
	v_mfma_f32_16x16x32_bf16 v[78:81], v[134:137], v[218:221], v[78:81]
	v_mfma_f32_16x16x32_bf16 v[74:77], v[158:161], v[218:221], v[74:77]
	s_setprio 0
	s_setprio 1
	v_mfma_f32_16x16x32_bf16 v[118:121], v[162:165], v[186:189], v[118:121]
	v_mfma_f32_16x16x32_bf16 v[114:117], v[178:181], v[186:189], v[114:117]
	v_mfma_f32_16x16x32_bf16 v[102:105], v[162:165], v[194:197], v[102:105]
	v_mfma_f32_16x16x32_bf16 v[98:101], v[178:181], v[194:197], v[98:101]
	v_mfma_f32_16x16x32_bf16 v[86:89], v[162:165], v[202:205], v[86:89]
	v_mfma_f32_16x16x32_bf16 v[82:85], v[178:181], v[202:205], v[82:85]
	v_mfma_f32_16x16x32_bf16 v[70:73], v[162:165], v[210:213], v[70:73]
	v_mfma_f32_16x16x32_bf16 v[66:69], v[178:181], v[210:213], v[66:69]
	v_mfma_f32_16x16x32_bf16 v[118:121], v[166:169], v[190:193], v[118:121]
	v_mfma_f32_16x16x32_bf16 v[114:117], v[182:185], v[190:193], v[114:117]
	v_mfma_f32_16x16x32_bf16 v[102:105], v[166:169], v[198:201], v[102:105]
	v_mfma_f32_16x16x32_bf16 v[98:101], v[182:185], v[198:201], v[98:101]
	v_mfma_f32_16x16x32_bf16 v[86:89], v[166:169], v[206:209], v[86:89]
	v_mfma_f32_16x16x32_bf16 v[82:85], v[182:185], v[206:209], v[82:85]
	v_mfma_f32_16x16x32_bf16 v[70:73], v[166:169], v[218:221], v[70:73]
	v_mfma_f32_16x16x32_bf16 v[66:69], v[182:185], v[218:221], v[66:69]
	s_setprio 0
	s_barrier
	s_add_i32 s61, s53, s31
	v_lshl_add_u64 v[170:171], s[34:35], 0, v[144:145]
	s_mov_b32 m0, s61
	s_nop 0
	global_load_lds_dwordx4 v[170:171], off
	s_add_i32 m0, s61, 0x2000
	s_add_u32 s62, s34, 0x160000
	v_lshl_add_u64 v[214:215], s[34:35], 0, v[148:149]
	s_addc_u32 s63, s35, 0
	s_add_i32 s61, s54, s31
	global_load_lds_dwordx4 v[214:215], off
	v_lshl_add_u64 v[222:223], s[62:63], 0, v[144:145]
	s_mov_b32 m0, s61
	v_lshl_add_u64 v[224:225], s[42:43], 0, v[146:147]
	global_load_lds_dwordx4 v[222:223], off
	v_lshl_add_u64 v[222:223], s[62:63], 0, v[148:149]
	s_add_i32 m0, s61, 0x2000
	s_nop 0
	global_load_lds_dwordx4 v[222:223], off
	v_lshl_add_u64 v[222:223], s[42:43], 0, v[142:143]
	s_mov_b32 m0, s33
	s_nop 0
	global_load_lds_dwordx4 v[222:223], off
	s_mov_b32 m0, s44
	s_nop 0
	global_load_lds_dwordx4 v[224:225], off
	ds_read_b128 v[186:189], v176 offset:16384
	ds_read_b128 v[190:193], v176 offset:17408
	ds_read_b128 v[194:197], v176 offset:18432
	ds_read_b128 v[198:201], v176 offset:19456
	ds_read_b128 v[202:205], v176 offset:20480
	ds_read_b128 v[206:209], v176 offset:21504
	ds_read_b128 v[210:213], v176 offset:22528
	ds_read_b128 v[218:221], v176 offset:23552
	s_waitcnt vmcnt(8)
	s_waitcnt lgkmcnt(0)
	s_barrier
	s_setprio 1
	s_waitcnt lgkmcnt(0)
	v_mfma_f32_16x16x32_bf16 v[62:65], v[130:133], v[186:189], v[62:65]
	v_mfma_f32_16x16x32_bf16 v[58:61], v[138:141], v[186:189], v[58:61]
	v_mfma_f32_16x16x32_bf16 v[50:53], v[130:133], v[194:197], v[50:53]
	v_mfma_f32_16x16x32_bf16 v[42:45], v[138:141], v[194:197], v[42:45]
	v_mfma_f32_16x16x32_bf16 v[38:41], v[130:133], v[202:205], v[38:41]
	v_mfma_f32_16x16x32_bf16 v[34:37], v[138:141], v[202:205], v[34:37]
	v_mfma_f32_16x16x32_bf16 v[14:17], v[130:133], v[210:213], v[14:17]
	v_mfma_f32_16x16x32_bf16 v[10:13], v[138:141], v[210:213], v[10:13]
	v_mfma_f32_16x16x32_bf16 v[62:65], v[134:137], v[190:193], v[62:65]
	v_mfma_f32_16x16x32_bf16 v[58:61], v[158:161], v[190:193], v[58:61]
	v_mfma_f32_16x16x32_bf16 v[50:53], v[134:137], v[198:201], v[50:53]
	v_mfma_f32_16x16x32_bf16 v[42:45], v[158:161], v[198:201], v[42:45]
	v_mfma_f32_16x16x32_bf16 v[38:41], v[134:137], v[206:209], v[38:41]
	v_mfma_f32_16x16x32_bf16 v[34:37], v[158:161], v[206:209], v[34:37]
	v_mfma_f32_16x16x32_bf16 v[14:17], v[134:137], v[218:221], v[14:17]
	v_mfma_f32_16x16x32_bf16 v[10:13], v[158:161], v[218:221], v[10:13]
	s_setprio 0
	s_setprio 1
	v_mfma_f32_16x16x32_bf16 v[54:57], v[162:165], v[186:189], v[54:57]
	v_mfma_f32_16x16x32_bf16 v[46:49], v[178:181], v[186:189], v[46:49]
	v_mfma_f32_16x16x32_bf16 v[30:33], v[162:165], v[194:197], v[30:33]
	v_mfma_f32_16x16x32_bf16 v[26:29], v[178:181], v[194:197], v[26:29]
	v_mfma_f32_16x16x32_bf16 v[22:25], v[162:165], v[202:205], v[22:25]
	v_mfma_f32_16x16x32_bf16 v[18:21], v[178:181], v[202:205], v[18:21]
	v_mfma_f32_16x16x32_bf16 v[6:9], v[162:165], v[210:213], v[6:9]
	v_mfma_f32_16x16x32_bf16 v[2:5], v[178:181], v[210:213], v[2:5]
	v_mfma_f32_16x16x32_bf16 v[54:57], v[166:169], v[190:193], v[54:57]
	v_mfma_f32_16x16x32_bf16 v[46:49], v[182:185], v[190:193], v[46:49]
	v_mfma_f32_16x16x32_bf16 v[30:33], v[166:169], v[198:201], v[30:33]
	v_mfma_f32_16x16x32_bf16 v[26:29], v[182:185], v[198:201], v[26:29]
	v_mfma_f32_16x16x32_bf16 v[22:25], v[166:169], v[206:209], v[22:25]
	v_mfma_f32_16x16x32_bf16 v[18:21], v[182:185], v[206:209], v[18:21]
	v_mfma_f32_16x16x32_bf16 v[6:9], v[166:169], v[218:221], v[6:9]
	v_mfma_f32_16x16x32_bf16 v[2:5], v[182:185], v[218:221], v[2:5]
	s_setprio 0
	s_barrier
	s_add_i32 s61, 0, 0x18000
	s_add_i32 s62, 0, 0x1c000
	s_add_u32 s42, s42, 0x160000
	s_addc_u32 s43, s43, 0
	s_mov_b32 m0, s45
	v_lshl_add_u64 v[226:227], s[42:43], 0, v[142:143]
	global_load_lds_dwordx4 v[226:227], off
	v_lshl_add_u64 v[226:227], s[42:43], 0, v[146:147]
	s_mov_b32 m0, s46
	s_nop 0
	global_load_lds_dwordx4 v[226:227], off
	v_add_u32_e32 v158, s61, v172
	v_add_u32_e32 v177, s62, v172
	ds_read_b128 v[130:133], v158
	ds_read_b128 v[134:137], v158 offset:1024
	ds_read_b128 v[138:141], v158 offset:2048
	ds_read_b128 v[158:161], v158 offset:3072
	ds_read_b128 v[162:165], v177
	ds_read_b128 v[166:169], v177 offset:1024
	ds_read_b128 v[178:181], v177 offset:2048
	ds_read_b128 v[182:185], v177 offset:3072
	ds_read_b128 v[186:189], v176 offset:32768
	ds_read_b128 v[190:193], v176 offset:33792
	ds_read_b128 v[194:197], v176 offset:34816
	ds_read_b128 v[198:201], v176 offset:35840
	ds_read_b128 v[202:205], v176 offset:36864
	ds_read_b128 v[206:209], v176 offset:37888
	ds_read_b128 v[210:213], v176 offset:38912
	ds_read_b128 v[218:221], v176 offset:39936
	s_waitcnt vmcnt(8)
	s_waitcnt lgkmcnt(0)
	s_barrier
	s_setprio 1
	s_waitcnt lgkmcnt(0)
	v_mfma_f32_16x16x32_bf16 v[126:129], v[130:133], v[186:189], v[126:129]
	v_mfma_f32_16x16x32_bf16 v[122:125], v[138:141], v[186:189], v[122:125]
	v_mfma_f32_16x16x32_bf16 v[110:113], v[130:133], v[194:197], v[110:113]
	v_mfma_f32_16x16x32_bf16 v[106:109], v[138:141], v[194:197], v[106:109]
	v_mfma_f32_16x16x32_bf16 v[94:97], v[130:133], v[202:205], v[94:97]
	v_mfma_f32_16x16x32_bf16 v[90:93], v[138:141], v[202:205], v[90:93]
	v_mfma_f32_16x16x32_bf16 v[78:81], v[130:133], v[210:213], v[78:81]
	v_mfma_f32_16x16x32_bf16 v[74:77], v[138:141], v[210:213], v[74:77]
	v_mfma_f32_16x16x32_bf16 v[126:129], v[134:137], v[190:193], v[126:129]
	v_mfma_f32_16x16x32_bf16 v[122:125], v[158:161], v[190:193], v[122:125]
	v_mfma_f32_16x16x32_bf16 v[110:113], v[134:137], v[198:201], v[110:113]
	v_mfma_f32_16x16x32_bf16 v[106:109], v[158:161], v[198:201], v[106:109]
	v_mfma_f32_16x16x32_bf16 v[94:97], v[134:137], v[206:209], v[94:97]
	v_mfma_f32_16x16x32_bf16 v[90:93], v[158:161], v[206:209], v[90:93]
	v_mfma_f32_16x16x32_bf16 v[78:81], v[134:137], v[218:221], v[78:81]
	v_mfma_f32_16x16x32_bf16 v[74:77], v[158:161], v[218:221], v[74:77]
	s_setprio 0
	s_setprio 1
	v_mfma_f32_16x16x32_bf16 v[118:121], v[162:165], v[186:189], v[118:121]
	v_mfma_f32_16x16x32_bf16 v[114:117], v[178:181], v[186:189], v[114:117]
	v_mfma_f32_16x16x32_bf16 v[102:105], v[162:165], v[194:197], v[102:105]
	v_mfma_f32_16x16x32_bf16 v[98:101], v[178:181], v[194:197], v[98:101]
	v_mfma_f32_16x16x32_bf16 v[86:89], v[162:165], v[202:205], v[86:89]
	v_mfma_f32_16x16x32_bf16 v[82:85], v[178:181], v[202:205], v[82:85]
	v_mfma_f32_16x16x32_bf16 v[70:73], v[162:165], v[210:213], v[70:73]
	v_mfma_f32_16x16x32_bf16 v[66:69], v[178:181], v[210:213], v[66:69]
	v_mfma_f32_16x16x32_bf16 v[118:121], v[166:169], v[190:193], v[118:121]
	v_mfma_f32_16x16x32_bf16 v[114:117], v[182:185], v[190:193], v[114:117]
	v_mfma_f32_16x16x32_bf16 v[102:105], v[166:169], v[198:201], v[102:105]
	v_mfma_f32_16x16x32_bf16 v[98:101], v[182:185], v[198:201], v[98:101]
	v_mfma_f32_16x16x32_bf16 v[86:89], v[166:169], v[206:209], v[86:89]
	v_mfma_f32_16x16x32_bf16 v[82:85], v[182:185], v[206:209], v[82:85]
	v_mfma_f32_16x16x32_bf16 v[70:73], v[166:169], v[218:221], v[70:73]
	v_mfma_f32_16x16x32_bf16 v[66:69], v[182:185], v[218:221], v[66:69]
	s_setprio 0
	s_barrier
	s_add_i32 s42, s61, s31
	v_lshl_add_u64 v[170:171], v[170:171], 0, s[24:25]
	s_mov_b32 m0, s42
	s_nop 0
	global_load_lds_dwordx4 v[170:171], off
	s_add_i32 m0, s42, 0x2000
	s_add_u32 s34, s34, 0x160080
	v_lshl_add_u64 v[170:171], v[214:215], 0, s[24:25]
	s_addc_u32 s35, s35, 0
	s_add_i32 s42, s62, s31
	global_load_lds_dwordx4 v[170:171], off
	v_lshl_add_u64 v[170:171], s[34:35], 0, v[144:145]
	s_mov_b32 m0, s42
	s_nop 0
	global_load_lds_dwordx4 v[170:171], off
	v_lshl_add_u64 v[170:171], s[34:35], 0, v[148:149]
	s_add_i32 m0, s42, 0x2000
	s_nop 0
	global_load_lds_dwordx4 v[170:171], off
	v_lshl_add_u64 v[170:171], v[222:223], 0, s[24:25]
	s_mov_b32 m0, s48
	s_nop 0
	global_load_lds_dwordx4 v[170:171], off
	v_lshl_add_u64 v[170:171], v[224:225], 0, s[24:25]
	s_mov_b32 m0, s49
	s_nop 0
	global_load_lds_dwordx4 v[170:171], off
	ds_read_b128 v[186:189], v176 offset:49152
	ds_read_b128 v[190:193], v176 offset:50176
	ds_read_b128 v[194:197], v176 offset:51200
	ds_read_b128 v[198:201], v176 offset:52224
	ds_read_b128 v[202:205], v176 offset:53248
	ds_read_b128 v[206:209], v176 offset:54272
	ds_read_b128 v[210:213], v176 offset:55296
	ds_read_b128 v[218:221], v176 offset:56320
	s_waitcnt vmcnt(8)
	s_waitcnt lgkmcnt(0)
	s_barrier
	s_setprio 1
	s_waitcnt lgkmcnt(0)
	v_mfma_f32_16x16x32_bf16 v[62:65], v[130:133], v[186:189], v[62:65]
	v_mfma_f32_16x16x32_bf16 v[58:61], v[138:141], v[186:189], v[58:61]
	v_mfma_f32_16x16x32_bf16 v[50:53], v[130:133], v[194:197], v[50:53]
	v_mfma_f32_16x16x32_bf16 v[42:45], v[138:141], v[194:197], v[42:45]
	v_mfma_f32_16x16x32_bf16 v[38:41], v[130:133], v[202:205], v[38:41]
	v_mfma_f32_16x16x32_bf16 v[34:37], v[138:141], v[202:205], v[34:37]
	v_mfma_f32_16x16x32_bf16 v[14:17], v[130:133], v[210:213], v[14:17]
	v_mfma_f32_16x16x32_bf16 v[10:13], v[138:141], v[210:213], v[10:13]
	v_mfma_f32_16x16x32_bf16 v[62:65], v[134:137], v[190:193], v[62:65]
	v_mfma_f32_16x16x32_bf16 v[58:61], v[158:161], v[190:193], v[58:61]
	v_mfma_f32_16x16x32_bf16 v[50:53], v[134:137], v[198:201], v[50:53]
	v_mfma_f32_16x16x32_bf16 v[42:45], v[158:161], v[198:201], v[42:45]
	v_mfma_f32_16x16x32_bf16 v[38:41], v[134:137], v[206:209], v[38:41]
	v_mfma_f32_16x16x32_bf16 v[34:37], v[158:161], v[206:209], v[34:37]
	v_mfma_f32_16x16x32_bf16 v[14:17], v[134:137], v[218:221], v[14:17]
	v_mfma_f32_16x16x32_bf16 v[10:13], v[158:161], v[218:221], v[10:13]
	s_setprio 0
	s_setprio 1
	v_mfma_f32_16x16x32_bf16 v[54:57], v[162:165], v[186:189], v[54:57]
	v_mfma_f32_16x16x32_bf16 v[46:49], v[178:181], v[186:189], v[46:49]
	v_mfma_f32_16x16x32_bf16 v[30:33], v[162:165], v[194:197], v[30:33]
	v_mfma_f32_16x16x32_bf16 v[26:29], v[178:181], v[194:197], v[26:29]
	v_mfma_f32_16x16x32_bf16 v[22:25], v[162:165], v[202:205], v[22:25]
	v_mfma_f32_16x16x32_bf16 v[18:21], v[178:181], v[202:205], v[18:21]
	v_mfma_f32_16x16x32_bf16 v[6:9], v[162:165], v[210:213], v[6:9]
	v_mfma_f32_16x16x32_bf16 v[2:5], v[178:181], v[210:213], v[2:5]
	v_mfma_f32_16x16x32_bf16 v[54:57], v[166:169], v[190:193], v[54:57]
	v_mfma_f32_16x16x32_bf16 v[46:49], v[182:185], v[190:193], v[46:49]
	v_mfma_f32_16x16x32_bf16 v[30:33], v[166:169], v[198:201], v[30:33]
	v_mfma_f32_16x16x32_bf16 v[26:29], v[182:185], v[198:201], v[26:29]
	v_mfma_f32_16x16x32_bf16 v[22:25], v[166:169], v[206:209], v[22:25]
	v_mfma_f32_16x16x32_bf16 v[18:21], v[182:185], v[206:209], v[18:21]
	v_mfma_f32_16x16x32_bf16 v[6:9], v[166:169], v[218:221], v[6:9]
	v_mfma_f32_16x16x32_bf16 v[2:5], v[182:185], v[218:221], v[2:5]
	s_setprio 0
	s_barrier
	s_add_i32 s60, s60, 2
	s_add_u32 s40, s40, 0x100
	s_addc_u32 s41, s41, 0
	s_add_u32 s0, s0, 0x100
	s_addc_u32 s1, s1, 0
	s_cmpk_gt_u32 s60, 0x55
	s_cbranch_scc0 .LBB0_3180
	s_and_b64 vcc, exec, s[26:27]
	s_cbranch_vccz .LBB0_3183
	s_barrier

.LBB0_3309:
	s_add_u32 s34, s44, 0xfff80080
	s_addc_u32 s35, s45, -1
	s_cmp_eq_u32 s69, 28
	s_cselect_b32 s47, s0, s35
	s_cselect_b32 s46, s1, s34
	s_cselect_b32 s35, s27, s68
	s_cselect_b32 s34, s37, s61
	v_lshl_add_u64 v[218:219], s[44:45], 0, v[138:139]
	s_add_i32 m0, s43, 0xc000
	s_nop 0
	global_load_lds_dwordx4 v[218:219], off
	v_lshl_add_u64 v[218:219], s[44:45], 0, v[140:141]
	s_add_i32 m0, s43, 0xe000
	s_nop 0
	global_load_lds_dwordx4 v[218:219], off
	ds_read_b128 v[146:149], v153
	ds_read_b128 v[156:159], v153 offset:1024
	ds_read_b128 v[160:163], v153 offset:2048
	ds_read_b128 v[164:167], v153 offset:3072
	ds_read_b128 v[168:171], v154
	ds_read_b128 v[172:175], v154 offset:1024
	ds_read_b128 v[176:179], v154 offset:2048
	ds_read_b128 v[180:183], v154 offset:3072
	ds_read_b128 v[184:187], v155
	ds_read_b128 v[188:191], v155 offset:1024
	ds_read_b128 v[192:195], v155 offset:2048
	ds_read_b128 v[196:199], v155 offset:3072
	ds_read_b128 v[200:203], v155 offset:4096
	ds_read_b128 v[204:207], v155 offset:5120
	ds_read_b128 v[208:211], v155 offset:6144
	ds_read_b128 v[212:215], v155 offset:7168
	s_waitcnt vmcnt(8)
	s_waitcnt lgkmcnt(0)
	s_barrier
	s_setprio 1
	s_waitcnt lgkmcnt(0)
	v_mfma_f32_16x16x32_bf16 v[126:129], v[146:149], v[184:187], v[126:129]
	v_mfma_f32_16x16x32_bf16 v[118:121], v[160:163], v[184:187], v[118:121]
	v_mfma_f32_16x16x32_bf16 v[110:113], v[146:149], v[192:195], v[110:113]
	v_mfma_f32_16x16x32_bf16 v[102:105], v[160:163], v[192:195], v[102:105]
	v_mfma_f32_16x16x32_bf16 v[94:97], v[146:149], v[200:203], v[94:97]
	v_mfma_f32_16x16x32_bf16 v[86:89], v[160:163], v[200:203], v[86:89]
	v_mfma_f32_16x16x32_bf16 v[78:81], v[146:149], v[208:211], v[78:81]
	v_mfma_f32_16x16x32_bf16 v[70:73], v[160:163], v[208:211], v[70:73]
	v_mfma_f32_16x16x32_bf16 v[126:129], v[156:159], v[188:191], v[126:129]
	v_mfma_f32_16x16x32_bf16 v[118:121], v[164:167], v[188:191], v[118:121]
	v_mfma_f32_16x16x32_bf16 v[110:113], v[156:159], v[196:199], v[110:113]
	v_mfma_f32_16x16x32_bf16 v[102:105], v[164:167], v[196:199], v[102:105]
	v_mfma_f32_16x16x32_bf16 v[94:97], v[156:159], v[204:207], v[94:97]
	v_mfma_f32_16x16x32_bf16 v[86:89], v[164:167], v[204:207], v[86:89]
	v_mfma_f32_16x16x32_bf16 v[78:81], v[156:159], v[212:215], v[78:81]
	v_mfma_f32_16x16x32_bf16 v[70:73], v[164:167], v[212:215], v[70:73]
	s_setprio 0
	s_setprio 1
	v_mfma_f32_16x16x32_bf16 v[122:125], v[168:171], v[184:187], v[122:125]
	v_mfma_f32_16x16x32_bf16 v[114:117], v[176:179], v[184:187], v[114:117]
	v_mfma_f32_16x16x32_bf16 v[106:109], v[168:171], v[192:195], v[106:109]
	v_mfma_f32_16x16x32_bf16 v[98:101], v[176:179], v[192:195], v[98:101]
	v_mfma_f32_16x16x32_bf16 v[90:93], v[168:171], v[200:203], v[90:93]
	v_mfma_f32_16x16x32_bf16 v[82:85], v[176:179], v[200:203], v[82:85]
	v_mfma_f32_16x16x32_bf16 v[74:77], v[168:171], v[208:211], v[74:77]
	v_mfma_f32_16x16x32_bf16 v[66:69], v[176:179], v[208:211], v[66:69]
	v_mfma_f32_16x16x32_bf16 v[122:125], v[172:175], v[188:191], v[122:125]
	v_mfma_f32_16x16x32_bf16 v[114:117], v[180:183], v[188:191], v[114:117]
	v_mfma_f32_16x16x32_bf16 v[106:109], v[172:175], v[196:199], v[106:109]
	v_mfma_f32_16x16x32_bf16 v[98:101], v[180:183], v[196:199], v[98:101]
	v_mfma_f32_16x16x32_bf16 v[90:93], v[172:175], v[204:207], v[90:93]
	v_mfma_f32_16x16x32_bf16 v[82:85], v[180:183], v[204:207], v[82:85]
	v_mfma_f32_16x16x32_bf16 v[74:77], v[172:175], v[212:215], v[74:77]
	v_mfma_f32_16x16x32_bf16 v[66:69], v[180:183], v[212:215], v[66:69]
	s_setprio 0
	s_barrier
	s_add_i32 s62, s57, s30
	v_lshl_add_u64 v[218:219], s[34:35], 0, v[134:135]
	s_mov_b32 m0, s62
	s_nop 0
	global_load_lds_dwordx4 v[218:219], off
	s_add_i32 m0, s62, 0x2000
	s_add_u32 s62, s34, 0x80000
	v_lshl_add_u64 v[220:221], s[34:35], 0, v[130:131]
	s_addc_u32 s63, s35, 0
	s_add_i32 s66, s58, s30
	global_load_lds_dwordx4 v[220:221], off
	v_lshl_add_u64 v[222:223], s[62:63], 0, v[134:135]
	s_mov_b32 m0, s66
	v_lshl_add_u64 v[224:225], s[46:47], 0, v[132:133]
	global_load_lds_dwordx4 v[222:223], off
	v_lshl_add_u64 v[222:223], s[62:63], 0, v[130:131]
	s_add_i32 m0, s66, 0x2000
	s_nop 0
	global_load_lds_dwordx4 v[222:223], off
	v_lshl_add_u64 v[222:223], s[46:47], 0, v[136:137]
	s_mov_b32 m0, s43
	s_nop 0
	global_load_lds_dwordx4 v[222:223], off
	s_mov_b32 m0, s48
	s_nop 0
	global_load_lds_dwordx4 v[224:225], off
	ds_read_b128 v[184:187], v155 offset:16384
	ds_read_b128 v[188:191], v155 offset:17408
	ds_read_b128 v[192:195], v155 offset:18432
	ds_read_b128 v[196:199], v155 offset:19456
	ds_read_b128 v[200:203], v155 offset:20480
	ds_read_b128 v[204:207], v155 offset:21504
	ds_read_b128 v[208:211], v155 offset:22528
	ds_read_b128 v[212:215], v155 offset:23552
	s_waitcnt vmcnt(8)
	s_waitcnt lgkmcnt(0)
	s_barrier
	s_setprio 1
	s_waitcnt lgkmcnt(0)
	v_mfma_f32_16x16x32_bf16 v[62:65], v[146:149], v[184:187], v[62:65]
	v_mfma_f32_16x16x32_bf16 v[54:57], v[160:163], v[184:187], v[54:57]
	v_mfma_f32_16x16x32_bf16 v[46:49], v[146:149], v[192:195], v[46:49]
	v_mfma_f32_16x16x32_bf16 v[38:41], v[160:163], v[192:195], v[38:41]
	v_mfma_f32_16x16x32_bf16 v[30:33], v[146:149], v[200:203], v[30:33]
	v_mfma_f32_16x16x32_bf16 v[22:25], v[160:163], v[200:203], v[22:25]
	v_mfma_f32_16x16x32_bf16 v[14:17], v[146:149], v[208:211], v[14:17]
	v_mfma_f32_16x16x32_bf16 v[6:9], v[160:163], v[208:211], v[6:9]
	v_mfma_f32_16x16x32_bf16 v[62:65], v[156:159], v[188:191], v[62:65]
	v_mfma_f32_16x16x32_bf16 v[54:57], v[164:167], v[188:191], v[54:57]
	v_mfma_f32_16x16x32_bf16 v[46:49], v[156:159], v[196:199], v[46:49]
	v_mfma_f32_16x16x32_bf16 v[38:41], v[164:167], v[196:199], v[38:41]
	v_mfma_f32_16x16x32_bf16 v[30:33], v[156:159], v[204:207], v[30:33]
	v_mfma_f32_16x16x32_bf16 v[22:25], v[164:167], v[204:207], v[22:25]
	v_mfma_f32_16x16x32_bf16 v[14:17], v[156:159], v[212:215], v[14:17]
	v_mfma_f32_16x16x32_bf16 v[6:9], v[164:167], v[212:215], v[6:9]
	s_setprio 0
	s_setprio 1
	v_mfma_f32_16x16x32_bf16 v[58:61], v[168:171], v[184:187], v[58:61]
	v_mfma_f32_16x16x32_bf16 v[50:53], v[176:179], v[184:187], v[50:53]
	v_mfma_f32_16x16x32_bf16 v[42:45], v[168:171], v[192:195], v[42:45]
	v_mfma_f32_16x16x32_bf16 v[34:37], v[176:179], v[192:195], v[34:37]
	v_mfma_f32_16x16x32_bf16 v[26:29], v[168:171], v[200:203], v[26:29]
	v_mfma_f32_16x16x32_bf16 v[18:21], v[176:179], v[200:203], v[18:21]
	v_mfma_f32_16x16x32_bf16 v[10:13], v[168:171], v[208:211], v[10:13]
	v_mfma_f32_16x16x32_bf16 v[2:5], v[176:179], v[208:211], v[2:5]
	v_mfma_f32_16x16x32_bf16 v[58:61], v[172:175], v[188:191], v[58:61]
	v_mfma_f32_16x16x32_bf16 v[50:53], v[180:183], v[188:191], v[50:53]
	v_mfma_f32_16x16x32_bf16 v[42:45], v[172:175], v[196:199], v[42:45]
	v_mfma_f32_16x16x32_bf16 v[34:37], v[180:183], v[196:199], v[34:37]
	v_mfma_f32_16x16x32_bf16 v[26:29], v[172:175], v[204:207], v[26:29]
	v_mfma_f32_16x16x32_bf16 v[18:21], v[180:183], v[204:207], v[18:21]
	v_mfma_f32_16x16x32_bf16 v[10:13], v[172:175], v[212:215], v[10:13]
	v_mfma_f32_16x16x32_bf16 v[2:5], v[180:183], v[212:215], v[2:5]
	s_setprio 0
	s_barrier
	s_add_i32 s62, 0, 0x18000
	s_add_i32 s63, 0, 0x1c000
	s_add_u32 s46, s46, 0x80000
	s_addc_u32 s47, s47, 0
	s_mov_b32 m0, s49
	v_lshl_add_u64 v[226:227], s[46:47], 0, v[136:137]
	global_load_lds_dwordx4 v[226:227], off
	v_lshl_add_u64 v[226:227], s[46:47], 0, v[132:133]
	s_mov_b32 m0, s52
	s_nop 0
	global_load_lds_dwordx4 v[226:227], off
	v_add_u32_e32 v164, s62, v151
	v_add_u32_e32 v180, s63, v151
	ds_read_b128 v[146:149], v164
	ds_read_b128 v[156:159], v164 offset:1024
	ds_read_b128 v[160:163], v164 offset:2048
	ds_read_b128 v[164:167], v164 offset:3072
	ds_read_b128 v[168:171], v180
	ds_read_b128 v[172:175], v180 offset:1024
	ds_read_b128 v[176:179], v180 offset:2048
	ds_read_b128 v[180:183], v180 offset:3072
	ds_read_b128 v[184:187], v155 offset:32768
	ds_read_b128 v[188:191], v155 offset:33792
	ds_read_b128 v[192:195], v155 offset:34816
	ds_read_b128 v[196:199], v155 offset:35840
	ds_read_b128 v[200:203], v155 offset:36864
	ds_read_b128 v[204:207], v155 offset:37888
	ds_read_b128 v[208:211], v155 offset:38912
	ds_read_b128 v[212:215], v155 offset:39936
	s_waitcnt vmcnt(8)
	s_waitcnt lgkmcnt(0)
	s_barrier
	s_setprio 1
	s_waitcnt lgkmcnt(0)
	v_mfma_f32_16x16x32_bf16 v[126:129], v[146:149], v[184:187], v[126:129]
	v_mfma_f32_16x16x32_bf16 v[118:121], v[160:163], v[184:187], v[118:121]
	v_mfma_f32_16x16x32_bf16 v[110:113], v[146:149], v[192:195], v[110:113]
	v_mfma_f32_16x16x32_bf16 v[102:105], v[160:163], v[192:195], v[102:105]
	v_mfma_f32_16x16x32_bf16 v[94:97], v[146:149], v[200:203], v[94:97]
	v_mfma_f32_16x16x32_bf16 v[86:89], v[160:163], v[200:203], v[86:89]
	v_mfma_f32_16x16x32_bf16 v[78:81], v[146:149], v[208:211], v[78:81]
	v_mfma_f32_16x16x32_bf16 v[70:73], v[160:163], v[208:211], v[70:73]
	v_mfma_f32_16x16x32_bf16 v[126:129], v[156:159], v[188:191], v[126:129]
	v_mfma_f32_16x16x32_bf16 v[118:121], v[164:167], v[188:191], v[118:121]
	v_mfma_f32_16x16x32_bf16 v[110:113], v[156:159], v[196:199], v[110:113]
	v_mfma_f32_16x16x32_bf16 v[102:105], v[164:167], v[196:199], v[102:105]
	v_mfma_f32_16x16x32_bf16 v[94:97], v[156:159], v[204:207], v[94:97]
	v_mfma_f32_16x16x32_bf16 v[86:89], v[164:167], v[204:207], v[86:89]
	v_mfma_f32_16x16x32_bf16 v[78:81], v[156:159], v[212:215], v[78:81]
	v_mfma_f32_16x16x32_bf16 v[70:73], v[164:167], v[212:215], v[70:73]
	s_setprio 0
	s_setprio 1
	v_mfma_f32_16x16x32_bf16 v[122:125], v[168:171], v[184:187], v[122:125]
	v_mfma_f32_16x16x32_bf16 v[114:117], v[176:179], v[184:187], v[114:117]
	v_mfma_f32_16x16x32_bf16 v[106:109], v[168:171], v[192:195], v[106:109]
	v_mfma_f32_16x16x32_bf16 v[98:101], v[176:179], v[192:195], v[98:101]
	v_mfma_f32_16x16x32_bf16 v[90:93], v[168:171], v[200:203], v[90:93]
	v_mfma_f32_16x16x32_bf16 v[82:85], v[176:179], v[200:203], v[82:85]
	v_mfma_f32_16x16x32_bf16 v[74:77], v[168:171], v[208:211], v[74:77]
	v_mfma_f32_16x16x32_bf16 v[66:69], v[176:179], v[208:211], v[66:69]
	v_mfma_f32_16x16x32_bf16 v[122:125], v[172:175], v[188:191], v[122:125]
	v_mfma_f32_16x16x32_bf16 v[114:117], v[180:183], v[188:191], v[114:117]
	v_mfma_f32_16x16x32_bf16 v[106:109], v[172:175], v[196:199], v[106:109]
	v_mfma_f32_16x16x32_bf16 v[98:101], v[180:183], v[196:199], v[98:101]
	v_mfma_f32_16x16x32_bf16 v[90:93], v[172:175], v[204:207], v[90:93]
	v_mfma_f32_16x16x32_bf16 v[82:85], v[180:183], v[204:207], v[82:85]
	v_mfma_f32_16x16x32_bf16 v[74:77], v[172:175], v[212:215], v[74:77]
	v_mfma_f32_16x16x32_bf16 v[66:69], v[180:183], v[212:215], v[66:69]
	s_setprio 0
	s_barrier
	s_add_i32 s46, s62, s30
	v_lshl_add_u64 v[218:219], v[218:219], 0, s[8:9]
	s_mov_b32 m0, s46
	s_nop 0
	global_load_lds_dwordx4 v[218:219], off
	s_add_i32 m0, s46, 0x2000
	s_add_u32 s34, s34, 0x80080
	v_lshl_add_u64 v[218:219], v[220:221], 0, s[8:9]
	s_addc_u32 s35, s35, 0
	s_add_i32 s46, s63, s30
	global_load_lds_dwordx4 v[218:219], off
	v_lshl_add_u64 v[218:219], s[34:35], 0, v[134:135]
	s_mov_b32 m0, s46
	s_nop 0
	global_load_lds_dwordx4 v[218:219], off
	v_lshl_add_u64 v[218:219], s[34:35], 0, v[130:131]
	s_add_i32 m0, s46, 0x2000
	s_nop 0
	global_load_lds_dwordx4 v[218:219], off
	v_lshl_add_u64 v[218:219], v[222:223], 0, s[8:9]
	s_mov_b32 m0, s54
	s_nop 0
	global_load_lds_dwordx4 v[218:219], off
	v_lshl_add_u64 v[218:219], v[224:225], 0, s[8:9]
	s_mov_b32 m0, s55
	s_nop 0
	global_load_lds_dwordx4 v[218:219], off
	ds_read_b128 v[184:187], v155 offset:49152
	ds_read_b128 v[188:191], v155 offset:50176
	ds_read_b128 v[192:195], v155 offset:51200
	ds_read_b128 v[196:199], v155 offset:52224
	ds_read_b128 v[200:203], v155 offset:53248
	ds_read_b128 v[204:207], v155 offset:54272
	ds_read_b128 v[208:211], v155 offset:55296
	ds_read_b128 v[212:215], v155 offset:56320
	s_waitcnt vmcnt(8)
	s_waitcnt lgkmcnt(0)
	s_barrier
	s_setprio 1
	s_waitcnt lgkmcnt(0)
	v_mfma_f32_16x16x32_bf16 v[62:65], v[146:149], v[184:187], v[62:65]
	v_mfma_f32_16x16x32_bf16 v[54:57], v[160:163], v[184:187], v[54:57]
	v_mfma_f32_16x16x32_bf16 v[46:49], v[146:149], v[192:195], v[46:49]
	v_mfma_f32_16x16x32_bf16 v[38:41], v[160:163], v[192:195], v[38:41]
	v_mfma_f32_16x16x32_bf16 v[30:33], v[146:149], v[200:203], v[30:33]
	v_mfma_f32_16x16x32_bf16 v[22:25], v[160:163], v[200:203], v[22:25]
	v_mfma_f32_16x16x32_bf16 v[14:17], v[146:149], v[208:211], v[14:17]
	v_mfma_f32_16x16x32_bf16 v[6:9], v[160:163], v[208:211], v[6:9]
	v_mfma_f32_16x16x32_bf16 v[62:65], v[156:159], v[188:191], v[62:65]
	v_mfma_f32_16x16x32_bf16 v[54:57], v[164:167], v[188:191], v[54:57]
	v_mfma_f32_16x16x32_bf16 v[46:49], v[156:159], v[196:199], v[46:49]
	v_mfma_f32_16x16x32_bf16 v[38:41], v[164:167], v[196:199], v[38:41]
	v_mfma_f32_16x16x32_bf16 v[30:33], v[156:159], v[204:207], v[30:33]
	v_mfma_f32_16x16x32_bf16 v[22:25], v[164:167], v[204:207], v[22:25]
	v_mfma_f32_16x16x32_bf16 v[14:17], v[156:159], v[212:215], v[14:17]
	v_mfma_f32_16x16x32_bf16 v[6:9], v[164:167], v[212:215], v[6:9]
	s_setprio 0
	s_setprio 1
	v_mfma_f32_16x16x32_bf16 v[58:61], v[168:171], v[184:187], v[58:61]
	v_mfma_f32_16x16x32_bf16 v[50:53], v[176:179], v[184:187], v[50:53]
	v_mfma_f32_16x16x32_bf16 v[42:45], v[168:171], v[192:195], v[42:45]
	v_mfma_f32_16x16x32_bf16 v[34:37], v[176:179], v[192:195], v[34:37]
	v_mfma_f32_16x16x32_bf16 v[26:29], v[168:171], v[200:203], v[26:29]
	v_mfma_f32_16x16x32_bf16 v[18:21], v[176:179], v[200:203], v[18:21]
	v_mfma_f32_16x16x32_bf16 v[10:13], v[168:171], v[208:211], v[10:13]
	v_mfma_f32_16x16x32_bf16 v[2:5], v[176:179], v[208:211], v[2:5]
	v_mfma_f32_16x16x32_bf16 v[58:61], v[172:175], v[188:191], v[58:61]
	v_mfma_f32_16x16x32_bf16 v[50:53], v[180:183], v[188:191], v[50:53]
	v_mfma_f32_16x16x32_bf16 v[42:45], v[172:175], v[196:199], v[42:45]
	v_mfma_f32_16x16x32_bf16 v[34:37], v[180:183], v[196:199], v[34:37]
	v_mfma_f32_16x16x32_bf16 v[26:29], v[172:175], v[204:207], v[26:29]
	v_mfma_f32_16x16x32_bf16 v[18:21], v[180:183], v[204:207], v[18:21]
	v_mfma_f32_16x16x32_bf16 v[10:13], v[172:175], v[212:215], v[10:13]
	v_mfma_f32_16x16x32_bf16 v[2:5], v[180:183], v[212:215], v[2:5]
	s_setprio 0
	s_barrier
	s_add_i32 s69, s69, 2
	s_add_u32 s44, s44, 0x100
	s_addc_u32 s45, s45, 0
	s_add_u32 s61, s61, 0x100
	s_addc_u32 s68, s68, 0
	s_cmp_gt_u32 s69, 29
	s_cbranch_scc0 .LBB0_3309
	s_and_b64 vcc, exec, s[24:25]
	s_cbranch_vccz .LBB0_3312
	s_barrier

.LBB0_3533:
	s_add_u32 s34, s44, 0xfff80080
	s_addc_u32 s35, s45, -1
	s_cmp_eq_u32 s68, 28
	s_cselect_b32 s47, s0, s35
	s_cselect_b32 s46, s1, s34
	s_cselect_b32 s35, s27, s61
	s_cselect_b32 s34, s37, s60
	v_lshl_add_u64 v[146:147], s[44:45], 0, v[138:139]
	s_add_i32 m0, s33, 0xc000
	s_nop 0
	global_load_lds_dwordx4 v[146:147], off
	v_lshl_add_u64 v[146:147], s[44:45], 0, v[140:141]
	s_add_i32 m0, s33, 0xe000
	s_nop 0
	global_load_lds_dwordx4 v[146:147], off
	ds_read_b128 v[154:157], v151
	ds_read_b128 v[158:161], v151 offset:1024
	ds_read_b128 v[162:165], v151 offset:2048
	ds_read_b128 v[166:169], v151 offset:3072
	ds_read_b128 v[170:173], v152
	ds_read_b128 v[174:177], v152 offset:1024
	ds_read_b128 v[178:181], v152 offset:2048
	ds_read_b128 v[182:185], v152 offset:3072
	ds_read_b128 v[186:189], v153
	ds_read_b128 v[190:193], v153 offset:1024
	ds_read_b128 v[194:197], v153 offset:2048
	ds_read_b128 v[198:201], v153 offset:3072
	ds_read_b128 v[202:205], v153 offset:4096
	ds_read_b128 v[206:209], v153 offset:5120
	ds_read_b128 v[210:213], v153 offset:6144
	ds_read_b128 v[218:221], v153 offset:7168
	s_waitcnt vmcnt(8)
	s_waitcnt lgkmcnt(0)
	s_barrier
	s_setprio 1
	s_waitcnt lgkmcnt(0)
	v_mfma_f32_16x16x32_bf16 v[126:129], v[154:157], v[186:189], v[126:129]
	v_mfma_f32_16x16x32_bf16 v[122:125], v[162:165], v[186:189], v[122:125]
	v_mfma_f32_16x16x32_bf16 v[114:117], v[154:157], v[194:197], v[114:117]
	v_mfma_f32_16x16x32_bf16 v[106:109], v[162:165], v[194:197], v[106:109]
	v_mfma_f32_16x16x32_bf16 v[98:101], v[154:157], v[202:205], v[98:101]
	v_mfma_f32_16x16x32_bf16 v[90:93], v[162:165], v[202:205], v[90:93]
	v_mfma_f32_16x16x32_bf16 v[82:85], v[154:157], v[210:213], v[82:85]
	v_mfma_f32_16x16x32_bf16 v[74:77], v[162:165], v[210:213], v[74:77]
	v_mfma_f32_16x16x32_bf16 v[126:129], v[158:161], v[190:193], v[126:129]
	v_mfma_f32_16x16x32_bf16 v[122:125], v[166:169], v[190:193], v[122:125]
	v_mfma_f32_16x16x32_bf16 v[114:117], v[158:161], v[198:201], v[114:117]
	v_mfma_f32_16x16x32_bf16 v[106:109], v[166:169], v[198:201], v[106:109]
	v_mfma_f32_16x16x32_bf16 v[98:101], v[158:161], v[206:209], v[98:101]
	v_mfma_f32_16x16x32_bf16 v[90:93], v[166:169], v[206:209], v[90:93]
	v_mfma_f32_16x16x32_bf16 v[82:85], v[158:161], v[218:221], v[82:85]
	v_mfma_f32_16x16x32_bf16 v[74:77], v[166:169], v[218:221], v[74:77]
	s_setprio 0
	s_setprio 1
	v_mfma_f32_16x16x32_bf16 v[118:121], v[170:173], v[186:189], v[118:121]
	v_mfma_f32_16x16x32_bf16 v[110:113], v[178:181], v[186:189], v[110:113]
	v_mfma_f32_16x16x32_bf16 v[102:105], v[170:173], v[194:197], v[102:105]
	v_mfma_f32_16x16x32_bf16 v[94:97], v[178:181], v[194:197], v[94:97]
	v_mfma_f32_16x16x32_bf16 v[86:89], v[170:173], v[202:205], v[86:89]
	v_mfma_f32_16x16x32_bf16 v[78:81], v[178:181], v[202:205], v[78:81]
	v_mfma_f32_16x16x32_bf16 v[70:73], v[170:173], v[210:213], v[70:73]
	v_mfma_f32_16x16x32_bf16 v[66:69], v[178:181], v[210:213], v[66:69]
	v_mfma_f32_16x16x32_bf16 v[118:121], v[174:177], v[190:193], v[118:121]
	v_mfma_f32_16x16x32_bf16 v[110:113], v[182:185], v[190:193], v[110:113]
	v_mfma_f32_16x16x32_bf16 v[102:105], v[174:177], v[198:201], v[102:105]
	v_mfma_f32_16x16x32_bf16 v[94:97], v[182:185], v[198:201], v[94:97]
	v_mfma_f32_16x16x32_bf16 v[86:89], v[174:177], v[206:209], v[86:89]
	v_mfma_f32_16x16x32_bf16 v[78:81], v[182:185], v[206:209], v[78:81]
	v_mfma_f32_16x16x32_bf16 v[70:73], v[174:177], v[218:221], v[70:73]
	v_mfma_f32_16x16x32_bf16 v[66:69], v[182:185], v[218:221], v[66:69]
	s_setprio 0
	s_barrier
	s_add_i32 s62, s56, s12
	v_lshl_add_u64 v[146:147], s[34:35], 0, v[134:135]
	s_mov_b32 m0, s62
	s_nop 0
	global_load_lds_dwordx4 v[146:147], off
	s_add_i32 m0, s62, 0x2000
	s_add_u32 s62, s34, 0x80000
	v_lshl_add_u64 v[214:215], s[34:35], 0, v[130:131]
	s_addc_u32 s63, s35, 0
	s_add_i32 s66, s57, s12
	global_load_lds_dwordx4 v[214:215], off
	v_lshl_add_u64 v[222:223], s[62:63], 0, v[134:135]
	s_mov_b32 m0, s66
	v_lshl_add_u64 v[224:225], s[46:47], 0, v[132:133]
	global_load_lds_dwordx4 v[222:223], off
	v_lshl_add_u64 v[222:223], s[62:63], 0, v[130:131]
	s_add_i32 m0, s66, 0x2000
	s_nop 0
	global_load_lds_dwordx4 v[222:223], off
	v_lshl_add_u64 v[222:223], s[46:47], 0, v[136:137]
	s_mov_b32 m0, s33
	s_nop 0
	global_load_lds_dwordx4 v[222:223], off
	s_mov_b32 m0, s43
	s_nop 0
	global_load_lds_dwordx4 v[224:225], off
	ds_read_b128 v[186:189], v153 offset:16384
	ds_read_b128 v[190:193], v153 offset:17408
	ds_read_b128 v[194:197], v153 offset:18432
	ds_read_b128 v[198:201], v153 offset:19456
	ds_read_b128 v[202:205], v153 offset:20480
	ds_read_b128 v[206:209], v153 offset:21504
	ds_read_b128 v[210:213], v153 offset:22528
	ds_read_b128 v[218:221], v153 offset:23552
	s_waitcnt vmcnt(8)
	s_waitcnt lgkmcnt(0)
	s_barrier
	s_setprio 1
	s_waitcnt lgkmcnt(0)
	v_mfma_f32_16x16x32_bf16 v[62:65], v[154:157], v[186:189], v[62:65]
	v_mfma_f32_16x16x32_bf16 v[58:61], v[162:165], v[186:189], v[58:61]
	v_mfma_f32_16x16x32_bf16 v[50:53], v[154:157], v[194:197], v[50:53]
	v_mfma_f32_16x16x32_bf16 v[42:45], v[162:165], v[194:197], v[42:45]
	v_mfma_f32_16x16x32_bf16 v[34:37], v[154:157], v[202:205], v[34:37]
	v_mfma_f32_16x16x32_bf16 v[26:29], v[162:165], v[202:205], v[26:29]
	v_mfma_f32_16x16x32_bf16 v[18:21], v[154:157], v[210:213], v[18:21]
	v_mfma_f32_16x16x32_bf16 v[10:13], v[162:165], v[210:213], v[10:13]
	v_mfma_f32_16x16x32_bf16 v[62:65], v[158:161], v[190:193], v[62:65]
	v_mfma_f32_16x16x32_bf16 v[58:61], v[166:169], v[190:193], v[58:61]
	v_mfma_f32_16x16x32_bf16 v[50:53], v[158:161], v[198:201], v[50:53]
	v_mfma_f32_16x16x32_bf16 v[42:45], v[166:169], v[198:201], v[42:45]
	v_mfma_f32_16x16x32_bf16 v[34:37], v[158:161], v[206:209], v[34:37]
	v_mfma_f32_16x16x32_bf16 v[26:29], v[166:169], v[206:209], v[26:29]
	v_mfma_f32_16x16x32_bf16 v[18:21], v[158:161], v[218:221], v[18:21]
	v_mfma_f32_16x16x32_bf16 v[10:13], v[166:169], v[218:221], v[10:13]
	s_setprio 0
	s_setprio 1
	v_mfma_f32_16x16x32_bf16 v[54:57], v[170:173], v[186:189], v[54:57]
	v_mfma_f32_16x16x32_bf16 v[46:49], v[178:181], v[186:189], v[46:49]
	v_mfma_f32_16x16x32_bf16 v[38:41], v[170:173], v[194:197], v[38:41]
	v_mfma_f32_16x16x32_bf16 v[30:33], v[178:181], v[194:197], v[30:33]
	v_mfma_f32_16x16x32_bf16 v[22:25], v[170:173], v[202:205], v[22:25]
	v_mfma_f32_16x16x32_bf16 v[14:17], v[178:181], v[202:205], v[14:17]
	v_mfma_f32_16x16x32_bf16 v[6:9], v[170:173], v[210:213], v[6:9]
	v_mfma_f32_16x16x32_bf16 v[2:5], v[178:181], v[210:213], v[2:5]
	v_mfma_f32_16x16x32_bf16 v[54:57], v[174:177], v[190:193], v[54:57]
	v_mfma_f32_16x16x32_bf16 v[46:49], v[182:185], v[190:193], v[46:49]
	v_mfma_f32_16x16x32_bf16 v[38:41], v[174:177], v[198:201], v[38:41]
	v_mfma_f32_16x16x32_bf16 v[30:33], v[182:185], v[198:201], v[30:33]
	v_mfma_f32_16x16x32_bf16 v[22:25], v[174:177], v[206:209], v[22:25]
	v_mfma_f32_16x16x32_bf16 v[14:17], v[182:185], v[206:209], v[14:17]
	v_mfma_f32_16x16x32_bf16 v[6:9], v[174:177], v[218:221], v[6:9]
	v_mfma_f32_16x16x32_bf16 v[2:5], v[182:185], v[218:221], v[2:5]
	s_setprio 0
	s_barrier
	s_add_i32 s62, 0, 0x18000
	s_add_i32 s63, 0, 0x1c000
	s_add_u32 s46, s46, 0x80000
	s_addc_u32 s47, s47, 0
	s_mov_b32 m0, s48
	v_lshl_add_u64 v[226:227], s[46:47], 0, v[136:137]
	global_load_lds_dwordx4 v[226:227], off
	v_lshl_add_u64 v[226:227], s[46:47], 0, v[132:133]
	s_mov_b32 m0, s49
	s_nop 0
	global_load_lds_dwordx4 v[226:227], off
	v_add_u32_e32 v166, s62, v149
	v_add_u32_e32 v182, s63, v149
	ds_read_b128 v[154:157], v166
	ds_read_b128 v[158:161], v166 offset:1024
	ds_read_b128 v[162:165], v166 offset:2048
	ds_read_b128 v[166:169], v166 offset:3072
	ds_read_b128 v[170:173], v182
	ds_read_b128 v[174:177], v182 offset:1024
	ds_read_b128 v[178:181], v182 offset:2048
	ds_read_b128 v[182:185], v182 offset:3072
	ds_read_b128 v[186:189], v153 offset:32768
	ds_read_b128 v[190:193], v153 offset:33792
	ds_read_b128 v[194:197], v153 offset:34816
	ds_read_b128 v[198:201], v153 offset:35840
	ds_read_b128 v[202:205], v153 offset:36864
	ds_read_b128 v[206:209], v153 offset:37888
	ds_read_b128 v[210:213], v153 offset:38912
	ds_read_b128 v[218:221], v153 offset:39936
	s_waitcnt vmcnt(8)
	s_waitcnt lgkmcnt(0)
	s_barrier
	s_setprio 1
	s_waitcnt lgkmcnt(0)
	v_mfma_f32_16x16x32_bf16 v[126:129], v[154:157], v[186:189], v[126:129]
	v_mfma_f32_16x16x32_bf16 v[122:125], v[162:165], v[186:189], v[122:125]
	v_mfma_f32_16x16x32_bf16 v[114:117], v[154:157], v[194:197], v[114:117]
	v_mfma_f32_16x16x32_bf16 v[106:109], v[162:165], v[194:197], v[106:109]
	v_mfma_f32_16x16x32_bf16 v[98:101], v[154:157], v[202:205], v[98:101]
	v_mfma_f32_16x16x32_bf16 v[90:93], v[162:165], v[202:205], v[90:93]
	v_mfma_f32_16x16x32_bf16 v[82:85], v[154:157], v[210:213], v[82:85]
	v_mfma_f32_16x16x32_bf16 v[74:77], v[162:165], v[210:213], v[74:77]
	v_mfma_f32_16x16x32_bf16 v[126:129], v[158:161], v[190:193], v[126:129]
	v_mfma_f32_16x16x32_bf16 v[122:125], v[166:169], v[190:193], v[122:125]
	v_mfma_f32_16x16x32_bf16 v[114:117], v[158:161], v[198:201], v[114:117]
	v_mfma_f32_16x16x32_bf16 v[106:109], v[166:169], v[198:201], v[106:109]
	v_mfma_f32_16x16x32_bf16 v[98:101], v[158:161], v[206:209], v[98:101]
	v_mfma_f32_16x16x32_bf16 v[90:93], v[166:169], v[206:209], v[90:93]
	v_mfma_f32_16x16x32_bf16 v[82:85], v[158:161], v[218:221], v[82:85]
	v_mfma_f32_16x16x32_bf16 v[74:77], v[166:169], v[218:221], v[74:77]
	s_setprio 0
	s_setprio 1
	v_mfma_f32_16x16x32_bf16 v[118:121], v[170:173], v[186:189], v[118:121]
	v_mfma_f32_16x16x32_bf16 v[110:113], v[178:181], v[186:189], v[110:113]
	v_mfma_f32_16x16x32_bf16 v[102:105], v[170:173], v[194:197], v[102:105]
	v_mfma_f32_16x16x32_bf16 v[94:97], v[178:181], v[194:197], v[94:97]
	v_mfma_f32_16x16x32_bf16 v[86:89], v[170:173], v[202:205], v[86:89]
	v_mfma_f32_16x16x32_bf16 v[78:81], v[178:181], v[202:205], v[78:81]
	v_mfma_f32_16x16x32_bf16 v[70:73], v[170:173], v[210:213], v[70:73]
	v_mfma_f32_16x16x32_bf16 v[66:69], v[178:181], v[210:213], v[66:69]
	v_mfma_f32_16x16x32_bf16 v[118:121], v[174:177], v[190:193], v[118:121]
	v_mfma_f32_16x16x32_bf16 v[110:113], v[182:185], v[190:193], v[110:113]
	v_mfma_f32_16x16x32_bf16 v[102:105], v[174:177], v[198:201], v[102:105]
	v_mfma_f32_16x16x32_bf16 v[94:97], v[182:185], v[198:201], v[94:97]
	v_mfma_f32_16x16x32_bf16 v[86:89], v[174:177], v[206:209], v[86:89]
	v_mfma_f32_16x16x32_bf16 v[78:81], v[182:185], v[206:209], v[78:81]
	v_mfma_f32_16x16x32_bf16 v[70:73], v[174:177], v[218:221], v[70:73]
	v_mfma_f32_16x16x32_bf16 v[66:69], v[182:185], v[218:221], v[66:69]
	s_setprio 0
	s_barrier
	s_add_i32 s46, s62, s12
	v_lshl_add_u64 v[146:147], v[146:147], 0, s[8:9]
	s_mov_b32 m0, s46
	s_nop 0
	global_load_lds_dwordx4 v[146:147], off
	s_add_i32 m0, s46, 0x2000
	s_add_u32 s34, s34, 0x80080
	v_lshl_add_u64 v[146:147], v[214:215], 0, s[8:9]
	s_addc_u32 s35, s35, 0
	s_add_i32 s46, s63, s12
	global_load_lds_dwordx4 v[146:147], off
	v_lshl_add_u64 v[146:147], s[34:35], 0, v[134:135]
	s_mov_b32 m0, s46
	s_nop 0
	global_load_lds_dwordx4 v[146:147], off
	v_lshl_add_u64 v[146:147], s[34:35], 0, v[130:131]
	s_add_i32 m0, s46, 0x2000
	s_nop 0
	global_load_lds_dwordx4 v[146:147], off
	v_lshl_add_u64 v[146:147], v[222:223], 0, s[8:9]
	s_mov_b32 m0, s53
	s_nop 0
	global_load_lds_dwordx4 v[146:147], off
	v_lshl_add_u64 v[146:147], v[224:225], 0, s[8:9]
	s_mov_b32 m0, s54
	s_nop 0
	global_load_lds_dwordx4 v[146:147], off
	ds_read_b128 v[186:189], v153 offset:49152
	ds_read_b128 v[190:193], v153 offset:50176
	ds_read_b128 v[194:197], v153 offset:51200
	ds_read_b128 v[198:201], v153 offset:52224
	ds_read_b128 v[202:205], v153 offset:53248
	ds_read_b128 v[206:209], v153 offset:54272
	ds_read_b128 v[210:213], v153 offset:55296
	ds_read_b128 v[218:221], v153 offset:56320
	s_waitcnt vmcnt(8)
	s_waitcnt lgkmcnt(0)
	s_barrier
	s_setprio 1
	s_waitcnt lgkmcnt(0)
	v_mfma_f32_16x16x32_bf16 v[62:65], v[154:157], v[186:189], v[62:65]
	v_mfma_f32_16x16x32_bf16 v[58:61], v[162:165], v[186:189], v[58:61]
	v_mfma_f32_16x16x32_bf16 v[50:53], v[154:157], v[194:197], v[50:53]
	v_mfma_f32_16x16x32_bf16 v[42:45], v[162:165], v[194:197], v[42:45]
	v_mfma_f32_16x16x32_bf16 v[34:37], v[154:157], v[202:205], v[34:37]
	v_mfma_f32_16x16x32_bf16 v[26:29], v[162:165], v[202:205], v[26:29]
	v_mfma_f32_16x16x32_bf16 v[18:21], v[154:157], v[210:213], v[18:21]
	v_mfma_f32_16x16x32_bf16 v[10:13], v[162:165], v[210:213], v[10:13]
	v_mfma_f32_16x16x32_bf16 v[62:65], v[158:161], v[190:193], v[62:65]
	v_mfma_f32_16x16x32_bf16 v[58:61], v[166:169], v[190:193], v[58:61]
	v_mfma_f32_16x16x32_bf16 v[50:53], v[158:161], v[198:201], v[50:53]
	v_mfma_f32_16x16x32_bf16 v[42:45], v[166:169], v[198:201], v[42:45]
	v_mfma_f32_16x16x32_bf16 v[34:37], v[158:161], v[206:209], v[34:37]
	v_mfma_f32_16x16x32_bf16 v[26:29], v[166:169], v[206:209], v[26:29]
	v_mfma_f32_16x16x32_bf16 v[18:21], v[158:161], v[218:221], v[18:21]
	v_mfma_f32_16x16x32_bf16 v[10:13], v[166:169], v[218:221], v[10:13]
	s_setprio 0
	s_setprio 1
	v_mfma_f32_16x16x32_bf16 v[54:57], v[170:173], v[186:189], v[54:57]
	v_mfma_f32_16x16x32_bf16 v[46:49], v[178:181], v[186:189], v[46:49]
	v_mfma_f32_16x16x32_bf16 v[38:41], v[170:173], v[194:197], v[38:41]
	v_mfma_f32_16x16x32_bf16 v[30:33], v[178:181], v[194:197], v[30:33]
	v_mfma_f32_16x16x32_bf16 v[22:25], v[170:173], v[202:205], v[22:25]
	v_mfma_f32_16x16x32_bf16 v[14:17], v[178:181], v[202:205], v[14:17]
	v_mfma_f32_16x16x32_bf16 v[6:9], v[170:173], v[210:213], v[6:9]
	v_mfma_f32_16x16x32_bf16 v[2:5], v[178:181], v[210:213], v[2:5]
	v_mfma_f32_16x16x32_bf16 v[54:57], v[174:177], v[190:193], v[54:57]
	v_mfma_f32_16x16x32_bf16 v[46:49], v[182:185], v[190:193], v[46:49]
	v_mfma_f32_16x16x32_bf16 v[38:41], v[174:177], v[198:201], v[38:41]
	v_mfma_f32_16x16x32_bf16 v[30:33], v[182:185], v[198:201], v[30:33]
	v_mfma_f32_16x16x32_bf16 v[22:25], v[174:177], v[206:209], v[22:25]
	v_mfma_f32_16x16x32_bf16 v[14:17], v[182:185], v[206:209], v[14:17]
	v_mfma_f32_16x16x32_bf16 v[6:9], v[174:177], v[218:221], v[6:9]
	v_mfma_f32_16x16x32_bf16 v[2:5], v[182:185], v[218:221], v[2:5]
	s_setprio 0
	s_barrier
	s_add_i32 s68, s68, 2
	s_add_u32 s44, s44, 0x100
	s_addc_u32 s45, s45, 0
	s_add_u32 s60, s60, 0x100
	s_addc_u32 s61, s61, 0
	s_cmp_gt_u32 s68, 29
	s_cbranch_scc0 .LBB0_3533
	s_and_b64 vcc, exec, s[24:25]
	s_cbranch_vccz .LBB0_3536
	s_barrier

.LBB0_3706:
	s_add_u32 s34, s42, 0xfff80080
	s_addc_u32 s35, s43, -1
	s_cmp_eq_u32 s60, 28
	s_cselect_b32 s45, s0, s35
	s_cselect_b32 s44, s1, s34
	s_cselect_b32 s35, s25, s59
	s_cselect_b32 s34, s27, s58
	v_lshl_add_u64 v[170:171], s[42:43], 0, v[150:151]
	s_add_i32 m0, s41, 0xc000
	s_nop 0
	global_load_lds_dwordx4 v[170:171], off
	v_lshl_add_u64 v[170:171], s[42:43], 0, v[152:153]
	s_add_i32 m0, s41, 0xe000
	s_nop 0
	global_load_lds_dwordx4 v[170:171], off
	ds_read_b128 v[130:133], v174
	ds_read_b128 v[134:137], v174 offset:1024
	ds_read_b128 v[138:141], v174 offset:2048
	ds_read_b128 v[158:161], v174 offset:3072
	ds_read_b128 v[162:165], v175
	ds_read_b128 v[166:169], v175 offset:1024
	ds_read_b128 v[178:181], v175 offset:2048
	ds_read_b128 v[182:185], v175 offset:3072
	ds_read_b128 v[186:189], v176
	ds_read_b128 v[190:193], v176 offset:1024
	ds_read_b128 v[194:197], v176 offset:2048
	ds_read_b128 v[198:201], v176 offset:3072
	ds_read_b128 v[202:205], v176 offset:4096
	ds_read_b128 v[206:209], v176 offset:5120
	ds_read_b128 v[210:213], v176 offset:6144
	ds_read_b128 v[218:221], v176 offset:7168
	s_waitcnt vmcnt(8)
	s_waitcnt lgkmcnt(0)
	s_barrier
	s_setprio 1
	s_waitcnt lgkmcnt(0)
	v_mfma_f32_16x16x32_bf16 v[126:129], v[130:133], v[186:189], v[126:129]
	v_mfma_f32_16x16x32_bf16 v[122:125], v[138:141], v[186:189], v[122:125]
	v_mfma_f32_16x16x32_bf16 v[110:113], v[130:133], v[194:197], v[110:113]
	v_mfma_f32_16x16x32_bf16 v[106:109], v[138:141], v[194:197], v[106:109]
	v_mfma_f32_16x16x32_bf16 v[94:97], v[130:133], v[202:205], v[94:97]
	v_mfma_f32_16x16x32_bf16 v[90:93], v[138:141], v[202:205], v[90:93]
	v_mfma_f32_16x16x32_bf16 v[78:81], v[130:133], v[210:213], v[78:81]
	v_mfma_f32_16x16x32_bf16 v[74:77], v[138:141], v[210:213], v[74:77]
	v_mfma_f32_16x16x32_bf16 v[126:129], v[134:137], v[190:193], v[126:129]
	v_mfma_f32_16x16x32_bf16 v[122:125], v[158:161], v[190:193], v[122:125]
	v_mfma_f32_16x16x32_bf16 v[110:113], v[134:137], v[198:201], v[110:113]
	v_mfma_f32_16x16x32_bf16 v[106:109], v[158:161], v[198:201], v[106:109]
	v_mfma_f32_16x16x32_bf16 v[94:97], v[134:137], v[206:209], v[94:97]
	v_mfma_f32_16x16x32_bf16 v[90:93], v[158:161], v[206:209], v[90:93]
	v_mfma_f32_16x16x32_bf16 v[78:81], v[134:137], v[218:221], v[78:81]
	v_mfma_f32_16x16x32_bf16 v[74:77], v[158:161], v[218:221], v[74:77]
	s_setprio 0
	s_setprio 1
	v_mfma_f32_16x16x32_bf16 v[118:121], v[162:165], v[186:189], v[118:121]
	v_mfma_f32_16x16x32_bf16 v[114:117], v[178:181], v[186:189], v[114:117]
	v_mfma_f32_16x16x32_bf16 v[102:105], v[162:165], v[194:197], v[102:105]
	v_mfma_f32_16x16x32_bf16 v[98:101], v[178:181], v[194:197], v[98:101]
	v_mfma_f32_16x16x32_bf16 v[86:89], v[162:165], v[202:205], v[86:89]
	v_mfma_f32_16x16x32_bf16 v[82:85], v[178:181], v[202:205], v[82:85]
	v_mfma_f32_16x16x32_bf16 v[70:73], v[162:165], v[210:213], v[70:73]
	v_mfma_f32_16x16x32_bf16 v[66:69], v[178:181], v[210:213], v[66:69]
	v_mfma_f32_16x16x32_bf16 v[118:121], v[166:169], v[190:193], v[118:121]
	v_mfma_f32_16x16x32_bf16 v[114:117], v[182:185], v[190:193], v[114:117]
	v_mfma_f32_16x16x32_bf16 v[102:105], v[166:169], v[198:201], v[102:105]
	v_mfma_f32_16x16x32_bf16 v[98:101], v[182:185], v[198:201], v[98:101]
	v_mfma_f32_16x16x32_bf16 v[86:89], v[166:169], v[206:209], v[86:89]
	v_mfma_f32_16x16x32_bf16 v[82:85], v[182:185], v[206:209], v[82:85]
	v_mfma_f32_16x16x32_bf16 v[70:73], v[166:169], v[218:221], v[70:73]
	v_mfma_f32_16x16x32_bf16 v[66:69], v[182:185], v[218:221], v[66:69]
	s_setprio 0
	s_barrier
	s_add_i32 s61, s54, s46
	v_lshl_add_u64 v[170:171], s[34:35], 0, v[144:145]
	s_mov_b32 m0, s61
	s_nop 0
	global_load_lds_dwordx4 v[170:171], off
	s_add_i32 m0, s61, 0x2000
	s_add_u32 s62, s34, 0x80000
	v_lshl_add_u64 v[214:215], s[34:35], 0, v[148:149]
	s_addc_u32 s63, s35, 0
	s_add_i32 s61, s55, s46
	global_load_lds_dwordx4 v[214:215], off
	v_lshl_add_u64 v[222:223], s[62:63], 0, v[144:145]
	s_mov_b32 m0, s61
	v_lshl_add_u64 v[224:225], s[44:45], 0, v[146:147]
	global_load_lds_dwordx4 v[222:223], off
	v_lshl_add_u64 v[222:223], s[62:63], 0, v[148:149]
	s_add_i32 m0, s61, 0x2000
	s_nop 0
	global_load_lds_dwordx4 v[222:223], off
	v_lshl_add_u64 v[222:223], s[44:45], 0, v[142:143]
	s_mov_b32 m0, s41
	s_nop 0
	global_load_lds_dwordx4 v[222:223], off
	s_mov_b32 m0, s47
	s_nop 0
	global_load_lds_dwordx4 v[224:225], off
	ds_read_b128 v[186:189], v176 offset:16384
	ds_read_b128 v[190:193], v176 offset:17408
	ds_read_b128 v[194:197], v176 offset:18432
	ds_read_b128 v[198:201], v176 offset:19456
	ds_read_b128 v[202:205], v176 offset:20480
	ds_read_b128 v[206:209], v176 offset:21504
	ds_read_b128 v[210:213], v176 offset:22528
	ds_read_b128 v[218:221], v176 offset:23552
	s_waitcnt vmcnt(8)
	s_waitcnt lgkmcnt(0)
	s_barrier
	s_setprio 1
	s_waitcnt lgkmcnt(0)
	v_mfma_f32_16x16x32_bf16 v[62:65], v[130:133], v[186:189], v[62:65]
	v_mfma_f32_16x16x32_bf16 v[58:61], v[138:141], v[186:189], v[58:61]
	v_mfma_f32_16x16x32_bf16 v[50:53], v[130:133], v[194:197], v[50:53]
	v_mfma_f32_16x16x32_bf16 v[42:45], v[138:141], v[194:197], v[42:45]
	v_mfma_f32_16x16x32_bf16 v[38:41], v[130:133], v[202:205], v[38:41]
	v_mfma_f32_16x16x32_bf16 v[34:37], v[138:141], v[202:205], v[34:37]
	v_mfma_f32_16x16x32_bf16 v[14:17], v[130:133], v[210:213], v[14:17]
	v_mfma_f32_16x16x32_bf16 v[10:13], v[138:141], v[210:213], v[10:13]
	v_mfma_f32_16x16x32_bf16 v[62:65], v[134:137], v[190:193], v[62:65]
	v_mfma_f32_16x16x32_bf16 v[58:61], v[158:161], v[190:193], v[58:61]
	v_mfma_f32_16x16x32_bf16 v[50:53], v[134:137], v[198:201], v[50:53]
	v_mfma_f32_16x16x32_bf16 v[42:45], v[158:161], v[198:201], v[42:45]
	v_mfma_f32_16x16x32_bf16 v[38:41], v[134:137], v[206:209], v[38:41]
	v_mfma_f32_16x16x32_bf16 v[34:37], v[158:161], v[206:209], v[34:37]
	v_mfma_f32_16x16x32_bf16 v[14:17], v[134:137], v[218:221], v[14:17]
	v_mfma_f32_16x16x32_bf16 v[10:13], v[158:161], v[218:221], v[10:13]
	s_setprio 0
	s_setprio 1
	v_mfma_f32_16x16x32_bf16 v[54:57], v[162:165], v[186:189], v[54:57]
	v_mfma_f32_16x16x32_bf16 v[46:49], v[178:181], v[186:189], v[46:49]
	v_mfma_f32_16x16x32_bf16 v[30:33], v[162:165], v[194:197], v[30:33]
	v_mfma_f32_16x16x32_bf16 v[26:29], v[178:181], v[194:197], v[26:29]
	v_mfma_f32_16x16x32_bf16 v[22:25], v[162:165], v[202:205], v[22:25]
	v_mfma_f32_16x16x32_bf16 v[18:21], v[178:181], v[202:205], v[18:21]
	v_mfma_f32_16x16x32_bf16 v[6:9], v[162:165], v[210:213], v[6:9]
	v_mfma_f32_16x16x32_bf16 v[2:5], v[178:181], v[210:213], v[2:5]
	v_mfma_f32_16x16x32_bf16 v[54:57], v[166:169], v[190:193], v[54:57]
	v_mfma_f32_16x16x32_bf16 v[46:49], v[182:185], v[190:193], v[46:49]
	v_mfma_f32_16x16x32_bf16 v[30:33], v[166:169], v[198:201], v[30:33]
	v_mfma_f32_16x16x32_bf16 v[26:29], v[182:185], v[198:201], v[26:29]
	v_mfma_f32_16x16x32_bf16 v[22:25], v[166:169], v[206:209], v[22:25]
	v_mfma_f32_16x16x32_bf16 v[18:21], v[182:185], v[206:209], v[18:21]
	v_mfma_f32_16x16x32_bf16 v[6:9], v[166:169], v[218:221], v[6:9]
	v_mfma_f32_16x16x32_bf16 v[2:5], v[182:185], v[218:221], v[2:5]
	s_setprio 0
	s_barrier
	s_add_i32 s61, 0, 0x18000
	s_add_i32 s62, 0, 0x1c000
	s_add_u32 s44, s44, 0x80000
	s_addc_u32 s45, s45, 0
	s_mov_b32 m0, s48
	v_lshl_add_u64 v[226:227], s[44:45], 0, v[142:143]
	global_load_lds_dwordx4 v[226:227], off
	v_lshl_add_u64 v[226:227], s[44:45], 0, v[146:147]
	s_mov_b32 m0, s49
	s_nop 0
	global_load_lds_dwordx4 v[226:227], off
	v_add_u32_e32 v158, s61, v172
	v_add_u32_e32 v177, s62, v172
	ds_read_b128 v[130:133], v158
	ds_read_b128 v[134:137], v158 offset:1024
	ds_read_b128 v[138:141], v158 offset:2048
	ds_read_b128 v[158:161], v158 offset:3072
	ds_read_b128 v[162:165], v177
	ds_read_b128 v[166:169], v177 offset:1024
	ds_read_b128 v[178:181], v177 offset:2048
	ds_read_b128 v[182:185], v177 offset:3072
	ds_read_b128 v[186:189], v176 offset:32768
	ds_read_b128 v[190:193], v176 offset:33792
	ds_read_b128 v[194:197], v176 offset:34816
	ds_read_b128 v[198:201], v176 offset:35840
	ds_read_b128 v[202:205], v176 offset:36864
	ds_read_b128 v[206:209], v176 offset:37888
	ds_read_b128 v[210:213], v176 offset:38912
	ds_read_b128 v[218:221], v176 offset:39936
	s_waitcnt vmcnt(8)
	s_waitcnt lgkmcnt(0)
	s_barrier
	s_setprio 1
	s_waitcnt lgkmcnt(0)
	v_mfma_f32_16x16x32_bf16 v[126:129], v[130:133], v[186:189], v[126:129]
	v_mfma_f32_16x16x32_bf16 v[122:125], v[138:141], v[186:189], v[122:125]
	v_mfma_f32_16x16x32_bf16 v[110:113], v[130:133], v[194:197], v[110:113]
	v_mfma_f32_16x16x32_bf16 v[106:109], v[138:141], v[194:197], v[106:109]
	v_mfma_f32_16x16x32_bf16 v[94:97], v[130:133], v[202:205], v[94:97]
	v_mfma_f32_16x16x32_bf16 v[90:93], v[138:141], v[202:205], v[90:93]
	v_mfma_f32_16x16x32_bf16 v[78:81], v[130:133], v[210:213], v[78:81]
	v_mfma_f32_16x16x32_bf16 v[74:77], v[138:141], v[210:213], v[74:77]
	v_mfma_f32_16x16x32_bf16 v[126:129], v[134:137], v[190:193], v[126:129]
	v_mfma_f32_16x16x32_bf16 v[122:125], v[158:161], v[190:193], v[122:125]
	v_mfma_f32_16x16x32_bf16 v[110:113], v[134:137], v[198:201], v[110:113]
	v_mfma_f32_16x16x32_bf16 v[106:109], v[158:161], v[198:201], v[106:109]
	v_mfma_f32_16x16x32_bf16 v[94:97], v[134:137], v[206:209], v[94:97]
	v_mfma_f32_16x16x32_bf16 v[90:93], v[158:161], v[206:209], v[90:93]
	v_mfma_f32_16x16x32_bf16 v[78:81], v[134:137], v[218:221], v[78:81]
	v_mfma_f32_16x16x32_bf16 v[74:77], v[158:161], v[218:221], v[74:77]
	s_setprio 0
	s_setprio 1
	v_mfma_f32_16x16x32_bf16 v[118:121], v[162:165], v[186:189], v[118:121]
	v_mfma_f32_16x16x32_bf16 v[114:117], v[178:181], v[186:189], v[114:117]
	v_mfma_f32_16x16x32_bf16 v[102:105], v[162:165], v[194:197], v[102:105]
	v_mfma_f32_16x16x32_bf16 v[98:101], v[178:181], v[194:197], v[98:101]
	v_mfma_f32_16x16x32_bf16 v[86:89], v[162:165], v[202:205], v[86:89]
	v_mfma_f32_16x16x32_bf16 v[82:85], v[178:181], v[202:205], v[82:85]
	v_mfma_f32_16x16x32_bf16 v[70:73], v[162:165], v[210:213], v[70:73]
	v_mfma_f32_16x16x32_bf16 v[66:69], v[178:181], v[210:213], v[66:69]
	v_mfma_f32_16x16x32_bf16 v[118:121], v[166:169], v[190:193], v[118:121]
	v_mfma_f32_16x16x32_bf16 v[114:117], v[182:185], v[190:193], v[114:117]
	v_mfma_f32_16x16x32_bf16 v[102:105], v[166:169], v[198:201], v[102:105]
	v_mfma_f32_16x16x32_bf16 v[98:101], v[182:185], v[198:201], v[98:101]
	v_mfma_f32_16x16x32_bf16 v[86:89], v[166:169], v[206:209], v[86:89]
	v_mfma_f32_16x16x32_bf16 v[82:85], v[182:185], v[206:209], v[82:85]
	v_mfma_f32_16x16x32_bf16 v[70:73], v[166:169], v[218:221], v[70:73]
	v_mfma_f32_16x16x32_bf16 v[66:69], v[182:185], v[218:221], v[66:69]
	s_setprio 0
	s_barrier
	s_add_i32 s44, s61, s46
	v_lshl_add_u64 v[170:171], v[170:171], 0, s[12:13]
	s_mov_b32 m0, s44
	s_nop 0
	global_load_lds_dwordx4 v[170:171], off
	s_add_i32 m0, s44, 0x2000
	s_add_u32 s34, s34, 0x80080
	v_lshl_add_u64 v[170:171], v[214:215], 0, s[12:13]
	s_addc_u32 s35, s35, 0
	s_add_i32 s44, s62, s46
	global_load_lds_dwordx4 v[170:171], off
	v_lshl_add_u64 v[170:171], s[34:35], 0, v[144:145]
	s_mov_b32 m0, s44
	s_nop 0
	global_load_lds_dwordx4 v[170:171], off
	v_lshl_add_u64 v[170:171], s[34:35], 0, v[148:149]
	s_add_i32 m0, s44, 0x2000
	s_nop 0
	global_load_lds_dwordx4 v[170:171], off
	v_lshl_add_u64 v[170:171], v[222:223], 0, s[12:13]
	s_mov_b32 m0, s51
	s_nop 0
	global_load_lds_dwordx4 v[170:171], off
	v_lshl_add_u64 v[170:171], v[224:225], 0, s[12:13]
	s_mov_b32 m0, s52
	s_nop 0
	global_load_lds_dwordx4 v[170:171], off
	ds_read_b128 v[186:189], v176 offset:49152
	ds_read_b128 v[190:193], v176 offset:50176
	ds_read_b128 v[194:197], v176 offset:51200
	ds_read_b128 v[198:201], v176 offset:52224
	ds_read_b128 v[202:205], v176 offset:53248
	ds_read_b128 v[206:209], v176 offset:54272
	ds_read_b128 v[210:213], v176 offset:55296
	ds_read_b128 v[218:221], v176 offset:56320
	s_waitcnt vmcnt(8)
	s_waitcnt lgkmcnt(0)
	s_barrier
	s_setprio 1
	s_waitcnt lgkmcnt(0)
	v_mfma_f32_16x16x32_bf16 v[62:65], v[130:133], v[186:189], v[62:65]
	v_mfma_f32_16x16x32_bf16 v[58:61], v[138:141], v[186:189], v[58:61]
	v_mfma_f32_16x16x32_bf16 v[50:53], v[130:133], v[194:197], v[50:53]
	v_mfma_f32_16x16x32_bf16 v[42:45], v[138:141], v[194:197], v[42:45]
	v_mfma_f32_16x16x32_bf16 v[38:41], v[130:133], v[202:205], v[38:41]
	v_mfma_f32_16x16x32_bf16 v[34:37], v[138:141], v[202:205], v[34:37]
	v_mfma_f32_16x16x32_bf16 v[14:17], v[130:133], v[210:213], v[14:17]
	v_mfma_f32_16x16x32_bf16 v[10:13], v[138:141], v[210:213], v[10:13]
	v_mfma_f32_16x16x32_bf16 v[62:65], v[134:137], v[190:193], v[62:65]
	v_mfma_f32_16x16x32_bf16 v[58:61], v[158:161], v[190:193], v[58:61]
	v_mfma_f32_16x16x32_bf16 v[50:53], v[134:137], v[198:201], v[50:53]
	v_mfma_f32_16x16x32_bf16 v[42:45], v[158:161], v[198:201], v[42:45]
	v_mfma_f32_16x16x32_bf16 v[38:41], v[134:137], v[206:209], v[38:41]
	v_mfma_f32_16x16x32_bf16 v[34:37], v[158:161], v[206:209], v[34:37]
	v_mfma_f32_16x16x32_bf16 v[14:17], v[134:137], v[218:221], v[14:17]
	v_mfma_f32_16x16x32_bf16 v[10:13], v[158:161], v[218:221], v[10:13]
	s_setprio 0
	s_setprio 1
	v_mfma_f32_16x16x32_bf16 v[54:57], v[162:165], v[186:189], v[54:57]
	v_mfma_f32_16x16x32_bf16 v[46:49], v[178:181], v[186:189], v[46:49]
	v_mfma_f32_16x16x32_bf16 v[30:33], v[162:165], v[194:197], v[30:33]
	v_mfma_f32_16x16x32_bf16 v[26:29], v[178:181], v[194:197], v[26:29]
	v_mfma_f32_16x16x32_bf16 v[22:25], v[162:165], v[202:205], v[22:25]
	v_mfma_f32_16x16x32_bf16 v[18:21], v[178:181], v[202:205], v[18:21]
	v_mfma_f32_16x16x32_bf16 v[6:9], v[162:165], v[210:213], v[6:9]
	v_mfma_f32_16x16x32_bf16 v[2:5], v[178:181], v[210:213], v[2:5]
	v_mfma_f32_16x16x32_bf16 v[54:57], v[166:169], v[190:193], v[54:57]
	v_mfma_f32_16x16x32_bf16 v[46:49], v[182:185], v[190:193], v[46:49]
	v_mfma_f32_16x16x32_bf16 v[30:33], v[166:169], v[198:201], v[30:33]
	v_mfma_f32_16x16x32_bf16 v[26:29], v[182:185], v[198:201], v[26:29]
	v_mfma_f32_16x16x32_bf16 v[22:25], v[166:169], v[206:209], v[22:25]
	v_mfma_f32_16x16x32_bf16 v[18:21], v[182:185], v[206:209], v[18:21]
	v_mfma_f32_16x16x32_bf16 v[6:9], v[166:169], v[218:221], v[6:9]
	v_mfma_f32_16x16x32_bf16 v[2:5], v[182:185], v[218:221], v[2:5]
	s_setprio 0
	s_barrier
	s_add_i32 s60, s60, 2
	s_add_u32 s42, s42, 0x100
	s_addc_u32 s43, s43, 0
	s_add_u32 s58, s58, 0x100
	s_addc_u32 s59, s59, 0
	s_cmp_gt_u32 s60, 29
	s_cbranch_scc0 .LBB0_3706
	s_and_b64 vcc, exec, s[14:15]
	s_cbranch_vccz .LBB0_3709
	s_barrier

.LBB0_3835:
	s_add_u32 s34, s38, 0xfff80080
	s_addc_u32 s35, s39, -1
	s_cmp_eq_u32 s57, 28
	s_cselect_b32 s41, s0, s35
	s_cselect_b32 s40, s1, s34
	s_cselect_b32 s35, s15, s56
	s_cselect_b32 s34, s17, s55
	v_lshl_add_u64 v[218:219], s[38:39], 0, v[138:139]
	s_add_i32 m0, s37, 0xc000
	s_nop 0
	global_load_lds_dwordx4 v[218:219], off
	v_lshl_add_u64 v[218:219], s[38:39], 0, v[140:141]
	s_add_i32 m0, s37, 0xe000
	s_nop 0
	global_load_lds_dwordx4 v[218:219], off
	ds_read_b128 v[146:149], v153
	ds_read_b128 v[156:159], v153 offset:1024
	ds_read_b128 v[160:163], v153 offset:2048
	ds_read_b128 v[164:167], v153 offset:3072
	ds_read_b128 v[168:171], v154
	ds_read_b128 v[172:175], v154 offset:1024
	ds_read_b128 v[176:179], v154 offset:2048
	ds_read_b128 v[180:183], v154 offset:3072
	ds_read_b128 v[184:187], v155
	ds_read_b128 v[188:191], v155 offset:1024
	ds_read_b128 v[192:195], v155 offset:2048
	ds_read_b128 v[196:199], v155 offset:3072
	ds_read_b128 v[200:203], v155 offset:4096
	ds_read_b128 v[204:207], v155 offset:5120
	ds_read_b128 v[208:211], v155 offset:6144
	ds_read_b128 v[212:215], v155 offset:7168
	s_waitcnt vmcnt(8)
	s_waitcnt lgkmcnt(0)
	s_barrier
	s_setprio 1
	s_waitcnt lgkmcnt(0)
	v_mfma_f32_16x16x32_bf16 v[126:129], v[146:149], v[184:187], v[126:129]
	v_mfma_f32_16x16x32_bf16 v[118:121], v[160:163], v[184:187], v[118:121]
	v_mfma_f32_16x16x32_bf16 v[110:113], v[146:149], v[192:195], v[110:113]
	v_mfma_f32_16x16x32_bf16 v[102:105], v[160:163], v[192:195], v[102:105]
	v_mfma_f32_16x16x32_bf16 v[94:97], v[146:149], v[200:203], v[94:97]
	v_mfma_f32_16x16x32_bf16 v[86:89], v[160:163], v[200:203], v[86:89]
	v_mfma_f32_16x16x32_bf16 v[78:81], v[146:149], v[208:211], v[78:81]
	v_mfma_f32_16x16x32_bf16 v[70:73], v[160:163], v[208:211], v[70:73]
	v_mfma_f32_16x16x32_bf16 v[126:129], v[156:159], v[188:191], v[126:129]
	v_mfma_f32_16x16x32_bf16 v[118:121], v[164:167], v[188:191], v[118:121]
	v_mfma_f32_16x16x32_bf16 v[110:113], v[156:159], v[196:199], v[110:113]
	v_mfma_f32_16x16x32_bf16 v[102:105], v[164:167], v[196:199], v[102:105]
	v_mfma_f32_16x16x32_bf16 v[94:97], v[156:159], v[204:207], v[94:97]
	v_mfma_f32_16x16x32_bf16 v[86:89], v[164:167], v[204:207], v[86:89]
	v_mfma_f32_16x16x32_bf16 v[78:81], v[156:159], v[212:215], v[78:81]
	v_mfma_f32_16x16x32_bf16 v[70:73], v[164:167], v[212:215], v[70:73]
	s_setprio 0
	s_setprio 1
	v_mfma_f32_16x16x32_bf16 v[122:125], v[168:171], v[184:187], v[122:125]
	v_mfma_f32_16x16x32_bf16 v[114:117], v[176:179], v[184:187], v[114:117]
	v_mfma_f32_16x16x32_bf16 v[106:109], v[168:171], v[192:195], v[106:109]
	v_mfma_f32_16x16x32_bf16 v[98:101], v[176:179], v[192:195], v[98:101]
	v_mfma_f32_16x16x32_bf16 v[90:93], v[168:171], v[200:203], v[90:93]
	v_mfma_f32_16x16x32_bf16 v[82:85], v[176:179], v[200:203], v[82:85]
	v_mfma_f32_16x16x32_bf16 v[74:77], v[168:171], v[208:211], v[74:77]
	v_mfma_f32_16x16x32_bf16 v[66:69], v[176:179], v[208:211], v[66:69]
	v_mfma_f32_16x16x32_bf16 v[122:125], v[172:175], v[188:191], v[122:125]
	v_mfma_f32_16x16x32_bf16 v[114:117], v[180:183], v[188:191], v[114:117]
	v_mfma_f32_16x16x32_bf16 v[106:109], v[172:175], v[196:199], v[106:109]
	v_mfma_f32_16x16x32_bf16 v[98:101], v[180:183], v[196:199], v[98:101]
	v_mfma_f32_16x16x32_bf16 v[90:93], v[172:175], v[204:207], v[90:93]
	v_mfma_f32_16x16x32_bf16 v[82:85], v[180:183], v[204:207], v[82:85]
	v_mfma_f32_16x16x32_bf16 v[74:77], v[172:175], v[212:215], v[74:77]
	v_mfma_f32_16x16x32_bf16 v[66:69], v[180:183], v[212:215], v[66:69]
	s_setprio 0
	s_barrier
	s_add_i32 s58, s51, s33
	v_lshl_add_u64 v[218:219], s[34:35], 0, v[134:135]
	s_mov_b32 m0, s58
	s_nop 0
	global_load_lds_dwordx4 v[218:219], off
	s_add_i32 m0, s58, 0x2000
	s_add_u32 s58, s34, 0x80000
	v_lshl_add_u64 v[220:221], s[34:35], 0, v[130:131]
	s_addc_u32 s59, s35, 0
	s_add_i32 s60, s52, s33
	global_load_lds_dwordx4 v[220:221], off
	v_lshl_add_u64 v[222:223], s[58:59], 0, v[134:135]
	s_mov_b32 m0, s60
	v_lshl_add_u64 v[224:225], s[40:41], 0, v[132:133]
	global_load_lds_dwordx4 v[222:223], off
	v_lshl_add_u64 v[222:223], s[58:59], 0, v[130:131]
	s_add_i32 m0, s60, 0x2000
	s_nop 0
	global_load_lds_dwordx4 v[222:223], off
	v_lshl_add_u64 v[222:223], s[40:41], 0, v[136:137]
	s_mov_b32 m0, s37
	s_nop 0
	global_load_lds_dwordx4 v[222:223], off
	s_mov_b32 m0, s44
	s_nop 0
	global_load_lds_dwordx4 v[224:225], off
	ds_read_b128 v[184:187], v155 offset:16384
	ds_read_b128 v[188:191], v155 offset:17408
	ds_read_b128 v[192:195], v155 offset:18432
	ds_read_b128 v[196:199], v155 offset:19456
	ds_read_b128 v[200:203], v155 offset:20480
	ds_read_b128 v[204:207], v155 offset:21504
	ds_read_b128 v[208:211], v155 offset:22528
	ds_read_b128 v[212:215], v155 offset:23552
	s_waitcnt vmcnt(8)
	s_waitcnt lgkmcnt(0)
	s_barrier
	s_setprio 1
	s_waitcnt lgkmcnt(0)
	v_mfma_f32_16x16x32_bf16 v[62:65], v[146:149], v[184:187], v[62:65]
	v_mfma_f32_16x16x32_bf16 v[54:57], v[160:163], v[184:187], v[54:57]
	v_mfma_f32_16x16x32_bf16 v[46:49], v[146:149], v[192:195], v[46:49]
	v_mfma_f32_16x16x32_bf16 v[38:41], v[160:163], v[192:195], v[38:41]
	v_mfma_f32_16x16x32_bf16 v[30:33], v[146:149], v[200:203], v[30:33]
	v_mfma_f32_16x16x32_bf16 v[22:25], v[160:163], v[200:203], v[22:25]
	v_mfma_f32_16x16x32_bf16 v[14:17], v[146:149], v[208:211], v[14:17]
	v_mfma_f32_16x16x32_bf16 v[6:9], v[160:163], v[208:211], v[6:9]
	v_mfma_f32_16x16x32_bf16 v[62:65], v[156:159], v[188:191], v[62:65]
	v_mfma_f32_16x16x32_bf16 v[54:57], v[164:167], v[188:191], v[54:57]
	v_mfma_f32_16x16x32_bf16 v[46:49], v[156:159], v[196:199], v[46:49]
	v_mfma_f32_16x16x32_bf16 v[38:41], v[164:167], v[196:199], v[38:41]
	v_mfma_f32_16x16x32_bf16 v[30:33], v[156:159], v[204:207], v[30:33]
	v_mfma_f32_16x16x32_bf16 v[22:25], v[164:167], v[204:207], v[22:25]
	v_mfma_f32_16x16x32_bf16 v[14:17], v[156:159], v[212:215], v[14:17]
	v_mfma_f32_16x16x32_bf16 v[6:9], v[164:167], v[212:215], v[6:9]
	s_setprio 0
	s_setprio 1
	v_mfma_f32_16x16x32_bf16 v[58:61], v[168:171], v[184:187], v[58:61]
	v_mfma_f32_16x16x32_bf16 v[50:53], v[176:179], v[184:187], v[50:53]
	v_mfma_f32_16x16x32_bf16 v[42:45], v[168:171], v[192:195], v[42:45]
	v_mfma_f32_16x16x32_bf16 v[34:37], v[176:179], v[192:195], v[34:37]
	v_mfma_f32_16x16x32_bf16 v[26:29], v[168:171], v[200:203], v[26:29]
	v_mfma_f32_16x16x32_bf16 v[18:21], v[176:179], v[200:203], v[18:21]
	v_mfma_f32_16x16x32_bf16 v[10:13], v[168:171], v[208:211], v[10:13]
	v_mfma_f32_16x16x32_bf16 v[2:5], v[176:179], v[208:211], v[2:5]
	v_mfma_f32_16x16x32_bf16 v[58:61], v[172:175], v[188:191], v[58:61]
	v_mfma_f32_16x16x32_bf16 v[50:53], v[180:183], v[188:191], v[50:53]
	v_mfma_f32_16x16x32_bf16 v[42:45], v[172:175], v[196:199], v[42:45]
	v_mfma_f32_16x16x32_bf16 v[34:37], v[180:183], v[196:199], v[34:37]
	v_mfma_f32_16x16x32_bf16 v[26:29], v[172:175], v[204:207], v[26:29]
	v_mfma_f32_16x16x32_bf16 v[18:21], v[180:183], v[204:207], v[18:21]
	v_mfma_f32_16x16x32_bf16 v[10:13], v[172:175], v[212:215], v[10:13]
	v_mfma_f32_16x16x32_bf16 v[2:5], v[180:183], v[212:215], v[2:5]
	s_setprio 0
	s_barrier
	s_add_i32 s58, 0, 0x18000
	s_add_i32 s59, 0, 0x1c000
	s_add_u32 s40, s40, 0x80000
	s_addc_u32 s41, s41, 0
	s_mov_b32 m0, s45
	v_lshl_add_u64 v[226:227], s[40:41], 0, v[136:137]
	global_load_lds_dwordx4 v[226:227], off
	v_lshl_add_u64 v[226:227], s[40:41], 0, v[132:133]
	s_mov_b32 m0, s46
	s_nop 0
	global_load_lds_dwordx4 v[226:227], off
	v_add_u32_e32 v164, s58, v151
	v_add_u32_e32 v180, s59, v151
	ds_read_b128 v[146:149], v164
	ds_read_b128 v[156:159], v164 offset:1024
	ds_read_b128 v[160:163], v164 offset:2048
	ds_read_b128 v[164:167], v164 offset:3072
	ds_read_b128 v[168:171], v180
	ds_read_b128 v[172:175], v180 offset:1024
	ds_read_b128 v[176:179], v180 offset:2048
	ds_read_b128 v[180:183], v180 offset:3072
	ds_read_b128 v[184:187], v155 offset:32768
	ds_read_b128 v[188:191], v155 offset:33792
	ds_read_b128 v[192:195], v155 offset:34816
	ds_read_b128 v[196:199], v155 offset:35840
	ds_read_b128 v[200:203], v155 offset:36864
	ds_read_b128 v[204:207], v155 offset:37888
	ds_read_b128 v[208:211], v155 offset:38912
	ds_read_b128 v[212:215], v155 offset:39936
	s_waitcnt vmcnt(8)
	s_waitcnt lgkmcnt(0)
	s_barrier
	s_setprio 1
	s_waitcnt lgkmcnt(0)
	v_mfma_f32_16x16x32_bf16 v[126:129], v[146:149], v[184:187], v[126:129]
	v_mfma_f32_16x16x32_bf16 v[118:121], v[160:163], v[184:187], v[118:121]
	v_mfma_f32_16x16x32_bf16 v[110:113], v[146:149], v[192:195], v[110:113]
	v_mfma_f32_16x16x32_bf16 v[102:105], v[160:163], v[192:195], v[102:105]
	v_mfma_f32_16x16x32_bf16 v[94:97], v[146:149], v[200:203], v[94:97]
	v_mfma_f32_16x16x32_bf16 v[86:89], v[160:163], v[200:203], v[86:89]
	v_mfma_f32_16x16x32_bf16 v[78:81], v[146:149], v[208:211], v[78:81]
	v_mfma_f32_16x16x32_bf16 v[70:73], v[160:163], v[208:211], v[70:73]
	v_mfma_f32_16x16x32_bf16 v[126:129], v[156:159], v[188:191], v[126:129]
	v_mfma_f32_16x16x32_bf16 v[118:121], v[164:167], v[188:191], v[118:121]
	v_mfma_f32_16x16x32_bf16 v[110:113], v[156:159], v[196:199], v[110:113]
	v_mfma_f32_16x16x32_bf16 v[102:105], v[164:167], v[196:199], v[102:105]
	v_mfma_f32_16x16x32_bf16 v[94:97], v[156:159], v[204:207], v[94:97]
	v_mfma_f32_16x16x32_bf16 v[86:89], v[164:167], v[204:207], v[86:89]
	v_mfma_f32_16x16x32_bf16 v[78:81], v[156:159], v[212:215], v[78:81]
	v_mfma_f32_16x16x32_bf16 v[70:73], v[164:167], v[212:215], v[70:73]
	s_setprio 0
	s_setprio 1
	v_mfma_f32_16x16x32_bf16 v[122:125], v[168:171], v[184:187], v[122:125]
	v_mfma_f32_16x16x32_bf16 v[114:117], v[176:179], v[184:187], v[114:117]
	v_mfma_f32_16x16x32_bf16 v[106:109], v[168:171], v[192:195], v[106:109]
	v_mfma_f32_16x16x32_bf16 v[98:101], v[176:179], v[192:195], v[98:101]
	v_mfma_f32_16x16x32_bf16 v[90:93], v[168:171], v[200:203], v[90:93]
	v_mfma_f32_16x16x32_bf16 v[82:85], v[176:179], v[200:203], v[82:85]
	v_mfma_f32_16x16x32_bf16 v[74:77], v[168:171], v[208:211], v[74:77]
	v_mfma_f32_16x16x32_bf16 v[66:69], v[176:179], v[208:211], v[66:69]
	v_mfma_f32_16x16x32_bf16 v[122:125], v[172:175], v[188:191], v[122:125]
	v_mfma_f32_16x16x32_bf16 v[114:117], v[180:183], v[188:191], v[114:117]
	v_mfma_f32_16x16x32_bf16 v[106:109], v[172:175], v[196:199], v[106:109]
	v_mfma_f32_16x16x32_bf16 v[98:101], v[180:183], v[196:199], v[98:101]
	v_mfma_f32_16x16x32_bf16 v[90:93], v[172:175], v[204:207], v[90:93]
	v_mfma_f32_16x16x32_bf16 v[82:85], v[180:183], v[204:207], v[82:85]
	v_mfma_f32_16x16x32_bf16 v[74:77], v[172:175], v[212:215], v[74:77]
	v_mfma_f32_16x16x32_bf16 v[66:69], v[180:183], v[212:215], v[66:69]
	s_setprio 0
	s_barrier
	s_add_i32 s40, s58, s33
	v_lshl_add_u64 v[218:219], v[218:219], 0, s[8:9]
	s_mov_b32 m0, s40
	s_nop 0
	global_load_lds_dwordx4 v[218:219], off
	s_add_i32 m0, s40, 0x2000
	s_add_u32 s34, s34, 0x80080
	v_lshl_add_u64 v[218:219], v[220:221], 0, s[8:9]
	s_addc_u32 s35, s35, 0
	s_add_i32 s40, s59, s33
	global_load_lds_dwordx4 v[218:219], off
	v_lshl_add_u64 v[218:219], s[34:35], 0, v[134:135]
	s_mov_b32 m0, s40
	s_nop 0
	global_load_lds_dwordx4 v[218:219], off
	v_lshl_add_u64 v[218:219], s[34:35], 0, v[130:131]
	s_add_i32 m0, s40, 0x2000
	s_nop 0
	global_load_lds_dwordx4 v[218:219], off
	v_lshl_add_u64 v[218:219], v[222:223], 0, s[8:9]
	s_mov_b32 m0, s48
	s_nop 0
	global_load_lds_dwordx4 v[218:219], off
	v_lshl_add_u64 v[218:219], v[224:225], 0, s[8:9]
	s_mov_b32 m0, s49
	s_nop 0
	global_load_lds_dwordx4 v[218:219], off
	ds_read_b128 v[184:187], v155 offset:49152
	ds_read_b128 v[188:191], v155 offset:50176
	ds_read_b128 v[192:195], v155 offset:51200
	ds_read_b128 v[196:199], v155 offset:52224
	ds_read_b128 v[200:203], v155 offset:53248
	ds_read_b128 v[204:207], v155 offset:54272
	ds_read_b128 v[208:211], v155 offset:55296
	ds_read_b128 v[212:215], v155 offset:56320
	s_waitcnt vmcnt(8)
	s_waitcnt lgkmcnt(0)
	s_barrier
	s_setprio 1
	s_waitcnt lgkmcnt(0)
	v_mfma_f32_16x16x32_bf16 v[62:65], v[146:149], v[184:187], v[62:65]
	v_mfma_f32_16x16x32_bf16 v[54:57], v[160:163], v[184:187], v[54:57]
	v_mfma_f32_16x16x32_bf16 v[46:49], v[146:149], v[192:195], v[46:49]
	v_mfma_f32_16x16x32_bf16 v[38:41], v[160:163], v[192:195], v[38:41]
	v_mfma_f32_16x16x32_bf16 v[30:33], v[146:149], v[200:203], v[30:33]
	v_mfma_f32_16x16x32_bf16 v[22:25], v[160:163], v[200:203], v[22:25]
	v_mfma_f32_16x16x32_bf16 v[14:17], v[146:149], v[208:211], v[14:17]
	v_mfma_f32_16x16x32_bf16 v[6:9], v[160:163], v[208:211], v[6:9]
	v_mfma_f32_16x16x32_bf16 v[62:65], v[156:159], v[188:191], v[62:65]
	v_mfma_f32_16x16x32_bf16 v[54:57], v[164:167], v[188:191], v[54:57]
	v_mfma_f32_16x16x32_bf16 v[46:49], v[156:159], v[196:199], v[46:49]
	v_mfma_f32_16x16x32_bf16 v[38:41], v[164:167], v[196:199], v[38:41]
	v_mfma_f32_16x16x32_bf16 v[30:33], v[156:159], v[204:207], v[30:33]
	v_mfma_f32_16x16x32_bf16 v[22:25], v[164:167], v[204:207], v[22:25]
	v_mfma_f32_16x16x32_bf16 v[14:17], v[156:159], v[212:215], v[14:17]
	v_mfma_f32_16x16x32_bf16 v[6:9], v[164:167], v[212:215], v[6:9]
	s_setprio 0
	s_setprio 1
	v_mfma_f32_16x16x32_bf16 v[58:61], v[168:171], v[184:187], v[58:61]
	v_mfma_f32_16x16x32_bf16 v[50:53], v[176:179], v[184:187], v[50:53]
	v_mfma_f32_16x16x32_bf16 v[42:45], v[168:171], v[192:195], v[42:45]
	v_mfma_f32_16x16x32_bf16 v[34:37], v[176:179], v[192:195], v[34:37]
	v_mfma_f32_16x16x32_bf16 v[26:29], v[168:171], v[200:203], v[26:29]
	v_mfma_f32_16x16x32_bf16 v[18:21], v[176:179], v[200:203], v[18:21]
	v_mfma_f32_16x16x32_bf16 v[10:13], v[168:171], v[208:211], v[10:13]
	v_mfma_f32_16x16x32_bf16 v[2:5], v[176:179], v[208:211], v[2:5]
	v_mfma_f32_16x16x32_bf16 v[58:61], v[172:175], v[188:191], v[58:61]
	v_mfma_f32_16x16x32_bf16 v[50:53], v[180:183], v[188:191], v[50:53]
	v_mfma_f32_16x16x32_bf16 v[42:45], v[172:175], v[196:199], v[42:45]
	v_mfma_f32_16x16x32_bf16 v[34:37], v[180:183], v[196:199], v[34:37]
	v_mfma_f32_16x16x32_bf16 v[26:29], v[172:175], v[204:207], v[26:29]
	v_mfma_f32_16x16x32_bf16 v[18:21], v[180:183], v[204:207], v[18:21]
	v_mfma_f32_16x16x32_bf16 v[10:13], v[172:175], v[212:215], v[10:13]
	v_mfma_f32_16x16x32_bf16 v[2:5], v[180:183], v[212:215], v[2:5]
	s_setprio 0
	s_barrier
	s_add_i32 s57, s57, 2
	s_add_u32 s38, s38, 0x100
	s_addc_u32 s39, s39, 0
	s_add_u32 s55, s55, 0x100
	s_addc_u32 s56, s56, 0
	s_cmp_gt_u32 s57, 29
	s_cbranch_scc0 .LBB0_3835
	s_and_b64 vcc, exec, s[12:13]
	s_cbranch_vccz .LBB0_3838
	s_barrier

.LBB0_3930:
	s_add_u32 s20, s18, 0xffea0080
	s_addc_u32 s21, s19, -1
	s_cmpk_eq_i32 s45, 0x54
	s_cselect_b32 s23, s5, s21
	s_cselect_b32 s22, s4, s20
	s_cselect_b32 s21, s17, s1
	s_cselect_b32 s20, s16, s0
	v_lshl_add_u64 v[214:215], s[18:19], 0, v[136:137]
	s_add_i32 m0, s30, 0xc000
	s_nop 0
	global_load_lds_dwordx4 v[214:215], off
	v_lshl_add_u64 v[214:215], s[18:19], 0, v[138:139]
	s_add_i32 m0, s30, 0xe000
	s_nop 0
	global_load_lds_dwordx4 v[214:215], off
	ds_read_b128 v[144:147], v155
	ds_read_b128 v[148:151], v155 offset:1024
	ds_read_b128 v[158:161], v155 offset:2048
	ds_read_b128 v[162:165], v155 offset:3072
	ds_read_b128 v[166:169], v156
	ds_read_b128 v[170:173], v156 offset:1024
	ds_read_b128 v[174:177], v156 offset:2048
	ds_read_b128 v[178:181], v156 offset:3072
	ds_read_b128 v[182:185], v157
	ds_read_b128 v[186:189], v157 offset:1024
	ds_read_b128 v[190:193], v157 offset:2048
	ds_read_b128 v[194:197], v157 offset:3072
	ds_read_b128 v[198:201], v157 offset:4096
	ds_read_b128 v[202:205], v157 offset:5120
	ds_read_b128 v[206:209], v157 offset:6144
	ds_read_b128 v[210:213], v157 offset:7168
	s_waitcnt vmcnt(8)
	s_waitcnt lgkmcnt(0)
	s_barrier
	s_setprio 1
	s_waitcnt lgkmcnt(0)
	v_mfma_f32_16x16x32_bf16 v[124:127], v[144:147], v[182:185], v[124:127]
	v_mfma_f32_16x16x32_bf16 v[120:123], v[158:161], v[182:185], v[120:123]
	v_mfma_f32_16x16x32_bf16 v[116:119], v[144:147], v[190:193], v[116:119]
	v_mfma_f32_16x16x32_bf16 v[112:115], v[158:161], v[190:193], v[112:115]
	v_mfma_f32_16x16x32_bf16 v[92:95], v[144:147], v[198:201], v[92:95]
	v_mfma_f32_16x16x32_bf16 v[88:91], v[158:161], v[198:201], v[88:91]
	v_mfma_f32_16x16x32_bf16 v[84:87], v[144:147], v[206:209], v[84:87]
	v_mfma_f32_16x16x32_bf16 v[80:83], v[158:161], v[206:209], v[80:83]
	v_mfma_f32_16x16x32_bf16 v[124:127], v[148:151], v[186:189], v[124:127]
	v_mfma_f32_16x16x32_bf16 v[120:123], v[162:165], v[186:189], v[120:123]
	v_mfma_f32_16x16x32_bf16 v[116:119], v[148:151], v[194:197], v[116:119]
	v_mfma_f32_16x16x32_bf16 v[112:115], v[162:165], v[194:197], v[112:115]
	v_mfma_f32_16x16x32_bf16 v[92:95], v[148:151], v[202:205], v[92:95]
	v_mfma_f32_16x16x32_bf16 v[88:91], v[162:165], v[202:205], v[88:91]
	v_mfma_f32_16x16x32_bf16 v[84:87], v[148:151], v[210:213], v[84:87]
	v_mfma_f32_16x16x32_bf16 v[80:83], v[162:165], v[210:213], v[80:83]
	s_setprio 0
	s_setprio 1
	v_mfma_f32_16x16x32_bf16 v[108:111], v[166:169], v[182:185], v[108:111]
	v_mfma_f32_16x16x32_bf16 v[104:107], v[174:177], v[182:185], v[104:107]
	v_mfma_f32_16x16x32_bf16 v[100:103], v[166:169], v[190:193], v[100:103]
	v_mfma_f32_16x16x32_bf16 v[96:99], v[174:177], v[190:193], v[96:99]
	v_mfma_f32_16x16x32_bf16 v[76:79], v[166:169], v[198:201], v[76:79]
	v_mfma_f32_16x16x32_bf16 v[72:75], v[174:177], v[198:201], v[72:75]
	v_mfma_f32_16x16x32_bf16 v[68:71], v[166:169], v[206:209], v[68:71]
	v_mfma_f32_16x16x32_bf16 v[64:67], v[174:177], v[206:209], v[64:67]
	v_mfma_f32_16x16x32_bf16 v[108:111], v[170:173], v[186:189], v[108:111]
	v_mfma_f32_16x16x32_bf16 v[104:107], v[178:181], v[186:189], v[104:107]
	v_mfma_f32_16x16x32_bf16 v[100:103], v[170:173], v[194:197], v[100:103]
	v_mfma_f32_16x16x32_bf16 v[96:99], v[178:181], v[194:197], v[96:99]
	v_mfma_f32_16x16x32_bf16 v[76:79], v[170:173], v[202:205], v[76:79]
	v_mfma_f32_16x16x32_bf16 v[72:75], v[178:181], v[202:205], v[72:75]
	v_mfma_f32_16x16x32_bf16 v[68:71], v[170:173], v[210:213], v[68:71]
	v_mfma_f32_16x16x32_bf16 v[64:67], v[178:181], v[210:213], v[64:67]
	s_setprio 0
	s_barrier
	s_add_i32 s46, s39, s27
	v_lshl_add_u64 v[214:215], s[20:21], 0, v[130:131]
	s_mov_b32 m0, s46
	s_nop 0
	global_load_lds_dwordx4 v[214:215], off
	s_add_i32 m0, s46, 0x2000
	s_add_u32 s46, s20, 0x160000
	v_lshl_add_u64 v[216:217], s[20:21], 0, v[134:135]
	s_addc_u32 s47, s21, 0
	s_add_i32 s48, s40, s27
	global_load_lds_dwordx4 v[216:217], off
	v_lshl_add_u64 v[218:219], s[46:47], 0, v[130:131]
	s_mov_b32 m0, s48
	v_lshl_add_u64 v[220:221], s[22:23], 0, v[132:133]
	global_load_lds_dwordx4 v[218:219], off
	v_lshl_add_u64 v[218:219], s[46:47], 0, v[134:135]
	s_add_i32 m0, s48, 0x2000
	s_nop 0
	global_load_lds_dwordx4 v[218:219], off
	v_lshl_add_u64 v[218:219], s[22:23], 0, v[128:129]
	s_mov_b32 m0, s30
	s_nop 0
	global_load_lds_dwordx4 v[218:219], off
	s_mov_b32 m0, s31
	s_nop 0
	global_load_lds_dwordx4 v[220:221], off
	ds_read_b128 v[182:185], v157 offset:16384
	ds_read_b128 v[186:189], v157 offset:17408
	ds_read_b128 v[190:193], v157 offset:18432
	ds_read_b128 v[194:197], v157 offset:19456
	ds_read_b128 v[198:201], v157 offset:20480
	ds_read_b128 v[202:205], v157 offset:21504
	ds_read_b128 v[206:209], v157 offset:22528
	ds_read_b128 v[210:213], v157 offset:23552
	s_waitcnt vmcnt(8)
	s_waitcnt lgkmcnt(0)
	s_barrier
	s_setprio 1
	s_waitcnt lgkmcnt(0)
	v_mfma_f32_16x16x32_bf16 v[60:63], v[144:147], v[182:185], v[60:63]
	v_mfma_f32_16x16x32_bf16 v[56:59], v[158:161], v[182:185], v[56:59]
	v_mfma_f32_16x16x32_bf16 v[52:55], v[144:147], v[190:193], v[52:55]
	v_mfma_f32_16x16x32_bf16 v[48:51], v[158:161], v[190:193], v[48:51]
	v_mfma_f32_16x16x32_bf16 v[28:31], v[144:147], v[198:201], v[28:31]
	v_mfma_f32_16x16x32_bf16 v[24:27], v[158:161], v[198:201], v[24:27]
	v_mfma_f32_16x16x32_bf16 v[20:23], v[144:147], v[206:209], v[20:23]
	v_mfma_f32_16x16x32_bf16 v[16:19], v[158:161], v[206:209], v[16:19]
	v_mfma_f32_16x16x32_bf16 v[60:63], v[148:151], v[186:189], v[60:63]
	v_mfma_f32_16x16x32_bf16 v[56:59], v[162:165], v[186:189], v[56:59]
	v_mfma_f32_16x16x32_bf16 v[52:55], v[148:151], v[194:197], v[52:55]
	v_mfma_f32_16x16x32_bf16 v[48:51], v[162:165], v[194:197], v[48:51]
	v_mfma_f32_16x16x32_bf16 v[28:31], v[148:151], v[202:205], v[28:31]
	v_mfma_f32_16x16x32_bf16 v[24:27], v[162:165], v[202:205], v[24:27]
	v_mfma_f32_16x16x32_bf16 v[20:23], v[148:151], v[210:213], v[20:23]
	v_mfma_f32_16x16x32_bf16 v[16:19], v[162:165], v[210:213], v[16:19]
	s_setprio 0
	s_setprio 1
	v_mfma_f32_16x16x32_bf16 v[44:47], v[166:169], v[182:185], v[44:47]
	v_mfma_f32_16x16x32_bf16 v[40:43], v[174:177], v[182:185], v[40:43]
	v_mfma_f32_16x16x32_bf16 v[36:39], v[166:169], v[190:193], v[36:39]
	v_mfma_f32_16x16x32_bf16 v[32:35], v[174:177], v[190:193], v[32:35]
	v_mfma_f32_16x16x32_bf16 v[12:15], v[166:169], v[198:201], v[12:15]
	v_mfma_f32_16x16x32_bf16 v[8:11], v[174:177], v[198:201], v[8:11]
	v_mfma_f32_16x16x32_bf16 v[4:7], v[166:169], v[206:209], v[4:7]
	v_mfma_f32_16x16x32_bf16 v[0:3], v[174:177], v[206:209], v[0:3]
	v_mfma_f32_16x16x32_bf16 v[44:47], v[170:173], v[186:189], v[44:47]
	v_mfma_f32_16x16x32_bf16 v[40:43], v[178:181], v[186:189], v[40:43]
	v_mfma_f32_16x16x32_bf16 v[36:39], v[170:173], v[194:197], v[36:39]
	v_mfma_f32_16x16x32_bf16 v[32:35], v[178:181], v[194:197], v[32:35]
	v_mfma_f32_16x16x32_bf16 v[12:15], v[170:173], v[202:205], v[12:15]
	v_mfma_f32_16x16x32_bf16 v[8:11], v[178:181], v[202:205], v[8:11]
	v_mfma_f32_16x16x32_bf16 v[4:7], v[170:173], v[210:213], v[4:7]
	v_mfma_f32_16x16x32_bf16 v[0:3], v[178:181], v[210:213], v[0:3]
	s_setprio 0
	s_barrier
	s_add_i32 s46, 0, 0x18000
	s_add_i32 s47, 0, 0x1c000
	s_add_u32 s22, s22, 0x160000
	s_addc_u32 s23, s23, 0
	s_mov_b32 m0, s33
	v_lshl_add_u64 v[222:223], s[22:23], 0, v[128:129]
	global_load_lds_dwordx4 v[222:223], off
	v_lshl_add_u64 v[222:223], s[22:23], 0, v[132:133]
	s_mov_b32 m0, s34
	s_nop 0
	global_load_lds_dwordx4 v[222:223], off
	v_add_u32_e32 v162, s46, v153
	v_add_u32_e32 v178, s47, v153
	ds_read_b128 v[144:147], v162
	ds_read_b128 v[148:151], v162 offset:1024
	ds_read_b128 v[158:161], v162 offset:2048
	ds_read_b128 v[162:165], v162 offset:3072
	ds_read_b128 v[166:169], v178
	ds_read_b128 v[170:173], v178 offset:1024
	ds_read_b128 v[174:177], v178 offset:2048
	ds_read_b128 v[178:181], v178 offset:3072
	ds_read_b128 v[182:185], v157 offset:32768
	ds_read_b128 v[186:189], v157 offset:33792
	ds_read_b128 v[190:193], v157 offset:34816
	ds_read_b128 v[194:197], v157 offset:35840
	ds_read_b128 v[198:201], v157 offset:36864
	ds_read_b128 v[202:205], v157 offset:37888
	ds_read_b128 v[206:209], v157 offset:38912
	ds_read_b128 v[210:213], v157 offset:39936
	s_waitcnt vmcnt(8)
	s_waitcnt lgkmcnt(0)
	s_barrier
	s_setprio 1
	s_waitcnt lgkmcnt(0)
	v_mfma_f32_16x16x32_bf16 v[124:127], v[144:147], v[182:185], v[124:127]
	v_mfma_f32_16x16x32_bf16 v[120:123], v[158:161], v[182:185], v[120:123]
	v_mfma_f32_16x16x32_bf16 v[116:119], v[144:147], v[190:193], v[116:119]
	v_mfma_f32_16x16x32_bf16 v[112:115], v[158:161], v[190:193], v[112:115]
	v_mfma_f32_16x16x32_bf16 v[92:95], v[144:147], v[198:201], v[92:95]
	v_mfma_f32_16x16x32_bf16 v[88:91], v[158:161], v[198:201], v[88:91]
	v_mfma_f32_16x16x32_bf16 v[84:87], v[144:147], v[206:209], v[84:87]
	v_mfma_f32_16x16x32_bf16 v[80:83], v[158:161], v[206:209], v[80:83]
	v_mfma_f32_16x16x32_bf16 v[124:127], v[148:151], v[186:189], v[124:127]
	v_mfma_f32_16x16x32_bf16 v[120:123], v[162:165], v[186:189], v[120:123]
	v_mfma_f32_16x16x32_bf16 v[116:119], v[148:151], v[194:197], v[116:119]
	v_mfma_f32_16x16x32_bf16 v[112:115], v[162:165], v[194:197], v[112:115]
	v_mfma_f32_16x16x32_bf16 v[92:95], v[148:151], v[202:205], v[92:95]
	v_mfma_f32_16x16x32_bf16 v[88:91], v[162:165], v[202:205], v[88:91]
	v_mfma_f32_16x16x32_bf16 v[84:87], v[148:151], v[210:213], v[84:87]
	v_mfma_f32_16x16x32_bf16 v[80:83], v[162:165], v[210:213], v[80:83]
	s_setprio 0
	s_setprio 1
	v_mfma_f32_16x16x32_bf16 v[108:111], v[166:169], v[182:185], v[108:111]
	v_mfma_f32_16x16x32_bf16 v[104:107], v[174:177], v[182:185], v[104:107]
	v_mfma_f32_16x16x32_bf16 v[100:103], v[166:169], v[190:193], v[100:103]
	v_mfma_f32_16x16x32_bf16 v[96:99], v[174:177], v[190:193], v[96:99]
	v_mfma_f32_16x16x32_bf16 v[76:79], v[166:169], v[198:201], v[76:79]
	v_mfma_f32_16x16x32_bf16 v[72:75], v[174:177], v[198:201], v[72:75]
	v_mfma_f32_16x16x32_bf16 v[68:71], v[166:169], v[206:209], v[68:71]
	v_mfma_f32_16x16x32_bf16 v[64:67], v[174:177], v[206:209], v[64:67]
	v_mfma_f32_16x16x32_bf16 v[108:111], v[170:173], v[186:189], v[108:111]
	v_mfma_f32_16x16x32_bf16 v[104:107], v[178:181], v[186:189], v[104:107]
	v_mfma_f32_16x16x32_bf16 v[100:103], v[170:173], v[194:197], v[100:103]
	v_mfma_f32_16x16x32_bf16 v[96:99], v[178:181], v[194:197], v[96:99]
	v_mfma_f32_16x16x32_bf16 v[76:79], v[170:173], v[202:205], v[76:79]
	v_mfma_f32_16x16x32_bf16 v[72:75], v[178:181], v[202:205], v[72:75]
	v_mfma_f32_16x16x32_bf16 v[68:71], v[170:173], v[210:213], v[68:71]
	v_mfma_f32_16x16x32_bf16 v[64:67], v[178:181], v[210:213], v[64:67]
	s_setprio 0
	s_barrier
	s_add_i32 s22, s46, s27
	v_lshl_add_u64 v[214:215], v[214:215], 0, s[12:13]
	s_mov_b32 m0, s22
	s_nop 0
	global_load_lds_dwordx4 v[214:215], off
	s_add_i32 m0, s22, 0x2000
	s_add_u32 s20, s20, 0x160080
	v_lshl_add_u64 v[214:215], v[216:217], 0, s[12:13]
	s_addc_u32 s21, s21, 0
	s_add_i32 s22, s47, s27
	global_load_lds_dwordx4 v[214:215], off
	v_lshl_add_u64 v[214:215], s[20:21], 0, v[130:131]
	s_mov_b32 m0, s22
	s_nop 0
	global_load_lds_dwordx4 v[214:215], off
	v_lshl_add_u64 v[214:215], s[20:21], 0, v[134:135]
	s_add_i32 m0, s22, 0x2000
	s_nop 0
	global_load_lds_dwordx4 v[214:215], off
	v_lshl_add_u64 v[214:215], v[218:219], 0, s[12:13]
	s_mov_b32 m0, s36
	s_nop 0
	global_load_lds_dwordx4 v[214:215], off
	v_lshl_add_u64 v[214:215], v[220:221], 0, s[12:13]
	s_mov_b32 m0, s37
	s_nop 0
	global_load_lds_dwordx4 v[214:215], off
	ds_read_b128 v[182:185], v157 offset:49152
	ds_read_b128 v[186:189], v157 offset:50176
	ds_read_b128 v[190:193], v157 offset:51200
	ds_read_b128 v[194:197], v157 offset:52224
	ds_read_b128 v[198:201], v157 offset:53248
	ds_read_b128 v[202:205], v157 offset:54272
	ds_read_b128 v[206:209], v157 offset:55296
	ds_read_b128 v[210:213], v157 offset:56320
	s_waitcnt vmcnt(8)
	s_waitcnt lgkmcnt(0)
	s_barrier
	s_setprio 1
	s_waitcnt lgkmcnt(0)
	v_mfma_f32_16x16x32_bf16 v[60:63], v[144:147], v[182:185], v[60:63]
	v_mfma_f32_16x16x32_bf16 v[56:59], v[158:161], v[182:185], v[56:59]
	v_mfma_f32_16x16x32_bf16 v[52:55], v[144:147], v[190:193], v[52:55]
	v_mfma_f32_16x16x32_bf16 v[48:51], v[158:161], v[190:193], v[48:51]
	v_mfma_f32_16x16x32_bf16 v[28:31], v[144:147], v[198:201], v[28:31]
	v_mfma_f32_16x16x32_bf16 v[24:27], v[158:161], v[198:201], v[24:27]
	v_mfma_f32_16x16x32_bf16 v[20:23], v[144:147], v[206:209], v[20:23]
	v_mfma_f32_16x16x32_bf16 v[16:19], v[158:161], v[206:209], v[16:19]
	v_mfma_f32_16x16x32_bf16 v[60:63], v[148:151], v[186:189], v[60:63]
	v_mfma_f32_16x16x32_bf16 v[56:59], v[162:165], v[186:189], v[56:59]
	v_mfma_f32_16x16x32_bf16 v[52:55], v[148:151], v[194:197], v[52:55]
	v_mfma_f32_16x16x32_bf16 v[48:51], v[162:165], v[194:197], v[48:51]
	v_mfma_f32_16x16x32_bf16 v[28:31], v[148:151], v[202:205], v[28:31]
	v_mfma_f32_16x16x32_bf16 v[24:27], v[162:165], v[202:205], v[24:27]
	v_mfma_f32_16x16x32_bf16 v[20:23], v[148:151], v[210:213], v[20:23]
	v_mfma_f32_16x16x32_bf16 v[16:19], v[162:165], v[210:213], v[16:19]
	s_setprio 0
	s_setprio 1
	v_mfma_f32_16x16x32_bf16 v[44:47], v[166:169], v[182:185], v[44:47]
	v_mfma_f32_16x16x32_bf16 v[40:43], v[174:177], v[182:185], v[40:43]
	v_mfma_f32_16x16x32_bf16 v[36:39], v[166:169], v[190:193], v[36:39]
	v_mfma_f32_16x16x32_bf16 v[32:35], v[174:177], v[190:193], v[32:35]
	v_mfma_f32_16x16x32_bf16 v[12:15], v[166:169], v[198:201], v[12:15]
	v_mfma_f32_16x16x32_bf16 v[8:11], v[174:177], v[198:201], v[8:11]
	v_mfma_f32_16x16x32_bf16 v[4:7], v[166:169], v[206:209], v[4:7]
	v_mfma_f32_16x16x32_bf16 v[0:3], v[174:177], v[206:209], v[0:3]
	v_mfma_f32_16x16x32_bf16 v[44:47], v[170:173], v[186:189], v[44:47]
	v_mfma_f32_16x16x32_bf16 v[40:43], v[178:181], v[186:189], v[40:43]
	v_mfma_f32_16x16x32_bf16 v[36:39], v[170:173], v[194:197], v[36:39]
	v_mfma_f32_16x16x32_bf16 v[32:35], v[178:181], v[194:197], v[32:35]
	v_mfma_f32_16x16x32_bf16 v[12:15], v[170:173], v[202:205], v[12:15]
	v_mfma_f32_16x16x32_bf16 v[8:11], v[178:181], v[202:205], v[8:11]
	v_mfma_f32_16x16x32_bf16 v[4:7], v[170:173], v[210:213], v[4:7]
	v_mfma_f32_16x16x32_bf16 v[0:3], v[178:181], v[210:213], v[0:3]
	s_setprio 0
	s_barrier
	s_add_i32 s45, s45, 2
	s_add_u32 s18, s18, 0x100
	s_addc_u32 s19, s19, 0
	s_add_u32 s0, s0, 0x100
	s_addc_u32 s1, s1, 0
	s_cmpk_gt_u32 s45, 0x55
	s_cbranch_scc0 .LBB0_3930
	s_and_b64 vcc, exec, s[14:15]
	s_cbranch_vccz .LBB0_3933
	s_barrier
